# row phases: first row's loads issued before the wait for the LDS parameter staging (staging temporaries moved to the second row buffer)
# speedup vs baseline: 1.0012x; 1.0012x over previous
.LBB0_100:
	s_cmp_lt_i32 s72, 3
	s_cselect_b64 s[0:1], -1, 0
	s_cmp_gt_i32 s73, 2
	s_cselect_b64 s[4:5], -1, 0
	s_and_b64 s[0:1], s[0:1], s[4:5]
	s_andn2_b64 vcc, exec, s[0:1]
	s_cbranch_vccnz .LBB0_104
	s_lshl_b32 s3, s2, 3
	s_add_i32 s4, s96, s3
	s_cmpk_gt_i32 s4, 0x2fff
	s_cbranch_scc1 .LBB0_104
	s_cmp_lg_u32 s33, 0x100
	s_cbranch_scc1 .Lh1_old
	v_readlane_b32 s12, v255, 6
	v_readlane_b32 s13, v255, 7
	v_lshl_add_u32 v162, s96, 6, v174
	v_lshlrev_b32_e32 v162, 4, v162
	v_add_u32_e32 v163, 0x2000, v162
	v_add_u32_e32 v164, 0x10000, v162
	v_add_u32_e32 v165, 0x12000, v162
	s_lshr_b32 s3, s2, 7
	s_add_i32 s5, s3, 1
	s_mul_i32 s5, s5, 0x18000
	s_add_u32 s18, s28, s5
	s_addc_u32 s19, s29, 0
	s_add_i32 s5, s3, 3
	s_mul_i32 s5, s5, 0x18000
	s_add_u32 s22, s28, s5
	s_addc_u32 s23, s29, 0
	s_nop 4
	s_add_u32 s6, s28, 0x4000
	s_addc_u32 s7, s29, 0
	s_add_u32 s8, s18, 0x4000
	s_addc_u32 s9, s19, 0
	s_add_u32 s36, s22, 0x4000
	s_addc_u32 s37, s23, 0
	global_load_dwordx4 v[66:69], v162, s[12:13]
	global_load_dwordx4 v[70:73], v163, s[12:13]
	global_load_dwordx4 v[74:77], v162, s[28:29]
	global_load_dwordx4 v[78:81], v163, s[28:29]
	global_load_dwordx4 v[82:85], v162, s[6:7]
	global_load_dwordx4 v[86:89], v163, s[6:7]
	global_load_dwordx4 v[90:93], v162, s[18:19]
	global_load_dwordx4 v[94:97], v163, s[18:19]
	global_load_dwordx4 v[98:101], v162, s[8:9]
	global_load_dwordx4 v[102:105], v163, s[8:9]
	global_load_dwordx4 v[106:109], v162, s[22:23]
	global_load_dwordx4 v[110:113], v163, s[22:23]
	global_load_dwordx4 v[114:117], v162, s[36:37]
	global_load_dwordx4 v[118:121], v163, s[36:37]
	v_lshlrev_b32_e32 v238, 4, v174
	v_add_u32_e32 v239, 0x10000, v238
	v_add_u32_e32 v241, 0x1000, v238
	v_add_u32_e32 v242, 0x2000, v238
	v_add_u32_e32 v243, 0x3000, v238
	v_lshlrev_b32_e32 v244, 3, v174
	v_add_u32_e32 v245, 0x1000, v244
	v_xor_b32_e32 v246, 1, v174
	v_lshlrev_b32_e32 v246, 2, v246
	v_xor_b32_e32 v247, 2, v174
	v_lshlrev_b32_e32 v247, 2, v247
	v_xor_b32_e32 v248, 4, v174
	v_lshlrev_b32_e32 v248, 2, v248
	v_xor_b32_e32 v249, 8, v174
	v_lshlrev_b32_e32 v249, 2, v249
	v_xor_b32_e32 v250, 16, v174
	v_lshlrev_b32_e32 v250, 2, v250
	v_xor_b32_e32 v251, 32, v174
	v_lshlrev_b32_e32 v251, 2, v251
	s_mov_b32 s20, 0x800000
	s_lshl_b32 s5, s4, 14
	s_add_u32 s14, s52, s5
	s_addc_u32 s15, s53, 0
	s_add_u32 s42, s54, s5
	s_addc_u32 s43, s55, 0
	s_lshl_b32 s5, s4, 13
	s_add_u32 s16, s70, s5
	s_addc_u32 s17, s71, 0
	s_add_u32 s16, s16, 0x3f000000
	s_addc_u32 s17, s17, 0
	global_load_dwordx4 v[2:5], v238, s[14:15] offset:0 nt
	global_load_dwordx4 v[6:9], v238, s[14:15] offset:1024 nt
	global_load_dwordx4 v[10:13], v238, s[14:15] offset:2048 nt
	global_load_dwordx4 v[14:17], v238, s[14:15] offset:3072 nt
	global_load_dwordx4 v[18:21], v241, s[14:15] offset:0 nt
	global_load_dwordx4 v[22:25], v241, s[14:15] offset:1024 nt
	global_load_dwordx4 v[26:29], v241, s[14:15] offset:2048 nt
	global_load_dwordx4 v[30:33], v241, s[14:15] offset:3072 nt
	global_load_dwordx4 v[34:37], v242, s[14:15] offset:0 nt
	global_load_dwordx4 v[38:41], v242, s[14:15] offset:1024 nt
	global_load_dwordx4 v[42:45], v242, s[14:15] offset:2048 nt
	global_load_dwordx4 v[46:49], v242, s[14:15] offset:3072 nt
	global_load_dwordx4 v[50:53], v243, s[14:15] offset:0 nt
	global_load_dwordx4 v[54:57], v243, s[14:15] offset:1024 nt
	global_load_dwordx4 v[58:61], v243, s[14:15] offset:2048 nt
	global_load_dwordx4 v[62:65], v243, s[14:15] offset:3072 nt
	s_waitcnt vmcnt(16)
	ds_write_b128 v162, v[66:69] offset:0
	ds_write_b128 v162, v[70:73] offset:8192
	ds_write_b128 v162, v[74:77] offset:16384
	ds_write_b128 v162, v[78:81] offset:24576
	ds_write_b128 v162, v[82:85] offset:32768
	ds_write_b128 v162, v[86:89] offset:40960
	ds_write_b128 v162, v[90:93] offset:49152
	ds_write_b128 v162, v[94:97] offset:57344
	ds_write_b128 v164, v[98:101] offset:0
	ds_write_b128 v164, v[102:105] offset:8192
	ds_write_b128 v164, v[106:109] offset:16384
	ds_write_b128 v164, v[110:113] offset:24576
	ds_write_b128 v164, v[114:117] offset:32768
	ds_write_b128 v164, v[118:121] offset:40960
	s_waitcnt lgkmcnt(0)
	s_barrier
	s_waitcnt vmcnt(0)
	s_add_u32 s14, s14, 0x2000000
	s_addc_u32 s15, s15, 0
	global_load_dwordx4 v[66:69], v238, s[14:15] offset:0 nt
	global_load_dwordx4 v[70:73], v238, s[14:15] offset:1024 nt
	global_load_dwordx4 v[74:77], v238, s[14:15] offset:2048 nt
	global_load_dwordx4 v[78:81], v238, s[14:15] offset:3072 nt
	global_load_dwordx4 v[82:85], v241, s[14:15] offset:0 nt
	global_load_dwordx4 v[86:89], v241, s[14:15] offset:1024 nt
	global_load_dwordx4 v[90:93], v241, s[14:15] offset:2048 nt
	global_load_dwordx4 v[94:97], v241, s[14:15] offset:3072 nt
	global_load_dwordx4 v[98:101], v242, s[14:15] offset:0 nt
	global_load_dwordx4 v[102:105], v242, s[14:15] offset:1024 nt
	global_load_dwordx4 v[106:109], v242, s[14:15] offset:2048 nt
	global_load_dwordx4 v[110:113], v242, s[14:15] offset:3072 nt
	global_load_dwordx4 v[114:117], v243, s[14:15] offset:0 nt
	global_load_dwordx4 v[118:121], v243, s[14:15] offset:1024 nt
	global_load_dwordx4 v[122:125], v243, s[14:15] offset:2048 nt
	global_load_dwordx4 v[126:129], v243, s[14:15] offset:3072 nt
	ds_read_b128 v[130:133], v238 offset:0
	ds_read_b128 v[134:137], v238 offset:16384
	ds_read_b128 v[138:141], v238 offset:32768
	ds_read_b128 v[142:145], v238 offset:1024
	ds_read_b128 v[146:149], v238 offset:17408
	ds_read_b128 v[150:153], v238 offset:33792
	v_pk_mul_f32 v[156:157], v[2:3], v[2:3]
	v_pk_mul_f32 v[158:159], v[4:5], v[4:5]
	v_pk_fma_f32 v[156:157], v[6:7], v[6:7], v[156:157]
	v_pk_fma_f32 v[158:159], v[8:9], v[8:9], v[158:159]
	v_pk_fma_f32 v[156:157], v[10:11], v[10:11], v[156:157]
	v_pk_fma_f32 v[158:159], v[12:13], v[12:13], v[158:159]
	v_pk_fma_f32 v[156:157], v[14:15], v[14:15], v[156:157]
	v_pk_fma_f32 v[158:159], v[16:17], v[16:17], v[158:159]
	v_pk_fma_f32 v[156:157], v[18:19], v[18:19], v[156:157]
	v_pk_fma_f32 v[158:159], v[20:21], v[20:21], v[158:159]
	v_pk_fma_f32 v[156:157], v[22:23], v[22:23], v[156:157]
	v_pk_fma_f32 v[158:159], v[24:25], v[24:25], v[158:159]
	v_pk_fma_f32 v[156:157], v[26:27], v[26:27], v[156:157]
	v_pk_fma_f32 v[158:159], v[28:29], v[28:29], v[158:159]
	v_pk_fma_f32 v[156:157], v[30:31], v[30:31], v[156:157]
	v_pk_fma_f32 v[158:159], v[32:33], v[32:33], v[158:159]
	v_pk_fma_f32 v[156:157], v[34:35], v[34:35], v[156:157]
	v_pk_fma_f32 v[158:159], v[36:37], v[36:37], v[158:159]
	v_pk_fma_f32 v[156:157], v[38:39], v[38:39], v[156:157]
	v_pk_fma_f32 v[158:159], v[40:41], v[40:41], v[158:159]
	v_pk_fma_f32 v[156:157], v[42:43], v[42:43], v[156:157]
	v_pk_fma_f32 v[158:159], v[44:45], v[44:45], v[158:159]
	v_pk_fma_f32 v[156:157], v[46:47], v[46:47], v[156:157]
	v_pk_fma_f32 v[158:159], v[48:49], v[48:49], v[158:159]
	v_pk_fma_f32 v[156:157], v[50:51], v[50:51], v[156:157]
	v_pk_fma_f32 v[158:159], v[52:53], v[52:53], v[158:159]
	v_pk_fma_f32 v[156:157], v[54:55], v[54:55], v[156:157]
	v_pk_fma_f32 v[158:159], v[56:57], v[56:57], v[158:159]
	v_pk_fma_f32 v[156:157], v[58:59], v[58:59], v[156:157]
	v_pk_fma_f32 v[158:159], v[60:61], v[60:61], v[158:159]
	v_pk_fma_f32 v[156:157], v[62:63], v[62:63], v[156:157]
	v_pk_fma_f32 v[158:159], v[64:65], v[64:65], v[158:159]
	v_pk_add_f32 v[156:157], v[156:157], v[158:159]
	s_nop 0
	v_add_f32_e32 v252, v156, v157
	s_waitcnt lgkmcnt(0)
	ds_bpermute_b32 v254, v246, v252
	s_waitcnt lgkmcnt(0)
	v_add_f32_e32 v252, v252, v254
	ds_bpermute_b32 v254, v247, v252
	s_waitcnt lgkmcnt(0)
	v_add_f32_e32 v252, v252, v254
	ds_bpermute_b32 v254, v248, v252
	s_waitcnt lgkmcnt(0)
	v_add_f32_e32 v252, v252, v254
	ds_bpermute_b32 v254, v249, v252
	s_waitcnt lgkmcnt(0)
	v_add_f32_e32 v252, v252, v254
	ds_bpermute_b32 v254, v250, v252
	s_waitcnt lgkmcnt(0)
	v_add_f32_e32 v252, v252, v254
	ds_bpermute_b32 v254, v251, v252
	s_waitcnt lgkmcnt(0)
	v_add_f32_e32 v252, v252, v254
	v_mov_b32_e32 v254, 0x358637bd
	v_fmac_f32_e32 v254, 0x39800000, v252
	v_mul_f32_e32 v252, 0x4b800000, v254
	v_cmp_gt_f32_e32 vcc, s20, v254
	s_nop 1
	v_cndmask_b32_e32 v254, v254, v252, vcc
	v_rsq_f32_e32 v254, v254
	s_nop 0
	v_mul_f32_e32 v252, 0x45800000, v254
	v_cndmask_b32_e32 v252, v254, v252, vcc
	ds_read_b128 v[214:217], v238 offset:2048
	ds_read_b128 v[218:221], v238 offset:18432
	ds_read_b128 v[222:225], v238 offset:34816
	ds_read_b128 v[226:229], v238 offset:3072
	ds_read_b128 v[230:233], v238 offset:19456
	ds_read_b128 v[234:237], v238 offset:35840
	s_waitcnt lgkmcnt(6)
	v_pk_mul_f32 v[2:3], v[2:3], v[252:253] op_sel_hi:[1,0]
	v_pk_mul_f32 v[4:5], v[4:5], v[252:253] op_sel_hi:[1,0]
	v_pk_mul_f32 v[2:3], v[130:131], v[2:3]
	v_pk_mul_f32 v[4:5], v[132:133], v[4:5]
	v_pk_add_f32 v[138:139], v[138:139], 1.0 op_sel_hi:[1,0]
	v_pk_add_f32 v[140:141], v[140:141], 1.0 op_sel_hi:[1,0]
	v_pk_fma_f32 v[2:3], v[138:139], v[2:3], v[134:135]
	v_pk_fma_f32 v[4:5], v[140:141], v[4:5], v[136:137]
	s_nop 0
	v_cvt_pk_bf16_f32 v2, v2, v3
	v_cvt_pk_bf16_f32 v3, v4, v5
	global_store_dwordx2 v244, v[2:3], s[16:17] offset:0
	v_pk_mul_f32 v[6:7], v[6:7], v[252:253] op_sel_hi:[1,0]
	v_pk_mul_f32 v[8:9], v[8:9], v[252:253] op_sel_hi:[1,0]
	v_pk_mul_f32 v[6:7], v[142:143], v[6:7]
	v_pk_mul_f32 v[8:9], v[144:145], v[8:9]
	v_pk_add_f32 v[150:151], v[150:151], 1.0 op_sel_hi:[1,0]
	v_pk_add_f32 v[152:153], v[152:153], 1.0 op_sel_hi:[1,0]
	v_pk_fma_f32 v[6:7], v[150:151], v[6:7], v[146:147]
	v_pk_fma_f32 v[8:9], v[152:153], v[8:9], v[148:149]
	s_nop 0
	v_cvt_pk_bf16_f32 v6, v6, v7
	v_cvt_pk_bf16_f32 v7, v8, v9
	global_store_dwordx2 v244, v[6:7], s[16:17] offset:512
	ds_read_b128 v[130:133], v238 offset:4096
	ds_read_b128 v[134:137], v238 offset:20480
	ds_read_b128 v[138:141], v238 offset:36864
	ds_read_b128 v[142:145], v238 offset:5120
	ds_read_b128 v[146:149], v238 offset:21504
	ds_read_b128 v[150:153], v238 offset:37888
	s_waitcnt lgkmcnt(6)
	v_pk_mul_f32 v[10:11], v[10:11], v[252:253] op_sel_hi:[1,0]
	v_pk_mul_f32 v[12:13], v[12:13], v[252:253] op_sel_hi:[1,0]
	v_pk_mul_f32 v[10:11], v[214:215], v[10:11]
	v_pk_mul_f32 v[12:13], v[216:217], v[12:13]
	v_pk_add_f32 v[222:223], v[222:223], 1.0 op_sel_hi:[1,0]
	v_pk_add_f32 v[224:225], v[224:225], 1.0 op_sel_hi:[1,0]
	v_pk_fma_f32 v[10:11], v[222:223], v[10:11], v[218:219]
	v_pk_fma_f32 v[12:13], v[224:225], v[12:13], v[220:221]
	s_nop 0
	v_cvt_pk_bf16_f32 v10, v10, v11
	v_cvt_pk_bf16_f32 v11, v12, v13
	global_store_dwordx2 v244, v[10:11], s[16:17] offset:1024
	v_pk_mul_f32 v[14:15], v[14:15], v[252:253] op_sel_hi:[1,0]
	v_pk_mul_f32 v[16:17], v[16:17], v[252:253] op_sel_hi:[1,0]
	v_pk_mul_f32 v[14:15], v[226:227], v[14:15]
	v_pk_mul_f32 v[16:17], v[228:229], v[16:17]
	v_pk_add_f32 v[234:235], v[234:235], 1.0 op_sel_hi:[1,0]
	v_pk_add_f32 v[236:237], v[236:237], 1.0 op_sel_hi:[1,0]
	v_pk_fma_f32 v[14:15], v[234:235], v[14:15], v[230:231]
	v_pk_fma_f32 v[16:17], v[236:237], v[16:17], v[232:233]
	s_nop 0
	v_cvt_pk_bf16_f32 v14, v14, v15
	v_cvt_pk_bf16_f32 v15, v16, v17
	global_store_dwordx2 v244, v[14:15], s[16:17] offset:1536
	ds_read_b128 v[214:217], v238 offset:6144
	ds_read_b128 v[218:221], v238 offset:22528
	ds_read_b128 v[222:225], v238 offset:38912
	ds_read_b128 v[226:229], v238 offset:7168
	ds_read_b128 v[230:233], v238 offset:23552
	ds_read_b128 v[234:237], v238 offset:39936
	s_waitcnt lgkmcnt(6)
	v_pk_mul_f32 v[18:19], v[18:19], v[252:253] op_sel_hi:[1,0]
	v_pk_mul_f32 v[20:21], v[20:21], v[252:253] op_sel_hi:[1,0]
	v_pk_mul_f32 v[18:19], v[130:131], v[18:19]
	v_pk_mul_f32 v[20:21], v[132:133], v[20:21]
	v_pk_add_f32 v[138:139], v[138:139], 1.0 op_sel_hi:[1,0]
	v_pk_add_f32 v[140:141], v[140:141], 1.0 op_sel_hi:[1,0]
	v_pk_fma_f32 v[18:19], v[138:139], v[18:19], v[134:135]
	v_pk_fma_f32 v[20:21], v[140:141], v[20:21], v[136:137]
	s_nop 0
	v_cvt_pk_bf16_f32 v18, v18, v19
	v_cvt_pk_bf16_f32 v19, v20, v21
	global_store_dwordx2 v244, v[18:19], s[16:17] offset:2048
	v_pk_mul_f32 v[22:23], v[22:23], v[252:253] op_sel_hi:[1,0]
	v_pk_mul_f32 v[24:25], v[24:25], v[252:253] op_sel_hi:[1,0]
	v_pk_mul_f32 v[22:23], v[142:143], v[22:23]
	v_pk_mul_f32 v[24:25], v[144:145], v[24:25]
	v_pk_add_f32 v[150:151], v[150:151], 1.0 op_sel_hi:[1,0]
	v_pk_add_f32 v[152:153], v[152:153], 1.0 op_sel_hi:[1,0]
	v_pk_fma_f32 v[22:23], v[150:151], v[22:23], v[146:147]
	v_pk_fma_f32 v[24:25], v[152:153], v[24:25], v[148:149]
	s_nop 0
	v_cvt_pk_bf16_f32 v22, v22, v23
	v_cvt_pk_bf16_f32 v23, v24, v25
	global_store_dwordx2 v244, v[22:23], s[16:17] offset:2560
	ds_read_b128 v[130:133], v238 offset:8192
	ds_read_b128 v[134:137], v238 offset:24576
	ds_read_b128 v[138:141], v238 offset:40960
	ds_read_b128 v[142:145], v238 offset:9216
	ds_read_b128 v[146:149], v238 offset:25600
	ds_read_b128 v[150:153], v238 offset:41984
	s_waitcnt lgkmcnt(6)
	v_pk_mul_f32 v[26:27], v[26:27], v[252:253] op_sel_hi:[1,0]
	v_pk_mul_f32 v[28:29], v[28:29], v[252:253] op_sel_hi:[1,0]
	v_pk_mul_f32 v[26:27], v[214:215], v[26:27]
	v_pk_mul_f32 v[28:29], v[216:217], v[28:29]
	v_pk_add_f32 v[222:223], v[222:223], 1.0 op_sel_hi:[1,0]
	v_pk_add_f32 v[224:225], v[224:225], 1.0 op_sel_hi:[1,0]
	v_pk_fma_f32 v[26:27], v[222:223], v[26:27], v[218:219]
	v_pk_fma_f32 v[28:29], v[224:225], v[28:29], v[220:221]
	s_nop 0
	v_cvt_pk_bf16_f32 v26, v26, v27
	v_cvt_pk_bf16_f32 v27, v28, v29
	global_store_dwordx2 v244, v[26:27], s[16:17] offset:3072
	v_pk_mul_f32 v[30:31], v[30:31], v[252:253] op_sel_hi:[1,0]
	v_pk_mul_f32 v[32:33], v[32:33], v[252:253] op_sel_hi:[1,0]
	v_pk_mul_f32 v[30:31], v[226:227], v[30:31]
	v_pk_mul_f32 v[32:33], v[228:229], v[32:33]
	v_pk_add_f32 v[234:235], v[234:235], 1.0 op_sel_hi:[1,0]
	v_pk_add_f32 v[236:237], v[236:237], 1.0 op_sel_hi:[1,0]
	v_pk_fma_f32 v[30:31], v[234:235], v[30:31], v[230:231]
	v_pk_fma_f32 v[32:33], v[236:237], v[32:33], v[232:233]
	s_nop 0
	v_cvt_pk_bf16_f32 v30, v30, v31
	v_cvt_pk_bf16_f32 v31, v32, v33
	global_store_dwordx2 v244, v[30:31], s[16:17] offset:3584
	ds_read_b128 v[214:217], v238 offset:10240
	ds_read_b128 v[218:221], v238 offset:26624
	ds_read_b128 v[222:225], v238 offset:43008
	ds_read_b128 v[226:229], v238 offset:11264
	ds_read_b128 v[230:233], v238 offset:27648
	ds_read_b128 v[234:237], v238 offset:44032
	s_waitcnt lgkmcnt(6)
	v_pk_mul_f32 v[34:35], v[34:35], v[252:253] op_sel_hi:[1,0]
	v_pk_mul_f32 v[36:37], v[36:37], v[252:253] op_sel_hi:[1,0]
	v_pk_mul_f32 v[34:35], v[130:131], v[34:35]
	v_pk_mul_f32 v[36:37], v[132:133], v[36:37]
	v_pk_add_f32 v[138:139], v[138:139], 1.0 op_sel_hi:[1,0]
	v_pk_add_f32 v[140:141], v[140:141], 1.0 op_sel_hi:[1,0]
	v_pk_fma_f32 v[34:35], v[138:139], v[34:35], v[134:135]
	v_pk_fma_f32 v[36:37], v[140:141], v[36:37], v[136:137]
	s_nop 0
	v_cvt_pk_bf16_f32 v34, v34, v35
	v_cvt_pk_bf16_f32 v35, v36, v37
	global_store_dwordx2 v245, v[34:35], s[16:17] offset:0
	v_pk_mul_f32 v[38:39], v[38:39], v[252:253] op_sel_hi:[1,0]
	v_pk_mul_f32 v[40:41], v[40:41], v[252:253] op_sel_hi:[1,0]
	v_pk_mul_f32 v[38:39], v[142:143], v[38:39]
	v_pk_mul_f32 v[40:41], v[144:145], v[40:41]
	v_pk_add_f32 v[150:151], v[150:151], 1.0 op_sel_hi:[1,0]
	v_pk_add_f32 v[152:153], v[152:153], 1.0 op_sel_hi:[1,0]
	v_pk_fma_f32 v[38:39], v[150:151], v[38:39], v[146:147]
	v_pk_fma_f32 v[40:41], v[152:153], v[40:41], v[148:149]
	s_nop 0
	v_cvt_pk_bf16_f32 v38, v38, v39
	v_cvt_pk_bf16_f32 v39, v40, v41
	global_store_dwordx2 v245, v[38:39], s[16:17] offset:512
	ds_read_b128 v[130:133], v238 offset:12288
	ds_read_b128 v[134:137], v238 offset:28672
	ds_read_b128 v[138:141], v238 offset:45056
	ds_read_b128 v[142:145], v238 offset:13312
	ds_read_b128 v[146:149], v238 offset:29696
	ds_read_b128 v[150:153], v238 offset:46080
	s_waitcnt lgkmcnt(6)
	v_pk_mul_f32 v[42:43], v[42:43], v[252:253] op_sel_hi:[1,0]
	v_pk_mul_f32 v[44:45], v[44:45], v[252:253] op_sel_hi:[1,0]
	v_pk_mul_f32 v[42:43], v[214:215], v[42:43]
	v_pk_mul_f32 v[44:45], v[216:217], v[44:45]
	v_pk_add_f32 v[222:223], v[222:223], 1.0 op_sel_hi:[1,0]
	v_pk_add_f32 v[224:225], v[224:225], 1.0 op_sel_hi:[1,0]
	v_pk_fma_f32 v[42:43], v[222:223], v[42:43], v[218:219]
	v_pk_fma_f32 v[44:45], v[224:225], v[44:45], v[220:221]
	s_nop 0
	v_cvt_pk_bf16_f32 v42, v42, v43
	v_cvt_pk_bf16_f32 v43, v44, v45
	global_store_dwordx2 v245, v[42:43], s[16:17] offset:1024
	v_pk_mul_f32 v[46:47], v[46:47], v[252:253] op_sel_hi:[1,0]
	v_pk_mul_f32 v[48:49], v[48:49], v[252:253] op_sel_hi:[1,0]
	v_pk_mul_f32 v[46:47], v[226:227], v[46:47]
	v_pk_mul_f32 v[48:49], v[228:229], v[48:49]
	v_pk_add_f32 v[234:235], v[234:235], 1.0 op_sel_hi:[1,0]
	v_pk_add_f32 v[236:237], v[236:237], 1.0 op_sel_hi:[1,0]
	v_pk_fma_f32 v[46:47], v[234:235], v[46:47], v[230:231]
	v_pk_fma_f32 v[48:49], v[236:237], v[48:49], v[232:233]
	s_nop 0
	v_cvt_pk_bf16_f32 v46, v46, v47
	v_cvt_pk_bf16_f32 v47, v48, v49
	global_store_dwordx2 v245, v[46:47], s[16:17] offset:1536
	ds_read_b128 v[214:217], v238 offset:14336
	ds_read_b128 v[218:221], v238 offset:30720
	ds_read_b128 v[222:225], v238 offset:47104
	ds_read_b128 v[226:229], v238 offset:15360
	ds_read_b128 v[230:233], v238 offset:31744
	ds_read_b128 v[234:237], v238 offset:48128
	s_waitcnt lgkmcnt(6)
	v_pk_mul_f32 v[50:51], v[50:51], v[252:253] op_sel_hi:[1,0]
	v_pk_mul_f32 v[52:53], v[52:53], v[252:253] op_sel_hi:[1,0]
	v_pk_mul_f32 v[50:51], v[130:131], v[50:51]
	v_pk_mul_f32 v[52:53], v[132:133], v[52:53]
	v_pk_add_f32 v[138:139], v[138:139], 1.0 op_sel_hi:[1,0]
	v_pk_add_f32 v[140:141], v[140:141], 1.0 op_sel_hi:[1,0]
	v_pk_fma_f32 v[50:51], v[138:139], v[50:51], v[134:135]
	v_pk_fma_f32 v[52:53], v[140:141], v[52:53], v[136:137]
	s_nop 0
	v_cvt_pk_bf16_f32 v50, v50, v51
	v_cvt_pk_bf16_f32 v51, v52, v53
	global_store_dwordx2 v245, v[50:51], s[16:17] offset:2048
	v_pk_mul_f32 v[54:55], v[54:55], v[252:253] op_sel_hi:[1,0]
	v_pk_mul_f32 v[56:57], v[56:57], v[252:253] op_sel_hi:[1,0]
	v_pk_mul_f32 v[54:55], v[142:143], v[54:55]
	v_pk_mul_f32 v[56:57], v[144:145], v[56:57]
	v_pk_add_f32 v[150:151], v[150:151], 1.0 op_sel_hi:[1,0]
	v_pk_add_f32 v[152:153], v[152:153], 1.0 op_sel_hi:[1,0]
	v_pk_fma_f32 v[54:55], v[150:151], v[54:55], v[146:147]
	v_pk_fma_f32 v[56:57], v[152:153], v[56:57], v[148:149]
	s_nop 0
	v_cvt_pk_bf16_f32 v54, v54, v55
	v_cvt_pk_bf16_f32 v55, v56, v57
	global_store_dwordx2 v245, v[54:55], s[16:17] offset:2560
	s_waitcnt lgkmcnt(0)
	v_pk_mul_f32 v[58:59], v[58:59], v[252:253] op_sel_hi:[1,0]
	v_pk_mul_f32 v[60:61], v[60:61], v[252:253] op_sel_hi:[1,0]
	v_pk_mul_f32 v[58:59], v[214:215], v[58:59]
	v_pk_mul_f32 v[60:61], v[216:217], v[60:61]
	v_pk_add_f32 v[222:223], v[222:223], 1.0 op_sel_hi:[1,0]
	v_pk_add_f32 v[224:225], v[224:225], 1.0 op_sel_hi:[1,0]
	v_pk_fma_f32 v[58:59], v[222:223], v[58:59], v[218:219]
	v_pk_fma_f32 v[60:61], v[224:225], v[60:61], v[220:221]
	s_nop 0
	v_cvt_pk_bf16_f32 v58, v58, v59
	v_cvt_pk_bf16_f32 v59, v60, v61
	global_store_dwordx2 v245, v[58:59], s[16:17] offset:3072
	v_pk_mul_f32 v[62:63], v[62:63], v[252:253] op_sel_hi:[1,0]
	v_pk_mul_f32 v[64:65], v[64:65], v[252:253] op_sel_hi:[1,0]
	v_pk_mul_f32 v[62:63], v[226:227], v[62:63]
	v_pk_mul_f32 v[64:65], v[228:229], v[64:65]
	v_pk_add_f32 v[234:235], v[234:235], 1.0 op_sel_hi:[1,0]
	v_pk_add_f32 v[236:237], v[236:237], 1.0 op_sel_hi:[1,0]
	v_pk_fma_f32 v[62:63], v[234:235], v[62:63], v[230:231]
	v_pk_fma_f32 v[64:65], v[236:237], v[64:65], v[232:233]
	s_nop 0
	v_cvt_pk_bf16_f32 v62, v62, v63
	v_cvt_pk_bf16_f32 v63, v64, v65
	global_store_dwordx2 v245, v[62:63], s[16:17] offset:3584
	s_add_u32 s16, s16, 0x1000000
	s_addc_u32 s17, s17, 0
	s_waitcnt vmcnt(16)
	s_add_u32 s14, s14, 0x2000000
	s_addc_u32 s15, s15, 0
	global_load_dwordx4 v[2:5], v238, s[14:15] offset:0 nt
	global_load_dwordx4 v[6:9], v238, s[14:15] offset:1024 nt
	global_load_dwordx4 v[10:13], v238, s[14:15] offset:2048 nt
	global_load_dwordx4 v[14:17], v238, s[14:15] offset:3072 nt
	global_load_dwordx4 v[18:21], v241, s[14:15] offset:0 nt
	global_load_dwordx4 v[22:25], v241, s[14:15] offset:1024 nt
	global_load_dwordx4 v[26:29], v241, s[14:15] offset:2048 nt
	global_load_dwordx4 v[30:33], v241, s[14:15] offset:3072 nt
	global_load_dwordx4 v[34:37], v242, s[14:15] offset:0 nt
	global_load_dwordx4 v[38:41], v242, s[14:15] offset:1024 nt
	global_load_dwordx4 v[42:45], v242, s[14:15] offset:2048 nt
	global_load_dwordx4 v[46:49], v242, s[14:15] offset:3072 nt
	global_load_dwordx4 v[50:53], v243, s[14:15] offset:0 nt
	global_load_dwordx4 v[54:57], v243, s[14:15] offset:1024 nt
	global_load_dwordx4 v[58:61], v243, s[14:15] offset:2048 nt
	global_load_dwordx4 v[62:65], v243, s[14:15] offset:3072 nt
	ds_read_b128 v[130:133], v238 offset:0
	ds_read_b128 v[134:137], v238 offset:16384
	ds_read_b128 v[138:141], v238 offset:32768
	ds_read_b128 v[142:145], v238 offset:1024
	ds_read_b128 v[146:149], v238 offset:17408
	ds_read_b128 v[150:153], v238 offset:33792
	v_pk_mul_f32 v[156:157], v[66:67], v[66:67]
	v_pk_mul_f32 v[158:159], v[68:69], v[68:69]
	v_pk_fma_f32 v[156:157], v[70:71], v[70:71], v[156:157]
	v_pk_fma_f32 v[158:159], v[72:73], v[72:73], v[158:159]
	v_pk_fma_f32 v[156:157], v[74:75], v[74:75], v[156:157]
	v_pk_fma_f32 v[158:159], v[76:77], v[76:77], v[158:159]
	v_pk_fma_f32 v[156:157], v[78:79], v[78:79], v[156:157]
	v_pk_fma_f32 v[158:159], v[80:81], v[80:81], v[158:159]
	v_pk_fma_f32 v[156:157], v[82:83], v[82:83], v[156:157]
	v_pk_fma_f32 v[158:159], v[84:85], v[84:85], v[158:159]
	v_pk_fma_f32 v[156:157], v[86:87], v[86:87], v[156:157]
	v_pk_fma_f32 v[158:159], v[88:89], v[88:89], v[158:159]
	v_pk_fma_f32 v[156:157], v[90:91], v[90:91], v[156:157]
	v_pk_fma_f32 v[158:159], v[92:93], v[92:93], v[158:159]
	v_pk_fma_f32 v[156:157], v[94:95], v[94:95], v[156:157]
	v_pk_fma_f32 v[158:159], v[96:97], v[96:97], v[158:159]
	v_pk_fma_f32 v[156:157], v[98:99], v[98:99], v[156:157]
	v_pk_fma_f32 v[158:159], v[100:101], v[100:101], v[158:159]
	v_pk_fma_f32 v[156:157], v[102:103], v[102:103], v[156:157]
	v_pk_fma_f32 v[158:159], v[104:105], v[104:105], v[158:159]
	v_pk_fma_f32 v[156:157], v[106:107], v[106:107], v[156:157]
	v_pk_fma_f32 v[158:159], v[108:109], v[108:109], v[158:159]
	v_pk_fma_f32 v[156:157], v[110:111], v[110:111], v[156:157]
	v_pk_fma_f32 v[158:159], v[112:113], v[112:113], v[158:159]
	v_pk_fma_f32 v[156:157], v[114:115], v[114:115], v[156:157]
	v_pk_fma_f32 v[158:159], v[116:117], v[116:117], v[158:159]
	v_pk_fma_f32 v[156:157], v[118:119], v[118:119], v[156:157]
	v_pk_fma_f32 v[158:159], v[120:121], v[120:121], v[158:159]
	v_pk_fma_f32 v[156:157], v[122:123], v[122:123], v[156:157]
	v_pk_fma_f32 v[158:159], v[124:125], v[124:125], v[158:159]
	v_pk_fma_f32 v[156:157], v[126:127], v[126:127], v[156:157]
	v_pk_fma_f32 v[158:159], v[128:129], v[128:129], v[158:159]
	v_pk_add_f32 v[156:157], v[156:157], v[158:159]
	s_nop 0
	v_add_f32_e32 v252, v156, v157
	s_waitcnt lgkmcnt(0)
	ds_bpermute_b32 v254, v246, v252
	s_waitcnt lgkmcnt(0)
	v_add_f32_e32 v252, v252, v254
	ds_bpermute_b32 v254, v247, v252
	s_waitcnt lgkmcnt(0)
	v_add_f32_e32 v252, v252, v254
	ds_bpermute_b32 v254, v248, v252
	s_waitcnt lgkmcnt(0)
	v_add_f32_e32 v252, v252, v254
	ds_bpermute_b32 v254, v249, v252
	s_waitcnt lgkmcnt(0)
	v_add_f32_e32 v252, v252, v254
	ds_bpermute_b32 v254, v250, v252
	s_waitcnt lgkmcnt(0)
	v_add_f32_e32 v252, v252, v254
	ds_bpermute_b32 v254, v251, v252
	s_waitcnt lgkmcnt(0)
	v_add_f32_e32 v252, v252, v254
	v_mov_b32_e32 v254, 0x358637bd
	v_fmac_f32_e32 v254, 0x39800000, v252
	v_mul_f32_e32 v252, 0x4b800000, v254
	v_cmp_gt_f32_e32 vcc, s20, v254
	s_nop 1
	v_cndmask_b32_e32 v254, v254, v252, vcc
	v_rsq_f32_e32 v254, v254
	s_nop 0
	v_mul_f32_e32 v252, 0x45800000, v254
	v_cndmask_b32_e32 v252, v254, v252, vcc
	ds_read_b128 v[214:217], v238 offset:2048
	ds_read_b128 v[218:221], v238 offset:18432
	ds_read_b128 v[222:225], v238 offset:34816
	ds_read_b128 v[226:229], v238 offset:3072
	ds_read_b128 v[230:233], v238 offset:19456
	ds_read_b128 v[234:237], v238 offset:35840
	s_waitcnt lgkmcnt(6)
	v_pk_mul_f32 v[66:67], v[66:67], v[252:253] op_sel_hi:[1,0]
	v_pk_mul_f32 v[68:69], v[68:69], v[252:253] op_sel_hi:[1,0]
	v_pk_mul_f32 v[66:67], v[130:131], v[66:67]
	v_pk_mul_f32 v[68:69], v[132:133], v[68:69]
	v_pk_add_f32 v[138:139], v[138:139], 1.0 op_sel_hi:[1,0]
	v_pk_add_f32 v[140:141], v[140:141], 1.0 op_sel_hi:[1,0]
	v_pk_fma_f32 v[66:67], v[138:139], v[66:67], v[134:135]
	v_pk_fma_f32 v[68:69], v[140:141], v[68:69], v[136:137]
	s_nop 0
	v_cvt_pk_bf16_f32 v66, v66, v67
	v_cvt_pk_bf16_f32 v67, v68, v69
	global_store_dwordx2 v244, v[66:67], s[16:17] offset:0
	v_pk_mul_f32 v[70:71], v[70:71], v[252:253] op_sel_hi:[1,0]
	v_pk_mul_f32 v[72:73], v[72:73], v[252:253] op_sel_hi:[1,0]
	v_pk_mul_f32 v[70:71], v[142:143], v[70:71]
	v_pk_mul_f32 v[72:73], v[144:145], v[72:73]
	v_pk_add_f32 v[150:151], v[150:151], 1.0 op_sel_hi:[1,0]
	v_pk_add_f32 v[152:153], v[152:153], 1.0 op_sel_hi:[1,0]
	v_pk_fma_f32 v[70:71], v[150:151], v[70:71], v[146:147]
	v_pk_fma_f32 v[72:73], v[152:153], v[72:73], v[148:149]
	s_nop 0
	v_cvt_pk_bf16_f32 v70, v70, v71
	v_cvt_pk_bf16_f32 v71, v72, v73
	global_store_dwordx2 v244, v[70:71], s[16:17] offset:512
	ds_read_b128 v[130:133], v238 offset:4096
	ds_read_b128 v[134:137], v238 offset:20480
	ds_read_b128 v[138:141], v238 offset:36864
	ds_read_b128 v[142:145], v238 offset:5120
	ds_read_b128 v[146:149], v238 offset:21504
	ds_read_b128 v[150:153], v238 offset:37888
	s_waitcnt lgkmcnt(6)
	v_pk_mul_f32 v[74:75], v[74:75], v[252:253] op_sel_hi:[1,0]
	v_pk_mul_f32 v[76:77], v[76:77], v[252:253] op_sel_hi:[1,0]
	v_pk_mul_f32 v[74:75], v[214:215], v[74:75]
	v_pk_mul_f32 v[76:77], v[216:217], v[76:77]
	v_pk_add_f32 v[222:223], v[222:223], 1.0 op_sel_hi:[1,0]
	v_pk_add_f32 v[224:225], v[224:225], 1.0 op_sel_hi:[1,0]
	v_pk_fma_f32 v[74:75], v[222:223], v[74:75], v[218:219]
	v_pk_fma_f32 v[76:77], v[224:225], v[76:77], v[220:221]
	s_nop 0
	v_cvt_pk_bf16_f32 v74, v74, v75
	v_cvt_pk_bf16_f32 v75, v76, v77
	global_store_dwordx2 v244, v[74:75], s[16:17] offset:1024
	v_pk_mul_f32 v[78:79], v[78:79], v[252:253] op_sel_hi:[1,0]
	v_pk_mul_f32 v[80:81], v[80:81], v[252:253] op_sel_hi:[1,0]
	v_pk_mul_f32 v[78:79], v[226:227], v[78:79]
	v_pk_mul_f32 v[80:81], v[228:229], v[80:81]
	v_pk_add_f32 v[234:235], v[234:235], 1.0 op_sel_hi:[1,0]
	v_pk_add_f32 v[236:237], v[236:237], 1.0 op_sel_hi:[1,0]
	v_pk_fma_f32 v[78:79], v[234:235], v[78:79], v[230:231]
	v_pk_fma_f32 v[80:81], v[236:237], v[80:81], v[232:233]
	s_nop 0
	v_cvt_pk_bf16_f32 v78, v78, v79
	v_cvt_pk_bf16_f32 v79, v80, v81
	global_store_dwordx2 v244, v[78:79], s[16:17] offset:1536
	ds_read_b128 v[214:217], v238 offset:6144
	ds_read_b128 v[218:221], v238 offset:22528
	ds_read_b128 v[222:225], v238 offset:38912
	ds_read_b128 v[226:229], v238 offset:7168
	ds_read_b128 v[230:233], v238 offset:23552
	ds_read_b128 v[234:237], v238 offset:39936
	s_waitcnt lgkmcnt(6)
	v_pk_mul_f32 v[82:83], v[82:83], v[252:253] op_sel_hi:[1,0]
	v_pk_mul_f32 v[84:85], v[84:85], v[252:253] op_sel_hi:[1,0]
	v_pk_mul_f32 v[82:83], v[130:131], v[82:83]
	v_pk_mul_f32 v[84:85], v[132:133], v[84:85]
	v_pk_add_f32 v[138:139], v[138:139], 1.0 op_sel_hi:[1,0]
	v_pk_add_f32 v[140:141], v[140:141], 1.0 op_sel_hi:[1,0]
	v_pk_fma_f32 v[82:83], v[138:139], v[82:83], v[134:135]
	v_pk_fma_f32 v[84:85], v[140:141], v[84:85], v[136:137]
	s_nop 0
	v_cvt_pk_bf16_f32 v82, v82, v83
	v_cvt_pk_bf16_f32 v83, v84, v85
	global_store_dwordx2 v244, v[82:83], s[16:17] offset:2048
	v_pk_mul_f32 v[86:87], v[86:87], v[252:253] op_sel_hi:[1,0]
	v_pk_mul_f32 v[88:89], v[88:89], v[252:253] op_sel_hi:[1,0]
	v_pk_mul_f32 v[86:87], v[142:143], v[86:87]
	v_pk_mul_f32 v[88:89], v[144:145], v[88:89]
	v_pk_add_f32 v[150:151], v[150:151], 1.0 op_sel_hi:[1,0]
	v_pk_add_f32 v[152:153], v[152:153], 1.0 op_sel_hi:[1,0]
	v_pk_fma_f32 v[86:87], v[150:151], v[86:87], v[146:147]
	v_pk_fma_f32 v[88:89], v[152:153], v[88:89], v[148:149]
	s_nop 0
	v_cvt_pk_bf16_f32 v86, v86, v87
	v_cvt_pk_bf16_f32 v87, v88, v89
	global_store_dwordx2 v244, v[86:87], s[16:17] offset:2560
	ds_read_b128 v[130:133], v238 offset:8192
	ds_read_b128 v[134:137], v238 offset:24576
	ds_read_b128 v[138:141], v238 offset:40960
	ds_read_b128 v[142:145], v238 offset:9216
	ds_read_b128 v[146:149], v238 offset:25600
	ds_read_b128 v[150:153], v238 offset:41984
	s_waitcnt lgkmcnt(6)
	v_pk_mul_f32 v[90:91], v[90:91], v[252:253] op_sel_hi:[1,0]
	v_pk_mul_f32 v[92:93], v[92:93], v[252:253] op_sel_hi:[1,0]
	v_pk_mul_f32 v[90:91], v[214:215], v[90:91]
	v_pk_mul_f32 v[92:93], v[216:217], v[92:93]
	v_pk_add_f32 v[222:223], v[222:223], 1.0 op_sel_hi:[1,0]
	v_pk_add_f32 v[224:225], v[224:225], 1.0 op_sel_hi:[1,0]
	v_pk_fma_f32 v[90:91], v[222:223], v[90:91], v[218:219]
	v_pk_fma_f32 v[92:93], v[224:225], v[92:93], v[220:221]
	s_nop 0
	v_cvt_pk_bf16_f32 v90, v90, v91
	v_cvt_pk_bf16_f32 v91, v92, v93
	global_store_dwordx2 v244, v[90:91], s[16:17] offset:3072
	v_pk_mul_f32 v[94:95], v[94:95], v[252:253] op_sel_hi:[1,0]
	v_pk_mul_f32 v[96:97], v[96:97], v[252:253] op_sel_hi:[1,0]
	v_pk_mul_f32 v[94:95], v[226:227], v[94:95]
	v_pk_mul_f32 v[96:97], v[228:229], v[96:97]
	v_pk_add_f32 v[234:235], v[234:235], 1.0 op_sel_hi:[1,0]
	v_pk_add_f32 v[236:237], v[236:237], 1.0 op_sel_hi:[1,0]
	v_pk_fma_f32 v[94:95], v[234:235], v[94:95], v[230:231]
	v_pk_fma_f32 v[96:97], v[236:237], v[96:97], v[232:233]
	s_nop 0
	v_cvt_pk_bf16_f32 v94, v94, v95
	v_cvt_pk_bf16_f32 v95, v96, v97
	global_store_dwordx2 v244, v[94:95], s[16:17] offset:3584
	ds_read_b128 v[214:217], v238 offset:10240
	ds_read_b128 v[218:221], v238 offset:26624
	ds_read_b128 v[222:225], v238 offset:43008
	ds_read_b128 v[226:229], v238 offset:11264
	ds_read_b128 v[230:233], v238 offset:27648
	ds_read_b128 v[234:237], v238 offset:44032
	s_waitcnt lgkmcnt(6)
	v_pk_mul_f32 v[98:99], v[98:99], v[252:253] op_sel_hi:[1,0]
	v_pk_mul_f32 v[100:101], v[100:101], v[252:253] op_sel_hi:[1,0]
	v_pk_mul_f32 v[98:99], v[130:131], v[98:99]
	v_pk_mul_f32 v[100:101], v[132:133], v[100:101]
	v_pk_add_f32 v[138:139], v[138:139], 1.0 op_sel_hi:[1,0]
	v_pk_add_f32 v[140:141], v[140:141], 1.0 op_sel_hi:[1,0]
	v_pk_fma_f32 v[98:99], v[138:139], v[98:99], v[134:135]
	v_pk_fma_f32 v[100:101], v[140:141], v[100:101], v[136:137]
	s_nop 0
	v_cvt_pk_bf16_f32 v98, v98, v99
	v_cvt_pk_bf16_f32 v99, v100, v101
	global_store_dwordx2 v245, v[98:99], s[16:17] offset:0
	v_pk_mul_f32 v[102:103], v[102:103], v[252:253] op_sel_hi:[1,0]
	v_pk_mul_f32 v[104:105], v[104:105], v[252:253] op_sel_hi:[1,0]
	v_pk_mul_f32 v[102:103], v[142:143], v[102:103]
	v_pk_mul_f32 v[104:105], v[144:145], v[104:105]
	v_pk_add_f32 v[150:151], v[150:151], 1.0 op_sel_hi:[1,0]
	v_pk_add_f32 v[152:153], v[152:153], 1.0 op_sel_hi:[1,0]
	v_pk_fma_f32 v[102:103], v[150:151], v[102:103], v[146:147]
	v_pk_fma_f32 v[104:105], v[152:153], v[104:105], v[148:149]
	s_nop 0
	v_cvt_pk_bf16_f32 v102, v102, v103
	v_cvt_pk_bf16_f32 v103, v104, v105
	global_store_dwordx2 v245, v[102:103], s[16:17] offset:512
	ds_read_b128 v[130:133], v238 offset:12288
	ds_read_b128 v[134:137], v238 offset:28672
	ds_read_b128 v[138:141], v238 offset:45056
	ds_read_b128 v[142:145], v238 offset:13312
	ds_read_b128 v[146:149], v238 offset:29696
	ds_read_b128 v[150:153], v238 offset:46080
	s_waitcnt lgkmcnt(6)
	v_pk_mul_f32 v[106:107], v[106:107], v[252:253] op_sel_hi:[1,0]
	v_pk_mul_f32 v[108:109], v[108:109], v[252:253] op_sel_hi:[1,0]
	v_pk_mul_f32 v[106:107], v[214:215], v[106:107]
	v_pk_mul_f32 v[108:109], v[216:217], v[108:109]
	v_pk_add_f32 v[222:223], v[222:223], 1.0 op_sel_hi:[1,0]
	v_pk_add_f32 v[224:225], v[224:225], 1.0 op_sel_hi:[1,0]
	v_pk_fma_f32 v[106:107], v[222:223], v[106:107], v[218:219]
	v_pk_fma_f32 v[108:109], v[224:225], v[108:109], v[220:221]
	s_nop 0
	v_cvt_pk_bf16_f32 v106, v106, v107
	v_cvt_pk_bf16_f32 v107, v108, v109
	global_store_dwordx2 v245, v[106:107], s[16:17] offset:1024
	v_pk_mul_f32 v[110:111], v[110:111], v[252:253] op_sel_hi:[1,0]
	v_pk_mul_f32 v[112:113], v[112:113], v[252:253] op_sel_hi:[1,0]
	v_pk_mul_f32 v[110:111], v[226:227], v[110:111]
	v_pk_mul_f32 v[112:113], v[228:229], v[112:113]
	v_pk_add_f32 v[234:235], v[234:235], 1.0 op_sel_hi:[1,0]
	v_pk_add_f32 v[236:237], v[236:237], 1.0 op_sel_hi:[1,0]
	v_pk_fma_f32 v[110:111], v[234:235], v[110:111], v[230:231]
	v_pk_fma_f32 v[112:113], v[236:237], v[112:113], v[232:233]
	s_nop 0
	v_cvt_pk_bf16_f32 v110, v110, v111
	v_cvt_pk_bf16_f32 v111, v112, v113
	global_store_dwordx2 v245, v[110:111], s[16:17] offset:1536
	ds_read_b128 v[214:217], v238 offset:14336
	ds_read_b128 v[218:221], v238 offset:30720
	ds_read_b128 v[222:225], v238 offset:47104
	ds_read_b128 v[226:229], v238 offset:15360
	ds_read_b128 v[230:233], v238 offset:31744
	ds_read_b128 v[234:237], v238 offset:48128
	s_waitcnt lgkmcnt(6)
	v_pk_mul_f32 v[114:115], v[114:115], v[252:253] op_sel_hi:[1,0]
	v_pk_mul_f32 v[116:117], v[116:117], v[252:253] op_sel_hi:[1,0]
	v_pk_mul_f32 v[114:115], v[130:131], v[114:115]
	v_pk_mul_f32 v[116:117], v[132:133], v[116:117]
	v_pk_add_f32 v[138:139], v[138:139], 1.0 op_sel_hi:[1,0]
	v_pk_add_f32 v[140:141], v[140:141], 1.0 op_sel_hi:[1,0]
	v_pk_fma_f32 v[114:115], v[138:139], v[114:115], v[134:135]
	v_pk_fma_f32 v[116:117], v[140:141], v[116:117], v[136:137]
	s_nop 0
	v_cvt_pk_bf16_f32 v114, v114, v115
	v_cvt_pk_bf16_f32 v115, v116, v117
	global_store_dwordx2 v245, v[114:115], s[16:17] offset:2048
	v_pk_mul_f32 v[118:119], v[118:119], v[252:253] op_sel_hi:[1,0]
	v_pk_mul_f32 v[120:121], v[120:121], v[252:253] op_sel_hi:[1,0]
	v_pk_mul_f32 v[118:119], v[142:143], v[118:119]
	v_pk_mul_f32 v[120:121], v[144:145], v[120:121]
	v_pk_add_f32 v[150:151], v[150:151], 1.0 op_sel_hi:[1,0]
	v_pk_add_f32 v[152:153], v[152:153], 1.0 op_sel_hi:[1,0]
	v_pk_fma_f32 v[118:119], v[150:151], v[118:119], v[146:147]
	v_pk_fma_f32 v[120:121], v[152:153], v[120:121], v[148:149]
	s_nop 0
	v_cvt_pk_bf16_f32 v118, v118, v119
	v_cvt_pk_bf16_f32 v119, v120, v121
	global_store_dwordx2 v245, v[118:119], s[16:17] offset:2560
	s_waitcnt lgkmcnt(0)
	v_pk_mul_f32 v[122:123], v[122:123], v[252:253] op_sel_hi:[1,0]
	v_pk_mul_f32 v[124:125], v[124:125], v[252:253] op_sel_hi:[1,0]
	v_pk_mul_f32 v[122:123], v[214:215], v[122:123]
	v_pk_mul_f32 v[124:125], v[216:217], v[124:125]
	v_pk_add_f32 v[222:223], v[222:223], 1.0 op_sel_hi:[1,0]
	v_pk_add_f32 v[224:225], v[224:225], 1.0 op_sel_hi:[1,0]
	v_pk_fma_f32 v[122:123], v[222:223], v[122:123], v[218:219]
	v_pk_fma_f32 v[124:125], v[224:225], v[124:125], v[220:221]
	s_nop 0
	v_cvt_pk_bf16_f32 v122, v122, v123
	v_cvt_pk_bf16_f32 v123, v124, v125
	global_store_dwordx2 v245, v[122:123], s[16:17] offset:3072
	v_pk_mul_f32 v[126:127], v[126:127], v[252:253] op_sel_hi:[1,0]
	v_pk_mul_f32 v[128:129], v[128:129], v[252:253] op_sel_hi:[1,0]
	v_pk_mul_f32 v[126:127], v[226:227], v[126:127]
	v_pk_mul_f32 v[128:129], v[228:229], v[128:129]
	v_pk_add_f32 v[234:235], v[234:235], 1.0 op_sel_hi:[1,0]
	v_pk_add_f32 v[236:237], v[236:237], 1.0 op_sel_hi:[1,0]
	v_pk_fma_f32 v[126:127], v[234:235], v[126:127], v[230:231]
	v_pk_fma_f32 v[128:129], v[236:237], v[128:129], v[232:233]
	s_nop 0
	v_cvt_pk_bf16_f32 v126, v126, v127
	v_cvt_pk_bf16_f32 v127, v128, v129
	global_store_dwordx2 v245, v[126:127], s[16:17] offset:3584
	s_add_u32 s16, s16, 0x1000000
	s_addc_u32 s17, s17, 0
	s_waitcnt vmcnt(16)
	s_add_u32 s14, s14, 0x2000000
	s_addc_u32 s15, s15, 0
	global_load_dwordx4 v[66:69], v238, s[14:15] offset:0 nt
	global_load_dwordx4 v[70:73], v238, s[14:15] offset:1024 nt
	global_load_dwordx4 v[74:77], v238, s[14:15] offset:2048 nt
	global_load_dwordx4 v[78:81], v238, s[14:15] offset:3072 nt
	global_load_dwordx4 v[82:85], v241, s[14:15] offset:0 nt
	global_load_dwordx4 v[86:89], v241, s[14:15] offset:1024 nt
	global_load_dwordx4 v[90:93], v241, s[14:15] offset:2048 nt
	global_load_dwordx4 v[94:97], v241, s[14:15] offset:3072 nt
	global_load_dwordx4 v[98:101], v242, s[14:15] offset:0 nt
	global_load_dwordx4 v[102:105], v242, s[14:15] offset:1024 nt
	global_load_dwordx4 v[106:109], v242, s[14:15] offset:2048 nt
	global_load_dwordx4 v[110:113], v242, s[14:15] offset:3072 nt
	global_load_dwordx4 v[114:117], v243, s[14:15] offset:0 nt
	global_load_dwordx4 v[118:121], v243, s[14:15] offset:1024 nt
	global_load_dwordx4 v[122:125], v243, s[14:15] offset:2048 nt
	global_load_dwordx4 v[126:129], v243, s[14:15] offset:3072 nt
	ds_read_b128 v[130:133], v238 offset:0
	ds_read_b128 v[134:137], v238 offset:16384
	ds_read_b128 v[138:141], v238 offset:32768
	ds_read_b128 v[142:145], v238 offset:1024
	ds_read_b128 v[146:149], v238 offset:17408
	ds_read_b128 v[150:153], v238 offset:33792
	v_pk_mul_f32 v[156:157], v[2:3], v[2:3]
	v_pk_mul_f32 v[158:159], v[4:5], v[4:5]
	v_pk_fma_f32 v[156:157], v[6:7], v[6:7], v[156:157]
	v_pk_fma_f32 v[158:159], v[8:9], v[8:9], v[158:159]
	v_pk_fma_f32 v[156:157], v[10:11], v[10:11], v[156:157]
	v_pk_fma_f32 v[158:159], v[12:13], v[12:13], v[158:159]
	v_pk_fma_f32 v[156:157], v[14:15], v[14:15], v[156:157]
	v_pk_fma_f32 v[158:159], v[16:17], v[16:17], v[158:159]
	v_pk_fma_f32 v[156:157], v[18:19], v[18:19], v[156:157]
	v_pk_fma_f32 v[158:159], v[20:21], v[20:21], v[158:159]
	v_pk_fma_f32 v[156:157], v[22:23], v[22:23], v[156:157]
	v_pk_fma_f32 v[158:159], v[24:25], v[24:25], v[158:159]
	v_pk_fma_f32 v[156:157], v[26:27], v[26:27], v[156:157]
	v_pk_fma_f32 v[158:159], v[28:29], v[28:29], v[158:159]
	v_pk_fma_f32 v[156:157], v[30:31], v[30:31], v[156:157]
	v_pk_fma_f32 v[158:159], v[32:33], v[32:33], v[158:159]
	v_pk_fma_f32 v[156:157], v[34:35], v[34:35], v[156:157]
	v_pk_fma_f32 v[158:159], v[36:37], v[36:37], v[158:159]
	v_pk_fma_f32 v[156:157], v[38:39], v[38:39], v[156:157]
	v_pk_fma_f32 v[158:159], v[40:41], v[40:41], v[158:159]
	v_pk_fma_f32 v[156:157], v[42:43], v[42:43], v[156:157]
	v_pk_fma_f32 v[158:159], v[44:45], v[44:45], v[158:159]
	v_pk_fma_f32 v[156:157], v[46:47], v[46:47], v[156:157]
	v_pk_fma_f32 v[158:159], v[48:49], v[48:49], v[158:159]
	v_pk_fma_f32 v[156:157], v[50:51], v[50:51], v[156:157]
	v_pk_fma_f32 v[158:159], v[52:53], v[52:53], v[158:159]
	v_pk_fma_f32 v[156:157], v[54:55], v[54:55], v[156:157]
	v_pk_fma_f32 v[158:159], v[56:57], v[56:57], v[158:159]
	v_pk_fma_f32 v[156:157], v[58:59], v[58:59], v[156:157]
	v_pk_fma_f32 v[158:159], v[60:61], v[60:61], v[158:159]
	v_pk_fma_f32 v[156:157], v[62:63], v[62:63], v[156:157]
	v_pk_fma_f32 v[158:159], v[64:65], v[64:65], v[158:159]
	v_pk_add_f32 v[156:157], v[156:157], v[158:159]
	s_nop 0
	v_add_f32_e32 v252, v156, v157
	s_waitcnt lgkmcnt(0)
	ds_bpermute_b32 v254, v246, v252
	s_waitcnt lgkmcnt(0)
	v_add_f32_e32 v252, v252, v254
	ds_bpermute_b32 v254, v247, v252
	s_waitcnt lgkmcnt(0)
	v_add_f32_e32 v252, v252, v254
	ds_bpermute_b32 v254, v248, v252
	s_waitcnt lgkmcnt(0)
	v_add_f32_e32 v252, v252, v254
	ds_bpermute_b32 v254, v249, v252
	s_waitcnt lgkmcnt(0)
	v_add_f32_e32 v252, v252, v254
	ds_bpermute_b32 v254, v250, v252
	s_waitcnt lgkmcnt(0)
	v_add_f32_e32 v252, v252, v254
	ds_bpermute_b32 v254, v251, v252
	s_waitcnt lgkmcnt(0)
	v_add_f32_e32 v252, v252, v254
	v_mov_b32_e32 v254, 0x358637bd
	v_fmac_f32_e32 v254, 0x39800000, v252
	v_mul_f32_e32 v252, 0x4b800000, v254
	v_cmp_gt_f32_e32 vcc, s20, v254
	s_nop 1
	v_cndmask_b32_e32 v254, v254, v252, vcc
	v_rsq_f32_e32 v254, v254
	s_nop 0
	v_mul_f32_e32 v252, 0x45800000, v254
	v_cndmask_b32_e32 v252, v254, v252, vcc
	ds_read_b128 v[214:217], v238 offset:2048
	ds_read_b128 v[218:221], v238 offset:18432
	ds_read_b128 v[222:225], v238 offset:34816
	ds_read_b128 v[226:229], v238 offset:3072
	ds_read_b128 v[230:233], v238 offset:19456
	ds_read_b128 v[234:237], v238 offset:35840
	s_waitcnt lgkmcnt(6)
	v_pk_mul_f32 v[2:3], v[2:3], v[252:253] op_sel_hi:[1,0]
	v_pk_mul_f32 v[4:5], v[4:5], v[252:253] op_sel_hi:[1,0]
	v_pk_mul_f32 v[2:3], v[130:131], v[2:3]
	v_pk_mul_f32 v[4:5], v[132:133], v[4:5]
	v_pk_add_f32 v[138:139], v[138:139], 1.0 op_sel_hi:[1,0]
	v_pk_add_f32 v[140:141], v[140:141], 1.0 op_sel_hi:[1,0]
	v_pk_fma_f32 v[2:3], v[138:139], v[2:3], v[134:135]
	v_pk_fma_f32 v[4:5], v[140:141], v[4:5], v[136:137]
	s_nop 0
	v_cvt_pk_bf16_f32 v2, v2, v3
	v_cvt_pk_bf16_f32 v3, v4, v5
	global_store_dwordx2 v244, v[2:3], s[16:17] offset:0
	v_pk_mul_f32 v[6:7], v[6:7], v[252:253] op_sel_hi:[1,0]
	v_pk_mul_f32 v[8:9], v[8:9], v[252:253] op_sel_hi:[1,0]
	v_pk_mul_f32 v[6:7], v[142:143], v[6:7]
	v_pk_mul_f32 v[8:9], v[144:145], v[8:9]
	v_pk_add_f32 v[150:151], v[150:151], 1.0 op_sel_hi:[1,0]
	v_pk_add_f32 v[152:153], v[152:153], 1.0 op_sel_hi:[1,0]
	v_pk_fma_f32 v[6:7], v[150:151], v[6:7], v[146:147]
	v_pk_fma_f32 v[8:9], v[152:153], v[8:9], v[148:149]
	s_nop 0
	v_cvt_pk_bf16_f32 v6, v6, v7
	v_cvt_pk_bf16_f32 v7, v8, v9
	global_store_dwordx2 v244, v[6:7], s[16:17] offset:512
	ds_read_b128 v[130:133], v238 offset:4096
	ds_read_b128 v[134:137], v238 offset:20480
	ds_read_b128 v[138:141], v238 offset:36864
	ds_read_b128 v[142:145], v238 offset:5120
	ds_read_b128 v[146:149], v238 offset:21504
	ds_read_b128 v[150:153], v238 offset:37888
	s_waitcnt lgkmcnt(6)
	v_pk_mul_f32 v[10:11], v[10:11], v[252:253] op_sel_hi:[1,0]
	v_pk_mul_f32 v[12:13], v[12:13], v[252:253] op_sel_hi:[1,0]
	v_pk_mul_f32 v[10:11], v[214:215], v[10:11]
	v_pk_mul_f32 v[12:13], v[216:217], v[12:13]
	v_pk_add_f32 v[222:223], v[222:223], 1.0 op_sel_hi:[1,0]
	v_pk_add_f32 v[224:225], v[224:225], 1.0 op_sel_hi:[1,0]
	v_pk_fma_f32 v[10:11], v[222:223], v[10:11], v[218:219]
	v_pk_fma_f32 v[12:13], v[224:225], v[12:13], v[220:221]
	s_nop 0
	v_cvt_pk_bf16_f32 v10, v10, v11
	v_cvt_pk_bf16_f32 v11, v12, v13
	global_store_dwordx2 v244, v[10:11], s[16:17] offset:1024
	v_pk_mul_f32 v[14:15], v[14:15], v[252:253] op_sel_hi:[1,0]
	v_pk_mul_f32 v[16:17], v[16:17], v[252:253] op_sel_hi:[1,0]
	v_pk_mul_f32 v[14:15], v[226:227], v[14:15]
	v_pk_mul_f32 v[16:17], v[228:229], v[16:17]
	v_pk_add_f32 v[234:235], v[234:235], 1.0 op_sel_hi:[1,0]
	v_pk_add_f32 v[236:237], v[236:237], 1.0 op_sel_hi:[1,0]
	v_pk_fma_f32 v[14:15], v[234:235], v[14:15], v[230:231]
	v_pk_fma_f32 v[16:17], v[236:237], v[16:17], v[232:233]
	s_nop 0
	v_cvt_pk_bf16_f32 v14, v14, v15
	v_cvt_pk_bf16_f32 v15, v16, v17
	global_store_dwordx2 v244, v[14:15], s[16:17] offset:1536
	ds_read_b128 v[214:217], v238 offset:6144
	ds_read_b128 v[218:221], v238 offset:22528
	ds_read_b128 v[222:225], v238 offset:38912
	ds_read_b128 v[226:229], v238 offset:7168
	ds_read_b128 v[230:233], v238 offset:23552
	ds_read_b128 v[234:237], v238 offset:39936
	s_waitcnt lgkmcnt(6)
	v_pk_mul_f32 v[18:19], v[18:19], v[252:253] op_sel_hi:[1,0]
	v_pk_mul_f32 v[20:21], v[20:21], v[252:253] op_sel_hi:[1,0]
	v_pk_mul_f32 v[18:19], v[130:131], v[18:19]
	v_pk_mul_f32 v[20:21], v[132:133], v[20:21]
	v_pk_add_f32 v[138:139], v[138:139], 1.0 op_sel_hi:[1,0]
	v_pk_add_f32 v[140:141], v[140:141], 1.0 op_sel_hi:[1,0]
	v_pk_fma_f32 v[18:19], v[138:139], v[18:19], v[134:135]
	v_pk_fma_f32 v[20:21], v[140:141], v[20:21], v[136:137]
	s_nop 0
	v_cvt_pk_bf16_f32 v18, v18, v19
	v_cvt_pk_bf16_f32 v19, v20, v21
	global_store_dwordx2 v244, v[18:19], s[16:17] offset:2048
	v_pk_mul_f32 v[22:23], v[22:23], v[252:253] op_sel_hi:[1,0]
	v_pk_mul_f32 v[24:25], v[24:25], v[252:253] op_sel_hi:[1,0]
	v_pk_mul_f32 v[22:23], v[142:143], v[22:23]
	v_pk_mul_f32 v[24:25], v[144:145], v[24:25]
	v_pk_add_f32 v[150:151], v[150:151], 1.0 op_sel_hi:[1,0]
	v_pk_add_f32 v[152:153], v[152:153], 1.0 op_sel_hi:[1,0]
	v_pk_fma_f32 v[22:23], v[150:151], v[22:23], v[146:147]
	v_pk_fma_f32 v[24:25], v[152:153], v[24:25], v[148:149]
	s_nop 0
	v_cvt_pk_bf16_f32 v22, v22, v23
	v_cvt_pk_bf16_f32 v23, v24, v25
	global_store_dwordx2 v244, v[22:23], s[16:17] offset:2560
	ds_read_b128 v[130:133], v238 offset:8192
	ds_read_b128 v[134:137], v238 offset:24576
	ds_read_b128 v[138:141], v238 offset:40960
	ds_read_b128 v[142:145], v238 offset:9216
	ds_read_b128 v[146:149], v238 offset:25600
	ds_read_b128 v[150:153], v238 offset:41984
	s_waitcnt lgkmcnt(6)
	v_pk_mul_f32 v[26:27], v[26:27], v[252:253] op_sel_hi:[1,0]
	v_pk_mul_f32 v[28:29], v[28:29], v[252:253] op_sel_hi:[1,0]
	v_pk_mul_f32 v[26:27], v[214:215], v[26:27]
	v_pk_mul_f32 v[28:29], v[216:217], v[28:29]
	v_pk_add_f32 v[222:223], v[222:223], 1.0 op_sel_hi:[1,0]
	v_pk_add_f32 v[224:225], v[224:225], 1.0 op_sel_hi:[1,0]
	v_pk_fma_f32 v[26:27], v[222:223], v[26:27], v[218:219]
	v_pk_fma_f32 v[28:29], v[224:225], v[28:29], v[220:221]
	s_nop 0
	v_cvt_pk_bf16_f32 v26, v26, v27
	v_cvt_pk_bf16_f32 v27, v28, v29
	global_store_dwordx2 v244, v[26:27], s[16:17] offset:3072
	v_pk_mul_f32 v[30:31], v[30:31], v[252:253] op_sel_hi:[1,0]
	v_pk_mul_f32 v[32:33], v[32:33], v[252:253] op_sel_hi:[1,0]
	v_pk_mul_f32 v[30:31], v[226:227], v[30:31]
	v_pk_mul_f32 v[32:33], v[228:229], v[32:33]
	v_pk_add_f32 v[234:235], v[234:235], 1.0 op_sel_hi:[1,0]
	v_pk_add_f32 v[236:237], v[236:237], 1.0 op_sel_hi:[1,0]
	v_pk_fma_f32 v[30:31], v[234:235], v[30:31], v[230:231]
	v_pk_fma_f32 v[32:33], v[236:237], v[32:33], v[232:233]
	s_nop 0
	v_cvt_pk_bf16_f32 v30, v30, v31
	v_cvt_pk_bf16_f32 v31, v32, v33
	global_store_dwordx2 v244, v[30:31], s[16:17] offset:3584
	ds_read_b128 v[214:217], v238 offset:10240
	ds_read_b128 v[218:221], v238 offset:26624
	ds_read_b128 v[222:225], v238 offset:43008
	ds_read_b128 v[226:229], v238 offset:11264
	ds_read_b128 v[230:233], v238 offset:27648
	ds_read_b128 v[234:237], v238 offset:44032
	s_waitcnt lgkmcnt(6)
	v_pk_mul_f32 v[34:35], v[34:35], v[252:253] op_sel_hi:[1,0]
	v_pk_mul_f32 v[36:37], v[36:37], v[252:253] op_sel_hi:[1,0]
	v_pk_mul_f32 v[34:35], v[130:131], v[34:35]
	v_pk_mul_f32 v[36:37], v[132:133], v[36:37]
	v_pk_add_f32 v[138:139], v[138:139], 1.0 op_sel_hi:[1,0]
	v_pk_add_f32 v[140:141], v[140:141], 1.0 op_sel_hi:[1,0]
	v_pk_fma_f32 v[34:35], v[138:139], v[34:35], v[134:135]
	v_pk_fma_f32 v[36:37], v[140:141], v[36:37], v[136:137]
	s_nop 0
	v_cvt_pk_bf16_f32 v34, v34, v35
	v_cvt_pk_bf16_f32 v35, v36, v37
	global_store_dwordx2 v245, v[34:35], s[16:17] offset:0
	v_pk_mul_f32 v[38:39], v[38:39], v[252:253] op_sel_hi:[1,0]
	v_pk_mul_f32 v[40:41], v[40:41], v[252:253] op_sel_hi:[1,0]
	v_pk_mul_f32 v[38:39], v[142:143], v[38:39]
	v_pk_mul_f32 v[40:41], v[144:145], v[40:41]
	v_pk_add_f32 v[150:151], v[150:151], 1.0 op_sel_hi:[1,0]
	v_pk_add_f32 v[152:153], v[152:153], 1.0 op_sel_hi:[1,0]
	v_pk_fma_f32 v[38:39], v[150:151], v[38:39], v[146:147]
	v_pk_fma_f32 v[40:41], v[152:153], v[40:41], v[148:149]
	s_nop 0
	v_cvt_pk_bf16_f32 v38, v38, v39
	v_cvt_pk_bf16_f32 v39, v40, v41
	global_store_dwordx2 v245, v[38:39], s[16:17] offset:512
	ds_read_b128 v[130:133], v238 offset:12288
	ds_read_b128 v[134:137], v238 offset:28672
	ds_read_b128 v[138:141], v238 offset:45056
	ds_read_b128 v[142:145], v238 offset:13312
	ds_read_b128 v[146:149], v238 offset:29696
	ds_read_b128 v[150:153], v238 offset:46080
	s_waitcnt lgkmcnt(6)
	v_pk_mul_f32 v[42:43], v[42:43], v[252:253] op_sel_hi:[1,0]
	v_pk_mul_f32 v[44:45], v[44:45], v[252:253] op_sel_hi:[1,0]
	v_pk_mul_f32 v[42:43], v[214:215], v[42:43]
	v_pk_mul_f32 v[44:45], v[216:217], v[44:45]
	v_pk_add_f32 v[222:223], v[222:223], 1.0 op_sel_hi:[1,0]
	v_pk_add_f32 v[224:225], v[224:225], 1.0 op_sel_hi:[1,0]
	v_pk_fma_f32 v[42:43], v[222:223], v[42:43], v[218:219]
	v_pk_fma_f32 v[44:45], v[224:225], v[44:45], v[220:221]
	s_nop 0
	v_cvt_pk_bf16_f32 v42, v42, v43
	v_cvt_pk_bf16_f32 v43, v44, v45
	global_store_dwordx2 v245, v[42:43], s[16:17] offset:1024
	v_pk_mul_f32 v[46:47], v[46:47], v[252:253] op_sel_hi:[1,0]
	v_pk_mul_f32 v[48:49], v[48:49], v[252:253] op_sel_hi:[1,0]
	v_pk_mul_f32 v[46:47], v[226:227], v[46:47]
	v_pk_mul_f32 v[48:49], v[228:229], v[48:49]
	v_pk_add_f32 v[234:235], v[234:235], 1.0 op_sel_hi:[1,0]
	v_pk_add_f32 v[236:237], v[236:237], 1.0 op_sel_hi:[1,0]
	v_pk_fma_f32 v[46:47], v[234:235], v[46:47], v[230:231]
	v_pk_fma_f32 v[48:49], v[236:237], v[48:49], v[232:233]
	s_nop 0
	v_cvt_pk_bf16_f32 v46, v46, v47
	v_cvt_pk_bf16_f32 v47, v48, v49
	global_store_dwordx2 v245, v[46:47], s[16:17] offset:1536
	ds_read_b128 v[214:217], v238 offset:14336
	ds_read_b128 v[218:221], v238 offset:30720
	ds_read_b128 v[222:225], v238 offset:47104
	ds_read_b128 v[226:229], v238 offset:15360
	ds_read_b128 v[230:233], v238 offset:31744
	ds_read_b128 v[234:237], v238 offset:48128
	s_waitcnt lgkmcnt(6)
	v_pk_mul_f32 v[50:51], v[50:51], v[252:253] op_sel_hi:[1,0]
	v_pk_mul_f32 v[52:53], v[52:53], v[252:253] op_sel_hi:[1,0]
	v_pk_mul_f32 v[50:51], v[130:131], v[50:51]
	v_pk_mul_f32 v[52:53], v[132:133], v[52:53]
	v_pk_add_f32 v[138:139], v[138:139], 1.0 op_sel_hi:[1,0]
	v_pk_add_f32 v[140:141], v[140:141], 1.0 op_sel_hi:[1,0]
	v_pk_fma_f32 v[50:51], v[138:139], v[50:51], v[134:135]
	v_pk_fma_f32 v[52:53], v[140:141], v[52:53], v[136:137]
	s_nop 0
	v_cvt_pk_bf16_f32 v50, v50, v51
	v_cvt_pk_bf16_f32 v51, v52, v53
	global_store_dwordx2 v245, v[50:51], s[16:17] offset:2048
	v_pk_mul_f32 v[54:55], v[54:55], v[252:253] op_sel_hi:[1,0]
	v_pk_mul_f32 v[56:57], v[56:57], v[252:253] op_sel_hi:[1,0]
	v_pk_mul_f32 v[54:55], v[142:143], v[54:55]
	v_pk_mul_f32 v[56:57], v[144:145], v[56:57]
	v_pk_add_f32 v[150:151], v[150:151], 1.0 op_sel_hi:[1,0]
	v_pk_add_f32 v[152:153], v[152:153], 1.0 op_sel_hi:[1,0]
	v_pk_fma_f32 v[54:55], v[150:151], v[54:55], v[146:147]
	v_pk_fma_f32 v[56:57], v[152:153], v[56:57], v[148:149]
	s_nop 0
	v_cvt_pk_bf16_f32 v54, v54, v55
	v_cvt_pk_bf16_f32 v55, v56, v57
	global_store_dwordx2 v245, v[54:55], s[16:17] offset:2560
	s_waitcnt lgkmcnt(0)
	v_pk_mul_f32 v[58:59], v[58:59], v[252:253] op_sel_hi:[1,0]
	v_pk_mul_f32 v[60:61], v[60:61], v[252:253] op_sel_hi:[1,0]
	v_pk_mul_f32 v[58:59], v[214:215], v[58:59]
	v_pk_mul_f32 v[60:61], v[216:217], v[60:61]
	v_pk_add_f32 v[222:223], v[222:223], 1.0 op_sel_hi:[1,0]
	v_pk_add_f32 v[224:225], v[224:225], 1.0 op_sel_hi:[1,0]
	v_pk_fma_f32 v[58:59], v[222:223], v[58:59], v[218:219]
	v_pk_fma_f32 v[60:61], v[224:225], v[60:61], v[220:221]
	s_nop 0
	v_cvt_pk_bf16_f32 v58, v58, v59
	v_cvt_pk_bf16_f32 v59, v60, v61
	global_store_dwordx2 v245, v[58:59], s[16:17] offset:3072
	v_pk_mul_f32 v[62:63], v[62:63], v[252:253] op_sel_hi:[1,0]
	v_pk_mul_f32 v[64:65], v[64:65], v[252:253] op_sel_hi:[1,0]
	v_pk_mul_f32 v[62:63], v[226:227], v[62:63]
	v_pk_mul_f32 v[64:65], v[228:229], v[64:65]
	v_pk_add_f32 v[234:235], v[234:235], 1.0 op_sel_hi:[1,0]
	v_pk_add_f32 v[236:237], v[236:237], 1.0 op_sel_hi:[1,0]
	v_pk_fma_f32 v[62:63], v[234:235], v[62:63], v[230:231]
	v_pk_fma_f32 v[64:65], v[236:237], v[64:65], v[232:233]
	s_nop 0
	v_cvt_pk_bf16_f32 v62, v62, v63
	v_cvt_pk_bf16_f32 v63, v64, v65
	global_store_dwordx2 v245, v[62:63], s[16:17] offset:3584
	s_add_u32 s16, s16, 0x1000000
	s_addc_u32 s17, s17, 0
	s_waitcnt vmcnt(16)
	global_load_dwordx4 v[2:5], v238, s[42:43] offset:0 nt
	global_load_dwordx4 v[6:9], v238, s[42:43] offset:1024 nt
	global_load_dwordx4 v[10:13], v238, s[42:43] offset:2048 nt
	global_load_dwordx4 v[14:17], v238, s[42:43] offset:3072 nt
	global_load_dwordx4 v[18:21], v241, s[42:43] offset:0 nt
	global_load_dwordx4 v[22:25], v241, s[42:43] offset:1024 nt
	global_load_dwordx4 v[26:29], v241, s[42:43] offset:2048 nt
	global_load_dwordx4 v[30:33], v241, s[42:43] offset:3072 nt
	global_load_dwordx4 v[34:37], v242, s[42:43] offset:0 nt
	global_load_dwordx4 v[38:41], v242, s[42:43] offset:1024 nt
	global_load_dwordx4 v[42:45], v242, s[42:43] offset:2048 nt
	global_load_dwordx4 v[46:49], v242, s[42:43] offset:3072 nt
	global_load_dwordx4 v[50:53], v243, s[42:43] offset:0 nt
	global_load_dwordx4 v[54:57], v243, s[42:43] offset:1024 nt
	global_load_dwordx4 v[58:61], v243, s[42:43] offset:2048 nt
	global_load_dwordx4 v[62:65], v243, s[42:43] offset:3072 nt
	ds_read_b128 v[130:133], v238 offset:0
	ds_read_b128 v[134:137], v238 offset:16384
	ds_read_b128 v[138:141], v238 offset:32768
	ds_read_b128 v[142:145], v238 offset:1024
	ds_read_b128 v[146:149], v238 offset:17408
	ds_read_b128 v[150:153], v238 offset:33792
	v_pk_mul_f32 v[156:157], v[66:67], v[66:67]
	v_pk_mul_f32 v[158:159], v[68:69], v[68:69]
	v_pk_fma_f32 v[156:157], v[70:71], v[70:71], v[156:157]
	v_pk_fma_f32 v[158:159], v[72:73], v[72:73], v[158:159]
	v_pk_fma_f32 v[156:157], v[74:75], v[74:75], v[156:157]
	v_pk_fma_f32 v[158:159], v[76:77], v[76:77], v[158:159]
	v_pk_fma_f32 v[156:157], v[78:79], v[78:79], v[156:157]
	v_pk_fma_f32 v[158:159], v[80:81], v[80:81], v[158:159]
	v_pk_fma_f32 v[156:157], v[82:83], v[82:83], v[156:157]
	v_pk_fma_f32 v[158:159], v[84:85], v[84:85], v[158:159]
	v_pk_fma_f32 v[156:157], v[86:87], v[86:87], v[156:157]
	v_pk_fma_f32 v[158:159], v[88:89], v[88:89], v[158:159]
	v_pk_fma_f32 v[156:157], v[90:91], v[90:91], v[156:157]
	v_pk_fma_f32 v[158:159], v[92:93], v[92:93], v[158:159]
	v_pk_fma_f32 v[156:157], v[94:95], v[94:95], v[156:157]
	v_pk_fma_f32 v[158:159], v[96:97], v[96:97], v[158:159]
	v_pk_fma_f32 v[156:157], v[98:99], v[98:99], v[156:157]
	v_pk_fma_f32 v[158:159], v[100:101], v[100:101], v[158:159]
	v_pk_fma_f32 v[156:157], v[102:103], v[102:103], v[156:157]
	v_pk_fma_f32 v[158:159], v[104:105], v[104:105], v[158:159]
	v_pk_fma_f32 v[156:157], v[106:107], v[106:107], v[156:157]
	v_pk_fma_f32 v[158:159], v[108:109], v[108:109], v[158:159]
	v_pk_fma_f32 v[156:157], v[110:111], v[110:111], v[156:157]
	v_pk_fma_f32 v[158:159], v[112:113], v[112:113], v[158:159]
	v_pk_fma_f32 v[156:157], v[114:115], v[114:115], v[156:157]
	v_pk_fma_f32 v[158:159], v[116:117], v[116:117], v[158:159]
	v_pk_fma_f32 v[156:157], v[118:119], v[118:119], v[156:157]
	v_pk_fma_f32 v[158:159], v[120:121], v[120:121], v[158:159]
	v_pk_fma_f32 v[156:157], v[122:123], v[122:123], v[156:157]
	v_pk_fma_f32 v[158:159], v[124:125], v[124:125], v[158:159]
	v_pk_fma_f32 v[156:157], v[126:127], v[126:127], v[156:157]
	v_pk_fma_f32 v[158:159], v[128:129], v[128:129], v[158:159]
	v_pk_add_f32 v[156:157], v[156:157], v[158:159]
	s_nop 0
	v_add_f32_e32 v252, v156, v157
	s_waitcnt lgkmcnt(0)
	ds_bpermute_b32 v254, v246, v252
	s_waitcnt lgkmcnt(0)
	v_add_f32_e32 v252, v252, v254
	ds_bpermute_b32 v254, v247, v252
	s_waitcnt lgkmcnt(0)
	v_add_f32_e32 v252, v252, v254
	ds_bpermute_b32 v254, v248, v252
	s_waitcnt lgkmcnt(0)
	v_add_f32_e32 v252, v252, v254
	ds_bpermute_b32 v254, v249, v252
	s_waitcnt lgkmcnt(0)
	v_add_f32_e32 v252, v252, v254
	ds_bpermute_b32 v254, v250, v252
	s_waitcnt lgkmcnt(0)
	v_add_f32_e32 v252, v252, v254
	ds_bpermute_b32 v254, v251, v252
	s_waitcnt lgkmcnt(0)
	v_add_f32_e32 v252, v252, v254
	v_mov_b32_e32 v254, 0x358637bd
	v_fmac_f32_e32 v254, 0x39800000, v252
	v_mul_f32_e32 v252, 0x4b800000, v254
	v_cmp_gt_f32_e32 vcc, s20, v254
	s_nop 1
	v_cndmask_b32_e32 v254, v254, v252, vcc
	v_rsq_f32_e32 v254, v254
	s_nop 0
	v_mul_f32_e32 v252, 0x45800000, v254
	v_cndmask_b32_e32 v252, v254, v252, vcc
	ds_read_b128 v[214:217], v238 offset:2048
	ds_read_b128 v[218:221], v238 offset:18432
	ds_read_b128 v[222:225], v238 offset:34816
	ds_read_b128 v[226:229], v238 offset:3072
	ds_read_b128 v[230:233], v238 offset:19456
	ds_read_b128 v[234:237], v238 offset:35840
	s_waitcnt lgkmcnt(6)
	v_pk_mul_f32 v[66:67], v[66:67], v[252:253] op_sel_hi:[1,0]
	v_pk_mul_f32 v[68:69], v[68:69], v[252:253] op_sel_hi:[1,0]
	v_pk_mul_f32 v[66:67], v[130:131], v[66:67]
	v_pk_mul_f32 v[68:69], v[132:133], v[68:69]
	v_pk_add_f32 v[138:139], v[138:139], 1.0 op_sel_hi:[1,0]
	v_pk_add_f32 v[140:141], v[140:141], 1.0 op_sel_hi:[1,0]
	v_pk_fma_f32 v[66:67], v[138:139], v[66:67], v[134:135]
	v_pk_fma_f32 v[68:69], v[140:141], v[68:69], v[136:137]
	s_nop 0
	v_cvt_pk_bf16_f32 v66, v66, v67
	v_cvt_pk_bf16_f32 v67, v68, v69
	global_store_dwordx2 v244, v[66:67], s[16:17] offset:0
	v_pk_mul_f32 v[70:71], v[70:71], v[252:253] op_sel_hi:[1,0]
	v_pk_mul_f32 v[72:73], v[72:73], v[252:253] op_sel_hi:[1,0]
	v_pk_mul_f32 v[70:71], v[142:143], v[70:71]
	v_pk_mul_f32 v[72:73], v[144:145], v[72:73]
	v_pk_add_f32 v[150:151], v[150:151], 1.0 op_sel_hi:[1,0]
	v_pk_add_f32 v[152:153], v[152:153], 1.0 op_sel_hi:[1,0]
	v_pk_fma_f32 v[70:71], v[150:151], v[70:71], v[146:147]
	v_pk_fma_f32 v[72:73], v[152:153], v[72:73], v[148:149]
	s_nop 0
	v_cvt_pk_bf16_f32 v70, v70, v71
	v_cvt_pk_bf16_f32 v71, v72, v73
	global_store_dwordx2 v244, v[70:71], s[16:17] offset:512
	ds_read_b128 v[130:133], v238 offset:4096
	ds_read_b128 v[134:137], v238 offset:20480
	ds_read_b128 v[138:141], v238 offset:36864
	ds_read_b128 v[142:145], v238 offset:5120
	ds_read_b128 v[146:149], v238 offset:21504
	ds_read_b128 v[150:153], v238 offset:37888
	s_waitcnt lgkmcnt(6)
	v_pk_mul_f32 v[74:75], v[74:75], v[252:253] op_sel_hi:[1,0]
	v_pk_mul_f32 v[76:77], v[76:77], v[252:253] op_sel_hi:[1,0]
	v_pk_mul_f32 v[74:75], v[214:215], v[74:75]
	v_pk_mul_f32 v[76:77], v[216:217], v[76:77]
	v_pk_add_f32 v[222:223], v[222:223], 1.0 op_sel_hi:[1,0]
	v_pk_add_f32 v[224:225], v[224:225], 1.0 op_sel_hi:[1,0]
	v_pk_fma_f32 v[74:75], v[222:223], v[74:75], v[218:219]
	v_pk_fma_f32 v[76:77], v[224:225], v[76:77], v[220:221]
	s_nop 0
	v_cvt_pk_bf16_f32 v74, v74, v75
	v_cvt_pk_bf16_f32 v75, v76, v77
	global_store_dwordx2 v244, v[74:75], s[16:17] offset:1024
	v_pk_mul_f32 v[78:79], v[78:79], v[252:253] op_sel_hi:[1,0]
	v_pk_mul_f32 v[80:81], v[80:81], v[252:253] op_sel_hi:[1,0]
	v_pk_mul_f32 v[78:79], v[226:227], v[78:79]
	v_pk_mul_f32 v[80:81], v[228:229], v[80:81]
	v_pk_add_f32 v[234:235], v[234:235], 1.0 op_sel_hi:[1,0]
	v_pk_add_f32 v[236:237], v[236:237], 1.0 op_sel_hi:[1,0]
	v_pk_fma_f32 v[78:79], v[234:235], v[78:79], v[230:231]
	v_pk_fma_f32 v[80:81], v[236:237], v[80:81], v[232:233]
	s_nop 0
	v_cvt_pk_bf16_f32 v78, v78, v79
	v_cvt_pk_bf16_f32 v79, v80, v81
	global_store_dwordx2 v244, v[78:79], s[16:17] offset:1536
	ds_read_b128 v[214:217], v238 offset:6144
	ds_read_b128 v[218:221], v238 offset:22528
	ds_read_b128 v[222:225], v238 offset:38912
	ds_read_b128 v[226:229], v238 offset:7168
	ds_read_b128 v[230:233], v238 offset:23552
	ds_read_b128 v[234:237], v238 offset:39936
	s_waitcnt lgkmcnt(6)
	v_pk_mul_f32 v[82:83], v[82:83], v[252:253] op_sel_hi:[1,0]
	v_pk_mul_f32 v[84:85], v[84:85], v[252:253] op_sel_hi:[1,0]
	v_pk_mul_f32 v[82:83], v[130:131], v[82:83]
	v_pk_mul_f32 v[84:85], v[132:133], v[84:85]
	v_pk_add_f32 v[138:139], v[138:139], 1.0 op_sel_hi:[1,0]
	v_pk_add_f32 v[140:141], v[140:141], 1.0 op_sel_hi:[1,0]
	v_pk_fma_f32 v[82:83], v[138:139], v[82:83], v[134:135]
	v_pk_fma_f32 v[84:85], v[140:141], v[84:85], v[136:137]
	s_nop 0
	v_cvt_pk_bf16_f32 v82, v82, v83
	v_cvt_pk_bf16_f32 v83, v84, v85
	global_store_dwordx2 v244, v[82:83], s[16:17] offset:2048
	v_pk_mul_f32 v[86:87], v[86:87], v[252:253] op_sel_hi:[1,0]
	v_pk_mul_f32 v[88:89], v[88:89], v[252:253] op_sel_hi:[1,0]
	v_pk_mul_f32 v[86:87], v[142:143], v[86:87]
	v_pk_mul_f32 v[88:89], v[144:145], v[88:89]
	v_pk_add_f32 v[150:151], v[150:151], 1.0 op_sel_hi:[1,0]
	v_pk_add_f32 v[152:153], v[152:153], 1.0 op_sel_hi:[1,0]
	v_pk_fma_f32 v[86:87], v[150:151], v[86:87], v[146:147]
	v_pk_fma_f32 v[88:89], v[152:153], v[88:89], v[148:149]
	s_nop 0
	v_cvt_pk_bf16_f32 v86, v86, v87
	v_cvt_pk_bf16_f32 v87, v88, v89
	global_store_dwordx2 v244, v[86:87], s[16:17] offset:2560
	ds_read_b128 v[130:133], v238 offset:8192
	ds_read_b128 v[134:137], v238 offset:24576
	ds_read_b128 v[138:141], v238 offset:40960
	ds_read_b128 v[142:145], v238 offset:9216
	ds_read_b128 v[146:149], v238 offset:25600
	ds_read_b128 v[150:153], v238 offset:41984
	s_waitcnt lgkmcnt(6)
	v_pk_mul_f32 v[90:91], v[90:91], v[252:253] op_sel_hi:[1,0]
	v_pk_mul_f32 v[92:93], v[92:93], v[252:253] op_sel_hi:[1,0]
	v_pk_mul_f32 v[90:91], v[214:215], v[90:91]
	v_pk_mul_f32 v[92:93], v[216:217], v[92:93]
	v_pk_add_f32 v[222:223], v[222:223], 1.0 op_sel_hi:[1,0]
	v_pk_add_f32 v[224:225], v[224:225], 1.0 op_sel_hi:[1,0]
	v_pk_fma_f32 v[90:91], v[222:223], v[90:91], v[218:219]
	v_pk_fma_f32 v[92:93], v[224:225], v[92:93], v[220:221]
	s_nop 0
	v_cvt_pk_bf16_f32 v90, v90, v91
	v_cvt_pk_bf16_f32 v91, v92, v93
	global_store_dwordx2 v244, v[90:91], s[16:17] offset:3072
	v_pk_mul_f32 v[94:95], v[94:95], v[252:253] op_sel_hi:[1,0]
	v_pk_mul_f32 v[96:97], v[96:97], v[252:253] op_sel_hi:[1,0]
	v_pk_mul_f32 v[94:95], v[226:227], v[94:95]
	v_pk_mul_f32 v[96:97], v[228:229], v[96:97]
	v_pk_add_f32 v[234:235], v[234:235], 1.0 op_sel_hi:[1,0]
	v_pk_add_f32 v[236:237], v[236:237], 1.0 op_sel_hi:[1,0]
	v_pk_fma_f32 v[94:95], v[234:235], v[94:95], v[230:231]
	v_pk_fma_f32 v[96:97], v[236:237], v[96:97], v[232:233]
	s_nop 0
	v_cvt_pk_bf16_f32 v94, v94, v95
	v_cvt_pk_bf16_f32 v95, v96, v97
	global_store_dwordx2 v244, v[94:95], s[16:17] offset:3584
	ds_read_b128 v[214:217], v238 offset:10240
	ds_read_b128 v[218:221], v238 offset:26624
	ds_read_b128 v[222:225], v238 offset:43008
	ds_read_b128 v[226:229], v238 offset:11264
	ds_read_b128 v[230:233], v238 offset:27648
	ds_read_b128 v[234:237], v238 offset:44032
	s_waitcnt lgkmcnt(6)
	v_pk_mul_f32 v[98:99], v[98:99], v[252:253] op_sel_hi:[1,0]
	v_pk_mul_f32 v[100:101], v[100:101], v[252:253] op_sel_hi:[1,0]
	v_pk_mul_f32 v[98:99], v[130:131], v[98:99]
	v_pk_mul_f32 v[100:101], v[132:133], v[100:101]
	v_pk_add_f32 v[138:139], v[138:139], 1.0 op_sel_hi:[1,0]
	v_pk_add_f32 v[140:141], v[140:141], 1.0 op_sel_hi:[1,0]
	v_pk_fma_f32 v[98:99], v[138:139], v[98:99], v[134:135]
	v_pk_fma_f32 v[100:101], v[140:141], v[100:101], v[136:137]
	s_nop 0
	v_cvt_pk_bf16_f32 v98, v98, v99
	v_cvt_pk_bf16_f32 v99, v100, v101
	global_store_dwordx2 v245, v[98:99], s[16:17] offset:0
	v_pk_mul_f32 v[102:103], v[102:103], v[252:253] op_sel_hi:[1,0]
	v_pk_mul_f32 v[104:105], v[104:105], v[252:253] op_sel_hi:[1,0]
	v_pk_mul_f32 v[102:103], v[142:143], v[102:103]
	v_pk_mul_f32 v[104:105], v[144:145], v[104:105]
	v_pk_add_f32 v[150:151], v[150:151], 1.0 op_sel_hi:[1,0]
	v_pk_add_f32 v[152:153], v[152:153], 1.0 op_sel_hi:[1,0]
	v_pk_fma_f32 v[102:103], v[150:151], v[102:103], v[146:147]
	v_pk_fma_f32 v[104:105], v[152:153], v[104:105], v[148:149]
	s_nop 0
	v_cvt_pk_bf16_f32 v102, v102, v103
	v_cvt_pk_bf16_f32 v103, v104, v105
	global_store_dwordx2 v245, v[102:103], s[16:17] offset:512
	ds_read_b128 v[130:133], v238 offset:12288
	ds_read_b128 v[134:137], v238 offset:28672
	ds_read_b128 v[138:141], v238 offset:45056
	ds_read_b128 v[142:145], v238 offset:13312
	ds_read_b128 v[146:149], v238 offset:29696
	ds_read_b128 v[150:153], v238 offset:46080
	s_waitcnt lgkmcnt(6)
	v_pk_mul_f32 v[106:107], v[106:107], v[252:253] op_sel_hi:[1,0]
	v_pk_mul_f32 v[108:109], v[108:109], v[252:253] op_sel_hi:[1,0]
	v_pk_mul_f32 v[106:107], v[214:215], v[106:107]
	v_pk_mul_f32 v[108:109], v[216:217], v[108:109]
	v_pk_add_f32 v[222:223], v[222:223], 1.0 op_sel_hi:[1,0]
	v_pk_add_f32 v[224:225], v[224:225], 1.0 op_sel_hi:[1,0]
	v_pk_fma_f32 v[106:107], v[222:223], v[106:107], v[218:219]
	v_pk_fma_f32 v[108:109], v[224:225], v[108:109], v[220:221]
	s_nop 0
	v_cvt_pk_bf16_f32 v106, v106, v107
	v_cvt_pk_bf16_f32 v107, v108, v109
	global_store_dwordx2 v245, v[106:107], s[16:17] offset:1024
	v_pk_mul_f32 v[110:111], v[110:111], v[252:253] op_sel_hi:[1,0]
	v_pk_mul_f32 v[112:113], v[112:113], v[252:253] op_sel_hi:[1,0]
	v_pk_mul_f32 v[110:111], v[226:227], v[110:111]
	v_pk_mul_f32 v[112:113], v[228:229], v[112:113]
	v_pk_add_f32 v[234:235], v[234:235], 1.0 op_sel_hi:[1,0]
	v_pk_add_f32 v[236:237], v[236:237], 1.0 op_sel_hi:[1,0]
	v_pk_fma_f32 v[110:111], v[234:235], v[110:111], v[230:231]
	v_pk_fma_f32 v[112:113], v[236:237], v[112:113], v[232:233]
	s_nop 0
	v_cvt_pk_bf16_f32 v110, v110, v111
	v_cvt_pk_bf16_f32 v111, v112, v113
	global_store_dwordx2 v245, v[110:111], s[16:17] offset:1536
	ds_read_b128 v[214:217], v238 offset:14336
	ds_read_b128 v[218:221], v238 offset:30720
	ds_read_b128 v[222:225], v238 offset:47104
	ds_read_b128 v[226:229], v238 offset:15360
	ds_read_b128 v[230:233], v238 offset:31744
	ds_read_b128 v[234:237], v238 offset:48128
	s_waitcnt lgkmcnt(6)
	v_pk_mul_f32 v[114:115], v[114:115], v[252:253] op_sel_hi:[1,0]
	v_pk_mul_f32 v[116:117], v[116:117], v[252:253] op_sel_hi:[1,0]
	v_pk_mul_f32 v[114:115], v[130:131], v[114:115]
	v_pk_mul_f32 v[116:117], v[132:133], v[116:117]
	v_pk_add_f32 v[138:139], v[138:139], 1.0 op_sel_hi:[1,0]
	v_pk_add_f32 v[140:141], v[140:141], 1.0 op_sel_hi:[1,0]
	v_pk_fma_f32 v[114:115], v[138:139], v[114:115], v[134:135]
	v_pk_fma_f32 v[116:117], v[140:141], v[116:117], v[136:137]
	s_nop 0
	v_cvt_pk_bf16_f32 v114, v114, v115
	v_cvt_pk_bf16_f32 v115, v116, v117
	global_store_dwordx2 v245, v[114:115], s[16:17] offset:2048
	v_pk_mul_f32 v[118:119], v[118:119], v[252:253] op_sel_hi:[1,0]
	v_pk_mul_f32 v[120:121], v[120:121], v[252:253] op_sel_hi:[1,0]
	v_pk_mul_f32 v[118:119], v[142:143], v[118:119]
	v_pk_mul_f32 v[120:121], v[144:145], v[120:121]
	v_pk_add_f32 v[150:151], v[150:151], 1.0 op_sel_hi:[1,0]
	v_pk_add_f32 v[152:153], v[152:153], 1.0 op_sel_hi:[1,0]
	v_pk_fma_f32 v[118:119], v[150:151], v[118:119], v[146:147]
	v_pk_fma_f32 v[120:121], v[152:153], v[120:121], v[148:149]
	s_nop 0
	v_cvt_pk_bf16_f32 v118, v118, v119
	v_cvt_pk_bf16_f32 v119, v120, v121
	global_store_dwordx2 v245, v[118:119], s[16:17] offset:2560
	s_waitcnt lgkmcnt(0)
	v_pk_mul_f32 v[122:123], v[122:123], v[252:253] op_sel_hi:[1,0]
	v_pk_mul_f32 v[124:125], v[124:125], v[252:253] op_sel_hi:[1,0]
	v_pk_mul_f32 v[122:123], v[214:215], v[122:123]
	v_pk_mul_f32 v[124:125], v[216:217], v[124:125]
	v_pk_add_f32 v[222:223], v[222:223], 1.0 op_sel_hi:[1,0]
	v_pk_add_f32 v[224:225], v[224:225], 1.0 op_sel_hi:[1,0]
	v_pk_fma_f32 v[122:123], v[222:223], v[122:123], v[218:219]
	v_pk_fma_f32 v[124:125], v[224:225], v[124:125], v[220:221]
	s_nop 0
	v_cvt_pk_bf16_f32 v122, v122, v123
	v_cvt_pk_bf16_f32 v123, v124, v125
	global_store_dwordx2 v245, v[122:123], s[16:17] offset:3072
	v_pk_mul_f32 v[126:127], v[126:127], v[252:253] op_sel_hi:[1,0]
	v_pk_mul_f32 v[128:129], v[128:129], v[252:253] op_sel_hi:[1,0]
	v_pk_mul_f32 v[126:127], v[226:227], v[126:127]
	v_pk_mul_f32 v[128:129], v[228:229], v[128:129]
	v_pk_add_f32 v[234:235], v[234:235], 1.0 op_sel_hi:[1,0]
	v_pk_add_f32 v[236:237], v[236:237], 1.0 op_sel_hi:[1,0]
	v_pk_fma_f32 v[126:127], v[234:235], v[126:127], v[230:231]
	v_pk_fma_f32 v[128:129], v[236:237], v[128:129], v[232:233]
	s_nop 0
	v_cvt_pk_bf16_f32 v126, v126, v127
	v_cvt_pk_bf16_f32 v127, v128, v129
	global_store_dwordx2 v245, v[126:127], s[16:17] offset:3584
	s_add_u32 s16, s16, 0x1000000
	s_addc_u32 s17, s17, 0
	s_waitcnt vmcnt(16)
	s_add_u32 s42, s42, 0x2000000
	s_addc_u32 s43, s43, 0
	global_load_dwordx4 v[66:69], v238, s[42:43] offset:0 nt
	global_load_dwordx4 v[70:73], v238, s[42:43] offset:1024 nt
	global_load_dwordx4 v[74:77], v238, s[42:43] offset:2048 nt
	global_load_dwordx4 v[78:81], v238, s[42:43] offset:3072 nt
	global_load_dwordx4 v[82:85], v241, s[42:43] offset:0 nt
	global_load_dwordx4 v[86:89], v241, s[42:43] offset:1024 nt
	global_load_dwordx4 v[90:93], v241, s[42:43] offset:2048 nt
	global_load_dwordx4 v[94:97], v241, s[42:43] offset:3072 nt
	global_load_dwordx4 v[98:101], v242, s[42:43] offset:0 nt
	global_load_dwordx4 v[102:105], v242, s[42:43] offset:1024 nt
	global_load_dwordx4 v[106:109], v242, s[42:43] offset:2048 nt
	global_load_dwordx4 v[110:113], v242, s[42:43] offset:3072 nt
	global_load_dwordx4 v[114:117], v243, s[42:43] offset:0 nt
	global_load_dwordx4 v[118:121], v243, s[42:43] offset:1024 nt
	global_load_dwordx4 v[122:125], v243, s[42:43] offset:2048 nt
	global_load_dwordx4 v[126:129], v243, s[42:43] offset:3072 nt
	ds_read_b128 v[130:133], v238 offset:0
	ds_read_b128 v[134:137], v238 offset:49152
	ds_read_b128 v[138:141], v239 offset:0
	ds_read_b128 v[142:145], v238 offset:1024
	ds_read_b128 v[146:149], v238 offset:50176
	ds_read_b128 v[150:153], v239 offset:1024
	v_pk_mul_f32 v[156:157], v[2:3], v[2:3]
	v_pk_mul_f32 v[158:159], v[4:5], v[4:5]
	v_pk_fma_f32 v[156:157], v[6:7], v[6:7], v[156:157]
	v_pk_fma_f32 v[158:159], v[8:9], v[8:9], v[158:159]
	v_pk_fma_f32 v[156:157], v[10:11], v[10:11], v[156:157]
	v_pk_fma_f32 v[158:159], v[12:13], v[12:13], v[158:159]
	v_pk_fma_f32 v[156:157], v[14:15], v[14:15], v[156:157]
	v_pk_fma_f32 v[158:159], v[16:17], v[16:17], v[158:159]
	v_pk_fma_f32 v[156:157], v[18:19], v[18:19], v[156:157]
	v_pk_fma_f32 v[158:159], v[20:21], v[20:21], v[158:159]
	v_pk_fma_f32 v[156:157], v[22:23], v[22:23], v[156:157]
	v_pk_fma_f32 v[158:159], v[24:25], v[24:25], v[158:159]
	v_pk_fma_f32 v[156:157], v[26:27], v[26:27], v[156:157]
	v_pk_fma_f32 v[158:159], v[28:29], v[28:29], v[158:159]
	v_pk_fma_f32 v[156:157], v[30:31], v[30:31], v[156:157]
	v_pk_fma_f32 v[158:159], v[32:33], v[32:33], v[158:159]
	v_pk_fma_f32 v[156:157], v[34:35], v[34:35], v[156:157]
	v_pk_fma_f32 v[158:159], v[36:37], v[36:37], v[158:159]
	v_pk_fma_f32 v[156:157], v[38:39], v[38:39], v[156:157]
	v_pk_fma_f32 v[158:159], v[40:41], v[40:41], v[158:159]
	v_pk_fma_f32 v[156:157], v[42:43], v[42:43], v[156:157]
	v_pk_fma_f32 v[158:159], v[44:45], v[44:45], v[158:159]
	v_pk_fma_f32 v[156:157], v[46:47], v[46:47], v[156:157]
	v_pk_fma_f32 v[158:159], v[48:49], v[48:49], v[158:159]
	v_pk_fma_f32 v[156:157], v[50:51], v[50:51], v[156:157]
	v_pk_fma_f32 v[158:159], v[52:53], v[52:53], v[158:159]
	v_pk_fma_f32 v[156:157], v[54:55], v[54:55], v[156:157]
	v_pk_fma_f32 v[158:159], v[56:57], v[56:57], v[158:159]
	v_pk_fma_f32 v[156:157], v[58:59], v[58:59], v[156:157]
	v_pk_fma_f32 v[158:159], v[60:61], v[60:61], v[158:159]
	v_pk_fma_f32 v[156:157], v[62:63], v[62:63], v[156:157]
	v_pk_fma_f32 v[158:159], v[64:65], v[64:65], v[158:159]
	v_pk_add_f32 v[156:157], v[156:157], v[158:159]
	s_nop 0
	v_add_f32_e32 v252, v156, v157
	s_waitcnt lgkmcnt(0)
	ds_bpermute_b32 v254, v246, v252
	s_waitcnt lgkmcnt(0)
	v_add_f32_e32 v252, v252, v254
	ds_bpermute_b32 v254, v247, v252
	s_waitcnt lgkmcnt(0)
	v_add_f32_e32 v252, v252, v254
	ds_bpermute_b32 v254, v248, v252
	s_waitcnt lgkmcnt(0)
	v_add_f32_e32 v252, v252, v254
	ds_bpermute_b32 v254, v249, v252
	s_waitcnt lgkmcnt(0)
	v_add_f32_e32 v252, v252, v254
	ds_bpermute_b32 v254, v250, v252
	s_waitcnt lgkmcnt(0)
	v_add_f32_e32 v252, v252, v254
	ds_bpermute_b32 v254, v251, v252
	s_waitcnt lgkmcnt(0)
	v_add_f32_e32 v252, v252, v254
	v_mov_b32_e32 v254, 0x358637bd
	v_fmac_f32_e32 v254, 0x39800000, v252
	v_mul_f32_e32 v252, 0x4b800000, v254
	v_cmp_gt_f32_e32 vcc, s20, v254
	s_nop 1
	v_cndmask_b32_e32 v254, v254, v252, vcc
	v_rsq_f32_e32 v254, v254
	s_nop 0
	v_mul_f32_e32 v252, 0x45800000, v254
	v_cndmask_b32_e32 v252, v254, v252, vcc
	ds_read_b128 v[214:217], v238 offset:2048
	ds_read_b128 v[218:221], v238 offset:51200
	ds_read_b128 v[222:225], v239 offset:2048
	ds_read_b128 v[226:229], v238 offset:3072
	ds_read_b128 v[230:233], v238 offset:52224
	ds_read_b128 v[234:237], v239 offset:3072
	s_waitcnt lgkmcnt(6)
	v_pk_mul_f32 v[2:3], v[2:3], v[252:253] op_sel_hi:[1,0]
	v_pk_mul_f32 v[4:5], v[4:5], v[252:253] op_sel_hi:[1,0]
	v_pk_mul_f32 v[2:3], v[130:131], v[2:3]
	v_pk_mul_f32 v[4:5], v[132:133], v[4:5]
	v_pk_add_f32 v[138:139], v[138:139], 1.0 op_sel_hi:[1,0]
	v_pk_add_f32 v[140:141], v[140:141], 1.0 op_sel_hi:[1,0]
	v_pk_fma_f32 v[2:3], v[138:139], v[2:3], v[134:135]
	v_pk_fma_f32 v[4:5], v[140:141], v[4:5], v[136:137]
	s_nop 0
	v_cvt_pk_bf16_f32 v2, v2, v3
	v_cvt_pk_bf16_f32 v3, v4, v5
	global_store_dwordx2 v244, v[2:3], s[16:17] offset:0
	v_pk_mul_f32 v[6:7], v[6:7], v[252:253] op_sel_hi:[1,0]
	v_pk_mul_f32 v[8:9], v[8:9], v[252:253] op_sel_hi:[1,0]
	v_pk_mul_f32 v[6:7], v[142:143], v[6:7]
	v_pk_mul_f32 v[8:9], v[144:145], v[8:9]
	v_pk_add_f32 v[150:151], v[150:151], 1.0 op_sel_hi:[1,0]
	v_pk_add_f32 v[152:153], v[152:153], 1.0 op_sel_hi:[1,0]
	v_pk_fma_f32 v[6:7], v[150:151], v[6:7], v[146:147]
	v_pk_fma_f32 v[8:9], v[152:153], v[8:9], v[148:149]
	s_nop 0
	v_cvt_pk_bf16_f32 v6, v6, v7
	v_cvt_pk_bf16_f32 v7, v8, v9
	global_store_dwordx2 v244, v[6:7], s[16:17] offset:512
	ds_read_b128 v[130:133], v238 offset:4096
	ds_read_b128 v[134:137], v238 offset:53248
	ds_read_b128 v[138:141], v239 offset:4096
	ds_read_b128 v[142:145], v238 offset:5120
	ds_read_b128 v[146:149], v238 offset:54272
	ds_read_b128 v[150:153], v239 offset:5120
	s_waitcnt lgkmcnt(6)
	v_pk_mul_f32 v[10:11], v[10:11], v[252:253] op_sel_hi:[1,0]
	v_pk_mul_f32 v[12:13], v[12:13], v[252:253] op_sel_hi:[1,0]
	v_pk_mul_f32 v[10:11], v[214:215], v[10:11]
	v_pk_mul_f32 v[12:13], v[216:217], v[12:13]
	v_pk_add_f32 v[222:223], v[222:223], 1.0 op_sel_hi:[1,0]
	v_pk_add_f32 v[224:225], v[224:225], 1.0 op_sel_hi:[1,0]
	v_pk_fma_f32 v[10:11], v[222:223], v[10:11], v[218:219]
	v_pk_fma_f32 v[12:13], v[224:225], v[12:13], v[220:221]
	s_nop 0
	v_cvt_pk_bf16_f32 v10, v10, v11
	v_cvt_pk_bf16_f32 v11, v12, v13
	global_store_dwordx2 v244, v[10:11], s[16:17] offset:1024
	v_pk_mul_f32 v[14:15], v[14:15], v[252:253] op_sel_hi:[1,0]
	v_pk_mul_f32 v[16:17], v[16:17], v[252:253] op_sel_hi:[1,0]
	v_pk_mul_f32 v[14:15], v[226:227], v[14:15]
	v_pk_mul_f32 v[16:17], v[228:229], v[16:17]
	v_pk_add_f32 v[234:235], v[234:235], 1.0 op_sel_hi:[1,0]
	v_pk_add_f32 v[236:237], v[236:237], 1.0 op_sel_hi:[1,0]
	v_pk_fma_f32 v[14:15], v[234:235], v[14:15], v[230:231]
	v_pk_fma_f32 v[16:17], v[236:237], v[16:17], v[232:233]
	s_nop 0
	v_cvt_pk_bf16_f32 v14, v14, v15
	v_cvt_pk_bf16_f32 v15, v16, v17
	global_store_dwordx2 v244, v[14:15], s[16:17] offset:1536
	ds_read_b128 v[214:217], v238 offset:6144
	ds_read_b128 v[218:221], v238 offset:55296
	ds_read_b128 v[222:225], v239 offset:6144
	ds_read_b128 v[226:229], v238 offset:7168
	ds_read_b128 v[230:233], v238 offset:56320
	ds_read_b128 v[234:237], v239 offset:7168
	s_waitcnt lgkmcnt(6)
	v_pk_mul_f32 v[18:19], v[18:19], v[252:253] op_sel_hi:[1,0]
	v_pk_mul_f32 v[20:21], v[20:21], v[252:253] op_sel_hi:[1,0]
	v_pk_mul_f32 v[18:19], v[130:131], v[18:19]
	v_pk_mul_f32 v[20:21], v[132:133], v[20:21]
	v_pk_add_f32 v[138:139], v[138:139], 1.0 op_sel_hi:[1,0]
	v_pk_add_f32 v[140:141], v[140:141], 1.0 op_sel_hi:[1,0]
	v_pk_fma_f32 v[18:19], v[138:139], v[18:19], v[134:135]
	v_pk_fma_f32 v[20:21], v[140:141], v[20:21], v[136:137]
	s_nop 0
	v_cvt_pk_bf16_f32 v18, v18, v19
	v_cvt_pk_bf16_f32 v19, v20, v21
	global_store_dwordx2 v244, v[18:19], s[16:17] offset:2048
	v_pk_mul_f32 v[22:23], v[22:23], v[252:253] op_sel_hi:[1,0]
	v_pk_mul_f32 v[24:25], v[24:25], v[252:253] op_sel_hi:[1,0]
	v_pk_mul_f32 v[22:23], v[142:143], v[22:23]
	v_pk_mul_f32 v[24:25], v[144:145], v[24:25]
	v_pk_add_f32 v[150:151], v[150:151], 1.0 op_sel_hi:[1,0]
	v_pk_add_f32 v[152:153], v[152:153], 1.0 op_sel_hi:[1,0]
	v_pk_fma_f32 v[22:23], v[150:151], v[22:23], v[146:147]
	v_pk_fma_f32 v[24:25], v[152:153], v[24:25], v[148:149]
	s_nop 0
	v_cvt_pk_bf16_f32 v22, v22, v23
	v_cvt_pk_bf16_f32 v23, v24, v25
	global_store_dwordx2 v244, v[22:23], s[16:17] offset:2560
	ds_read_b128 v[130:133], v238 offset:8192
	ds_read_b128 v[134:137], v238 offset:57344
	ds_read_b128 v[138:141], v239 offset:8192
	ds_read_b128 v[142:145], v238 offset:9216
	ds_read_b128 v[146:149], v238 offset:58368
	ds_read_b128 v[150:153], v239 offset:9216
	s_waitcnt lgkmcnt(6)
	v_pk_mul_f32 v[26:27], v[26:27], v[252:253] op_sel_hi:[1,0]
	v_pk_mul_f32 v[28:29], v[28:29], v[252:253] op_sel_hi:[1,0]
	v_pk_mul_f32 v[26:27], v[214:215], v[26:27]
	v_pk_mul_f32 v[28:29], v[216:217], v[28:29]
	v_pk_add_f32 v[222:223], v[222:223], 1.0 op_sel_hi:[1,0]
	v_pk_add_f32 v[224:225], v[224:225], 1.0 op_sel_hi:[1,0]
	v_pk_fma_f32 v[26:27], v[222:223], v[26:27], v[218:219]
	v_pk_fma_f32 v[28:29], v[224:225], v[28:29], v[220:221]
	s_nop 0
	v_cvt_pk_bf16_f32 v26, v26, v27
	v_cvt_pk_bf16_f32 v27, v28, v29
	global_store_dwordx2 v244, v[26:27], s[16:17] offset:3072
	v_pk_mul_f32 v[30:31], v[30:31], v[252:253] op_sel_hi:[1,0]
	v_pk_mul_f32 v[32:33], v[32:33], v[252:253] op_sel_hi:[1,0]
	v_pk_mul_f32 v[30:31], v[226:227], v[30:31]
	v_pk_mul_f32 v[32:33], v[228:229], v[32:33]
	v_pk_add_f32 v[234:235], v[234:235], 1.0 op_sel_hi:[1,0]
	v_pk_add_f32 v[236:237], v[236:237], 1.0 op_sel_hi:[1,0]
	v_pk_fma_f32 v[30:31], v[234:235], v[30:31], v[230:231]
	v_pk_fma_f32 v[32:33], v[236:237], v[32:33], v[232:233]
	s_nop 0
	v_cvt_pk_bf16_f32 v30, v30, v31
	v_cvt_pk_bf16_f32 v31, v32, v33
	global_store_dwordx2 v244, v[30:31], s[16:17] offset:3584
	ds_read_b128 v[214:217], v238 offset:10240
	ds_read_b128 v[218:221], v238 offset:59392
	ds_read_b128 v[222:225], v239 offset:10240
	ds_read_b128 v[226:229], v238 offset:11264
	ds_read_b128 v[230:233], v238 offset:60416
	ds_read_b128 v[234:237], v239 offset:11264
	s_waitcnt lgkmcnt(6)
	v_pk_mul_f32 v[34:35], v[34:35], v[252:253] op_sel_hi:[1,0]
	v_pk_mul_f32 v[36:37], v[36:37], v[252:253] op_sel_hi:[1,0]
	v_pk_mul_f32 v[34:35], v[130:131], v[34:35]
	v_pk_mul_f32 v[36:37], v[132:133], v[36:37]
	v_pk_add_f32 v[138:139], v[138:139], 1.0 op_sel_hi:[1,0]
	v_pk_add_f32 v[140:141], v[140:141], 1.0 op_sel_hi:[1,0]
	v_pk_fma_f32 v[34:35], v[138:139], v[34:35], v[134:135]
	v_pk_fma_f32 v[36:37], v[140:141], v[36:37], v[136:137]
	s_nop 0
	v_cvt_pk_bf16_f32 v34, v34, v35
	v_cvt_pk_bf16_f32 v35, v36, v37
	global_store_dwordx2 v245, v[34:35], s[16:17] offset:0
	v_pk_mul_f32 v[38:39], v[38:39], v[252:253] op_sel_hi:[1,0]
	v_pk_mul_f32 v[40:41], v[40:41], v[252:253] op_sel_hi:[1,0]
	v_pk_mul_f32 v[38:39], v[142:143], v[38:39]
	v_pk_mul_f32 v[40:41], v[144:145], v[40:41]
	v_pk_add_f32 v[150:151], v[150:151], 1.0 op_sel_hi:[1,0]
	v_pk_add_f32 v[152:153], v[152:153], 1.0 op_sel_hi:[1,0]
	v_pk_fma_f32 v[38:39], v[150:151], v[38:39], v[146:147]
	v_pk_fma_f32 v[40:41], v[152:153], v[40:41], v[148:149]
	s_nop 0
	v_cvt_pk_bf16_f32 v38, v38, v39
	v_cvt_pk_bf16_f32 v39, v40, v41
	global_store_dwordx2 v245, v[38:39], s[16:17] offset:512
	ds_read_b128 v[130:133], v238 offset:12288
	ds_read_b128 v[134:137], v238 offset:61440
	ds_read_b128 v[138:141], v239 offset:12288
	ds_read_b128 v[142:145], v238 offset:13312
	ds_read_b128 v[146:149], v238 offset:62464
	ds_read_b128 v[150:153], v239 offset:13312
	s_waitcnt lgkmcnt(6)
	v_pk_mul_f32 v[42:43], v[42:43], v[252:253] op_sel_hi:[1,0]
	v_pk_mul_f32 v[44:45], v[44:45], v[252:253] op_sel_hi:[1,0]
	v_pk_mul_f32 v[42:43], v[214:215], v[42:43]
	v_pk_mul_f32 v[44:45], v[216:217], v[44:45]
	v_pk_add_f32 v[222:223], v[222:223], 1.0 op_sel_hi:[1,0]
	v_pk_add_f32 v[224:225], v[224:225], 1.0 op_sel_hi:[1,0]
	v_pk_fma_f32 v[42:43], v[222:223], v[42:43], v[218:219]
	v_pk_fma_f32 v[44:45], v[224:225], v[44:45], v[220:221]
	s_nop 0
	v_cvt_pk_bf16_f32 v42, v42, v43
	v_cvt_pk_bf16_f32 v43, v44, v45
	global_store_dwordx2 v245, v[42:43], s[16:17] offset:1024
	v_pk_mul_f32 v[46:47], v[46:47], v[252:253] op_sel_hi:[1,0]
	v_pk_mul_f32 v[48:49], v[48:49], v[252:253] op_sel_hi:[1,0]
	v_pk_mul_f32 v[46:47], v[226:227], v[46:47]
	v_pk_mul_f32 v[48:49], v[228:229], v[48:49]
	v_pk_add_f32 v[234:235], v[234:235], 1.0 op_sel_hi:[1,0]
	v_pk_add_f32 v[236:237], v[236:237], 1.0 op_sel_hi:[1,0]
	v_pk_fma_f32 v[46:47], v[234:235], v[46:47], v[230:231]
	v_pk_fma_f32 v[48:49], v[236:237], v[48:49], v[232:233]
	s_nop 0
	v_cvt_pk_bf16_f32 v46, v46, v47
	v_cvt_pk_bf16_f32 v47, v48, v49
	global_store_dwordx2 v245, v[46:47], s[16:17] offset:1536
	ds_read_b128 v[214:217], v238 offset:14336
	ds_read_b128 v[218:221], v238 offset:63488
	ds_read_b128 v[222:225], v239 offset:14336
	ds_read_b128 v[226:229], v238 offset:15360
	ds_read_b128 v[230:233], v238 offset:64512
	ds_read_b128 v[234:237], v239 offset:15360
	s_waitcnt lgkmcnt(6)
	v_pk_mul_f32 v[50:51], v[50:51], v[252:253] op_sel_hi:[1,0]
	v_pk_mul_f32 v[52:53], v[52:53], v[252:253] op_sel_hi:[1,0]
	v_pk_mul_f32 v[50:51], v[130:131], v[50:51]
	v_pk_mul_f32 v[52:53], v[132:133], v[52:53]
	v_pk_add_f32 v[138:139], v[138:139], 1.0 op_sel_hi:[1,0]
	v_pk_add_f32 v[140:141], v[140:141], 1.0 op_sel_hi:[1,0]
	v_pk_fma_f32 v[50:51], v[138:139], v[50:51], v[134:135]
	v_pk_fma_f32 v[52:53], v[140:141], v[52:53], v[136:137]
	s_nop 0
	v_cvt_pk_bf16_f32 v50, v50, v51
	v_cvt_pk_bf16_f32 v51, v52, v53
	global_store_dwordx2 v245, v[50:51], s[16:17] offset:2048
	v_pk_mul_f32 v[54:55], v[54:55], v[252:253] op_sel_hi:[1,0]
	v_pk_mul_f32 v[56:57], v[56:57], v[252:253] op_sel_hi:[1,0]
	v_pk_mul_f32 v[54:55], v[142:143], v[54:55]
	v_pk_mul_f32 v[56:57], v[144:145], v[56:57]
	v_pk_add_f32 v[150:151], v[150:151], 1.0 op_sel_hi:[1,0]
	v_pk_add_f32 v[152:153], v[152:153], 1.0 op_sel_hi:[1,0]
	v_pk_fma_f32 v[54:55], v[150:151], v[54:55], v[146:147]
	v_pk_fma_f32 v[56:57], v[152:153], v[56:57], v[148:149]
	s_nop 0
	v_cvt_pk_bf16_f32 v54, v54, v55
	v_cvt_pk_bf16_f32 v55, v56, v57
	global_store_dwordx2 v245, v[54:55], s[16:17] offset:2560
	s_waitcnt lgkmcnt(0)
	v_pk_mul_f32 v[58:59], v[58:59], v[252:253] op_sel_hi:[1,0]
	v_pk_mul_f32 v[60:61], v[60:61], v[252:253] op_sel_hi:[1,0]
	v_pk_mul_f32 v[58:59], v[214:215], v[58:59]
	v_pk_mul_f32 v[60:61], v[216:217], v[60:61]
	v_pk_add_f32 v[222:223], v[222:223], 1.0 op_sel_hi:[1,0]
	v_pk_add_f32 v[224:225], v[224:225], 1.0 op_sel_hi:[1,0]
	v_pk_fma_f32 v[58:59], v[222:223], v[58:59], v[218:219]
	v_pk_fma_f32 v[60:61], v[224:225], v[60:61], v[220:221]
	s_nop 0
	v_cvt_pk_bf16_f32 v58, v58, v59
	v_cvt_pk_bf16_f32 v59, v60, v61
	global_store_dwordx2 v245, v[58:59], s[16:17] offset:3072
	v_pk_mul_f32 v[62:63], v[62:63], v[252:253] op_sel_hi:[1,0]
	v_pk_mul_f32 v[64:65], v[64:65], v[252:253] op_sel_hi:[1,0]
	v_pk_mul_f32 v[62:63], v[226:227], v[62:63]
	v_pk_mul_f32 v[64:65], v[228:229], v[64:65]
	v_pk_add_f32 v[234:235], v[234:235], 1.0 op_sel_hi:[1,0]
	v_pk_add_f32 v[236:237], v[236:237], 1.0 op_sel_hi:[1,0]
	v_pk_fma_f32 v[62:63], v[234:235], v[62:63], v[230:231]
	v_pk_fma_f32 v[64:65], v[236:237], v[64:65], v[232:233]
	s_nop 0
	v_cvt_pk_bf16_f32 v62, v62, v63
	v_cvt_pk_bf16_f32 v63, v64, v65
	global_store_dwordx2 v245, v[62:63], s[16:17] offset:3584
	s_add_u32 s16, s16, 0x1000000
	s_addc_u32 s17, s17, 0
	s_waitcnt vmcnt(16)
	ds_read_b128 v[130:133], v238 offset:0
	ds_read_b128 v[134:137], v239 offset:16384
	ds_read_b128 v[138:141], v239 offset:32768
	ds_read_b128 v[142:145], v238 offset:1024
	ds_read_b128 v[146:149], v239 offset:17408
	ds_read_b128 v[150:153], v239 offset:33792
	v_pk_mul_f32 v[156:157], v[66:67], v[66:67]
	v_pk_mul_f32 v[158:159], v[68:69], v[68:69]
	v_pk_fma_f32 v[156:157], v[70:71], v[70:71], v[156:157]
	v_pk_fma_f32 v[158:159], v[72:73], v[72:73], v[158:159]
	v_pk_fma_f32 v[156:157], v[74:75], v[74:75], v[156:157]
	v_pk_fma_f32 v[158:159], v[76:77], v[76:77], v[158:159]
	v_pk_fma_f32 v[156:157], v[78:79], v[78:79], v[156:157]
	v_pk_fma_f32 v[158:159], v[80:81], v[80:81], v[158:159]
	v_pk_fma_f32 v[156:157], v[82:83], v[82:83], v[156:157]
	v_pk_fma_f32 v[158:159], v[84:85], v[84:85], v[158:159]
	v_pk_fma_f32 v[156:157], v[86:87], v[86:87], v[156:157]
	v_pk_fma_f32 v[158:159], v[88:89], v[88:89], v[158:159]
	v_pk_fma_f32 v[156:157], v[90:91], v[90:91], v[156:157]
	v_pk_fma_f32 v[158:159], v[92:93], v[92:93], v[158:159]
	v_pk_fma_f32 v[156:157], v[94:95], v[94:95], v[156:157]
	v_pk_fma_f32 v[158:159], v[96:97], v[96:97], v[158:159]
	v_pk_fma_f32 v[156:157], v[98:99], v[98:99], v[156:157]
	v_pk_fma_f32 v[158:159], v[100:101], v[100:101], v[158:159]
	v_pk_fma_f32 v[156:157], v[102:103], v[102:103], v[156:157]
	v_pk_fma_f32 v[158:159], v[104:105], v[104:105], v[158:159]
	v_pk_fma_f32 v[156:157], v[106:107], v[106:107], v[156:157]
	v_pk_fma_f32 v[158:159], v[108:109], v[108:109], v[158:159]
	v_pk_fma_f32 v[156:157], v[110:111], v[110:111], v[156:157]
	v_pk_fma_f32 v[158:159], v[112:113], v[112:113], v[158:159]
	v_pk_fma_f32 v[156:157], v[114:115], v[114:115], v[156:157]
	v_pk_fma_f32 v[158:159], v[116:117], v[116:117], v[158:159]
	v_pk_fma_f32 v[156:157], v[118:119], v[118:119], v[156:157]
	v_pk_fma_f32 v[158:159], v[120:121], v[120:121], v[158:159]
	v_pk_fma_f32 v[156:157], v[122:123], v[122:123], v[156:157]
	v_pk_fma_f32 v[158:159], v[124:125], v[124:125], v[158:159]
	v_pk_fma_f32 v[156:157], v[126:127], v[126:127], v[156:157]
	v_pk_fma_f32 v[158:159], v[128:129], v[128:129], v[158:159]
	v_pk_add_f32 v[156:157], v[156:157], v[158:159]
	s_nop 0
	v_add_f32_e32 v252, v156, v157
	s_waitcnt lgkmcnt(0)
	ds_bpermute_b32 v254, v246, v252
	s_waitcnt lgkmcnt(0)
	v_add_f32_e32 v252, v252, v254
	ds_bpermute_b32 v254, v247, v252
	s_waitcnt lgkmcnt(0)
	v_add_f32_e32 v252, v252, v254
	ds_bpermute_b32 v254, v248, v252
	s_waitcnt lgkmcnt(0)
	v_add_f32_e32 v252, v252, v254
	ds_bpermute_b32 v254, v249, v252
	s_waitcnt lgkmcnt(0)
	v_add_f32_e32 v252, v252, v254
	ds_bpermute_b32 v254, v250, v252
	s_waitcnt lgkmcnt(0)
	v_add_f32_e32 v252, v252, v254
	ds_bpermute_b32 v254, v251, v252
	s_waitcnt lgkmcnt(0)
	v_add_f32_e32 v252, v252, v254
	v_mov_b32_e32 v254, 0x358637bd
	v_fmac_f32_e32 v254, 0x39800000, v252
	v_mul_f32_e32 v252, 0x4b800000, v254
	v_cmp_gt_f32_e32 vcc, s20, v254
	s_nop 1
	v_cndmask_b32_e32 v254, v254, v252, vcc
	v_rsq_f32_e32 v254, v254
	s_nop 0
	v_mul_f32_e32 v252, 0x45800000, v254
	v_cndmask_b32_e32 v252, v254, v252, vcc
	ds_read_b128 v[214:217], v238 offset:2048
	ds_read_b128 v[218:221], v239 offset:18432
	ds_read_b128 v[222:225], v239 offset:34816
	ds_read_b128 v[226:229], v238 offset:3072
	ds_read_b128 v[230:233], v239 offset:19456
	ds_read_b128 v[234:237], v239 offset:35840
	s_waitcnt lgkmcnt(6)
	v_pk_mul_f32 v[66:67], v[66:67], v[252:253] op_sel_hi:[1,0]
	v_pk_mul_f32 v[68:69], v[68:69], v[252:253] op_sel_hi:[1,0]
	v_pk_mul_f32 v[66:67], v[130:131], v[66:67]
	v_pk_mul_f32 v[68:69], v[132:133], v[68:69]
	v_pk_add_f32 v[138:139], v[138:139], 1.0 op_sel_hi:[1,0]
	v_pk_add_f32 v[140:141], v[140:141], 1.0 op_sel_hi:[1,0]
	v_pk_fma_f32 v[66:67], v[138:139], v[66:67], v[134:135]
	v_pk_fma_f32 v[68:69], v[140:141], v[68:69], v[136:137]
	s_nop 0
	v_cvt_pk_bf16_f32 v66, v66, v67
	v_cvt_pk_bf16_f32 v67, v68, v69
	global_store_dwordx2 v244, v[66:67], s[16:17] offset:0
	v_pk_mul_f32 v[70:71], v[70:71], v[252:253] op_sel_hi:[1,0]
	v_pk_mul_f32 v[72:73], v[72:73], v[252:253] op_sel_hi:[1,0]
	v_pk_mul_f32 v[70:71], v[142:143], v[70:71]
	v_pk_mul_f32 v[72:73], v[144:145], v[72:73]
	v_pk_add_f32 v[150:151], v[150:151], 1.0 op_sel_hi:[1,0]
	v_pk_add_f32 v[152:153], v[152:153], 1.0 op_sel_hi:[1,0]
	v_pk_fma_f32 v[70:71], v[150:151], v[70:71], v[146:147]
	v_pk_fma_f32 v[72:73], v[152:153], v[72:73], v[148:149]
	s_nop 0
	v_cvt_pk_bf16_f32 v70, v70, v71
	v_cvt_pk_bf16_f32 v71, v72, v73
	global_store_dwordx2 v244, v[70:71], s[16:17] offset:512
	ds_read_b128 v[130:133], v238 offset:4096
	ds_read_b128 v[134:137], v239 offset:20480
	ds_read_b128 v[138:141], v239 offset:36864
	ds_read_b128 v[142:145], v238 offset:5120
	ds_read_b128 v[146:149], v239 offset:21504
	ds_read_b128 v[150:153], v239 offset:37888
	s_waitcnt lgkmcnt(6)
	v_pk_mul_f32 v[74:75], v[74:75], v[252:253] op_sel_hi:[1,0]
	v_pk_mul_f32 v[76:77], v[76:77], v[252:253] op_sel_hi:[1,0]
	v_pk_mul_f32 v[74:75], v[214:215], v[74:75]
	v_pk_mul_f32 v[76:77], v[216:217], v[76:77]
	v_pk_add_f32 v[222:223], v[222:223], 1.0 op_sel_hi:[1,0]
	v_pk_add_f32 v[224:225], v[224:225], 1.0 op_sel_hi:[1,0]
	v_pk_fma_f32 v[74:75], v[222:223], v[74:75], v[218:219]
	v_pk_fma_f32 v[76:77], v[224:225], v[76:77], v[220:221]
	s_nop 0
	v_cvt_pk_bf16_f32 v74, v74, v75
	v_cvt_pk_bf16_f32 v75, v76, v77
	global_store_dwordx2 v244, v[74:75], s[16:17] offset:1024
	v_pk_mul_f32 v[78:79], v[78:79], v[252:253] op_sel_hi:[1,0]
	v_pk_mul_f32 v[80:81], v[80:81], v[252:253] op_sel_hi:[1,0]
	v_pk_mul_f32 v[78:79], v[226:227], v[78:79]
	v_pk_mul_f32 v[80:81], v[228:229], v[80:81]
	v_pk_add_f32 v[234:235], v[234:235], 1.0 op_sel_hi:[1,0]
	v_pk_add_f32 v[236:237], v[236:237], 1.0 op_sel_hi:[1,0]
	v_pk_fma_f32 v[78:79], v[234:235], v[78:79], v[230:231]
	v_pk_fma_f32 v[80:81], v[236:237], v[80:81], v[232:233]
	s_nop 0
	v_cvt_pk_bf16_f32 v78, v78, v79
	v_cvt_pk_bf16_f32 v79, v80, v81
	global_store_dwordx2 v244, v[78:79], s[16:17] offset:1536
	ds_read_b128 v[214:217], v238 offset:6144
	ds_read_b128 v[218:221], v239 offset:22528
	ds_read_b128 v[222:225], v239 offset:38912
	ds_read_b128 v[226:229], v238 offset:7168
	ds_read_b128 v[230:233], v239 offset:23552
	ds_read_b128 v[234:237], v239 offset:39936
	s_waitcnt lgkmcnt(6)
	v_pk_mul_f32 v[82:83], v[82:83], v[252:253] op_sel_hi:[1,0]
	v_pk_mul_f32 v[84:85], v[84:85], v[252:253] op_sel_hi:[1,0]
	v_pk_mul_f32 v[82:83], v[130:131], v[82:83]
	v_pk_mul_f32 v[84:85], v[132:133], v[84:85]
	v_pk_add_f32 v[138:139], v[138:139], 1.0 op_sel_hi:[1,0]
	v_pk_add_f32 v[140:141], v[140:141], 1.0 op_sel_hi:[1,0]
	v_pk_fma_f32 v[82:83], v[138:139], v[82:83], v[134:135]
	v_pk_fma_f32 v[84:85], v[140:141], v[84:85], v[136:137]
	s_nop 0
	v_cvt_pk_bf16_f32 v82, v82, v83
	v_cvt_pk_bf16_f32 v83, v84, v85
	global_store_dwordx2 v244, v[82:83], s[16:17] offset:2048
	v_pk_mul_f32 v[86:87], v[86:87], v[252:253] op_sel_hi:[1,0]
	v_pk_mul_f32 v[88:89], v[88:89], v[252:253] op_sel_hi:[1,0]
	v_pk_mul_f32 v[86:87], v[142:143], v[86:87]
	v_pk_mul_f32 v[88:89], v[144:145], v[88:89]
	v_pk_add_f32 v[150:151], v[150:151], 1.0 op_sel_hi:[1,0]
	v_pk_add_f32 v[152:153], v[152:153], 1.0 op_sel_hi:[1,0]
	v_pk_fma_f32 v[86:87], v[150:151], v[86:87], v[146:147]
	v_pk_fma_f32 v[88:89], v[152:153], v[88:89], v[148:149]
	s_nop 0
	v_cvt_pk_bf16_f32 v86, v86, v87
	v_cvt_pk_bf16_f32 v87, v88, v89
	global_store_dwordx2 v244, v[86:87], s[16:17] offset:2560
	ds_read_b128 v[130:133], v238 offset:8192
	ds_read_b128 v[134:137], v239 offset:24576
	ds_read_b128 v[138:141], v239 offset:40960
	ds_read_b128 v[142:145], v238 offset:9216
	ds_read_b128 v[146:149], v239 offset:25600
	ds_read_b128 v[150:153], v239 offset:41984
	s_waitcnt lgkmcnt(6)
	v_pk_mul_f32 v[90:91], v[90:91], v[252:253] op_sel_hi:[1,0]
	v_pk_mul_f32 v[92:93], v[92:93], v[252:253] op_sel_hi:[1,0]
	v_pk_mul_f32 v[90:91], v[214:215], v[90:91]
	v_pk_mul_f32 v[92:93], v[216:217], v[92:93]
	v_pk_add_f32 v[222:223], v[222:223], 1.0 op_sel_hi:[1,0]
	v_pk_add_f32 v[224:225], v[224:225], 1.0 op_sel_hi:[1,0]
	v_pk_fma_f32 v[90:91], v[222:223], v[90:91], v[218:219]
	v_pk_fma_f32 v[92:93], v[224:225], v[92:93], v[220:221]
	s_nop 0
	v_cvt_pk_bf16_f32 v90, v90, v91
	v_cvt_pk_bf16_f32 v91, v92, v93
	global_store_dwordx2 v244, v[90:91], s[16:17] offset:3072
	v_pk_mul_f32 v[94:95], v[94:95], v[252:253] op_sel_hi:[1,0]
	v_pk_mul_f32 v[96:97], v[96:97], v[252:253] op_sel_hi:[1,0]
	v_pk_mul_f32 v[94:95], v[226:227], v[94:95]
	v_pk_mul_f32 v[96:97], v[228:229], v[96:97]
	v_pk_add_f32 v[234:235], v[234:235], 1.0 op_sel_hi:[1,0]
	v_pk_add_f32 v[236:237], v[236:237], 1.0 op_sel_hi:[1,0]
	v_pk_fma_f32 v[94:95], v[234:235], v[94:95], v[230:231]
	v_pk_fma_f32 v[96:97], v[236:237], v[96:97], v[232:233]
	s_nop 0
	v_cvt_pk_bf16_f32 v94, v94, v95
	v_cvt_pk_bf16_f32 v95, v96, v97
	global_store_dwordx2 v244, v[94:95], s[16:17] offset:3584
	ds_read_b128 v[214:217], v238 offset:10240
	ds_read_b128 v[218:221], v239 offset:26624
	ds_read_b128 v[222:225], v239 offset:43008
	ds_read_b128 v[226:229], v238 offset:11264
	ds_read_b128 v[230:233], v239 offset:27648
	ds_read_b128 v[234:237], v239 offset:44032
	s_waitcnt lgkmcnt(6)
	v_pk_mul_f32 v[98:99], v[98:99], v[252:253] op_sel_hi:[1,0]
	v_pk_mul_f32 v[100:101], v[100:101], v[252:253] op_sel_hi:[1,0]
	v_pk_mul_f32 v[98:99], v[130:131], v[98:99]
	v_pk_mul_f32 v[100:101], v[132:133], v[100:101]
	v_pk_add_f32 v[138:139], v[138:139], 1.0 op_sel_hi:[1,0]
	v_pk_add_f32 v[140:141], v[140:141], 1.0 op_sel_hi:[1,0]
	v_pk_fma_f32 v[98:99], v[138:139], v[98:99], v[134:135]
	v_pk_fma_f32 v[100:101], v[140:141], v[100:101], v[136:137]
	s_nop 0
	v_cvt_pk_bf16_f32 v98, v98, v99
	v_cvt_pk_bf16_f32 v99, v100, v101
	global_store_dwordx2 v245, v[98:99], s[16:17] offset:0
	v_pk_mul_f32 v[102:103], v[102:103], v[252:253] op_sel_hi:[1,0]
	v_pk_mul_f32 v[104:105], v[104:105], v[252:253] op_sel_hi:[1,0]
	v_pk_mul_f32 v[102:103], v[142:143], v[102:103]
	v_pk_mul_f32 v[104:105], v[144:145], v[104:105]
	v_pk_add_f32 v[150:151], v[150:151], 1.0 op_sel_hi:[1,0]
	v_pk_add_f32 v[152:153], v[152:153], 1.0 op_sel_hi:[1,0]
	v_pk_fma_f32 v[102:103], v[150:151], v[102:103], v[146:147]
	v_pk_fma_f32 v[104:105], v[152:153], v[104:105], v[148:149]
	s_nop 0
	v_cvt_pk_bf16_f32 v102, v102, v103
	v_cvt_pk_bf16_f32 v103, v104, v105
	global_store_dwordx2 v245, v[102:103], s[16:17] offset:512
	ds_read_b128 v[130:133], v238 offset:12288
	ds_read_b128 v[134:137], v239 offset:28672
	ds_read_b128 v[138:141], v239 offset:45056
	ds_read_b128 v[142:145], v238 offset:13312
	ds_read_b128 v[146:149], v239 offset:29696
	ds_read_b128 v[150:153], v239 offset:46080
	s_waitcnt lgkmcnt(6)
	v_pk_mul_f32 v[106:107], v[106:107], v[252:253] op_sel_hi:[1,0]
	v_pk_mul_f32 v[108:109], v[108:109], v[252:253] op_sel_hi:[1,0]
	v_pk_mul_f32 v[106:107], v[214:215], v[106:107]
	v_pk_mul_f32 v[108:109], v[216:217], v[108:109]
	v_pk_add_f32 v[222:223], v[222:223], 1.0 op_sel_hi:[1,0]
	v_pk_add_f32 v[224:225], v[224:225], 1.0 op_sel_hi:[1,0]
	v_pk_fma_f32 v[106:107], v[222:223], v[106:107], v[218:219]
	v_pk_fma_f32 v[108:109], v[224:225], v[108:109], v[220:221]
	s_nop 0
	v_cvt_pk_bf16_f32 v106, v106, v107
	v_cvt_pk_bf16_f32 v107, v108, v109
	global_store_dwordx2 v245, v[106:107], s[16:17] offset:1024
	v_pk_mul_f32 v[110:111], v[110:111], v[252:253] op_sel_hi:[1,0]
	v_pk_mul_f32 v[112:113], v[112:113], v[252:253] op_sel_hi:[1,0]
	v_pk_mul_f32 v[110:111], v[226:227], v[110:111]
	v_pk_mul_f32 v[112:113], v[228:229], v[112:113]
	v_pk_add_f32 v[234:235], v[234:235], 1.0 op_sel_hi:[1,0]
	v_pk_add_f32 v[236:237], v[236:237], 1.0 op_sel_hi:[1,0]
	v_pk_fma_f32 v[110:111], v[234:235], v[110:111], v[230:231]
	v_pk_fma_f32 v[112:113], v[236:237], v[112:113], v[232:233]
	s_nop 0
	v_cvt_pk_bf16_f32 v110, v110, v111
	v_cvt_pk_bf16_f32 v111, v112, v113
	global_store_dwordx2 v245, v[110:111], s[16:17] offset:1536
	ds_read_b128 v[214:217], v238 offset:14336
	ds_read_b128 v[218:221], v239 offset:30720
	ds_read_b128 v[222:225], v239 offset:47104
	ds_read_b128 v[226:229], v238 offset:15360
	ds_read_b128 v[230:233], v239 offset:31744
	ds_read_b128 v[234:237], v239 offset:48128
	s_waitcnt lgkmcnt(6)
	v_pk_mul_f32 v[114:115], v[114:115], v[252:253] op_sel_hi:[1,0]
	v_pk_mul_f32 v[116:117], v[116:117], v[252:253] op_sel_hi:[1,0]
	v_pk_mul_f32 v[114:115], v[130:131], v[114:115]
	v_pk_mul_f32 v[116:117], v[132:133], v[116:117]
	v_pk_add_f32 v[138:139], v[138:139], 1.0 op_sel_hi:[1,0]
	v_pk_add_f32 v[140:141], v[140:141], 1.0 op_sel_hi:[1,0]
	v_pk_fma_f32 v[114:115], v[138:139], v[114:115], v[134:135]
	v_pk_fma_f32 v[116:117], v[140:141], v[116:117], v[136:137]
	s_nop 0
	v_cvt_pk_bf16_f32 v114, v114, v115
	v_cvt_pk_bf16_f32 v115, v116, v117
	global_store_dwordx2 v245, v[114:115], s[16:17] offset:2048
	v_pk_mul_f32 v[118:119], v[118:119], v[252:253] op_sel_hi:[1,0]
	v_pk_mul_f32 v[120:121], v[120:121], v[252:253] op_sel_hi:[1,0]
	v_pk_mul_f32 v[118:119], v[142:143], v[118:119]
	v_pk_mul_f32 v[120:121], v[144:145], v[120:121]
	v_pk_add_f32 v[150:151], v[150:151], 1.0 op_sel_hi:[1,0]
	v_pk_add_f32 v[152:153], v[152:153], 1.0 op_sel_hi:[1,0]
	v_pk_fma_f32 v[118:119], v[150:151], v[118:119], v[146:147]
	v_pk_fma_f32 v[120:121], v[152:153], v[120:121], v[148:149]
	s_nop 0
	v_cvt_pk_bf16_f32 v118, v118, v119
	v_cvt_pk_bf16_f32 v119, v120, v121
	global_store_dwordx2 v245, v[118:119], s[16:17] offset:2560
	s_waitcnt lgkmcnt(0)
	v_pk_mul_f32 v[122:123], v[122:123], v[252:253] op_sel_hi:[1,0]
	v_pk_mul_f32 v[124:125], v[124:125], v[252:253] op_sel_hi:[1,0]
	v_pk_mul_f32 v[122:123], v[214:215], v[122:123]
	v_pk_mul_f32 v[124:125], v[216:217], v[124:125]
	v_pk_add_f32 v[222:223], v[222:223], 1.0 op_sel_hi:[1,0]
	v_pk_add_f32 v[224:225], v[224:225], 1.0 op_sel_hi:[1,0]
	v_pk_fma_f32 v[122:123], v[222:223], v[122:123], v[218:219]
	v_pk_fma_f32 v[124:125], v[224:225], v[124:125], v[220:221]
	s_nop 0
	v_cvt_pk_bf16_f32 v122, v122, v123
	v_cvt_pk_bf16_f32 v123, v124, v125
	global_store_dwordx2 v245, v[122:123], s[16:17] offset:3072
	v_pk_mul_f32 v[126:127], v[126:127], v[252:253] op_sel_hi:[1,0]
	v_pk_mul_f32 v[128:129], v[128:129], v[252:253] op_sel_hi:[1,0]
	v_pk_mul_f32 v[126:127], v[226:227], v[126:127]
	v_pk_mul_f32 v[128:129], v[228:229], v[128:129]
	v_pk_add_f32 v[234:235], v[234:235], 1.0 op_sel_hi:[1,0]
	v_pk_add_f32 v[236:237], v[236:237], 1.0 op_sel_hi:[1,0]
	v_pk_fma_f32 v[126:127], v[234:235], v[126:127], v[230:231]
	v_pk_fma_f32 v[128:129], v[236:237], v[128:129], v[232:233]
	s_nop 0
	v_cvt_pk_bf16_f32 v126, v126, v127
	v_cvt_pk_bf16_f32 v127, v128, v129
	global_store_dwordx2 v245, v[126:127], s[16:17] offset:3584
	s_branch .LBB0_104

.LBB0_711:
	s_cmp_lt_i32 s72, 11
	s_cselect_b64 s[6:7], -1, 0
	s_and_b64 s[4:5], s[6:7], s[4:5]
	s_andn2_b64 vcc, exec, s[4:5]
	s_cbranch_vccnz .LBB0_715
	s_lshl_b32 s3, s2, 3
	s_add_i32 s6, s96, s3
	s_cmpk_gt_i32 s6, 0x2fff
	s_cbranch_scc1 .LBB0_715
	s_cmp_lg_u32 s33, 0x100
	s_cbranch_scc1 .LrA_old
	v_readlane_b32 s18, v255, 8
	v_readlane_b32 s19, v255, 9
	v_readlane_b32 s20, v255, 10
	v_readlane_b32 s21, v255, 11
	v_lshlrev_b32_e32 v238, 4, v174
	v_add_u32_e32 v239, 0x10000, v238
	s_lshl_b32 s7, s96, 11
	v_add_u32_e32 v240, s7, v238
	v_add_u32_e32 v241, 0x1000, v238
	v_add_u32_e32 v242, 0x2000, v238
	v_add_u32_e32 v243, 0x3000, v238
	v_lshlrev_b32_e32 v244, 3, v174
	v_add_u32_e32 v245, 0x1000, v244
	v_xor_b32_e32 v246, 1, v174
	v_lshlrev_b32_e32 v246, 2, v246
	v_xor_b32_e32 v247, 2, v174
	v_lshlrev_b32_e32 v247, 2, v247
	v_xor_b32_e32 v248, 4, v174
	v_lshlrev_b32_e32 v248, 2, v248
	v_xor_b32_e32 v249, 8, v174
	v_lshlrev_b32_e32 v249, 2, v249
	v_xor_b32_e32 v250, 16, v174
	v_lshlrev_b32_e32 v250, 2, v250
	v_xor_b32_e32 v251, 32, v174
	v_lshlrev_b32_e32 v251, 2, v251
	s_mov_b32 s32, 0x800000
	s_lshr_b32 s3, s2, 7
	s_nop 4
	s_add_u32 s8, s7, 0x0
	s_mov_b32 m0, s8
	s_nop 0
	global_load_lds_dwordx4 v240, s[18:19]
	global_load_lds_dwordx4 v240, s[18:19] offset:1024
	s_add_u32 s8, s7, 0x4000
	s_mov_b32 m0, s8
	s_nop 0
	global_load_lds_dwordx4 v240, s[20:21]
	global_load_lds_dwordx4 v240, s[20:21] offset:1024
	s_mov_b32 s10, s28
	s_mov_b32 s11, s29
	s_add_u32 s12, s10, 0x8000
	s_addc_u32 s13, s11, 0
	s_add_u32 s8, s7, 0x8000
	s_mov_b32 m0, s8
	s_nop 0
	global_load_lds_dwordx4 v240, s[12:13]
	global_load_lds_dwordx4 v240, s[12:13] offset:1024
	s_add_u32 s12, s10, 0xc000
	s_addc_u32 s13, s11, 0
	s_add_u32 s8, s7, 0xc000
	s_mov_b32 m0, s8
	s_nop 0
	global_load_lds_dwordx4 v240, s[12:13]
	global_load_lds_dwordx4 v240, s[12:13] offset:1024
	s_add_u32 s12, s10, 0x10000
	s_addc_u32 s13, s11, 0
	s_add_u32 s8, s7, 0x10000
	s_mov_b32 m0, s8
	s_nop 0
	global_load_lds_dwordx4 v240, s[12:13]
	global_load_lds_dwordx4 v240, s[12:13] offset:1024
	s_add_i32 s9, s3, 1
	s_mul_i32 s9, s9, 0x18000
	s_add_u32 s10, s28, s9
	s_addc_u32 s11, s29, 0
	s_add_u32 s12, s10, 0x8000
	s_addc_u32 s13, s11, 0
	s_add_u32 s8, s7, 0x14000
	s_mov_b32 m0, s8
	s_nop 0
	global_load_lds_dwordx4 v240, s[12:13]
	global_load_lds_dwordx4 v240, s[12:13] offset:1024
	s_add_u32 s12, s10, 0xc000
	s_addc_u32 s13, s11, 0
	s_add_u32 s8, s7, 0x18000
	s_mov_b32 m0, s8
	s_nop 0
	global_load_lds_dwordx4 v240, s[12:13]
	global_load_lds_dwordx4 v240, s[12:13] offset:1024
	s_add_u32 s12, s10, 0x10000
	s_addc_u32 s13, s11, 0
	s_add_u32 s8, s7, 0x1c000
	s_mov_b32 m0, s8
	s_nop 0
	global_load_lds_dwordx4 v240, s[12:13]
	global_load_lds_dwordx4 v240, s[12:13] offset:1024
	s_lshl_b32 s9, s6, 14
	s_add_u32 s14, s52, s9
	s_addc_u32 s15, s53, 0
	s_add_u32 s44, s54, s9
	s_addc_u32 s45, s55, 0
	s_lshl_b32 s9, s6, 13
	s_add_u32 s22, s70, s9
	s_addc_u32 s23, s71, 0
	s_add_u32 s16, s22, 0x1ec00000
	s_addc_u32 s17, s23, 0
	s_add_u32 s38, s22, 0x4b000000
	s_addc_u32 s39, s23, 0
	s_add_u32 s22, s22, 0x3f000000
	s_addc_u32 s23, s23, 0
	global_load_dwordx4 v[2:5], v238, s[14:15] offset:0
	global_load_dwordx4 v[6:9], v238, s[14:15] offset:1024
	global_load_dwordx4 v[10:13], v238, s[14:15] offset:2048
	global_load_dwordx4 v[14:17], v238, s[14:15] offset:3072
	global_load_dwordx4 v[18:21], v241, s[14:15] offset:0
	global_load_dwordx4 v[22:25], v241, s[14:15] offset:1024
	global_load_dwordx4 v[26:29], v241, s[14:15] offset:2048
	global_load_dwordx4 v[30:33], v241, s[14:15] offset:3072
	global_load_dwordx4 v[34:37], v242, s[14:15] offset:0
	global_load_dwordx4 v[38:41], v242, s[14:15] offset:1024
	global_load_dwordx4 v[42:45], v242, s[14:15] offset:2048
	global_load_dwordx4 v[46:49], v242, s[14:15] offset:3072
	global_load_dwordx4 v[50:53], v243, s[14:15] offset:0
	global_load_dwordx4 v[54:57], v243, s[14:15] offset:1024
	global_load_dwordx4 v[58:61], v243, s[14:15] offset:2048
	global_load_dwordx4 v[62:65], v243, s[14:15] offset:3072
	global_load_dwordx2 v[130:131], v244, s[16:17] offset:0
	global_load_dwordx2 v[132:133], v244, s[16:17] offset:512
	global_load_dwordx2 v[134:135], v244, s[16:17] offset:1024
	global_load_dwordx2 v[136:137], v244, s[16:17] offset:1536
	global_load_dwordx2 v[138:139], v244, s[16:17] offset:2048
	global_load_dwordx2 v[140:141], v244, s[16:17] offset:2560
	global_load_dwordx2 v[142:143], v244, s[16:17] offset:3072
	global_load_dwordx2 v[144:145], v244, s[16:17] offset:3584
	global_load_dwordx2 v[146:147], v245, s[16:17] offset:0
	global_load_dwordx2 v[148:149], v245, s[16:17] offset:512
	global_load_dwordx2 v[150:151], v245, s[16:17] offset:1024
	global_load_dwordx2 v[152:153], v245, s[16:17] offset:1536
	global_load_dwordx2 v[154:155], v245, s[16:17] offset:2048
	global_load_dwordx2 v[156:157], v245, s[16:17] offset:2560
	global_load_dwordx2 v[158:159], v245, s[16:17] offset:3072
	global_load_dwordx2 v[160:161], v245, s[16:17] offset:3584
	s_waitcnt vmcnt(32)
	s_barrier
	s_waitcnt vmcnt(0)
	s_add_u32 s14, s14, 0x2000000
	s_addc_u32 s15, s15, 0
	global_load_dwordx4 v[66:69], v238, s[14:15] offset:0
	global_load_dwordx4 v[70:73], v238, s[14:15] offset:1024
	global_load_dwordx4 v[74:77], v238, s[14:15] offset:2048
	global_load_dwordx4 v[78:81], v238, s[14:15] offset:3072
	global_load_dwordx4 v[82:85], v241, s[14:15] offset:0
	global_load_dwordx4 v[86:89], v241, s[14:15] offset:1024
	global_load_dwordx4 v[90:93], v241, s[14:15] offset:2048
	global_load_dwordx4 v[94:97], v241, s[14:15] offset:3072
	global_load_dwordx4 v[98:101], v242, s[14:15] offset:0
	global_load_dwordx4 v[102:105], v242, s[14:15] offset:1024
	global_load_dwordx4 v[106:109], v242, s[14:15] offset:2048
	global_load_dwordx4 v[110:113], v242, s[14:15] offset:3072
	global_load_dwordx4 v[114:117], v243, s[14:15] offset:0
	global_load_dwordx4 v[118:121], v243, s[14:15] offset:1024
	global_load_dwordx4 v[122:125], v243, s[14:15] offset:2048
	global_load_dwordx4 v[126:129], v243, s[14:15] offset:3072
	ds_read_b128 v[214:217], v238 offset:0
	ds_read_b128 v[218:221], v238 offset:32768
	v_lshlrev_b32_e32 v162, 16, v130
	v_and_b32_e32 v163, 0xffff0000, v130
	v_lshlrev_b32_e32 v164, 16, v131
	v_and_b32_e32 v165, 0xffff0000, v131
	v_pk_mul_f32 v[170:171], v[162:163], v[162:163]
	v_pk_mul_f32 v[172:173], v[164:165], v[164:165]
	v_lshlrev_b32_e32 v166, 16, v132
	v_and_b32_e32 v167, 0xffff0000, v132
	v_lshlrev_b32_e32 v168, 16, v133
	v_and_b32_e32 v169, 0xffff0000, v133
	v_pk_fma_f32 v[170:171], v[166:167], v[166:167], v[170:171]
	v_pk_fma_f32 v[172:173], v[168:169], v[168:169], v[172:173]
	v_lshlrev_b32_e32 v162, 16, v134
	v_and_b32_e32 v163, 0xffff0000, v134
	v_lshlrev_b32_e32 v164, 16, v135
	v_and_b32_e32 v165, 0xffff0000, v135
	v_pk_fma_f32 v[170:171], v[162:163], v[162:163], v[170:171]
	v_pk_fma_f32 v[172:173], v[164:165], v[164:165], v[172:173]
	v_lshlrev_b32_e32 v166, 16, v136
	v_and_b32_e32 v167, 0xffff0000, v136
	v_lshlrev_b32_e32 v168, 16, v137
	v_and_b32_e32 v169, 0xffff0000, v137
	v_pk_fma_f32 v[170:171], v[166:167], v[166:167], v[170:171]
	v_pk_fma_f32 v[172:173], v[168:169], v[168:169], v[172:173]
	v_lshlrev_b32_e32 v162, 16, v138
	v_and_b32_e32 v163, 0xffff0000, v138
	v_lshlrev_b32_e32 v164, 16, v139
	v_and_b32_e32 v165, 0xffff0000, v139
	v_pk_fma_f32 v[170:171], v[162:163], v[162:163], v[170:171]
	v_pk_fma_f32 v[172:173], v[164:165], v[164:165], v[172:173]
	v_lshlrev_b32_e32 v166, 16, v140
	v_and_b32_e32 v167, 0xffff0000, v140
	v_lshlrev_b32_e32 v168, 16, v141
	v_and_b32_e32 v169, 0xffff0000, v141
	v_pk_fma_f32 v[170:171], v[166:167], v[166:167], v[170:171]
	v_pk_fma_f32 v[172:173], v[168:169], v[168:169], v[172:173]
	v_lshlrev_b32_e32 v162, 16, v142
	v_and_b32_e32 v163, 0xffff0000, v142
	v_lshlrev_b32_e32 v164, 16, v143
	v_and_b32_e32 v165, 0xffff0000, v143
	v_pk_fma_f32 v[170:171], v[162:163], v[162:163], v[170:171]
	v_pk_fma_f32 v[172:173], v[164:165], v[164:165], v[172:173]
	v_lshlrev_b32_e32 v166, 16, v144
	v_and_b32_e32 v167, 0xffff0000, v144
	v_lshlrev_b32_e32 v168, 16, v145
	v_and_b32_e32 v169, 0xffff0000, v145
	v_pk_fma_f32 v[170:171], v[166:167], v[166:167], v[170:171]
	v_pk_fma_f32 v[172:173], v[168:169], v[168:169], v[172:173]
	v_lshlrev_b32_e32 v162, 16, v146
	v_and_b32_e32 v163, 0xffff0000, v146
	v_lshlrev_b32_e32 v164, 16, v147
	v_and_b32_e32 v165, 0xffff0000, v147
	v_pk_fma_f32 v[170:171], v[162:163], v[162:163], v[170:171]
	v_pk_fma_f32 v[172:173], v[164:165], v[164:165], v[172:173]
	v_lshlrev_b32_e32 v166, 16, v148
	v_and_b32_e32 v167, 0xffff0000, v148
	v_lshlrev_b32_e32 v168, 16, v149
	v_and_b32_e32 v169, 0xffff0000, v149
	v_pk_fma_f32 v[170:171], v[166:167], v[166:167], v[170:171]
	v_pk_fma_f32 v[172:173], v[168:169], v[168:169], v[172:173]
	v_lshlrev_b32_e32 v162, 16, v150
	v_and_b32_e32 v163, 0xffff0000, v150
	v_lshlrev_b32_e32 v164, 16, v151
	v_and_b32_e32 v165, 0xffff0000, v151
	v_pk_fma_f32 v[170:171], v[162:163], v[162:163], v[170:171]
	v_pk_fma_f32 v[172:173], v[164:165], v[164:165], v[172:173]
	v_lshlrev_b32_e32 v166, 16, v152
	v_and_b32_e32 v167, 0xffff0000, v152
	v_lshlrev_b32_e32 v168, 16, v153
	v_and_b32_e32 v169, 0xffff0000, v153
	v_pk_fma_f32 v[170:171], v[166:167], v[166:167], v[170:171]
	v_pk_fma_f32 v[172:173], v[168:169], v[168:169], v[172:173]
	v_lshlrev_b32_e32 v162, 16, v154
	v_and_b32_e32 v163, 0xffff0000, v154
	v_lshlrev_b32_e32 v164, 16, v155
	v_and_b32_e32 v165, 0xffff0000, v155
	v_pk_fma_f32 v[170:171], v[162:163], v[162:163], v[170:171]
	v_pk_fma_f32 v[172:173], v[164:165], v[164:165], v[172:173]
	v_lshlrev_b32_e32 v166, 16, v156
	v_and_b32_e32 v167, 0xffff0000, v156
	v_lshlrev_b32_e32 v168, 16, v157
	v_and_b32_e32 v169, 0xffff0000, v157
	v_pk_fma_f32 v[170:171], v[166:167], v[166:167], v[170:171]
	v_pk_fma_f32 v[172:173], v[168:169], v[168:169], v[172:173]
	v_lshlrev_b32_e32 v162, 16, v158
	v_and_b32_e32 v163, 0xffff0000, v158
	v_lshlrev_b32_e32 v164, 16, v159
	v_and_b32_e32 v165, 0xffff0000, v159
	v_pk_fma_f32 v[170:171], v[162:163], v[162:163], v[170:171]
	v_pk_fma_f32 v[172:173], v[164:165], v[164:165], v[172:173]
	v_lshlrev_b32_e32 v166, 16, v160
	v_and_b32_e32 v167, 0xffff0000, v160
	v_lshlrev_b32_e32 v168, 16, v161
	v_and_b32_e32 v169, 0xffff0000, v161
	v_pk_fma_f32 v[170:171], v[166:167], v[166:167], v[170:171]
	v_pk_fma_f32 v[172:173], v[168:169], v[168:169], v[172:173]
	v_pk_add_f32 v[170:171], v[170:171], v[172:173]
	s_nop 0
	v_add_f32_e32 v252, v170, v171
	s_waitcnt lgkmcnt(0)
	ds_bpermute_b32 v254, v246, v252
	s_waitcnt lgkmcnt(0)
	v_add_f32_e32 v252, v252, v254
	ds_bpermute_b32 v254, v247, v252
	s_waitcnt lgkmcnt(0)
	v_add_f32_e32 v252, v252, v254
	ds_bpermute_b32 v254, v248, v252
	s_waitcnt lgkmcnt(0)
	v_add_f32_e32 v252, v252, v254
	ds_bpermute_b32 v254, v249, v252
	s_waitcnt lgkmcnt(0)
	v_add_f32_e32 v252, v252, v254
	ds_bpermute_b32 v254, v250, v252
	s_waitcnt lgkmcnt(0)
	v_add_f32_e32 v252, v252, v254
	ds_bpermute_b32 v254, v251, v252
	s_waitcnt lgkmcnt(0)
	v_add_f32_e32 v252, v252, v254
	v_mov_b32_e32 v254, 0x358637bd
	v_fmac_f32_e32 v254, 0x39800000, v252
	v_mul_f32_e32 v252, 0x4b800000, v254
	v_cmp_gt_f32_e32 vcc, s32, v254
	s_nop 1
	v_cndmask_b32_e32 v254, v254, v252, vcc
	v_rsq_f32_e32 v254, v254
	s_nop 0
	v_mul_f32_e32 v252, 0x45800000, v254
	v_cndmask_b32_e32 v252, v254, v252, vcc
	ds_read_b128 v[226:229], v238 offset:1024
	ds_read_b128 v[230:233], v238 offset:33792
	s_waitcnt lgkmcnt(2)
	v_lshlrev_b32_e32 v162, 16, v130
	v_and_b32_e32 v163, 0xffff0000, v130
	v_lshlrev_b32_e32 v164, 16, v131
	v_and_b32_e32 v165, 0xffff0000, v131
	v_pk_mul_f32 v[162:163], v[162:163], v[252:253] op_sel_hi:[1,0]
	v_pk_mul_f32 v[164:165], v[164:165], v[252:253] op_sel_hi:[1,0]
	v_pk_mul_f32 v[162:163], v[162:163], v[214:215]
	v_pk_mul_f32 v[164:165], v[164:165], v[216:217]
	v_pk_fma_f32 v[2:3], v[218:219], v[162:163], v[2:3]
	v_pk_fma_f32 v[4:5], v[220:221], v[164:165], v[4:5]
	v_pk_mul_f32 v[170:171], v[2:3], v[2:3]
	v_pk_mul_f32 v[172:173], v[4:5], v[4:5]
	v_cvt_pk_bf16_f32 v166, v2, v3
	v_cvt_pk_bf16_f32 v167, v4, v5
	global_store_dwordx2 v244, v[166:167], s[22:23] offset:0
	ds_read_b128 v[214:217], v238 offset:2048
	ds_read_b128 v[218:221], v238 offset:34816
	s_waitcnt lgkmcnt(2)
	v_lshlrev_b32_e32 v162, 16, v132
	v_and_b32_e32 v163, 0xffff0000, v132
	v_lshlrev_b32_e32 v164, 16, v133
	v_and_b32_e32 v165, 0xffff0000, v133
	v_pk_mul_f32 v[162:163], v[162:163], v[252:253] op_sel_hi:[1,0]
	v_pk_mul_f32 v[164:165], v[164:165], v[252:253] op_sel_hi:[1,0]
	v_pk_mul_f32 v[162:163], v[162:163], v[226:227]
	v_pk_mul_f32 v[164:165], v[164:165], v[228:229]
	v_pk_fma_f32 v[6:7], v[230:231], v[162:163], v[6:7]
	v_pk_fma_f32 v[8:9], v[232:233], v[164:165], v[8:9]
	v_pk_fma_f32 v[170:171], v[6:7], v[6:7], v[170:171]
	v_pk_fma_f32 v[172:173], v[8:9], v[8:9], v[172:173]
	v_cvt_pk_bf16_f32 v168, v6, v7
	v_cvt_pk_bf16_f32 v169, v8, v9
	global_store_dwordx2 v244, v[168:169], s[22:23] offset:512
	ds_read_b128 v[226:229], v238 offset:3072
	ds_read_b128 v[230:233], v238 offset:35840
	s_waitcnt lgkmcnt(2)
	v_lshlrev_b32_e32 v162, 16, v134
	v_and_b32_e32 v163, 0xffff0000, v134
	v_lshlrev_b32_e32 v164, 16, v135
	v_and_b32_e32 v165, 0xffff0000, v135
	v_pk_mul_f32 v[162:163], v[162:163], v[252:253] op_sel_hi:[1,0]
	v_pk_mul_f32 v[164:165], v[164:165], v[252:253] op_sel_hi:[1,0]
	v_pk_mul_f32 v[162:163], v[162:163], v[214:215]
	v_pk_mul_f32 v[164:165], v[164:165], v[216:217]
	v_pk_fma_f32 v[10:11], v[218:219], v[162:163], v[10:11]
	v_pk_fma_f32 v[12:13], v[220:221], v[164:165], v[12:13]
	v_pk_fma_f32 v[170:171], v[10:11], v[10:11], v[170:171]
	v_pk_fma_f32 v[172:173], v[12:13], v[12:13], v[172:173]
	v_cvt_pk_bf16_f32 v166, v10, v11
	v_cvt_pk_bf16_f32 v167, v12, v13
	global_store_dwordx2 v244, v[166:167], s[22:23] offset:1024
	ds_read_b128 v[214:217], v238 offset:4096
	ds_read_b128 v[218:221], v238 offset:36864
	s_waitcnt lgkmcnt(2)
	v_lshlrev_b32_e32 v162, 16, v136
	v_and_b32_e32 v163, 0xffff0000, v136
	v_lshlrev_b32_e32 v164, 16, v137
	v_and_b32_e32 v165, 0xffff0000, v137
	v_pk_mul_f32 v[162:163], v[162:163], v[252:253] op_sel_hi:[1,0]
	v_pk_mul_f32 v[164:165], v[164:165], v[252:253] op_sel_hi:[1,0]
	v_pk_mul_f32 v[162:163], v[162:163], v[226:227]
	v_pk_mul_f32 v[164:165], v[164:165], v[228:229]
	v_pk_fma_f32 v[14:15], v[230:231], v[162:163], v[14:15]
	v_pk_fma_f32 v[16:17], v[232:233], v[164:165], v[16:17]
	v_pk_fma_f32 v[170:171], v[14:15], v[14:15], v[170:171]
	v_pk_fma_f32 v[172:173], v[16:17], v[16:17], v[172:173]
	v_cvt_pk_bf16_f32 v168, v14, v15
	v_cvt_pk_bf16_f32 v169, v16, v17
	global_store_dwordx2 v244, v[168:169], s[22:23] offset:1536
	ds_read_b128 v[226:229], v238 offset:5120
	ds_read_b128 v[230:233], v238 offset:37888
	s_waitcnt lgkmcnt(2)
	v_lshlrev_b32_e32 v162, 16, v138
	v_and_b32_e32 v163, 0xffff0000, v138
	v_lshlrev_b32_e32 v164, 16, v139
	v_and_b32_e32 v165, 0xffff0000, v139
	v_pk_mul_f32 v[162:163], v[162:163], v[252:253] op_sel_hi:[1,0]
	v_pk_mul_f32 v[164:165], v[164:165], v[252:253] op_sel_hi:[1,0]
	v_pk_mul_f32 v[162:163], v[162:163], v[214:215]
	v_pk_mul_f32 v[164:165], v[164:165], v[216:217]
	v_pk_fma_f32 v[18:19], v[218:219], v[162:163], v[18:19]
	v_pk_fma_f32 v[20:21], v[220:221], v[164:165], v[20:21]
	v_pk_fma_f32 v[170:171], v[18:19], v[18:19], v[170:171]
	v_pk_fma_f32 v[172:173], v[20:21], v[20:21], v[172:173]
	v_cvt_pk_bf16_f32 v166, v18, v19
	v_cvt_pk_bf16_f32 v167, v20, v21
	global_store_dwordx2 v244, v[166:167], s[22:23] offset:2048
	ds_read_b128 v[214:217], v238 offset:6144
	ds_read_b128 v[218:221], v238 offset:38912
	s_waitcnt lgkmcnt(2)
	v_lshlrev_b32_e32 v162, 16, v140
	v_and_b32_e32 v163, 0xffff0000, v140
	v_lshlrev_b32_e32 v164, 16, v141
	v_and_b32_e32 v165, 0xffff0000, v141
	v_pk_mul_f32 v[162:163], v[162:163], v[252:253] op_sel_hi:[1,0]
	v_pk_mul_f32 v[164:165], v[164:165], v[252:253] op_sel_hi:[1,0]
	v_pk_mul_f32 v[162:163], v[162:163], v[226:227]
	v_pk_mul_f32 v[164:165], v[164:165], v[228:229]
	v_pk_fma_f32 v[22:23], v[230:231], v[162:163], v[22:23]
	v_pk_fma_f32 v[24:25], v[232:233], v[164:165], v[24:25]
	v_pk_fma_f32 v[170:171], v[22:23], v[22:23], v[170:171]
	v_pk_fma_f32 v[172:173], v[24:25], v[24:25], v[172:173]
	v_cvt_pk_bf16_f32 v168, v22, v23
	v_cvt_pk_bf16_f32 v169, v24, v25
	global_store_dwordx2 v244, v[168:169], s[22:23] offset:2560
	ds_read_b128 v[226:229], v238 offset:7168
	ds_read_b128 v[230:233], v238 offset:39936
	s_waitcnt lgkmcnt(2)
	v_lshlrev_b32_e32 v162, 16, v142
	v_and_b32_e32 v163, 0xffff0000, v142
	v_lshlrev_b32_e32 v164, 16, v143
	v_and_b32_e32 v165, 0xffff0000, v143
	v_pk_mul_f32 v[162:163], v[162:163], v[252:253] op_sel_hi:[1,0]
	v_pk_mul_f32 v[164:165], v[164:165], v[252:253] op_sel_hi:[1,0]
	v_pk_mul_f32 v[162:163], v[162:163], v[214:215]
	v_pk_mul_f32 v[164:165], v[164:165], v[216:217]
	v_pk_fma_f32 v[26:27], v[218:219], v[162:163], v[26:27]
	v_pk_fma_f32 v[28:29], v[220:221], v[164:165], v[28:29]
	v_pk_fma_f32 v[170:171], v[26:27], v[26:27], v[170:171]
	v_pk_fma_f32 v[172:173], v[28:29], v[28:29], v[172:173]
	v_cvt_pk_bf16_f32 v166, v26, v27
	v_cvt_pk_bf16_f32 v167, v28, v29
	global_store_dwordx2 v244, v[166:167], s[22:23] offset:3072
	ds_read_b128 v[214:217], v238 offset:8192
	ds_read_b128 v[218:221], v238 offset:40960
	s_waitcnt lgkmcnt(2)
	v_lshlrev_b32_e32 v162, 16, v144
	v_and_b32_e32 v163, 0xffff0000, v144
	v_lshlrev_b32_e32 v164, 16, v145
	v_and_b32_e32 v165, 0xffff0000, v145
	v_pk_mul_f32 v[162:163], v[162:163], v[252:253] op_sel_hi:[1,0]
	v_pk_mul_f32 v[164:165], v[164:165], v[252:253] op_sel_hi:[1,0]
	v_pk_mul_f32 v[162:163], v[162:163], v[226:227]
	v_pk_mul_f32 v[164:165], v[164:165], v[228:229]
	v_pk_fma_f32 v[30:31], v[230:231], v[162:163], v[30:31]
	v_pk_fma_f32 v[32:33], v[232:233], v[164:165], v[32:33]
	v_pk_fma_f32 v[170:171], v[30:31], v[30:31], v[170:171]
	v_pk_fma_f32 v[172:173], v[32:33], v[32:33], v[172:173]
	v_cvt_pk_bf16_f32 v168, v30, v31
	v_cvt_pk_bf16_f32 v169, v32, v33
	global_store_dwordx2 v244, v[168:169], s[22:23] offset:3584
	ds_read_b128 v[226:229], v238 offset:9216
	ds_read_b128 v[230:233], v238 offset:41984
	s_waitcnt lgkmcnt(2)
	v_lshlrev_b32_e32 v162, 16, v146
	v_and_b32_e32 v163, 0xffff0000, v146
	v_lshlrev_b32_e32 v164, 16, v147
	v_and_b32_e32 v165, 0xffff0000, v147
	v_pk_mul_f32 v[162:163], v[162:163], v[252:253] op_sel_hi:[1,0]
	v_pk_mul_f32 v[164:165], v[164:165], v[252:253] op_sel_hi:[1,0]
	v_pk_mul_f32 v[162:163], v[162:163], v[214:215]
	v_pk_mul_f32 v[164:165], v[164:165], v[216:217]
	v_pk_fma_f32 v[34:35], v[218:219], v[162:163], v[34:35]
	v_pk_fma_f32 v[36:37], v[220:221], v[164:165], v[36:37]
	v_pk_fma_f32 v[170:171], v[34:35], v[34:35], v[170:171]
	v_pk_fma_f32 v[172:173], v[36:37], v[36:37], v[172:173]
	v_cvt_pk_bf16_f32 v166, v34, v35
	v_cvt_pk_bf16_f32 v167, v36, v37
	global_store_dwordx2 v245, v[166:167], s[22:23] offset:0
	ds_read_b128 v[214:217], v238 offset:10240
	ds_read_b128 v[218:221], v238 offset:43008
	s_waitcnt lgkmcnt(2)
	v_lshlrev_b32_e32 v162, 16, v148
	v_and_b32_e32 v163, 0xffff0000, v148
	v_lshlrev_b32_e32 v164, 16, v149
	v_and_b32_e32 v165, 0xffff0000, v149
	v_pk_mul_f32 v[162:163], v[162:163], v[252:253] op_sel_hi:[1,0]
	v_pk_mul_f32 v[164:165], v[164:165], v[252:253] op_sel_hi:[1,0]
	v_pk_mul_f32 v[162:163], v[162:163], v[226:227]
	v_pk_mul_f32 v[164:165], v[164:165], v[228:229]
	v_pk_fma_f32 v[38:39], v[230:231], v[162:163], v[38:39]
	v_pk_fma_f32 v[40:41], v[232:233], v[164:165], v[40:41]
	v_pk_fma_f32 v[170:171], v[38:39], v[38:39], v[170:171]
	v_pk_fma_f32 v[172:173], v[40:41], v[40:41], v[172:173]
	v_cvt_pk_bf16_f32 v168, v38, v39
	v_cvt_pk_bf16_f32 v169, v40, v41
	global_store_dwordx2 v245, v[168:169], s[22:23] offset:512
	ds_read_b128 v[226:229], v238 offset:11264
	ds_read_b128 v[230:233], v238 offset:44032
	s_waitcnt lgkmcnt(2)
	v_lshlrev_b32_e32 v162, 16, v150
	v_and_b32_e32 v163, 0xffff0000, v150
	v_lshlrev_b32_e32 v164, 16, v151
	v_and_b32_e32 v165, 0xffff0000, v151
	v_pk_mul_f32 v[162:163], v[162:163], v[252:253] op_sel_hi:[1,0]
	v_pk_mul_f32 v[164:165], v[164:165], v[252:253] op_sel_hi:[1,0]
	v_pk_mul_f32 v[162:163], v[162:163], v[214:215]
	v_pk_mul_f32 v[164:165], v[164:165], v[216:217]
	v_pk_fma_f32 v[42:43], v[218:219], v[162:163], v[42:43]
	v_pk_fma_f32 v[44:45], v[220:221], v[164:165], v[44:45]
	v_pk_fma_f32 v[170:171], v[42:43], v[42:43], v[170:171]
	v_pk_fma_f32 v[172:173], v[44:45], v[44:45], v[172:173]
	v_cvt_pk_bf16_f32 v166, v42, v43
	v_cvt_pk_bf16_f32 v167, v44, v45
	global_store_dwordx2 v245, v[166:167], s[22:23] offset:1024
	ds_read_b128 v[214:217], v238 offset:12288
	ds_read_b128 v[218:221], v238 offset:45056
	s_waitcnt lgkmcnt(2)
	v_lshlrev_b32_e32 v162, 16, v152
	v_and_b32_e32 v163, 0xffff0000, v152
	v_lshlrev_b32_e32 v164, 16, v153
	v_and_b32_e32 v165, 0xffff0000, v153
	v_pk_mul_f32 v[162:163], v[162:163], v[252:253] op_sel_hi:[1,0]
	v_pk_mul_f32 v[164:165], v[164:165], v[252:253] op_sel_hi:[1,0]
	v_pk_mul_f32 v[162:163], v[162:163], v[226:227]
	v_pk_mul_f32 v[164:165], v[164:165], v[228:229]
	v_pk_fma_f32 v[46:47], v[230:231], v[162:163], v[46:47]
	v_pk_fma_f32 v[48:49], v[232:233], v[164:165], v[48:49]
	v_pk_fma_f32 v[170:171], v[46:47], v[46:47], v[170:171]
	v_pk_fma_f32 v[172:173], v[48:49], v[48:49], v[172:173]
	v_cvt_pk_bf16_f32 v168, v46, v47
	v_cvt_pk_bf16_f32 v169, v48, v49
	global_store_dwordx2 v245, v[168:169], s[22:23] offset:1536
	ds_read_b128 v[226:229], v238 offset:13312
	ds_read_b128 v[230:233], v238 offset:46080
	s_waitcnt lgkmcnt(2)
	v_lshlrev_b32_e32 v162, 16, v154
	v_and_b32_e32 v163, 0xffff0000, v154
	v_lshlrev_b32_e32 v164, 16, v155
	v_and_b32_e32 v165, 0xffff0000, v155
	v_pk_mul_f32 v[162:163], v[162:163], v[252:253] op_sel_hi:[1,0]
	v_pk_mul_f32 v[164:165], v[164:165], v[252:253] op_sel_hi:[1,0]
	v_pk_mul_f32 v[162:163], v[162:163], v[214:215]
	v_pk_mul_f32 v[164:165], v[164:165], v[216:217]
	v_pk_fma_f32 v[50:51], v[218:219], v[162:163], v[50:51]
	v_pk_fma_f32 v[52:53], v[220:221], v[164:165], v[52:53]
	v_pk_fma_f32 v[170:171], v[50:51], v[50:51], v[170:171]
	v_pk_fma_f32 v[172:173], v[52:53], v[52:53], v[172:173]
	v_cvt_pk_bf16_f32 v166, v50, v51
	v_cvt_pk_bf16_f32 v167, v52, v53
	global_store_dwordx2 v245, v[166:167], s[22:23] offset:2048
	ds_read_b128 v[214:217], v238 offset:14336
	ds_read_b128 v[218:221], v238 offset:47104
	s_waitcnt lgkmcnt(2)
	v_lshlrev_b32_e32 v162, 16, v156
	v_and_b32_e32 v163, 0xffff0000, v156
	v_lshlrev_b32_e32 v164, 16, v157
	v_and_b32_e32 v165, 0xffff0000, v157
	v_pk_mul_f32 v[162:163], v[162:163], v[252:253] op_sel_hi:[1,0]
	v_pk_mul_f32 v[164:165], v[164:165], v[252:253] op_sel_hi:[1,0]
	v_pk_mul_f32 v[162:163], v[162:163], v[226:227]
	v_pk_mul_f32 v[164:165], v[164:165], v[228:229]
	v_pk_fma_f32 v[54:55], v[230:231], v[162:163], v[54:55]
	v_pk_fma_f32 v[56:57], v[232:233], v[164:165], v[56:57]
	v_pk_fma_f32 v[170:171], v[54:55], v[54:55], v[170:171]
	v_pk_fma_f32 v[172:173], v[56:57], v[56:57], v[172:173]
	v_cvt_pk_bf16_f32 v168, v54, v55
	v_cvt_pk_bf16_f32 v169, v56, v57
	global_store_dwordx2 v245, v[168:169], s[22:23] offset:2560
	ds_read_b128 v[226:229], v238 offset:15360
	ds_read_b128 v[230:233], v238 offset:48128
	s_waitcnt lgkmcnt(2)
	v_lshlrev_b32_e32 v162, 16, v158
	v_and_b32_e32 v163, 0xffff0000, v158
	v_lshlrev_b32_e32 v164, 16, v159
	v_and_b32_e32 v165, 0xffff0000, v159
	v_pk_mul_f32 v[162:163], v[162:163], v[252:253] op_sel_hi:[1,0]
	v_pk_mul_f32 v[164:165], v[164:165], v[252:253] op_sel_hi:[1,0]
	v_pk_mul_f32 v[162:163], v[162:163], v[214:215]
	v_pk_mul_f32 v[164:165], v[164:165], v[216:217]
	v_pk_fma_f32 v[58:59], v[218:219], v[162:163], v[58:59]
	v_pk_fma_f32 v[60:61], v[220:221], v[164:165], v[60:61]
	v_pk_fma_f32 v[170:171], v[58:59], v[58:59], v[170:171]
	v_pk_fma_f32 v[172:173], v[60:61], v[60:61], v[172:173]
	v_cvt_pk_bf16_f32 v166, v58, v59
	v_cvt_pk_bf16_f32 v167, v60, v61
	global_store_dwordx2 v245, v[166:167], s[22:23] offset:3072
	s_waitcnt lgkmcnt(0)
	v_lshlrev_b32_e32 v162, 16, v160
	v_and_b32_e32 v163, 0xffff0000, v160
	v_lshlrev_b32_e32 v164, 16, v161
	v_and_b32_e32 v165, 0xffff0000, v161
	v_pk_mul_f32 v[162:163], v[162:163], v[252:253] op_sel_hi:[1,0]
	v_pk_mul_f32 v[164:165], v[164:165], v[252:253] op_sel_hi:[1,0]
	v_pk_mul_f32 v[162:163], v[162:163], v[226:227]
	v_pk_mul_f32 v[164:165], v[164:165], v[228:229]
	v_pk_fma_f32 v[62:63], v[230:231], v[162:163], v[62:63]
	v_pk_fma_f32 v[64:65], v[232:233], v[164:165], v[64:65]
	v_pk_fma_f32 v[170:171], v[62:63], v[62:63], v[170:171]
	v_pk_fma_f32 v[172:173], v[64:65], v[64:65], v[172:173]
	v_cvt_pk_bf16_f32 v168, v62, v63
	v_cvt_pk_bf16_f32 v169, v64, v65
	global_store_dwordx2 v245, v[168:169], s[22:23] offset:3584
	ds_read_b128 v[214:217], v238 offset:16384
	ds_read_b128 v[218:221], v238 offset:49152
	ds_read_b128 v[222:225], v239 offset:0
	v_pk_add_f32 v[170:171], v[170:171], v[172:173]
	s_nop 0
	v_add_f32_e32 v252, v170, v171
	s_waitcnt lgkmcnt(0)
	ds_bpermute_b32 v254, v246, v252
	s_waitcnt lgkmcnt(0)
	v_add_f32_e32 v252, v252, v254
	ds_bpermute_b32 v254, v247, v252
	s_waitcnt lgkmcnt(0)
	v_add_f32_e32 v252, v252, v254
	ds_bpermute_b32 v254, v248, v252
	s_waitcnt lgkmcnt(0)
	v_add_f32_e32 v252, v252, v254
	ds_bpermute_b32 v254, v249, v252
	s_waitcnt lgkmcnt(0)
	v_add_f32_e32 v252, v252, v254
	ds_bpermute_b32 v254, v250, v252
	s_waitcnt lgkmcnt(0)
	v_add_f32_e32 v252, v252, v254
	ds_bpermute_b32 v254, v251, v252
	s_waitcnt lgkmcnt(0)
	v_add_f32_e32 v252, v252, v254
	v_mov_b32_e32 v254, 0x358637bd
	v_fmac_f32_e32 v254, 0x39800000, v252
	v_mul_f32_e32 v252, 0x4b800000, v254
	v_cmp_gt_f32_e32 vcc, s32, v254
	s_nop 1
	v_cndmask_b32_e32 v254, v254, v252, vcc
	v_rsq_f32_e32 v254, v254
	s_nop 0
	v_mul_f32_e32 v252, 0x45800000, v254
	v_cndmask_b32_e32 v252, v254, v252, vcc
	s_add_u32 s16, s16, 0x1000000
	s_addc_u32 s17, s17, 0
	global_load_dwordx2 v[130:131], v244, s[16:17] offset:0
	global_load_dwordx2 v[132:133], v244, s[16:17] offset:512
	global_load_dwordx2 v[134:135], v244, s[16:17] offset:1024
	global_load_dwordx2 v[136:137], v244, s[16:17] offset:1536
	global_load_dwordx2 v[138:139], v244, s[16:17] offset:2048
	global_load_dwordx2 v[140:141], v244, s[16:17] offset:2560
	global_load_dwordx2 v[142:143], v244, s[16:17] offset:3072
	global_load_dwordx2 v[144:145], v244, s[16:17] offset:3584
	global_load_dwordx2 v[146:147], v245, s[16:17] offset:0
	global_load_dwordx2 v[148:149], v245, s[16:17] offset:512
	global_load_dwordx2 v[150:151], v245, s[16:17] offset:1024
	global_load_dwordx2 v[152:153], v245, s[16:17] offset:1536
	global_load_dwordx2 v[154:155], v245, s[16:17] offset:2048
	global_load_dwordx2 v[156:157], v245, s[16:17] offset:2560
	global_load_dwordx2 v[158:159], v245, s[16:17] offset:3072
	global_load_dwordx2 v[160:161], v245, s[16:17] offset:3584
	ds_read_b128 v[226:229], v238 offset:17408
	ds_read_b128 v[230:233], v238 offset:50176
	ds_read_b128 v[234:237], v239 offset:1024
	s_waitcnt lgkmcnt(3)
	v_pk_mul_f32 v[2:3], v[2:3], v[252:253] op_sel_hi:[1,0]
	v_pk_mul_f32 v[4:5], v[4:5], v[252:253] op_sel_hi:[1,0]
	v_pk_mul_f32 v[2:3], v[2:3], v[214:215]
	v_pk_mul_f32 v[4:5], v[4:5], v[216:217]
	v_pk_add_f32 v[222:223], v[222:223], 1.0 op_sel_hi:[1,0]
	v_pk_add_f32 v[224:225], v[224:225], 1.0 op_sel_hi:[1,0]
	v_pk_fma_f32 v[2:3], v[2:3], v[222:223], v[218:219]
	v_pk_fma_f32 v[4:5], v[4:5], v[224:225], v[220:221]
	s_nop 0
	v_cvt_pk_bf16_f32 v2, v2, v3
	v_cvt_pk_bf16_f32 v3, v4, v5
	global_store_dwordx2 v244, v[2:3], s[38:39] offset:0
	ds_read_b128 v[214:217], v238 offset:18432
	ds_read_b128 v[218:221], v238 offset:51200
	ds_read_b128 v[222:225], v239 offset:2048
	s_waitcnt lgkmcnt(3)
	v_pk_mul_f32 v[6:7], v[6:7], v[252:253] op_sel_hi:[1,0]
	v_pk_mul_f32 v[8:9], v[8:9], v[252:253] op_sel_hi:[1,0]
	v_pk_mul_f32 v[6:7], v[6:7], v[226:227]
	v_pk_mul_f32 v[8:9], v[8:9], v[228:229]
	v_pk_add_f32 v[234:235], v[234:235], 1.0 op_sel_hi:[1,0]
	v_pk_add_f32 v[236:237], v[236:237], 1.0 op_sel_hi:[1,0]
	v_pk_fma_f32 v[6:7], v[6:7], v[234:235], v[230:231]
	v_pk_fma_f32 v[8:9], v[8:9], v[236:237], v[232:233]
	s_nop 0
	v_cvt_pk_bf16_f32 v6, v6, v7
	v_cvt_pk_bf16_f32 v7, v8, v9
	global_store_dwordx2 v244, v[6:7], s[38:39] offset:512
	ds_read_b128 v[226:229], v238 offset:19456
	ds_read_b128 v[230:233], v238 offset:52224
	ds_read_b128 v[234:237], v239 offset:3072
	s_waitcnt lgkmcnt(3)
	v_pk_mul_f32 v[10:11], v[10:11], v[252:253] op_sel_hi:[1,0]
	v_pk_mul_f32 v[12:13], v[12:13], v[252:253] op_sel_hi:[1,0]
	v_pk_mul_f32 v[10:11], v[10:11], v[214:215]
	v_pk_mul_f32 v[12:13], v[12:13], v[216:217]
	v_pk_add_f32 v[222:223], v[222:223], 1.0 op_sel_hi:[1,0]
	v_pk_add_f32 v[224:225], v[224:225], 1.0 op_sel_hi:[1,0]
	v_pk_fma_f32 v[10:11], v[10:11], v[222:223], v[218:219]
	v_pk_fma_f32 v[12:13], v[12:13], v[224:225], v[220:221]
	s_nop 0
	v_cvt_pk_bf16_f32 v10, v10, v11
	v_cvt_pk_bf16_f32 v11, v12, v13
	global_store_dwordx2 v244, v[10:11], s[38:39] offset:1024
	ds_read_b128 v[214:217], v238 offset:20480
	ds_read_b128 v[218:221], v238 offset:53248
	ds_read_b128 v[222:225], v239 offset:4096
	s_waitcnt lgkmcnt(3)
	v_pk_mul_f32 v[14:15], v[14:15], v[252:253] op_sel_hi:[1,0]
	v_pk_mul_f32 v[16:17], v[16:17], v[252:253] op_sel_hi:[1,0]
	v_pk_mul_f32 v[14:15], v[14:15], v[226:227]
	v_pk_mul_f32 v[16:17], v[16:17], v[228:229]
	v_pk_add_f32 v[234:235], v[234:235], 1.0 op_sel_hi:[1,0]
	v_pk_add_f32 v[236:237], v[236:237], 1.0 op_sel_hi:[1,0]
	v_pk_fma_f32 v[14:15], v[14:15], v[234:235], v[230:231]
	v_pk_fma_f32 v[16:17], v[16:17], v[236:237], v[232:233]
	s_nop 0
	v_cvt_pk_bf16_f32 v14, v14, v15
	v_cvt_pk_bf16_f32 v15, v16, v17
	global_store_dwordx2 v244, v[14:15], s[38:39] offset:1536
	ds_read_b128 v[226:229], v238 offset:21504
	ds_read_b128 v[230:233], v238 offset:54272
	ds_read_b128 v[234:237], v239 offset:5120
	s_waitcnt lgkmcnt(3)
	v_pk_mul_f32 v[18:19], v[18:19], v[252:253] op_sel_hi:[1,0]
	v_pk_mul_f32 v[20:21], v[20:21], v[252:253] op_sel_hi:[1,0]
	v_pk_mul_f32 v[18:19], v[18:19], v[214:215]
	v_pk_mul_f32 v[20:21], v[20:21], v[216:217]
	v_pk_add_f32 v[222:223], v[222:223], 1.0 op_sel_hi:[1,0]
	v_pk_add_f32 v[224:225], v[224:225], 1.0 op_sel_hi:[1,0]
	v_pk_fma_f32 v[18:19], v[18:19], v[222:223], v[218:219]
	v_pk_fma_f32 v[20:21], v[20:21], v[224:225], v[220:221]
	s_nop 0
	v_cvt_pk_bf16_f32 v18, v18, v19
	v_cvt_pk_bf16_f32 v19, v20, v21
	global_store_dwordx2 v244, v[18:19], s[38:39] offset:2048
	ds_read_b128 v[214:217], v238 offset:22528
	ds_read_b128 v[218:221], v238 offset:55296
	ds_read_b128 v[222:225], v239 offset:6144
	s_waitcnt lgkmcnt(3)
	v_pk_mul_f32 v[22:23], v[22:23], v[252:253] op_sel_hi:[1,0]
	v_pk_mul_f32 v[24:25], v[24:25], v[252:253] op_sel_hi:[1,0]
	v_pk_mul_f32 v[22:23], v[22:23], v[226:227]
	v_pk_mul_f32 v[24:25], v[24:25], v[228:229]
	v_pk_add_f32 v[234:235], v[234:235], 1.0 op_sel_hi:[1,0]
	v_pk_add_f32 v[236:237], v[236:237], 1.0 op_sel_hi:[1,0]
	v_pk_fma_f32 v[22:23], v[22:23], v[234:235], v[230:231]
	v_pk_fma_f32 v[24:25], v[24:25], v[236:237], v[232:233]
	s_nop 0
	v_cvt_pk_bf16_f32 v22, v22, v23
	v_cvt_pk_bf16_f32 v23, v24, v25
	global_store_dwordx2 v244, v[22:23], s[38:39] offset:2560
	ds_read_b128 v[226:229], v238 offset:23552
	ds_read_b128 v[230:233], v238 offset:56320
	ds_read_b128 v[234:237], v239 offset:7168
	s_waitcnt lgkmcnt(3)
	v_pk_mul_f32 v[26:27], v[26:27], v[252:253] op_sel_hi:[1,0]
	v_pk_mul_f32 v[28:29], v[28:29], v[252:253] op_sel_hi:[1,0]
	v_pk_mul_f32 v[26:27], v[26:27], v[214:215]
	v_pk_mul_f32 v[28:29], v[28:29], v[216:217]
	v_pk_add_f32 v[222:223], v[222:223], 1.0 op_sel_hi:[1,0]
	v_pk_add_f32 v[224:225], v[224:225], 1.0 op_sel_hi:[1,0]
	v_pk_fma_f32 v[26:27], v[26:27], v[222:223], v[218:219]
	v_pk_fma_f32 v[28:29], v[28:29], v[224:225], v[220:221]
	s_nop 0
	v_cvt_pk_bf16_f32 v26, v26, v27
	v_cvt_pk_bf16_f32 v27, v28, v29
	global_store_dwordx2 v244, v[26:27], s[38:39] offset:3072
	ds_read_b128 v[214:217], v238 offset:24576
	ds_read_b128 v[218:221], v238 offset:57344
	ds_read_b128 v[222:225], v239 offset:8192
	s_waitcnt lgkmcnt(3)
	v_pk_mul_f32 v[30:31], v[30:31], v[252:253] op_sel_hi:[1,0]
	v_pk_mul_f32 v[32:33], v[32:33], v[252:253] op_sel_hi:[1,0]
	v_pk_mul_f32 v[30:31], v[30:31], v[226:227]
	v_pk_mul_f32 v[32:33], v[32:33], v[228:229]
	v_pk_add_f32 v[234:235], v[234:235], 1.0 op_sel_hi:[1,0]
	v_pk_add_f32 v[236:237], v[236:237], 1.0 op_sel_hi:[1,0]
	v_pk_fma_f32 v[30:31], v[30:31], v[234:235], v[230:231]
	v_pk_fma_f32 v[32:33], v[32:33], v[236:237], v[232:233]
	s_nop 0
	v_cvt_pk_bf16_f32 v30, v30, v31
	v_cvt_pk_bf16_f32 v31, v32, v33
	global_store_dwordx2 v244, v[30:31], s[38:39] offset:3584
	ds_read_b128 v[226:229], v238 offset:25600
	ds_read_b128 v[230:233], v238 offset:58368
	ds_read_b128 v[234:237], v239 offset:9216
	s_waitcnt lgkmcnt(3)
	v_pk_mul_f32 v[34:35], v[34:35], v[252:253] op_sel_hi:[1,0]
	v_pk_mul_f32 v[36:37], v[36:37], v[252:253] op_sel_hi:[1,0]
	v_pk_mul_f32 v[34:35], v[34:35], v[214:215]
	v_pk_mul_f32 v[36:37], v[36:37], v[216:217]
	v_pk_add_f32 v[222:223], v[222:223], 1.0 op_sel_hi:[1,0]
	v_pk_add_f32 v[224:225], v[224:225], 1.0 op_sel_hi:[1,0]
	v_pk_fma_f32 v[34:35], v[34:35], v[222:223], v[218:219]
	v_pk_fma_f32 v[36:37], v[36:37], v[224:225], v[220:221]
	s_nop 0
	v_cvt_pk_bf16_f32 v34, v34, v35
	v_cvt_pk_bf16_f32 v35, v36, v37
	global_store_dwordx2 v245, v[34:35], s[38:39] offset:0
	ds_read_b128 v[214:217], v238 offset:26624
	ds_read_b128 v[218:221], v238 offset:59392
	ds_read_b128 v[222:225], v239 offset:10240
	s_waitcnt lgkmcnt(3)
	v_pk_mul_f32 v[38:39], v[38:39], v[252:253] op_sel_hi:[1,0]
	v_pk_mul_f32 v[40:41], v[40:41], v[252:253] op_sel_hi:[1,0]
	v_pk_mul_f32 v[38:39], v[38:39], v[226:227]
	v_pk_mul_f32 v[40:41], v[40:41], v[228:229]
	v_pk_add_f32 v[234:235], v[234:235], 1.0 op_sel_hi:[1,0]
	v_pk_add_f32 v[236:237], v[236:237], 1.0 op_sel_hi:[1,0]
	v_pk_fma_f32 v[38:39], v[38:39], v[234:235], v[230:231]
	v_pk_fma_f32 v[40:41], v[40:41], v[236:237], v[232:233]
	s_nop 0
	v_cvt_pk_bf16_f32 v38, v38, v39
	v_cvt_pk_bf16_f32 v39, v40, v41
	global_store_dwordx2 v245, v[38:39], s[38:39] offset:512
	ds_read_b128 v[226:229], v238 offset:27648
	ds_read_b128 v[230:233], v238 offset:60416
	ds_read_b128 v[234:237], v239 offset:11264
	s_waitcnt lgkmcnt(3)
	v_pk_mul_f32 v[42:43], v[42:43], v[252:253] op_sel_hi:[1,0]
	v_pk_mul_f32 v[44:45], v[44:45], v[252:253] op_sel_hi:[1,0]
	v_pk_mul_f32 v[42:43], v[42:43], v[214:215]
	v_pk_mul_f32 v[44:45], v[44:45], v[216:217]
	v_pk_add_f32 v[222:223], v[222:223], 1.0 op_sel_hi:[1,0]
	v_pk_add_f32 v[224:225], v[224:225], 1.0 op_sel_hi:[1,0]
	v_pk_fma_f32 v[42:43], v[42:43], v[222:223], v[218:219]
	v_pk_fma_f32 v[44:45], v[44:45], v[224:225], v[220:221]
	s_nop 0
	v_cvt_pk_bf16_f32 v42, v42, v43
	v_cvt_pk_bf16_f32 v43, v44, v45
	global_store_dwordx2 v245, v[42:43], s[38:39] offset:1024
	ds_read_b128 v[214:217], v238 offset:28672
	ds_read_b128 v[218:221], v238 offset:61440
	ds_read_b128 v[222:225], v239 offset:12288
	s_waitcnt lgkmcnt(3)
	v_pk_mul_f32 v[46:47], v[46:47], v[252:253] op_sel_hi:[1,0]
	v_pk_mul_f32 v[48:49], v[48:49], v[252:253] op_sel_hi:[1,0]
	v_pk_mul_f32 v[46:47], v[46:47], v[226:227]
	v_pk_mul_f32 v[48:49], v[48:49], v[228:229]
	v_pk_add_f32 v[234:235], v[234:235], 1.0 op_sel_hi:[1,0]
	v_pk_add_f32 v[236:237], v[236:237], 1.0 op_sel_hi:[1,0]
	v_pk_fma_f32 v[46:47], v[46:47], v[234:235], v[230:231]
	v_pk_fma_f32 v[48:49], v[48:49], v[236:237], v[232:233]
	s_nop 0
	v_cvt_pk_bf16_f32 v46, v46, v47
	v_cvt_pk_bf16_f32 v47, v48, v49
	global_store_dwordx2 v245, v[46:47], s[38:39] offset:1536
	ds_read_b128 v[226:229], v238 offset:29696
	ds_read_b128 v[230:233], v238 offset:62464
	ds_read_b128 v[234:237], v239 offset:13312
	s_waitcnt lgkmcnt(3)
	v_pk_mul_f32 v[50:51], v[50:51], v[252:253] op_sel_hi:[1,0]
	v_pk_mul_f32 v[52:53], v[52:53], v[252:253] op_sel_hi:[1,0]
	v_pk_mul_f32 v[50:51], v[50:51], v[214:215]
	v_pk_mul_f32 v[52:53], v[52:53], v[216:217]
	v_pk_add_f32 v[222:223], v[222:223], 1.0 op_sel_hi:[1,0]
	v_pk_add_f32 v[224:225], v[224:225], 1.0 op_sel_hi:[1,0]
	v_pk_fma_f32 v[50:51], v[50:51], v[222:223], v[218:219]
	v_pk_fma_f32 v[52:53], v[52:53], v[224:225], v[220:221]
	s_nop 0
	v_cvt_pk_bf16_f32 v50, v50, v51
	v_cvt_pk_bf16_f32 v51, v52, v53
	global_store_dwordx2 v245, v[50:51], s[38:39] offset:2048
	ds_read_b128 v[214:217], v238 offset:30720
	ds_read_b128 v[218:221], v238 offset:63488
	ds_read_b128 v[222:225], v239 offset:14336
	s_waitcnt lgkmcnt(3)
	v_pk_mul_f32 v[54:55], v[54:55], v[252:253] op_sel_hi:[1,0]
	v_pk_mul_f32 v[56:57], v[56:57], v[252:253] op_sel_hi:[1,0]
	v_pk_mul_f32 v[54:55], v[54:55], v[226:227]
	v_pk_mul_f32 v[56:57], v[56:57], v[228:229]
	v_pk_add_f32 v[234:235], v[234:235], 1.0 op_sel_hi:[1,0]
	v_pk_add_f32 v[236:237], v[236:237], 1.0 op_sel_hi:[1,0]
	v_pk_fma_f32 v[54:55], v[54:55], v[234:235], v[230:231]
	v_pk_fma_f32 v[56:57], v[56:57], v[236:237], v[232:233]
	s_nop 0
	v_cvt_pk_bf16_f32 v54, v54, v55
	v_cvt_pk_bf16_f32 v55, v56, v57
	global_store_dwordx2 v245, v[54:55], s[38:39] offset:2560
	ds_read_b128 v[226:229], v238 offset:31744
	ds_read_b128 v[230:233], v238 offset:64512
	ds_read_b128 v[234:237], v239 offset:15360
	s_waitcnt lgkmcnt(3)
	v_pk_mul_f32 v[58:59], v[58:59], v[252:253] op_sel_hi:[1,0]
	v_pk_mul_f32 v[60:61], v[60:61], v[252:253] op_sel_hi:[1,0]
	v_pk_mul_f32 v[58:59], v[58:59], v[214:215]
	v_pk_mul_f32 v[60:61], v[60:61], v[216:217]
	v_pk_add_f32 v[222:223], v[222:223], 1.0 op_sel_hi:[1,0]
	v_pk_add_f32 v[224:225], v[224:225], 1.0 op_sel_hi:[1,0]
	v_pk_fma_f32 v[58:59], v[58:59], v[222:223], v[218:219]
	v_pk_fma_f32 v[60:61], v[60:61], v[224:225], v[220:221]
	s_nop 0
	v_cvt_pk_bf16_f32 v58, v58, v59
	v_cvt_pk_bf16_f32 v59, v60, v61
	global_store_dwordx2 v245, v[58:59], s[38:39] offset:3072
	s_waitcnt lgkmcnt(0)
	v_pk_mul_f32 v[62:63], v[62:63], v[252:253] op_sel_hi:[1,0]
	v_pk_mul_f32 v[64:65], v[64:65], v[252:253] op_sel_hi:[1,0]
	v_pk_mul_f32 v[62:63], v[62:63], v[226:227]
	v_pk_mul_f32 v[64:65], v[64:65], v[228:229]
	v_pk_add_f32 v[234:235], v[234:235], 1.0 op_sel_hi:[1,0]
	v_pk_add_f32 v[236:237], v[236:237], 1.0 op_sel_hi:[1,0]
	v_pk_fma_f32 v[62:63], v[62:63], v[234:235], v[230:231]
	v_pk_fma_f32 v[64:65], v[64:65], v[236:237], v[232:233]
	s_nop 0
	v_cvt_pk_bf16_f32 v62, v62, v63
	v_cvt_pk_bf16_f32 v63, v64, v65
	global_store_dwordx2 v245, v[62:63], s[38:39] offset:3584
	s_add_u32 s22, s22, 0x1000000
	s_addc_u32 s23, s23, 0
	s_add_u32 s38, s38, 0x1000000
	s_addc_u32 s39, s39, 0
	s_waitcnt vmcnt(16)
	s_add_u32 s14, s14, 0x2000000
	s_addc_u32 s15, s15, 0
	global_load_dwordx4 v[2:5], v238, s[14:15] offset:0
	global_load_dwordx4 v[6:9], v238, s[14:15] offset:1024
	global_load_dwordx4 v[10:13], v238, s[14:15] offset:2048
	global_load_dwordx4 v[14:17], v238, s[14:15] offset:3072
	global_load_dwordx4 v[18:21], v241, s[14:15] offset:0
	global_load_dwordx4 v[22:25], v241, s[14:15] offset:1024
	global_load_dwordx4 v[26:29], v241, s[14:15] offset:2048
	global_load_dwordx4 v[30:33], v241, s[14:15] offset:3072
	global_load_dwordx4 v[34:37], v242, s[14:15] offset:0
	global_load_dwordx4 v[38:41], v242, s[14:15] offset:1024
	global_load_dwordx4 v[42:45], v242, s[14:15] offset:2048
	global_load_dwordx4 v[46:49], v242, s[14:15] offset:3072
	global_load_dwordx4 v[50:53], v243, s[14:15] offset:0
	global_load_dwordx4 v[54:57], v243, s[14:15] offset:1024
	global_load_dwordx4 v[58:61], v243, s[14:15] offset:2048
	global_load_dwordx4 v[62:65], v243, s[14:15] offset:3072
	ds_read_b128 v[214:217], v238 offset:0
	ds_read_b128 v[218:221], v238 offset:32768
	v_lshlrev_b32_e32 v162, 16, v130
	v_and_b32_e32 v163, 0xffff0000, v130
	v_lshlrev_b32_e32 v164, 16, v131
	v_and_b32_e32 v165, 0xffff0000, v131
	v_pk_mul_f32 v[170:171], v[162:163], v[162:163]
	v_pk_mul_f32 v[172:173], v[164:165], v[164:165]
	v_lshlrev_b32_e32 v166, 16, v132
	v_and_b32_e32 v167, 0xffff0000, v132
	v_lshlrev_b32_e32 v168, 16, v133
	v_and_b32_e32 v169, 0xffff0000, v133
	v_pk_fma_f32 v[170:171], v[166:167], v[166:167], v[170:171]
	v_pk_fma_f32 v[172:173], v[168:169], v[168:169], v[172:173]
	v_lshlrev_b32_e32 v162, 16, v134
	v_and_b32_e32 v163, 0xffff0000, v134
	v_lshlrev_b32_e32 v164, 16, v135
	v_and_b32_e32 v165, 0xffff0000, v135
	v_pk_fma_f32 v[170:171], v[162:163], v[162:163], v[170:171]
	v_pk_fma_f32 v[172:173], v[164:165], v[164:165], v[172:173]
	v_lshlrev_b32_e32 v166, 16, v136
	v_and_b32_e32 v167, 0xffff0000, v136
	v_lshlrev_b32_e32 v168, 16, v137
	v_and_b32_e32 v169, 0xffff0000, v137
	v_pk_fma_f32 v[170:171], v[166:167], v[166:167], v[170:171]
	v_pk_fma_f32 v[172:173], v[168:169], v[168:169], v[172:173]
	v_lshlrev_b32_e32 v162, 16, v138
	v_and_b32_e32 v163, 0xffff0000, v138
	v_lshlrev_b32_e32 v164, 16, v139
	v_and_b32_e32 v165, 0xffff0000, v139
	v_pk_fma_f32 v[170:171], v[162:163], v[162:163], v[170:171]
	v_pk_fma_f32 v[172:173], v[164:165], v[164:165], v[172:173]
	v_lshlrev_b32_e32 v166, 16, v140
	v_and_b32_e32 v167, 0xffff0000, v140
	v_lshlrev_b32_e32 v168, 16, v141
	v_and_b32_e32 v169, 0xffff0000, v141
	v_pk_fma_f32 v[170:171], v[166:167], v[166:167], v[170:171]
	v_pk_fma_f32 v[172:173], v[168:169], v[168:169], v[172:173]
	v_lshlrev_b32_e32 v162, 16, v142
	v_and_b32_e32 v163, 0xffff0000, v142
	v_lshlrev_b32_e32 v164, 16, v143
	v_and_b32_e32 v165, 0xffff0000, v143
	v_pk_fma_f32 v[170:171], v[162:163], v[162:163], v[170:171]
	v_pk_fma_f32 v[172:173], v[164:165], v[164:165], v[172:173]
	v_lshlrev_b32_e32 v166, 16, v144
	v_and_b32_e32 v167, 0xffff0000, v144
	v_lshlrev_b32_e32 v168, 16, v145
	v_and_b32_e32 v169, 0xffff0000, v145
	v_pk_fma_f32 v[170:171], v[166:167], v[166:167], v[170:171]
	v_pk_fma_f32 v[172:173], v[168:169], v[168:169], v[172:173]
	v_lshlrev_b32_e32 v162, 16, v146
	v_and_b32_e32 v163, 0xffff0000, v146
	v_lshlrev_b32_e32 v164, 16, v147
	v_and_b32_e32 v165, 0xffff0000, v147
	v_pk_fma_f32 v[170:171], v[162:163], v[162:163], v[170:171]
	v_pk_fma_f32 v[172:173], v[164:165], v[164:165], v[172:173]
	v_lshlrev_b32_e32 v166, 16, v148
	v_and_b32_e32 v167, 0xffff0000, v148
	v_lshlrev_b32_e32 v168, 16, v149
	v_and_b32_e32 v169, 0xffff0000, v149
	v_pk_fma_f32 v[170:171], v[166:167], v[166:167], v[170:171]
	v_pk_fma_f32 v[172:173], v[168:169], v[168:169], v[172:173]
	v_lshlrev_b32_e32 v162, 16, v150
	v_and_b32_e32 v163, 0xffff0000, v150
	v_lshlrev_b32_e32 v164, 16, v151
	v_and_b32_e32 v165, 0xffff0000, v151
	v_pk_fma_f32 v[170:171], v[162:163], v[162:163], v[170:171]
	v_pk_fma_f32 v[172:173], v[164:165], v[164:165], v[172:173]
	v_lshlrev_b32_e32 v166, 16, v152
	v_and_b32_e32 v167, 0xffff0000, v152
	v_lshlrev_b32_e32 v168, 16, v153
	v_and_b32_e32 v169, 0xffff0000, v153
	v_pk_fma_f32 v[170:171], v[166:167], v[166:167], v[170:171]
	v_pk_fma_f32 v[172:173], v[168:169], v[168:169], v[172:173]
	v_lshlrev_b32_e32 v162, 16, v154
	v_and_b32_e32 v163, 0xffff0000, v154
	v_lshlrev_b32_e32 v164, 16, v155
	v_and_b32_e32 v165, 0xffff0000, v155
	v_pk_fma_f32 v[170:171], v[162:163], v[162:163], v[170:171]
	v_pk_fma_f32 v[172:173], v[164:165], v[164:165], v[172:173]
	v_lshlrev_b32_e32 v166, 16, v156
	v_and_b32_e32 v167, 0xffff0000, v156
	v_lshlrev_b32_e32 v168, 16, v157
	v_and_b32_e32 v169, 0xffff0000, v157
	v_pk_fma_f32 v[170:171], v[166:167], v[166:167], v[170:171]
	v_pk_fma_f32 v[172:173], v[168:169], v[168:169], v[172:173]
	v_lshlrev_b32_e32 v162, 16, v158
	v_and_b32_e32 v163, 0xffff0000, v158
	v_lshlrev_b32_e32 v164, 16, v159
	v_and_b32_e32 v165, 0xffff0000, v159
	v_pk_fma_f32 v[170:171], v[162:163], v[162:163], v[170:171]
	v_pk_fma_f32 v[172:173], v[164:165], v[164:165], v[172:173]
	v_lshlrev_b32_e32 v166, 16, v160
	v_and_b32_e32 v167, 0xffff0000, v160
	v_lshlrev_b32_e32 v168, 16, v161
	v_and_b32_e32 v169, 0xffff0000, v161
	v_pk_fma_f32 v[170:171], v[166:167], v[166:167], v[170:171]
	v_pk_fma_f32 v[172:173], v[168:169], v[168:169], v[172:173]
	v_pk_add_f32 v[170:171], v[170:171], v[172:173]
	s_nop 0
	v_add_f32_e32 v252, v170, v171
	s_waitcnt lgkmcnt(0)
	ds_bpermute_b32 v254, v246, v252
	s_waitcnt lgkmcnt(0)
	v_add_f32_e32 v252, v252, v254
	ds_bpermute_b32 v254, v247, v252
	s_waitcnt lgkmcnt(0)
	v_add_f32_e32 v252, v252, v254
	ds_bpermute_b32 v254, v248, v252
	s_waitcnt lgkmcnt(0)
	v_add_f32_e32 v252, v252, v254
	ds_bpermute_b32 v254, v249, v252
	s_waitcnt lgkmcnt(0)
	v_add_f32_e32 v252, v252, v254
	ds_bpermute_b32 v254, v250, v252
	s_waitcnt lgkmcnt(0)
	v_add_f32_e32 v252, v252, v254
	ds_bpermute_b32 v254, v251, v252
	s_waitcnt lgkmcnt(0)
	v_add_f32_e32 v252, v252, v254
	v_mov_b32_e32 v254, 0x358637bd
	v_fmac_f32_e32 v254, 0x39800000, v252
	v_mul_f32_e32 v252, 0x4b800000, v254
	v_cmp_gt_f32_e32 vcc, s32, v254
	s_nop 1
	v_cndmask_b32_e32 v254, v254, v252, vcc
	v_rsq_f32_e32 v254, v254
	s_nop 0
	v_mul_f32_e32 v252, 0x45800000, v254
	v_cndmask_b32_e32 v252, v254, v252, vcc
	ds_read_b128 v[226:229], v238 offset:1024
	ds_read_b128 v[230:233], v238 offset:33792
	s_waitcnt lgkmcnt(2)
	v_lshlrev_b32_e32 v162, 16, v130
	v_and_b32_e32 v163, 0xffff0000, v130
	v_lshlrev_b32_e32 v164, 16, v131
	v_and_b32_e32 v165, 0xffff0000, v131
	v_pk_mul_f32 v[162:163], v[162:163], v[252:253] op_sel_hi:[1,0]
	v_pk_mul_f32 v[164:165], v[164:165], v[252:253] op_sel_hi:[1,0]
	v_pk_mul_f32 v[162:163], v[162:163], v[214:215]
	v_pk_mul_f32 v[164:165], v[164:165], v[216:217]
	v_pk_fma_f32 v[66:67], v[218:219], v[162:163], v[66:67]
	v_pk_fma_f32 v[68:69], v[220:221], v[164:165], v[68:69]
	v_pk_mul_f32 v[170:171], v[66:67], v[66:67]
	v_pk_mul_f32 v[172:173], v[68:69], v[68:69]
	v_cvt_pk_bf16_f32 v166, v66, v67
	v_cvt_pk_bf16_f32 v167, v68, v69
	global_store_dwordx2 v244, v[166:167], s[22:23] offset:0
	ds_read_b128 v[214:217], v238 offset:2048
	ds_read_b128 v[218:221], v238 offset:34816
	s_waitcnt lgkmcnt(2)
	v_lshlrev_b32_e32 v162, 16, v132
	v_and_b32_e32 v163, 0xffff0000, v132
	v_lshlrev_b32_e32 v164, 16, v133
	v_and_b32_e32 v165, 0xffff0000, v133
	v_pk_mul_f32 v[162:163], v[162:163], v[252:253] op_sel_hi:[1,0]
	v_pk_mul_f32 v[164:165], v[164:165], v[252:253] op_sel_hi:[1,0]
	v_pk_mul_f32 v[162:163], v[162:163], v[226:227]
	v_pk_mul_f32 v[164:165], v[164:165], v[228:229]
	v_pk_fma_f32 v[70:71], v[230:231], v[162:163], v[70:71]
	v_pk_fma_f32 v[72:73], v[232:233], v[164:165], v[72:73]
	v_pk_fma_f32 v[170:171], v[70:71], v[70:71], v[170:171]
	v_pk_fma_f32 v[172:173], v[72:73], v[72:73], v[172:173]
	v_cvt_pk_bf16_f32 v168, v70, v71
	v_cvt_pk_bf16_f32 v169, v72, v73
	global_store_dwordx2 v244, v[168:169], s[22:23] offset:512
	ds_read_b128 v[226:229], v238 offset:3072
	ds_read_b128 v[230:233], v238 offset:35840
	s_waitcnt lgkmcnt(2)
	v_lshlrev_b32_e32 v162, 16, v134
	v_and_b32_e32 v163, 0xffff0000, v134
	v_lshlrev_b32_e32 v164, 16, v135
	v_and_b32_e32 v165, 0xffff0000, v135
	v_pk_mul_f32 v[162:163], v[162:163], v[252:253] op_sel_hi:[1,0]
	v_pk_mul_f32 v[164:165], v[164:165], v[252:253] op_sel_hi:[1,0]
	v_pk_mul_f32 v[162:163], v[162:163], v[214:215]
	v_pk_mul_f32 v[164:165], v[164:165], v[216:217]
	v_pk_fma_f32 v[74:75], v[218:219], v[162:163], v[74:75]
	v_pk_fma_f32 v[76:77], v[220:221], v[164:165], v[76:77]
	v_pk_fma_f32 v[170:171], v[74:75], v[74:75], v[170:171]
	v_pk_fma_f32 v[172:173], v[76:77], v[76:77], v[172:173]
	v_cvt_pk_bf16_f32 v166, v74, v75
	v_cvt_pk_bf16_f32 v167, v76, v77
	global_store_dwordx2 v244, v[166:167], s[22:23] offset:1024
	ds_read_b128 v[214:217], v238 offset:4096
	ds_read_b128 v[218:221], v238 offset:36864
	s_waitcnt lgkmcnt(2)
	v_lshlrev_b32_e32 v162, 16, v136
	v_and_b32_e32 v163, 0xffff0000, v136
	v_lshlrev_b32_e32 v164, 16, v137
	v_and_b32_e32 v165, 0xffff0000, v137
	v_pk_mul_f32 v[162:163], v[162:163], v[252:253] op_sel_hi:[1,0]
	v_pk_mul_f32 v[164:165], v[164:165], v[252:253] op_sel_hi:[1,0]
	v_pk_mul_f32 v[162:163], v[162:163], v[226:227]
	v_pk_mul_f32 v[164:165], v[164:165], v[228:229]
	v_pk_fma_f32 v[78:79], v[230:231], v[162:163], v[78:79]
	v_pk_fma_f32 v[80:81], v[232:233], v[164:165], v[80:81]
	v_pk_fma_f32 v[170:171], v[78:79], v[78:79], v[170:171]
	v_pk_fma_f32 v[172:173], v[80:81], v[80:81], v[172:173]
	v_cvt_pk_bf16_f32 v168, v78, v79
	v_cvt_pk_bf16_f32 v169, v80, v81
	global_store_dwordx2 v244, v[168:169], s[22:23] offset:1536
	ds_read_b128 v[226:229], v238 offset:5120
	ds_read_b128 v[230:233], v238 offset:37888
	s_waitcnt lgkmcnt(2)
	v_lshlrev_b32_e32 v162, 16, v138
	v_and_b32_e32 v163, 0xffff0000, v138
	v_lshlrev_b32_e32 v164, 16, v139
	v_and_b32_e32 v165, 0xffff0000, v139
	v_pk_mul_f32 v[162:163], v[162:163], v[252:253] op_sel_hi:[1,0]
	v_pk_mul_f32 v[164:165], v[164:165], v[252:253] op_sel_hi:[1,0]
	v_pk_mul_f32 v[162:163], v[162:163], v[214:215]
	v_pk_mul_f32 v[164:165], v[164:165], v[216:217]
	v_pk_fma_f32 v[82:83], v[218:219], v[162:163], v[82:83]
	v_pk_fma_f32 v[84:85], v[220:221], v[164:165], v[84:85]
	v_pk_fma_f32 v[170:171], v[82:83], v[82:83], v[170:171]
	v_pk_fma_f32 v[172:173], v[84:85], v[84:85], v[172:173]
	v_cvt_pk_bf16_f32 v166, v82, v83
	v_cvt_pk_bf16_f32 v167, v84, v85
	global_store_dwordx2 v244, v[166:167], s[22:23] offset:2048
	ds_read_b128 v[214:217], v238 offset:6144
	ds_read_b128 v[218:221], v238 offset:38912
	s_waitcnt lgkmcnt(2)
	v_lshlrev_b32_e32 v162, 16, v140
	v_and_b32_e32 v163, 0xffff0000, v140
	v_lshlrev_b32_e32 v164, 16, v141
	v_and_b32_e32 v165, 0xffff0000, v141
	v_pk_mul_f32 v[162:163], v[162:163], v[252:253] op_sel_hi:[1,0]
	v_pk_mul_f32 v[164:165], v[164:165], v[252:253] op_sel_hi:[1,0]
	v_pk_mul_f32 v[162:163], v[162:163], v[226:227]
	v_pk_mul_f32 v[164:165], v[164:165], v[228:229]
	v_pk_fma_f32 v[86:87], v[230:231], v[162:163], v[86:87]
	v_pk_fma_f32 v[88:89], v[232:233], v[164:165], v[88:89]
	v_pk_fma_f32 v[170:171], v[86:87], v[86:87], v[170:171]
	v_pk_fma_f32 v[172:173], v[88:89], v[88:89], v[172:173]
	v_cvt_pk_bf16_f32 v168, v86, v87
	v_cvt_pk_bf16_f32 v169, v88, v89
	global_store_dwordx2 v244, v[168:169], s[22:23] offset:2560
	ds_read_b128 v[226:229], v238 offset:7168
	ds_read_b128 v[230:233], v238 offset:39936
	s_waitcnt lgkmcnt(2)
	v_lshlrev_b32_e32 v162, 16, v142
	v_and_b32_e32 v163, 0xffff0000, v142
	v_lshlrev_b32_e32 v164, 16, v143
	v_and_b32_e32 v165, 0xffff0000, v143
	v_pk_mul_f32 v[162:163], v[162:163], v[252:253] op_sel_hi:[1,0]
	v_pk_mul_f32 v[164:165], v[164:165], v[252:253] op_sel_hi:[1,0]
	v_pk_mul_f32 v[162:163], v[162:163], v[214:215]
	v_pk_mul_f32 v[164:165], v[164:165], v[216:217]
	v_pk_fma_f32 v[90:91], v[218:219], v[162:163], v[90:91]
	v_pk_fma_f32 v[92:93], v[220:221], v[164:165], v[92:93]
	v_pk_fma_f32 v[170:171], v[90:91], v[90:91], v[170:171]
	v_pk_fma_f32 v[172:173], v[92:93], v[92:93], v[172:173]
	v_cvt_pk_bf16_f32 v166, v90, v91
	v_cvt_pk_bf16_f32 v167, v92, v93
	global_store_dwordx2 v244, v[166:167], s[22:23] offset:3072
	ds_read_b128 v[214:217], v238 offset:8192
	ds_read_b128 v[218:221], v238 offset:40960
	s_waitcnt lgkmcnt(2)
	v_lshlrev_b32_e32 v162, 16, v144
	v_and_b32_e32 v163, 0xffff0000, v144
	v_lshlrev_b32_e32 v164, 16, v145
	v_and_b32_e32 v165, 0xffff0000, v145
	v_pk_mul_f32 v[162:163], v[162:163], v[252:253] op_sel_hi:[1,0]
	v_pk_mul_f32 v[164:165], v[164:165], v[252:253] op_sel_hi:[1,0]
	v_pk_mul_f32 v[162:163], v[162:163], v[226:227]
	v_pk_mul_f32 v[164:165], v[164:165], v[228:229]
	v_pk_fma_f32 v[94:95], v[230:231], v[162:163], v[94:95]
	v_pk_fma_f32 v[96:97], v[232:233], v[164:165], v[96:97]
	v_pk_fma_f32 v[170:171], v[94:95], v[94:95], v[170:171]
	v_pk_fma_f32 v[172:173], v[96:97], v[96:97], v[172:173]
	v_cvt_pk_bf16_f32 v168, v94, v95
	v_cvt_pk_bf16_f32 v169, v96, v97
	global_store_dwordx2 v244, v[168:169], s[22:23] offset:3584
	ds_read_b128 v[226:229], v238 offset:9216
	ds_read_b128 v[230:233], v238 offset:41984
	s_waitcnt lgkmcnt(2)
	v_lshlrev_b32_e32 v162, 16, v146
	v_and_b32_e32 v163, 0xffff0000, v146
	v_lshlrev_b32_e32 v164, 16, v147
	v_and_b32_e32 v165, 0xffff0000, v147
	v_pk_mul_f32 v[162:163], v[162:163], v[252:253] op_sel_hi:[1,0]
	v_pk_mul_f32 v[164:165], v[164:165], v[252:253] op_sel_hi:[1,0]
	v_pk_mul_f32 v[162:163], v[162:163], v[214:215]
	v_pk_mul_f32 v[164:165], v[164:165], v[216:217]
	v_pk_fma_f32 v[98:99], v[218:219], v[162:163], v[98:99]
	v_pk_fma_f32 v[100:101], v[220:221], v[164:165], v[100:101]
	v_pk_fma_f32 v[170:171], v[98:99], v[98:99], v[170:171]
	v_pk_fma_f32 v[172:173], v[100:101], v[100:101], v[172:173]
	v_cvt_pk_bf16_f32 v166, v98, v99
	v_cvt_pk_bf16_f32 v167, v100, v101
	global_store_dwordx2 v245, v[166:167], s[22:23] offset:0
	ds_read_b128 v[214:217], v238 offset:10240
	ds_read_b128 v[218:221], v238 offset:43008
	s_waitcnt lgkmcnt(2)
	v_lshlrev_b32_e32 v162, 16, v148
	v_and_b32_e32 v163, 0xffff0000, v148
	v_lshlrev_b32_e32 v164, 16, v149
	v_and_b32_e32 v165, 0xffff0000, v149
	v_pk_mul_f32 v[162:163], v[162:163], v[252:253] op_sel_hi:[1,0]
	v_pk_mul_f32 v[164:165], v[164:165], v[252:253] op_sel_hi:[1,0]
	v_pk_mul_f32 v[162:163], v[162:163], v[226:227]
	v_pk_mul_f32 v[164:165], v[164:165], v[228:229]
	v_pk_fma_f32 v[102:103], v[230:231], v[162:163], v[102:103]
	v_pk_fma_f32 v[104:105], v[232:233], v[164:165], v[104:105]
	v_pk_fma_f32 v[170:171], v[102:103], v[102:103], v[170:171]
	v_pk_fma_f32 v[172:173], v[104:105], v[104:105], v[172:173]
	v_cvt_pk_bf16_f32 v168, v102, v103
	v_cvt_pk_bf16_f32 v169, v104, v105
	global_store_dwordx2 v245, v[168:169], s[22:23] offset:512
	ds_read_b128 v[226:229], v238 offset:11264
	ds_read_b128 v[230:233], v238 offset:44032
	s_waitcnt lgkmcnt(2)
	v_lshlrev_b32_e32 v162, 16, v150
	v_and_b32_e32 v163, 0xffff0000, v150
	v_lshlrev_b32_e32 v164, 16, v151
	v_and_b32_e32 v165, 0xffff0000, v151
	v_pk_mul_f32 v[162:163], v[162:163], v[252:253] op_sel_hi:[1,0]
	v_pk_mul_f32 v[164:165], v[164:165], v[252:253] op_sel_hi:[1,0]
	v_pk_mul_f32 v[162:163], v[162:163], v[214:215]
	v_pk_mul_f32 v[164:165], v[164:165], v[216:217]
	v_pk_fma_f32 v[106:107], v[218:219], v[162:163], v[106:107]
	v_pk_fma_f32 v[108:109], v[220:221], v[164:165], v[108:109]
	v_pk_fma_f32 v[170:171], v[106:107], v[106:107], v[170:171]
	v_pk_fma_f32 v[172:173], v[108:109], v[108:109], v[172:173]
	v_cvt_pk_bf16_f32 v166, v106, v107
	v_cvt_pk_bf16_f32 v167, v108, v109
	global_store_dwordx2 v245, v[166:167], s[22:23] offset:1024
	ds_read_b128 v[214:217], v238 offset:12288
	ds_read_b128 v[218:221], v238 offset:45056
	s_waitcnt lgkmcnt(2)
	v_lshlrev_b32_e32 v162, 16, v152
	v_and_b32_e32 v163, 0xffff0000, v152
	v_lshlrev_b32_e32 v164, 16, v153
	v_and_b32_e32 v165, 0xffff0000, v153
	v_pk_mul_f32 v[162:163], v[162:163], v[252:253] op_sel_hi:[1,0]
	v_pk_mul_f32 v[164:165], v[164:165], v[252:253] op_sel_hi:[1,0]
	v_pk_mul_f32 v[162:163], v[162:163], v[226:227]
	v_pk_mul_f32 v[164:165], v[164:165], v[228:229]
	v_pk_fma_f32 v[110:111], v[230:231], v[162:163], v[110:111]
	v_pk_fma_f32 v[112:113], v[232:233], v[164:165], v[112:113]
	v_pk_fma_f32 v[170:171], v[110:111], v[110:111], v[170:171]
	v_pk_fma_f32 v[172:173], v[112:113], v[112:113], v[172:173]
	v_cvt_pk_bf16_f32 v168, v110, v111
	v_cvt_pk_bf16_f32 v169, v112, v113
	global_store_dwordx2 v245, v[168:169], s[22:23] offset:1536
	ds_read_b128 v[226:229], v238 offset:13312
	ds_read_b128 v[230:233], v238 offset:46080
	s_waitcnt lgkmcnt(2)
	v_lshlrev_b32_e32 v162, 16, v154
	v_and_b32_e32 v163, 0xffff0000, v154
	v_lshlrev_b32_e32 v164, 16, v155
	v_and_b32_e32 v165, 0xffff0000, v155
	v_pk_mul_f32 v[162:163], v[162:163], v[252:253] op_sel_hi:[1,0]
	v_pk_mul_f32 v[164:165], v[164:165], v[252:253] op_sel_hi:[1,0]
	v_pk_mul_f32 v[162:163], v[162:163], v[214:215]
	v_pk_mul_f32 v[164:165], v[164:165], v[216:217]
	v_pk_fma_f32 v[114:115], v[218:219], v[162:163], v[114:115]
	v_pk_fma_f32 v[116:117], v[220:221], v[164:165], v[116:117]
	v_pk_fma_f32 v[170:171], v[114:115], v[114:115], v[170:171]
	v_pk_fma_f32 v[172:173], v[116:117], v[116:117], v[172:173]
	v_cvt_pk_bf16_f32 v166, v114, v115
	v_cvt_pk_bf16_f32 v167, v116, v117
	global_store_dwordx2 v245, v[166:167], s[22:23] offset:2048
	ds_read_b128 v[214:217], v238 offset:14336
	ds_read_b128 v[218:221], v238 offset:47104
	s_waitcnt lgkmcnt(2)
	v_lshlrev_b32_e32 v162, 16, v156
	v_and_b32_e32 v163, 0xffff0000, v156
	v_lshlrev_b32_e32 v164, 16, v157
	v_and_b32_e32 v165, 0xffff0000, v157
	v_pk_mul_f32 v[162:163], v[162:163], v[252:253] op_sel_hi:[1,0]
	v_pk_mul_f32 v[164:165], v[164:165], v[252:253] op_sel_hi:[1,0]
	v_pk_mul_f32 v[162:163], v[162:163], v[226:227]
	v_pk_mul_f32 v[164:165], v[164:165], v[228:229]
	v_pk_fma_f32 v[118:119], v[230:231], v[162:163], v[118:119]
	v_pk_fma_f32 v[120:121], v[232:233], v[164:165], v[120:121]
	v_pk_fma_f32 v[170:171], v[118:119], v[118:119], v[170:171]
	v_pk_fma_f32 v[172:173], v[120:121], v[120:121], v[172:173]
	v_cvt_pk_bf16_f32 v168, v118, v119
	v_cvt_pk_bf16_f32 v169, v120, v121
	global_store_dwordx2 v245, v[168:169], s[22:23] offset:2560
	ds_read_b128 v[226:229], v238 offset:15360
	ds_read_b128 v[230:233], v238 offset:48128
	s_waitcnt lgkmcnt(2)
	v_lshlrev_b32_e32 v162, 16, v158
	v_and_b32_e32 v163, 0xffff0000, v158
	v_lshlrev_b32_e32 v164, 16, v159
	v_and_b32_e32 v165, 0xffff0000, v159
	v_pk_mul_f32 v[162:163], v[162:163], v[252:253] op_sel_hi:[1,0]
	v_pk_mul_f32 v[164:165], v[164:165], v[252:253] op_sel_hi:[1,0]
	v_pk_mul_f32 v[162:163], v[162:163], v[214:215]
	v_pk_mul_f32 v[164:165], v[164:165], v[216:217]
	v_pk_fma_f32 v[122:123], v[218:219], v[162:163], v[122:123]
	v_pk_fma_f32 v[124:125], v[220:221], v[164:165], v[124:125]
	v_pk_fma_f32 v[170:171], v[122:123], v[122:123], v[170:171]
	v_pk_fma_f32 v[172:173], v[124:125], v[124:125], v[172:173]
	v_cvt_pk_bf16_f32 v166, v122, v123
	v_cvt_pk_bf16_f32 v167, v124, v125
	global_store_dwordx2 v245, v[166:167], s[22:23] offset:3072
	s_waitcnt lgkmcnt(0)
	v_lshlrev_b32_e32 v162, 16, v160
	v_and_b32_e32 v163, 0xffff0000, v160
	v_lshlrev_b32_e32 v164, 16, v161
	v_and_b32_e32 v165, 0xffff0000, v161
	v_pk_mul_f32 v[162:163], v[162:163], v[252:253] op_sel_hi:[1,0]
	v_pk_mul_f32 v[164:165], v[164:165], v[252:253] op_sel_hi:[1,0]
	v_pk_mul_f32 v[162:163], v[162:163], v[226:227]
	v_pk_mul_f32 v[164:165], v[164:165], v[228:229]
	v_pk_fma_f32 v[126:127], v[230:231], v[162:163], v[126:127]
	v_pk_fma_f32 v[128:129], v[232:233], v[164:165], v[128:129]
	v_pk_fma_f32 v[170:171], v[126:127], v[126:127], v[170:171]
	v_pk_fma_f32 v[172:173], v[128:129], v[128:129], v[172:173]
	v_cvt_pk_bf16_f32 v168, v126, v127
	v_cvt_pk_bf16_f32 v169, v128, v129
	global_store_dwordx2 v245, v[168:169], s[22:23] offset:3584
	ds_read_b128 v[214:217], v238 offset:16384
	ds_read_b128 v[218:221], v238 offset:49152
	ds_read_b128 v[222:225], v239 offset:0
	v_pk_add_f32 v[170:171], v[170:171], v[172:173]
	s_nop 0
	v_add_f32_e32 v252, v170, v171
	s_waitcnt lgkmcnt(0)
	ds_bpermute_b32 v254, v246, v252
	s_waitcnt lgkmcnt(0)
	v_add_f32_e32 v252, v252, v254
	ds_bpermute_b32 v254, v247, v252
	s_waitcnt lgkmcnt(0)
	v_add_f32_e32 v252, v252, v254
	ds_bpermute_b32 v254, v248, v252
	s_waitcnt lgkmcnt(0)
	v_add_f32_e32 v252, v252, v254
	ds_bpermute_b32 v254, v249, v252
	s_waitcnt lgkmcnt(0)
	v_add_f32_e32 v252, v252, v254
	ds_bpermute_b32 v254, v250, v252
	s_waitcnt lgkmcnt(0)
	v_add_f32_e32 v252, v252, v254
	ds_bpermute_b32 v254, v251, v252
	s_waitcnt lgkmcnt(0)
	v_add_f32_e32 v252, v252, v254
	v_mov_b32_e32 v254, 0x358637bd
	v_fmac_f32_e32 v254, 0x39800000, v252
	v_mul_f32_e32 v252, 0x4b800000, v254
	v_cmp_gt_f32_e32 vcc, s32, v254
	s_nop 1
	v_cndmask_b32_e32 v254, v254, v252, vcc
	v_rsq_f32_e32 v254, v254
	s_nop 0
	v_mul_f32_e32 v252, 0x45800000, v254
	v_cndmask_b32_e32 v252, v254, v252, vcc
	s_add_u32 s16, s16, 0x1000000
	s_addc_u32 s17, s17, 0
	global_load_dwordx2 v[130:131], v244, s[16:17] offset:0
	global_load_dwordx2 v[132:133], v244, s[16:17] offset:512
	global_load_dwordx2 v[134:135], v244, s[16:17] offset:1024
	global_load_dwordx2 v[136:137], v244, s[16:17] offset:1536
	global_load_dwordx2 v[138:139], v244, s[16:17] offset:2048
	global_load_dwordx2 v[140:141], v244, s[16:17] offset:2560
	global_load_dwordx2 v[142:143], v244, s[16:17] offset:3072
	global_load_dwordx2 v[144:145], v244, s[16:17] offset:3584
	global_load_dwordx2 v[146:147], v245, s[16:17] offset:0
	global_load_dwordx2 v[148:149], v245, s[16:17] offset:512
	global_load_dwordx2 v[150:151], v245, s[16:17] offset:1024
	global_load_dwordx2 v[152:153], v245, s[16:17] offset:1536
	global_load_dwordx2 v[154:155], v245, s[16:17] offset:2048
	global_load_dwordx2 v[156:157], v245, s[16:17] offset:2560
	global_load_dwordx2 v[158:159], v245, s[16:17] offset:3072
	global_load_dwordx2 v[160:161], v245, s[16:17] offset:3584
	ds_read_b128 v[226:229], v238 offset:17408
	ds_read_b128 v[230:233], v238 offset:50176
	ds_read_b128 v[234:237], v239 offset:1024
	s_waitcnt lgkmcnt(3)
	v_pk_mul_f32 v[66:67], v[66:67], v[252:253] op_sel_hi:[1,0]
	v_pk_mul_f32 v[68:69], v[68:69], v[252:253] op_sel_hi:[1,0]
	v_pk_mul_f32 v[66:67], v[66:67], v[214:215]
	v_pk_mul_f32 v[68:69], v[68:69], v[216:217]
	v_pk_add_f32 v[222:223], v[222:223], 1.0 op_sel_hi:[1,0]
	v_pk_add_f32 v[224:225], v[224:225], 1.0 op_sel_hi:[1,0]
	v_pk_fma_f32 v[66:67], v[66:67], v[222:223], v[218:219]
	v_pk_fma_f32 v[68:69], v[68:69], v[224:225], v[220:221]
	s_nop 0
	v_cvt_pk_bf16_f32 v66, v66, v67
	v_cvt_pk_bf16_f32 v67, v68, v69
	global_store_dwordx2 v244, v[66:67], s[38:39] offset:0
	ds_read_b128 v[214:217], v238 offset:18432
	ds_read_b128 v[218:221], v238 offset:51200
	ds_read_b128 v[222:225], v239 offset:2048
	s_waitcnt lgkmcnt(3)
	v_pk_mul_f32 v[70:71], v[70:71], v[252:253] op_sel_hi:[1,0]
	v_pk_mul_f32 v[72:73], v[72:73], v[252:253] op_sel_hi:[1,0]
	v_pk_mul_f32 v[70:71], v[70:71], v[226:227]
	v_pk_mul_f32 v[72:73], v[72:73], v[228:229]
	v_pk_add_f32 v[234:235], v[234:235], 1.0 op_sel_hi:[1,0]
	v_pk_add_f32 v[236:237], v[236:237], 1.0 op_sel_hi:[1,0]
	v_pk_fma_f32 v[70:71], v[70:71], v[234:235], v[230:231]
	v_pk_fma_f32 v[72:73], v[72:73], v[236:237], v[232:233]
	s_nop 0
	v_cvt_pk_bf16_f32 v70, v70, v71
	v_cvt_pk_bf16_f32 v71, v72, v73
	global_store_dwordx2 v244, v[70:71], s[38:39] offset:512
	ds_read_b128 v[226:229], v238 offset:19456
	ds_read_b128 v[230:233], v238 offset:52224
	ds_read_b128 v[234:237], v239 offset:3072
	s_waitcnt lgkmcnt(3)
	v_pk_mul_f32 v[74:75], v[74:75], v[252:253] op_sel_hi:[1,0]
	v_pk_mul_f32 v[76:77], v[76:77], v[252:253] op_sel_hi:[1,0]
	v_pk_mul_f32 v[74:75], v[74:75], v[214:215]
	v_pk_mul_f32 v[76:77], v[76:77], v[216:217]
	v_pk_add_f32 v[222:223], v[222:223], 1.0 op_sel_hi:[1,0]
	v_pk_add_f32 v[224:225], v[224:225], 1.0 op_sel_hi:[1,0]
	v_pk_fma_f32 v[74:75], v[74:75], v[222:223], v[218:219]
	v_pk_fma_f32 v[76:77], v[76:77], v[224:225], v[220:221]
	s_nop 0
	v_cvt_pk_bf16_f32 v74, v74, v75
	v_cvt_pk_bf16_f32 v75, v76, v77
	global_store_dwordx2 v244, v[74:75], s[38:39] offset:1024
	ds_read_b128 v[214:217], v238 offset:20480
	ds_read_b128 v[218:221], v238 offset:53248
	ds_read_b128 v[222:225], v239 offset:4096
	s_waitcnt lgkmcnt(3)
	v_pk_mul_f32 v[78:79], v[78:79], v[252:253] op_sel_hi:[1,0]
	v_pk_mul_f32 v[80:81], v[80:81], v[252:253] op_sel_hi:[1,0]
	v_pk_mul_f32 v[78:79], v[78:79], v[226:227]
	v_pk_mul_f32 v[80:81], v[80:81], v[228:229]
	v_pk_add_f32 v[234:235], v[234:235], 1.0 op_sel_hi:[1,0]
	v_pk_add_f32 v[236:237], v[236:237], 1.0 op_sel_hi:[1,0]
	v_pk_fma_f32 v[78:79], v[78:79], v[234:235], v[230:231]
	v_pk_fma_f32 v[80:81], v[80:81], v[236:237], v[232:233]
	s_nop 0
	v_cvt_pk_bf16_f32 v78, v78, v79
	v_cvt_pk_bf16_f32 v79, v80, v81
	global_store_dwordx2 v244, v[78:79], s[38:39] offset:1536
	ds_read_b128 v[226:229], v238 offset:21504
	ds_read_b128 v[230:233], v238 offset:54272
	ds_read_b128 v[234:237], v239 offset:5120
	s_waitcnt lgkmcnt(3)
	v_pk_mul_f32 v[82:83], v[82:83], v[252:253] op_sel_hi:[1,0]
	v_pk_mul_f32 v[84:85], v[84:85], v[252:253] op_sel_hi:[1,0]
	v_pk_mul_f32 v[82:83], v[82:83], v[214:215]
	v_pk_mul_f32 v[84:85], v[84:85], v[216:217]
	v_pk_add_f32 v[222:223], v[222:223], 1.0 op_sel_hi:[1,0]
	v_pk_add_f32 v[224:225], v[224:225], 1.0 op_sel_hi:[1,0]
	v_pk_fma_f32 v[82:83], v[82:83], v[222:223], v[218:219]
	v_pk_fma_f32 v[84:85], v[84:85], v[224:225], v[220:221]
	s_nop 0
	v_cvt_pk_bf16_f32 v82, v82, v83
	v_cvt_pk_bf16_f32 v83, v84, v85
	global_store_dwordx2 v244, v[82:83], s[38:39] offset:2048
	ds_read_b128 v[214:217], v238 offset:22528
	ds_read_b128 v[218:221], v238 offset:55296
	ds_read_b128 v[222:225], v239 offset:6144
	s_waitcnt lgkmcnt(3)
	v_pk_mul_f32 v[86:87], v[86:87], v[252:253] op_sel_hi:[1,0]
	v_pk_mul_f32 v[88:89], v[88:89], v[252:253] op_sel_hi:[1,0]
	v_pk_mul_f32 v[86:87], v[86:87], v[226:227]
	v_pk_mul_f32 v[88:89], v[88:89], v[228:229]
	v_pk_add_f32 v[234:235], v[234:235], 1.0 op_sel_hi:[1,0]
	v_pk_add_f32 v[236:237], v[236:237], 1.0 op_sel_hi:[1,0]
	v_pk_fma_f32 v[86:87], v[86:87], v[234:235], v[230:231]
	v_pk_fma_f32 v[88:89], v[88:89], v[236:237], v[232:233]
	s_nop 0
	v_cvt_pk_bf16_f32 v86, v86, v87
	v_cvt_pk_bf16_f32 v87, v88, v89
	global_store_dwordx2 v244, v[86:87], s[38:39] offset:2560
	ds_read_b128 v[226:229], v238 offset:23552
	ds_read_b128 v[230:233], v238 offset:56320
	ds_read_b128 v[234:237], v239 offset:7168
	s_waitcnt lgkmcnt(3)
	v_pk_mul_f32 v[90:91], v[90:91], v[252:253] op_sel_hi:[1,0]
	v_pk_mul_f32 v[92:93], v[92:93], v[252:253] op_sel_hi:[1,0]
	v_pk_mul_f32 v[90:91], v[90:91], v[214:215]
	v_pk_mul_f32 v[92:93], v[92:93], v[216:217]
	v_pk_add_f32 v[222:223], v[222:223], 1.0 op_sel_hi:[1,0]
	v_pk_add_f32 v[224:225], v[224:225], 1.0 op_sel_hi:[1,0]
	v_pk_fma_f32 v[90:91], v[90:91], v[222:223], v[218:219]
	v_pk_fma_f32 v[92:93], v[92:93], v[224:225], v[220:221]
	s_nop 0
	v_cvt_pk_bf16_f32 v90, v90, v91
	v_cvt_pk_bf16_f32 v91, v92, v93
	global_store_dwordx2 v244, v[90:91], s[38:39] offset:3072
	ds_read_b128 v[214:217], v238 offset:24576
	ds_read_b128 v[218:221], v238 offset:57344
	ds_read_b128 v[222:225], v239 offset:8192
	s_waitcnt lgkmcnt(3)
	v_pk_mul_f32 v[94:95], v[94:95], v[252:253] op_sel_hi:[1,0]
	v_pk_mul_f32 v[96:97], v[96:97], v[252:253] op_sel_hi:[1,0]
	v_pk_mul_f32 v[94:95], v[94:95], v[226:227]
	v_pk_mul_f32 v[96:97], v[96:97], v[228:229]
	v_pk_add_f32 v[234:235], v[234:235], 1.0 op_sel_hi:[1,0]
	v_pk_add_f32 v[236:237], v[236:237], 1.0 op_sel_hi:[1,0]
	v_pk_fma_f32 v[94:95], v[94:95], v[234:235], v[230:231]
	v_pk_fma_f32 v[96:97], v[96:97], v[236:237], v[232:233]
	s_nop 0
	v_cvt_pk_bf16_f32 v94, v94, v95
	v_cvt_pk_bf16_f32 v95, v96, v97
	global_store_dwordx2 v244, v[94:95], s[38:39] offset:3584
	ds_read_b128 v[226:229], v238 offset:25600
	ds_read_b128 v[230:233], v238 offset:58368
	ds_read_b128 v[234:237], v239 offset:9216
	s_waitcnt lgkmcnt(3)
	v_pk_mul_f32 v[98:99], v[98:99], v[252:253] op_sel_hi:[1,0]
	v_pk_mul_f32 v[100:101], v[100:101], v[252:253] op_sel_hi:[1,0]
	v_pk_mul_f32 v[98:99], v[98:99], v[214:215]
	v_pk_mul_f32 v[100:101], v[100:101], v[216:217]
	v_pk_add_f32 v[222:223], v[222:223], 1.0 op_sel_hi:[1,0]
	v_pk_add_f32 v[224:225], v[224:225], 1.0 op_sel_hi:[1,0]
	v_pk_fma_f32 v[98:99], v[98:99], v[222:223], v[218:219]
	v_pk_fma_f32 v[100:101], v[100:101], v[224:225], v[220:221]
	s_nop 0
	v_cvt_pk_bf16_f32 v98, v98, v99
	v_cvt_pk_bf16_f32 v99, v100, v101
	global_store_dwordx2 v245, v[98:99], s[38:39] offset:0
	ds_read_b128 v[214:217], v238 offset:26624
	ds_read_b128 v[218:221], v238 offset:59392
	ds_read_b128 v[222:225], v239 offset:10240
	s_waitcnt lgkmcnt(3)
	v_pk_mul_f32 v[102:103], v[102:103], v[252:253] op_sel_hi:[1,0]
	v_pk_mul_f32 v[104:105], v[104:105], v[252:253] op_sel_hi:[1,0]
	v_pk_mul_f32 v[102:103], v[102:103], v[226:227]
	v_pk_mul_f32 v[104:105], v[104:105], v[228:229]
	v_pk_add_f32 v[234:235], v[234:235], 1.0 op_sel_hi:[1,0]
	v_pk_add_f32 v[236:237], v[236:237], 1.0 op_sel_hi:[1,0]
	v_pk_fma_f32 v[102:103], v[102:103], v[234:235], v[230:231]
	v_pk_fma_f32 v[104:105], v[104:105], v[236:237], v[232:233]
	s_nop 0
	v_cvt_pk_bf16_f32 v102, v102, v103
	v_cvt_pk_bf16_f32 v103, v104, v105
	global_store_dwordx2 v245, v[102:103], s[38:39] offset:512
	ds_read_b128 v[226:229], v238 offset:27648
	ds_read_b128 v[230:233], v238 offset:60416
	ds_read_b128 v[234:237], v239 offset:11264
	s_waitcnt lgkmcnt(3)
	v_pk_mul_f32 v[106:107], v[106:107], v[252:253] op_sel_hi:[1,0]
	v_pk_mul_f32 v[108:109], v[108:109], v[252:253] op_sel_hi:[1,0]
	v_pk_mul_f32 v[106:107], v[106:107], v[214:215]
	v_pk_mul_f32 v[108:109], v[108:109], v[216:217]
	v_pk_add_f32 v[222:223], v[222:223], 1.0 op_sel_hi:[1,0]
	v_pk_add_f32 v[224:225], v[224:225], 1.0 op_sel_hi:[1,0]
	v_pk_fma_f32 v[106:107], v[106:107], v[222:223], v[218:219]
	v_pk_fma_f32 v[108:109], v[108:109], v[224:225], v[220:221]
	s_nop 0
	v_cvt_pk_bf16_f32 v106, v106, v107
	v_cvt_pk_bf16_f32 v107, v108, v109
	global_store_dwordx2 v245, v[106:107], s[38:39] offset:1024
	ds_read_b128 v[214:217], v238 offset:28672
	ds_read_b128 v[218:221], v238 offset:61440
	ds_read_b128 v[222:225], v239 offset:12288
	s_waitcnt lgkmcnt(3)
	v_pk_mul_f32 v[110:111], v[110:111], v[252:253] op_sel_hi:[1,0]
	v_pk_mul_f32 v[112:113], v[112:113], v[252:253] op_sel_hi:[1,0]
	v_pk_mul_f32 v[110:111], v[110:111], v[226:227]
	v_pk_mul_f32 v[112:113], v[112:113], v[228:229]
	v_pk_add_f32 v[234:235], v[234:235], 1.0 op_sel_hi:[1,0]
	v_pk_add_f32 v[236:237], v[236:237], 1.0 op_sel_hi:[1,0]
	v_pk_fma_f32 v[110:111], v[110:111], v[234:235], v[230:231]
	v_pk_fma_f32 v[112:113], v[112:113], v[236:237], v[232:233]
	s_nop 0
	v_cvt_pk_bf16_f32 v110, v110, v111
	v_cvt_pk_bf16_f32 v111, v112, v113
	global_store_dwordx2 v245, v[110:111], s[38:39] offset:1536
	ds_read_b128 v[226:229], v238 offset:29696
	ds_read_b128 v[230:233], v238 offset:62464
	ds_read_b128 v[234:237], v239 offset:13312
	s_waitcnt lgkmcnt(3)
	v_pk_mul_f32 v[114:115], v[114:115], v[252:253] op_sel_hi:[1,0]
	v_pk_mul_f32 v[116:117], v[116:117], v[252:253] op_sel_hi:[1,0]
	v_pk_mul_f32 v[114:115], v[114:115], v[214:215]
	v_pk_mul_f32 v[116:117], v[116:117], v[216:217]
	v_pk_add_f32 v[222:223], v[222:223], 1.0 op_sel_hi:[1,0]
	v_pk_add_f32 v[224:225], v[224:225], 1.0 op_sel_hi:[1,0]
	v_pk_fma_f32 v[114:115], v[114:115], v[222:223], v[218:219]
	v_pk_fma_f32 v[116:117], v[116:117], v[224:225], v[220:221]
	s_nop 0
	v_cvt_pk_bf16_f32 v114, v114, v115
	v_cvt_pk_bf16_f32 v115, v116, v117
	global_store_dwordx2 v245, v[114:115], s[38:39] offset:2048
	ds_read_b128 v[214:217], v238 offset:30720
	ds_read_b128 v[218:221], v238 offset:63488
	ds_read_b128 v[222:225], v239 offset:14336
	s_waitcnt lgkmcnt(3)
	v_pk_mul_f32 v[118:119], v[118:119], v[252:253] op_sel_hi:[1,0]
	v_pk_mul_f32 v[120:121], v[120:121], v[252:253] op_sel_hi:[1,0]
	v_pk_mul_f32 v[118:119], v[118:119], v[226:227]
	v_pk_mul_f32 v[120:121], v[120:121], v[228:229]
	v_pk_add_f32 v[234:235], v[234:235], 1.0 op_sel_hi:[1,0]
	v_pk_add_f32 v[236:237], v[236:237], 1.0 op_sel_hi:[1,0]
	v_pk_fma_f32 v[118:119], v[118:119], v[234:235], v[230:231]
	v_pk_fma_f32 v[120:121], v[120:121], v[236:237], v[232:233]
	s_nop 0
	v_cvt_pk_bf16_f32 v118, v118, v119
	v_cvt_pk_bf16_f32 v119, v120, v121
	global_store_dwordx2 v245, v[118:119], s[38:39] offset:2560
	ds_read_b128 v[226:229], v238 offset:31744
	ds_read_b128 v[230:233], v238 offset:64512
	ds_read_b128 v[234:237], v239 offset:15360
	s_waitcnt lgkmcnt(3)
	v_pk_mul_f32 v[122:123], v[122:123], v[252:253] op_sel_hi:[1,0]
	v_pk_mul_f32 v[124:125], v[124:125], v[252:253] op_sel_hi:[1,0]
	v_pk_mul_f32 v[122:123], v[122:123], v[214:215]
	v_pk_mul_f32 v[124:125], v[124:125], v[216:217]
	v_pk_add_f32 v[222:223], v[222:223], 1.0 op_sel_hi:[1,0]
	v_pk_add_f32 v[224:225], v[224:225], 1.0 op_sel_hi:[1,0]
	v_pk_fma_f32 v[122:123], v[122:123], v[222:223], v[218:219]
	v_pk_fma_f32 v[124:125], v[124:125], v[224:225], v[220:221]
	s_nop 0
	v_cvt_pk_bf16_f32 v122, v122, v123
	v_cvt_pk_bf16_f32 v123, v124, v125
	global_store_dwordx2 v245, v[122:123], s[38:39] offset:3072
	s_waitcnt lgkmcnt(0)
	v_pk_mul_f32 v[126:127], v[126:127], v[252:253] op_sel_hi:[1,0]
	v_pk_mul_f32 v[128:129], v[128:129], v[252:253] op_sel_hi:[1,0]
	v_pk_mul_f32 v[126:127], v[126:127], v[226:227]
	v_pk_mul_f32 v[128:129], v[128:129], v[228:229]
	v_pk_add_f32 v[234:235], v[234:235], 1.0 op_sel_hi:[1,0]
	v_pk_add_f32 v[236:237], v[236:237], 1.0 op_sel_hi:[1,0]
	v_pk_fma_f32 v[126:127], v[126:127], v[234:235], v[230:231]
	v_pk_fma_f32 v[128:129], v[128:129], v[236:237], v[232:233]
	s_nop 0
	v_cvt_pk_bf16_f32 v126, v126, v127
	v_cvt_pk_bf16_f32 v127, v128, v129
	global_store_dwordx2 v245, v[126:127], s[38:39] offset:3584
	s_add_u32 s22, s22, 0x1000000
	s_addc_u32 s23, s23, 0
	s_add_u32 s38, s38, 0x1000000
	s_addc_u32 s39, s39, 0
	s_waitcnt vmcnt(16)
	s_add_u32 s14, s14, 0x2000000
	s_addc_u32 s15, s15, 0
	global_load_dwordx4 v[66:69], v238, s[14:15] offset:0
	global_load_dwordx4 v[70:73], v238, s[14:15] offset:1024
	global_load_dwordx4 v[74:77], v238, s[14:15] offset:2048
	global_load_dwordx4 v[78:81], v238, s[14:15] offset:3072
	global_load_dwordx4 v[82:85], v241, s[14:15] offset:0
	global_load_dwordx4 v[86:89], v241, s[14:15] offset:1024
	global_load_dwordx4 v[90:93], v241, s[14:15] offset:2048
	global_load_dwordx4 v[94:97], v241, s[14:15] offset:3072
	global_load_dwordx4 v[98:101], v242, s[14:15] offset:0
	global_load_dwordx4 v[102:105], v242, s[14:15] offset:1024
	global_load_dwordx4 v[106:109], v242, s[14:15] offset:2048
	global_load_dwordx4 v[110:113], v242, s[14:15] offset:3072
	global_load_dwordx4 v[114:117], v243, s[14:15] offset:0
	global_load_dwordx4 v[118:121], v243, s[14:15] offset:1024
	global_load_dwordx4 v[122:125], v243, s[14:15] offset:2048
	global_load_dwordx4 v[126:129], v243, s[14:15] offset:3072
	ds_read_b128 v[214:217], v238 offset:0
	ds_read_b128 v[218:221], v238 offset:32768
	v_lshlrev_b32_e32 v162, 16, v130
	v_and_b32_e32 v163, 0xffff0000, v130
	v_lshlrev_b32_e32 v164, 16, v131
	v_and_b32_e32 v165, 0xffff0000, v131
	v_pk_mul_f32 v[170:171], v[162:163], v[162:163]
	v_pk_mul_f32 v[172:173], v[164:165], v[164:165]
	v_lshlrev_b32_e32 v166, 16, v132
	v_and_b32_e32 v167, 0xffff0000, v132
	v_lshlrev_b32_e32 v168, 16, v133
	v_and_b32_e32 v169, 0xffff0000, v133
	v_pk_fma_f32 v[170:171], v[166:167], v[166:167], v[170:171]
	v_pk_fma_f32 v[172:173], v[168:169], v[168:169], v[172:173]
	v_lshlrev_b32_e32 v162, 16, v134
	v_and_b32_e32 v163, 0xffff0000, v134
	v_lshlrev_b32_e32 v164, 16, v135
	v_and_b32_e32 v165, 0xffff0000, v135
	v_pk_fma_f32 v[170:171], v[162:163], v[162:163], v[170:171]
	v_pk_fma_f32 v[172:173], v[164:165], v[164:165], v[172:173]
	v_lshlrev_b32_e32 v166, 16, v136
	v_and_b32_e32 v167, 0xffff0000, v136
	v_lshlrev_b32_e32 v168, 16, v137
	v_and_b32_e32 v169, 0xffff0000, v137
	v_pk_fma_f32 v[170:171], v[166:167], v[166:167], v[170:171]
	v_pk_fma_f32 v[172:173], v[168:169], v[168:169], v[172:173]
	v_lshlrev_b32_e32 v162, 16, v138
	v_and_b32_e32 v163, 0xffff0000, v138
	v_lshlrev_b32_e32 v164, 16, v139
	v_and_b32_e32 v165, 0xffff0000, v139
	v_pk_fma_f32 v[170:171], v[162:163], v[162:163], v[170:171]
	v_pk_fma_f32 v[172:173], v[164:165], v[164:165], v[172:173]
	v_lshlrev_b32_e32 v166, 16, v140
	v_and_b32_e32 v167, 0xffff0000, v140
	v_lshlrev_b32_e32 v168, 16, v141
	v_and_b32_e32 v169, 0xffff0000, v141
	v_pk_fma_f32 v[170:171], v[166:167], v[166:167], v[170:171]
	v_pk_fma_f32 v[172:173], v[168:169], v[168:169], v[172:173]
	v_lshlrev_b32_e32 v162, 16, v142
	v_and_b32_e32 v163, 0xffff0000, v142
	v_lshlrev_b32_e32 v164, 16, v143
	v_and_b32_e32 v165, 0xffff0000, v143
	v_pk_fma_f32 v[170:171], v[162:163], v[162:163], v[170:171]
	v_pk_fma_f32 v[172:173], v[164:165], v[164:165], v[172:173]
	v_lshlrev_b32_e32 v166, 16, v144
	v_and_b32_e32 v167, 0xffff0000, v144
	v_lshlrev_b32_e32 v168, 16, v145
	v_and_b32_e32 v169, 0xffff0000, v145
	v_pk_fma_f32 v[170:171], v[166:167], v[166:167], v[170:171]
	v_pk_fma_f32 v[172:173], v[168:169], v[168:169], v[172:173]
	v_lshlrev_b32_e32 v162, 16, v146
	v_and_b32_e32 v163, 0xffff0000, v146
	v_lshlrev_b32_e32 v164, 16, v147
	v_and_b32_e32 v165, 0xffff0000, v147
	v_pk_fma_f32 v[170:171], v[162:163], v[162:163], v[170:171]
	v_pk_fma_f32 v[172:173], v[164:165], v[164:165], v[172:173]
	v_lshlrev_b32_e32 v166, 16, v148
	v_and_b32_e32 v167, 0xffff0000, v148
	v_lshlrev_b32_e32 v168, 16, v149
	v_and_b32_e32 v169, 0xffff0000, v149
	v_pk_fma_f32 v[170:171], v[166:167], v[166:167], v[170:171]
	v_pk_fma_f32 v[172:173], v[168:169], v[168:169], v[172:173]
	v_lshlrev_b32_e32 v162, 16, v150
	v_and_b32_e32 v163, 0xffff0000, v150
	v_lshlrev_b32_e32 v164, 16, v151
	v_and_b32_e32 v165, 0xffff0000, v151
	v_pk_fma_f32 v[170:171], v[162:163], v[162:163], v[170:171]
	v_pk_fma_f32 v[172:173], v[164:165], v[164:165], v[172:173]
	v_lshlrev_b32_e32 v166, 16, v152
	v_and_b32_e32 v167, 0xffff0000, v152
	v_lshlrev_b32_e32 v168, 16, v153
	v_and_b32_e32 v169, 0xffff0000, v153
	v_pk_fma_f32 v[170:171], v[166:167], v[166:167], v[170:171]
	v_pk_fma_f32 v[172:173], v[168:169], v[168:169], v[172:173]
	v_lshlrev_b32_e32 v162, 16, v154
	v_and_b32_e32 v163, 0xffff0000, v154
	v_lshlrev_b32_e32 v164, 16, v155
	v_and_b32_e32 v165, 0xffff0000, v155
	v_pk_fma_f32 v[170:171], v[162:163], v[162:163], v[170:171]
	v_pk_fma_f32 v[172:173], v[164:165], v[164:165], v[172:173]
	v_lshlrev_b32_e32 v166, 16, v156
	v_and_b32_e32 v167, 0xffff0000, v156
	v_lshlrev_b32_e32 v168, 16, v157
	v_and_b32_e32 v169, 0xffff0000, v157
	v_pk_fma_f32 v[170:171], v[166:167], v[166:167], v[170:171]
	v_pk_fma_f32 v[172:173], v[168:169], v[168:169], v[172:173]
	v_lshlrev_b32_e32 v162, 16, v158
	v_and_b32_e32 v163, 0xffff0000, v158
	v_lshlrev_b32_e32 v164, 16, v159
	v_and_b32_e32 v165, 0xffff0000, v159
	v_pk_fma_f32 v[170:171], v[162:163], v[162:163], v[170:171]
	v_pk_fma_f32 v[172:173], v[164:165], v[164:165], v[172:173]
	v_lshlrev_b32_e32 v166, 16, v160
	v_and_b32_e32 v167, 0xffff0000, v160
	v_lshlrev_b32_e32 v168, 16, v161
	v_and_b32_e32 v169, 0xffff0000, v161
	v_pk_fma_f32 v[170:171], v[166:167], v[166:167], v[170:171]
	v_pk_fma_f32 v[172:173], v[168:169], v[168:169], v[172:173]
	v_pk_add_f32 v[170:171], v[170:171], v[172:173]
	s_nop 0
	v_add_f32_e32 v252, v170, v171
	s_waitcnt lgkmcnt(0)
	ds_bpermute_b32 v254, v246, v252
	s_waitcnt lgkmcnt(0)
	v_add_f32_e32 v252, v252, v254
	ds_bpermute_b32 v254, v247, v252
	s_waitcnt lgkmcnt(0)
	v_add_f32_e32 v252, v252, v254
	ds_bpermute_b32 v254, v248, v252
	s_waitcnt lgkmcnt(0)
	v_add_f32_e32 v252, v252, v254
	ds_bpermute_b32 v254, v249, v252
	s_waitcnt lgkmcnt(0)
	v_add_f32_e32 v252, v252, v254
	ds_bpermute_b32 v254, v250, v252
	s_waitcnt lgkmcnt(0)
	v_add_f32_e32 v252, v252, v254
	ds_bpermute_b32 v254, v251, v252
	s_waitcnt lgkmcnt(0)
	v_add_f32_e32 v252, v252, v254
	v_mov_b32_e32 v254, 0x358637bd
	v_fmac_f32_e32 v254, 0x39800000, v252
	v_mul_f32_e32 v252, 0x4b800000, v254
	v_cmp_gt_f32_e32 vcc, s32, v254
	s_nop 1
	v_cndmask_b32_e32 v254, v254, v252, vcc
	v_rsq_f32_e32 v254, v254
	s_nop 0
	v_mul_f32_e32 v252, 0x45800000, v254
	v_cndmask_b32_e32 v252, v254, v252, vcc
	ds_read_b128 v[226:229], v238 offset:1024
	ds_read_b128 v[230:233], v238 offset:33792
	s_waitcnt lgkmcnt(2)
	v_lshlrev_b32_e32 v162, 16, v130
	v_and_b32_e32 v163, 0xffff0000, v130
	v_lshlrev_b32_e32 v164, 16, v131
	v_and_b32_e32 v165, 0xffff0000, v131
	v_pk_mul_f32 v[162:163], v[162:163], v[252:253] op_sel_hi:[1,0]
	v_pk_mul_f32 v[164:165], v[164:165], v[252:253] op_sel_hi:[1,0]
	v_pk_mul_f32 v[162:163], v[162:163], v[214:215]
	v_pk_mul_f32 v[164:165], v[164:165], v[216:217]
	v_pk_fma_f32 v[2:3], v[218:219], v[162:163], v[2:3]
	v_pk_fma_f32 v[4:5], v[220:221], v[164:165], v[4:5]
	v_pk_mul_f32 v[170:171], v[2:3], v[2:3]
	v_pk_mul_f32 v[172:173], v[4:5], v[4:5]
	v_cvt_pk_bf16_f32 v166, v2, v3
	v_cvt_pk_bf16_f32 v167, v4, v5
	global_store_dwordx2 v244, v[166:167], s[22:23] offset:0
	ds_read_b128 v[214:217], v238 offset:2048
	ds_read_b128 v[218:221], v238 offset:34816
	s_waitcnt lgkmcnt(2)
	v_lshlrev_b32_e32 v162, 16, v132
	v_and_b32_e32 v163, 0xffff0000, v132
	v_lshlrev_b32_e32 v164, 16, v133
	v_and_b32_e32 v165, 0xffff0000, v133
	v_pk_mul_f32 v[162:163], v[162:163], v[252:253] op_sel_hi:[1,0]
	v_pk_mul_f32 v[164:165], v[164:165], v[252:253] op_sel_hi:[1,0]
	v_pk_mul_f32 v[162:163], v[162:163], v[226:227]
	v_pk_mul_f32 v[164:165], v[164:165], v[228:229]
	v_pk_fma_f32 v[6:7], v[230:231], v[162:163], v[6:7]
	v_pk_fma_f32 v[8:9], v[232:233], v[164:165], v[8:9]
	v_pk_fma_f32 v[170:171], v[6:7], v[6:7], v[170:171]
	v_pk_fma_f32 v[172:173], v[8:9], v[8:9], v[172:173]
	v_cvt_pk_bf16_f32 v168, v6, v7
	v_cvt_pk_bf16_f32 v169, v8, v9
	global_store_dwordx2 v244, v[168:169], s[22:23] offset:512
	ds_read_b128 v[226:229], v238 offset:3072
	ds_read_b128 v[230:233], v238 offset:35840
	s_waitcnt lgkmcnt(2)
	v_lshlrev_b32_e32 v162, 16, v134
	v_and_b32_e32 v163, 0xffff0000, v134
	v_lshlrev_b32_e32 v164, 16, v135
	v_and_b32_e32 v165, 0xffff0000, v135
	v_pk_mul_f32 v[162:163], v[162:163], v[252:253] op_sel_hi:[1,0]
	v_pk_mul_f32 v[164:165], v[164:165], v[252:253] op_sel_hi:[1,0]
	v_pk_mul_f32 v[162:163], v[162:163], v[214:215]
	v_pk_mul_f32 v[164:165], v[164:165], v[216:217]
	v_pk_fma_f32 v[10:11], v[218:219], v[162:163], v[10:11]
	v_pk_fma_f32 v[12:13], v[220:221], v[164:165], v[12:13]
	v_pk_fma_f32 v[170:171], v[10:11], v[10:11], v[170:171]
	v_pk_fma_f32 v[172:173], v[12:13], v[12:13], v[172:173]
	v_cvt_pk_bf16_f32 v166, v10, v11
	v_cvt_pk_bf16_f32 v167, v12, v13
	global_store_dwordx2 v244, v[166:167], s[22:23] offset:1024
	ds_read_b128 v[214:217], v238 offset:4096
	ds_read_b128 v[218:221], v238 offset:36864
	s_waitcnt lgkmcnt(2)
	v_lshlrev_b32_e32 v162, 16, v136
	v_and_b32_e32 v163, 0xffff0000, v136
	v_lshlrev_b32_e32 v164, 16, v137
	v_and_b32_e32 v165, 0xffff0000, v137
	v_pk_mul_f32 v[162:163], v[162:163], v[252:253] op_sel_hi:[1,0]
	v_pk_mul_f32 v[164:165], v[164:165], v[252:253] op_sel_hi:[1,0]
	v_pk_mul_f32 v[162:163], v[162:163], v[226:227]
	v_pk_mul_f32 v[164:165], v[164:165], v[228:229]
	v_pk_fma_f32 v[14:15], v[230:231], v[162:163], v[14:15]
	v_pk_fma_f32 v[16:17], v[232:233], v[164:165], v[16:17]
	v_pk_fma_f32 v[170:171], v[14:15], v[14:15], v[170:171]
	v_pk_fma_f32 v[172:173], v[16:17], v[16:17], v[172:173]
	v_cvt_pk_bf16_f32 v168, v14, v15
	v_cvt_pk_bf16_f32 v169, v16, v17
	global_store_dwordx2 v244, v[168:169], s[22:23] offset:1536
	ds_read_b128 v[226:229], v238 offset:5120
	ds_read_b128 v[230:233], v238 offset:37888
	s_waitcnt lgkmcnt(2)
	v_lshlrev_b32_e32 v162, 16, v138
	v_and_b32_e32 v163, 0xffff0000, v138
	v_lshlrev_b32_e32 v164, 16, v139
	v_and_b32_e32 v165, 0xffff0000, v139
	v_pk_mul_f32 v[162:163], v[162:163], v[252:253] op_sel_hi:[1,0]
	v_pk_mul_f32 v[164:165], v[164:165], v[252:253] op_sel_hi:[1,0]
	v_pk_mul_f32 v[162:163], v[162:163], v[214:215]
	v_pk_mul_f32 v[164:165], v[164:165], v[216:217]
	v_pk_fma_f32 v[18:19], v[218:219], v[162:163], v[18:19]
	v_pk_fma_f32 v[20:21], v[220:221], v[164:165], v[20:21]
	v_pk_fma_f32 v[170:171], v[18:19], v[18:19], v[170:171]
	v_pk_fma_f32 v[172:173], v[20:21], v[20:21], v[172:173]
	v_cvt_pk_bf16_f32 v166, v18, v19
	v_cvt_pk_bf16_f32 v167, v20, v21
	global_store_dwordx2 v244, v[166:167], s[22:23] offset:2048
	ds_read_b128 v[214:217], v238 offset:6144
	ds_read_b128 v[218:221], v238 offset:38912
	s_waitcnt lgkmcnt(2)
	v_lshlrev_b32_e32 v162, 16, v140
	v_and_b32_e32 v163, 0xffff0000, v140
	v_lshlrev_b32_e32 v164, 16, v141
	v_and_b32_e32 v165, 0xffff0000, v141
	v_pk_mul_f32 v[162:163], v[162:163], v[252:253] op_sel_hi:[1,0]
	v_pk_mul_f32 v[164:165], v[164:165], v[252:253] op_sel_hi:[1,0]
	v_pk_mul_f32 v[162:163], v[162:163], v[226:227]
	v_pk_mul_f32 v[164:165], v[164:165], v[228:229]
	v_pk_fma_f32 v[22:23], v[230:231], v[162:163], v[22:23]
	v_pk_fma_f32 v[24:25], v[232:233], v[164:165], v[24:25]
	v_pk_fma_f32 v[170:171], v[22:23], v[22:23], v[170:171]
	v_pk_fma_f32 v[172:173], v[24:25], v[24:25], v[172:173]
	v_cvt_pk_bf16_f32 v168, v22, v23
	v_cvt_pk_bf16_f32 v169, v24, v25
	global_store_dwordx2 v244, v[168:169], s[22:23] offset:2560
	ds_read_b128 v[226:229], v238 offset:7168
	ds_read_b128 v[230:233], v238 offset:39936
	s_waitcnt lgkmcnt(2)
	v_lshlrev_b32_e32 v162, 16, v142
	v_and_b32_e32 v163, 0xffff0000, v142
	v_lshlrev_b32_e32 v164, 16, v143
	v_and_b32_e32 v165, 0xffff0000, v143
	v_pk_mul_f32 v[162:163], v[162:163], v[252:253] op_sel_hi:[1,0]
	v_pk_mul_f32 v[164:165], v[164:165], v[252:253] op_sel_hi:[1,0]
	v_pk_mul_f32 v[162:163], v[162:163], v[214:215]
	v_pk_mul_f32 v[164:165], v[164:165], v[216:217]
	v_pk_fma_f32 v[26:27], v[218:219], v[162:163], v[26:27]
	v_pk_fma_f32 v[28:29], v[220:221], v[164:165], v[28:29]
	v_pk_fma_f32 v[170:171], v[26:27], v[26:27], v[170:171]
	v_pk_fma_f32 v[172:173], v[28:29], v[28:29], v[172:173]
	v_cvt_pk_bf16_f32 v166, v26, v27
	v_cvt_pk_bf16_f32 v167, v28, v29
	global_store_dwordx2 v244, v[166:167], s[22:23] offset:3072
	ds_read_b128 v[214:217], v238 offset:8192
	ds_read_b128 v[218:221], v238 offset:40960
	s_waitcnt lgkmcnt(2)
	v_lshlrev_b32_e32 v162, 16, v144
	v_and_b32_e32 v163, 0xffff0000, v144
	v_lshlrev_b32_e32 v164, 16, v145
	v_and_b32_e32 v165, 0xffff0000, v145
	v_pk_mul_f32 v[162:163], v[162:163], v[252:253] op_sel_hi:[1,0]
	v_pk_mul_f32 v[164:165], v[164:165], v[252:253] op_sel_hi:[1,0]
	v_pk_mul_f32 v[162:163], v[162:163], v[226:227]
	v_pk_mul_f32 v[164:165], v[164:165], v[228:229]
	v_pk_fma_f32 v[30:31], v[230:231], v[162:163], v[30:31]
	v_pk_fma_f32 v[32:33], v[232:233], v[164:165], v[32:33]
	v_pk_fma_f32 v[170:171], v[30:31], v[30:31], v[170:171]
	v_pk_fma_f32 v[172:173], v[32:33], v[32:33], v[172:173]
	v_cvt_pk_bf16_f32 v168, v30, v31
	v_cvt_pk_bf16_f32 v169, v32, v33
	global_store_dwordx2 v244, v[168:169], s[22:23] offset:3584
	ds_read_b128 v[226:229], v238 offset:9216
	ds_read_b128 v[230:233], v238 offset:41984
	s_waitcnt lgkmcnt(2)
	v_lshlrev_b32_e32 v162, 16, v146
	v_and_b32_e32 v163, 0xffff0000, v146
	v_lshlrev_b32_e32 v164, 16, v147
	v_and_b32_e32 v165, 0xffff0000, v147
	v_pk_mul_f32 v[162:163], v[162:163], v[252:253] op_sel_hi:[1,0]
	v_pk_mul_f32 v[164:165], v[164:165], v[252:253] op_sel_hi:[1,0]
	v_pk_mul_f32 v[162:163], v[162:163], v[214:215]
	v_pk_mul_f32 v[164:165], v[164:165], v[216:217]
	v_pk_fma_f32 v[34:35], v[218:219], v[162:163], v[34:35]
	v_pk_fma_f32 v[36:37], v[220:221], v[164:165], v[36:37]
	v_pk_fma_f32 v[170:171], v[34:35], v[34:35], v[170:171]
	v_pk_fma_f32 v[172:173], v[36:37], v[36:37], v[172:173]
	v_cvt_pk_bf16_f32 v166, v34, v35
	v_cvt_pk_bf16_f32 v167, v36, v37
	global_store_dwordx2 v245, v[166:167], s[22:23] offset:0
	ds_read_b128 v[214:217], v238 offset:10240
	ds_read_b128 v[218:221], v238 offset:43008
	s_waitcnt lgkmcnt(2)
	v_lshlrev_b32_e32 v162, 16, v148
	v_and_b32_e32 v163, 0xffff0000, v148
	v_lshlrev_b32_e32 v164, 16, v149
	v_and_b32_e32 v165, 0xffff0000, v149
	v_pk_mul_f32 v[162:163], v[162:163], v[252:253] op_sel_hi:[1,0]
	v_pk_mul_f32 v[164:165], v[164:165], v[252:253] op_sel_hi:[1,0]
	v_pk_mul_f32 v[162:163], v[162:163], v[226:227]
	v_pk_mul_f32 v[164:165], v[164:165], v[228:229]
	v_pk_fma_f32 v[38:39], v[230:231], v[162:163], v[38:39]
	v_pk_fma_f32 v[40:41], v[232:233], v[164:165], v[40:41]
	v_pk_fma_f32 v[170:171], v[38:39], v[38:39], v[170:171]
	v_pk_fma_f32 v[172:173], v[40:41], v[40:41], v[172:173]
	v_cvt_pk_bf16_f32 v168, v38, v39
	v_cvt_pk_bf16_f32 v169, v40, v41
	global_store_dwordx2 v245, v[168:169], s[22:23] offset:512
	ds_read_b128 v[226:229], v238 offset:11264
	ds_read_b128 v[230:233], v238 offset:44032
	s_waitcnt lgkmcnt(2)
	v_lshlrev_b32_e32 v162, 16, v150
	v_and_b32_e32 v163, 0xffff0000, v150
	v_lshlrev_b32_e32 v164, 16, v151
	v_and_b32_e32 v165, 0xffff0000, v151
	v_pk_mul_f32 v[162:163], v[162:163], v[252:253] op_sel_hi:[1,0]
	v_pk_mul_f32 v[164:165], v[164:165], v[252:253] op_sel_hi:[1,0]
	v_pk_mul_f32 v[162:163], v[162:163], v[214:215]
	v_pk_mul_f32 v[164:165], v[164:165], v[216:217]
	v_pk_fma_f32 v[42:43], v[218:219], v[162:163], v[42:43]
	v_pk_fma_f32 v[44:45], v[220:221], v[164:165], v[44:45]
	v_pk_fma_f32 v[170:171], v[42:43], v[42:43], v[170:171]
	v_pk_fma_f32 v[172:173], v[44:45], v[44:45], v[172:173]
	v_cvt_pk_bf16_f32 v166, v42, v43
	v_cvt_pk_bf16_f32 v167, v44, v45
	global_store_dwordx2 v245, v[166:167], s[22:23] offset:1024
	ds_read_b128 v[214:217], v238 offset:12288
	ds_read_b128 v[218:221], v238 offset:45056
	s_waitcnt lgkmcnt(2)
	v_lshlrev_b32_e32 v162, 16, v152
	v_and_b32_e32 v163, 0xffff0000, v152
	v_lshlrev_b32_e32 v164, 16, v153
	v_and_b32_e32 v165, 0xffff0000, v153
	v_pk_mul_f32 v[162:163], v[162:163], v[252:253] op_sel_hi:[1,0]
	v_pk_mul_f32 v[164:165], v[164:165], v[252:253] op_sel_hi:[1,0]
	v_pk_mul_f32 v[162:163], v[162:163], v[226:227]
	v_pk_mul_f32 v[164:165], v[164:165], v[228:229]
	v_pk_fma_f32 v[46:47], v[230:231], v[162:163], v[46:47]
	v_pk_fma_f32 v[48:49], v[232:233], v[164:165], v[48:49]
	v_pk_fma_f32 v[170:171], v[46:47], v[46:47], v[170:171]
	v_pk_fma_f32 v[172:173], v[48:49], v[48:49], v[172:173]
	v_cvt_pk_bf16_f32 v168, v46, v47
	v_cvt_pk_bf16_f32 v169, v48, v49
	global_store_dwordx2 v245, v[168:169], s[22:23] offset:1536
	ds_read_b128 v[226:229], v238 offset:13312
	ds_read_b128 v[230:233], v238 offset:46080
	s_waitcnt lgkmcnt(2)
	v_lshlrev_b32_e32 v162, 16, v154
	v_and_b32_e32 v163, 0xffff0000, v154
	v_lshlrev_b32_e32 v164, 16, v155
	v_and_b32_e32 v165, 0xffff0000, v155
	v_pk_mul_f32 v[162:163], v[162:163], v[252:253] op_sel_hi:[1,0]
	v_pk_mul_f32 v[164:165], v[164:165], v[252:253] op_sel_hi:[1,0]
	v_pk_mul_f32 v[162:163], v[162:163], v[214:215]
	v_pk_mul_f32 v[164:165], v[164:165], v[216:217]
	v_pk_fma_f32 v[50:51], v[218:219], v[162:163], v[50:51]
	v_pk_fma_f32 v[52:53], v[220:221], v[164:165], v[52:53]
	v_pk_fma_f32 v[170:171], v[50:51], v[50:51], v[170:171]
	v_pk_fma_f32 v[172:173], v[52:53], v[52:53], v[172:173]
	v_cvt_pk_bf16_f32 v166, v50, v51
	v_cvt_pk_bf16_f32 v167, v52, v53
	global_store_dwordx2 v245, v[166:167], s[22:23] offset:2048
	ds_read_b128 v[214:217], v238 offset:14336
	ds_read_b128 v[218:221], v238 offset:47104
	s_waitcnt lgkmcnt(2)
	v_lshlrev_b32_e32 v162, 16, v156
	v_and_b32_e32 v163, 0xffff0000, v156
	v_lshlrev_b32_e32 v164, 16, v157
	v_and_b32_e32 v165, 0xffff0000, v157
	v_pk_mul_f32 v[162:163], v[162:163], v[252:253] op_sel_hi:[1,0]
	v_pk_mul_f32 v[164:165], v[164:165], v[252:253] op_sel_hi:[1,0]
	v_pk_mul_f32 v[162:163], v[162:163], v[226:227]
	v_pk_mul_f32 v[164:165], v[164:165], v[228:229]
	v_pk_fma_f32 v[54:55], v[230:231], v[162:163], v[54:55]
	v_pk_fma_f32 v[56:57], v[232:233], v[164:165], v[56:57]
	v_pk_fma_f32 v[170:171], v[54:55], v[54:55], v[170:171]
	v_pk_fma_f32 v[172:173], v[56:57], v[56:57], v[172:173]
	v_cvt_pk_bf16_f32 v168, v54, v55
	v_cvt_pk_bf16_f32 v169, v56, v57
	global_store_dwordx2 v245, v[168:169], s[22:23] offset:2560
	ds_read_b128 v[226:229], v238 offset:15360
	ds_read_b128 v[230:233], v238 offset:48128
	s_waitcnt lgkmcnt(2)
	v_lshlrev_b32_e32 v162, 16, v158
	v_and_b32_e32 v163, 0xffff0000, v158
	v_lshlrev_b32_e32 v164, 16, v159
	v_and_b32_e32 v165, 0xffff0000, v159
	v_pk_mul_f32 v[162:163], v[162:163], v[252:253] op_sel_hi:[1,0]
	v_pk_mul_f32 v[164:165], v[164:165], v[252:253] op_sel_hi:[1,0]
	v_pk_mul_f32 v[162:163], v[162:163], v[214:215]
	v_pk_mul_f32 v[164:165], v[164:165], v[216:217]
	v_pk_fma_f32 v[58:59], v[218:219], v[162:163], v[58:59]
	v_pk_fma_f32 v[60:61], v[220:221], v[164:165], v[60:61]
	v_pk_fma_f32 v[170:171], v[58:59], v[58:59], v[170:171]
	v_pk_fma_f32 v[172:173], v[60:61], v[60:61], v[172:173]
	v_cvt_pk_bf16_f32 v166, v58, v59
	v_cvt_pk_bf16_f32 v167, v60, v61
	global_store_dwordx2 v245, v[166:167], s[22:23] offset:3072
	s_waitcnt lgkmcnt(0)
	v_lshlrev_b32_e32 v162, 16, v160
	v_and_b32_e32 v163, 0xffff0000, v160
	v_lshlrev_b32_e32 v164, 16, v161
	v_and_b32_e32 v165, 0xffff0000, v161
	v_pk_mul_f32 v[162:163], v[162:163], v[252:253] op_sel_hi:[1,0]
	v_pk_mul_f32 v[164:165], v[164:165], v[252:253] op_sel_hi:[1,0]
	v_pk_mul_f32 v[162:163], v[162:163], v[226:227]
	v_pk_mul_f32 v[164:165], v[164:165], v[228:229]
	v_pk_fma_f32 v[62:63], v[230:231], v[162:163], v[62:63]
	v_pk_fma_f32 v[64:65], v[232:233], v[164:165], v[64:65]
	v_pk_fma_f32 v[170:171], v[62:63], v[62:63], v[170:171]
	v_pk_fma_f32 v[172:173], v[64:65], v[64:65], v[172:173]
	v_cvt_pk_bf16_f32 v168, v62, v63
	v_cvt_pk_bf16_f32 v169, v64, v65
	global_store_dwordx2 v245, v[168:169], s[22:23] offset:3584
	ds_read_b128 v[214:217], v238 offset:16384
	ds_read_b128 v[218:221], v238 offset:49152
	ds_read_b128 v[222:225], v239 offset:0
	v_pk_add_f32 v[170:171], v[170:171], v[172:173]
	s_nop 0
	v_add_f32_e32 v252, v170, v171
	s_waitcnt lgkmcnt(0)
	ds_bpermute_b32 v254, v246, v252
	s_waitcnt lgkmcnt(0)
	v_add_f32_e32 v252, v252, v254
	ds_bpermute_b32 v254, v247, v252
	s_waitcnt lgkmcnt(0)
	v_add_f32_e32 v252, v252, v254
	ds_bpermute_b32 v254, v248, v252
	s_waitcnt lgkmcnt(0)
	v_add_f32_e32 v252, v252, v254
	ds_bpermute_b32 v254, v249, v252
	s_waitcnt lgkmcnt(0)
	v_add_f32_e32 v252, v252, v254
	ds_bpermute_b32 v254, v250, v252
	s_waitcnt lgkmcnt(0)
	v_add_f32_e32 v252, v252, v254
	ds_bpermute_b32 v254, v251, v252
	s_waitcnt lgkmcnt(0)
	v_add_f32_e32 v252, v252, v254
	v_mov_b32_e32 v254, 0x358637bd
	v_fmac_f32_e32 v254, 0x39800000, v252
	v_mul_f32_e32 v252, 0x4b800000, v254
	v_cmp_gt_f32_e32 vcc, s32, v254
	s_nop 1
	v_cndmask_b32_e32 v254, v254, v252, vcc
	v_rsq_f32_e32 v254, v254
	s_nop 0
	v_mul_f32_e32 v252, 0x45800000, v254
	v_cndmask_b32_e32 v252, v254, v252, vcc
	s_add_u32 s16, s16, 0x1000000
	s_addc_u32 s17, s17, 0
	global_load_dwordx2 v[130:131], v244, s[16:17] offset:0
	global_load_dwordx2 v[132:133], v244, s[16:17] offset:512
	global_load_dwordx2 v[134:135], v244, s[16:17] offset:1024
	global_load_dwordx2 v[136:137], v244, s[16:17] offset:1536
	global_load_dwordx2 v[138:139], v244, s[16:17] offset:2048
	global_load_dwordx2 v[140:141], v244, s[16:17] offset:2560
	global_load_dwordx2 v[142:143], v244, s[16:17] offset:3072
	global_load_dwordx2 v[144:145], v244, s[16:17] offset:3584
	global_load_dwordx2 v[146:147], v245, s[16:17] offset:0
	global_load_dwordx2 v[148:149], v245, s[16:17] offset:512
	global_load_dwordx2 v[150:151], v245, s[16:17] offset:1024
	global_load_dwordx2 v[152:153], v245, s[16:17] offset:1536
	global_load_dwordx2 v[154:155], v245, s[16:17] offset:2048
	global_load_dwordx2 v[156:157], v245, s[16:17] offset:2560
	global_load_dwordx2 v[158:159], v245, s[16:17] offset:3072
	global_load_dwordx2 v[160:161], v245, s[16:17] offset:3584
	ds_read_b128 v[226:229], v238 offset:17408
	ds_read_b128 v[230:233], v238 offset:50176
	ds_read_b128 v[234:237], v239 offset:1024
	s_waitcnt lgkmcnt(3)
	v_pk_mul_f32 v[2:3], v[2:3], v[252:253] op_sel_hi:[1,0]
	v_pk_mul_f32 v[4:5], v[4:5], v[252:253] op_sel_hi:[1,0]
	v_pk_mul_f32 v[2:3], v[2:3], v[214:215]
	v_pk_mul_f32 v[4:5], v[4:5], v[216:217]
	v_pk_add_f32 v[222:223], v[222:223], 1.0 op_sel_hi:[1,0]
	v_pk_add_f32 v[224:225], v[224:225], 1.0 op_sel_hi:[1,0]
	v_pk_fma_f32 v[2:3], v[2:3], v[222:223], v[218:219]
	v_pk_fma_f32 v[4:5], v[4:5], v[224:225], v[220:221]
	s_nop 0
	v_cvt_pk_bf16_f32 v2, v2, v3
	v_cvt_pk_bf16_f32 v3, v4, v5
	global_store_dwordx2 v244, v[2:3], s[38:39] offset:0
	ds_read_b128 v[214:217], v238 offset:18432
	ds_read_b128 v[218:221], v238 offset:51200
	ds_read_b128 v[222:225], v239 offset:2048
	s_waitcnt lgkmcnt(3)
	v_pk_mul_f32 v[6:7], v[6:7], v[252:253] op_sel_hi:[1,0]
	v_pk_mul_f32 v[8:9], v[8:9], v[252:253] op_sel_hi:[1,0]
	v_pk_mul_f32 v[6:7], v[6:7], v[226:227]
	v_pk_mul_f32 v[8:9], v[8:9], v[228:229]
	v_pk_add_f32 v[234:235], v[234:235], 1.0 op_sel_hi:[1,0]
	v_pk_add_f32 v[236:237], v[236:237], 1.0 op_sel_hi:[1,0]
	v_pk_fma_f32 v[6:7], v[6:7], v[234:235], v[230:231]
	v_pk_fma_f32 v[8:9], v[8:9], v[236:237], v[232:233]
	s_nop 0
	v_cvt_pk_bf16_f32 v6, v6, v7
	v_cvt_pk_bf16_f32 v7, v8, v9
	global_store_dwordx2 v244, v[6:7], s[38:39] offset:512
	ds_read_b128 v[226:229], v238 offset:19456
	ds_read_b128 v[230:233], v238 offset:52224
	ds_read_b128 v[234:237], v239 offset:3072
	s_waitcnt lgkmcnt(3)
	v_pk_mul_f32 v[10:11], v[10:11], v[252:253] op_sel_hi:[1,0]
	v_pk_mul_f32 v[12:13], v[12:13], v[252:253] op_sel_hi:[1,0]
	v_pk_mul_f32 v[10:11], v[10:11], v[214:215]
	v_pk_mul_f32 v[12:13], v[12:13], v[216:217]
	v_pk_add_f32 v[222:223], v[222:223], 1.0 op_sel_hi:[1,0]
	v_pk_add_f32 v[224:225], v[224:225], 1.0 op_sel_hi:[1,0]
	v_pk_fma_f32 v[10:11], v[10:11], v[222:223], v[218:219]
	v_pk_fma_f32 v[12:13], v[12:13], v[224:225], v[220:221]
	s_nop 0
	v_cvt_pk_bf16_f32 v10, v10, v11
	v_cvt_pk_bf16_f32 v11, v12, v13
	global_store_dwordx2 v244, v[10:11], s[38:39] offset:1024
	ds_read_b128 v[214:217], v238 offset:20480
	ds_read_b128 v[218:221], v238 offset:53248
	ds_read_b128 v[222:225], v239 offset:4096
	s_waitcnt lgkmcnt(3)
	v_pk_mul_f32 v[14:15], v[14:15], v[252:253] op_sel_hi:[1,0]
	v_pk_mul_f32 v[16:17], v[16:17], v[252:253] op_sel_hi:[1,0]
	v_pk_mul_f32 v[14:15], v[14:15], v[226:227]
	v_pk_mul_f32 v[16:17], v[16:17], v[228:229]
	v_pk_add_f32 v[234:235], v[234:235], 1.0 op_sel_hi:[1,0]
	v_pk_add_f32 v[236:237], v[236:237], 1.0 op_sel_hi:[1,0]
	v_pk_fma_f32 v[14:15], v[14:15], v[234:235], v[230:231]
	v_pk_fma_f32 v[16:17], v[16:17], v[236:237], v[232:233]
	s_nop 0
	v_cvt_pk_bf16_f32 v14, v14, v15
	v_cvt_pk_bf16_f32 v15, v16, v17
	global_store_dwordx2 v244, v[14:15], s[38:39] offset:1536
	ds_read_b128 v[226:229], v238 offset:21504
	ds_read_b128 v[230:233], v238 offset:54272
	ds_read_b128 v[234:237], v239 offset:5120
	s_waitcnt lgkmcnt(3)
	v_pk_mul_f32 v[18:19], v[18:19], v[252:253] op_sel_hi:[1,0]
	v_pk_mul_f32 v[20:21], v[20:21], v[252:253] op_sel_hi:[1,0]
	v_pk_mul_f32 v[18:19], v[18:19], v[214:215]
	v_pk_mul_f32 v[20:21], v[20:21], v[216:217]
	v_pk_add_f32 v[222:223], v[222:223], 1.0 op_sel_hi:[1,0]
	v_pk_add_f32 v[224:225], v[224:225], 1.0 op_sel_hi:[1,0]
	v_pk_fma_f32 v[18:19], v[18:19], v[222:223], v[218:219]
	v_pk_fma_f32 v[20:21], v[20:21], v[224:225], v[220:221]
	s_nop 0
	v_cvt_pk_bf16_f32 v18, v18, v19
	v_cvt_pk_bf16_f32 v19, v20, v21
	global_store_dwordx2 v244, v[18:19], s[38:39] offset:2048
	ds_read_b128 v[214:217], v238 offset:22528
	ds_read_b128 v[218:221], v238 offset:55296
	ds_read_b128 v[222:225], v239 offset:6144
	s_waitcnt lgkmcnt(3)
	v_pk_mul_f32 v[22:23], v[22:23], v[252:253] op_sel_hi:[1,0]
	v_pk_mul_f32 v[24:25], v[24:25], v[252:253] op_sel_hi:[1,0]
	v_pk_mul_f32 v[22:23], v[22:23], v[226:227]
	v_pk_mul_f32 v[24:25], v[24:25], v[228:229]
	v_pk_add_f32 v[234:235], v[234:235], 1.0 op_sel_hi:[1,0]
	v_pk_add_f32 v[236:237], v[236:237], 1.0 op_sel_hi:[1,0]
	v_pk_fma_f32 v[22:23], v[22:23], v[234:235], v[230:231]
	v_pk_fma_f32 v[24:25], v[24:25], v[236:237], v[232:233]
	s_nop 0
	v_cvt_pk_bf16_f32 v22, v22, v23
	v_cvt_pk_bf16_f32 v23, v24, v25
	global_store_dwordx2 v244, v[22:23], s[38:39] offset:2560
	ds_read_b128 v[226:229], v238 offset:23552
	ds_read_b128 v[230:233], v238 offset:56320
	ds_read_b128 v[234:237], v239 offset:7168
	s_waitcnt lgkmcnt(3)
	v_pk_mul_f32 v[26:27], v[26:27], v[252:253] op_sel_hi:[1,0]
	v_pk_mul_f32 v[28:29], v[28:29], v[252:253] op_sel_hi:[1,0]
	v_pk_mul_f32 v[26:27], v[26:27], v[214:215]
	v_pk_mul_f32 v[28:29], v[28:29], v[216:217]
	v_pk_add_f32 v[222:223], v[222:223], 1.0 op_sel_hi:[1,0]
	v_pk_add_f32 v[224:225], v[224:225], 1.0 op_sel_hi:[1,0]
	v_pk_fma_f32 v[26:27], v[26:27], v[222:223], v[218:219]
	v_pk_fma_f32 v[28:29], v[28:29], v[224:225], v[220:221]
	s_nop 0
	v_cvt_pk_bf16_f32 v26, v26, v27
	v_cvt_pk_bf16_f32 v27, v28, v29
	global_store_dwordx2 v244, v[26:27], s[38:39] offset:3072
	ds_read_b128 v[214:217], v238 offset:24576
	ds_read_b128 v[218:221], v238 offset:57344
	ds_read_b128 v[222:225], v239 offset:8192
	s_waitcnt lgkmcnt(3)
	v_pk_mul_f32 v[30:31], v[30:31], v[252:253] op_sel_hi:[1,0]
	v_pk_mul_f32 v[32:33], v[32:33], v[252:253] op_sel_hi:[1,0]
	v_pk_mul_f32 v[30:31], v[30:31], v[226:227]
	v_pk_mul_f32 v[32:33], v[32:33], v[228:229]
	v_pk_add_f32 v[234:235], v[234:235], 1.0 op_sel_hi:[1,0]
	v_pk_add_f32 v[236:237], v[236:237], 1.0 op_sel_hi:[1,0]
	v_pk_fma_f32 v[30:31], v[30:31], v[234:235], v[230:231]
	v_pk_fma_f32 v[32:33], v[32:33], v[236:237], v[232:233]
	s_nop 0
	v_cvt_pk_bf16_f32 v30, v30, v31
	v_cvt_pk_bf16_f32 v31, v32, v33
	global_store_dwordx2 v244, v[30:31], s[38:39] offset:3584
	ds_read_b128 v[226:229], v238 offset:25600
	ds_read_b128 v[230:233], v238 offset:58368
	ds_read_b128 v[234:237], v239 offset:9216
	s_waitcnt lgkmcnt(3)
	v_pk_mul_f32 v[34:35], v[34:35], v[252:253] op_sel_hi:[1,0]
	v_pk_mul_f32 v[36:37], v[36:37], v[252:253] op_sel_hi:[1,0]
	v_pk_mul_f32 v[34:35], v[34:35], v[214:215]
	v_pk_mul_f32 v[36:37], v[36:37], v[216:217]
	v_pk_add_f32 v[222:223], v[222:223], 1.0 op_sel_hi:[1,0]
	v_pk_add_f32 v[224:225], v[224:225], 1.0 op_sel_hi:[1,0]
	v_pk_fma_f32 v[34:35], v[34:35], v[222:223], v[218:219]
	v_pk_fma_f32 v[36:37], v[36:37], v[224:225], v[220:221]
	s_nop 0
	v_cvt_pk_bf16_f32 v34, v34, v35
	v_cvt_pk_bf16_f32 v35, v36, v37
	global_store_dwordx2 v245, v[34:35], s[38:39] offset:0
	ds_read_b128 v[214:217], v238 offset:26624
	ds_read_b128 v[218:221], v238 offset:59392
	ds_read_b128 v[222:225], v239 offset:10240
	s_waitcnt lgkmcnt(3)
	v_pk_mul_f32 v[38:39], v[38:39], v[252:253] op_sel_hi:[1,0]
	v_pk_mul_f32 v[40:41], v[40:41], v[252:253] op_sel_hi:[1,0]
	v_pk_mul_f32 v[38:39], v[38:39], v[226:227]
	v_pk_mul_f32 v[40:41], v[40:41], v[228:229]
	v_pk_add_f32 v[234:235], v[234:235], 1.0 op_sel_hi:[1,0]
	v_pk_add_f32 v[236:237], v[236:237], 1.0 op_sel_hi:[1,0]
	v_pk_fma_f32 v[38:39], v[38:39], v[234:235], v[230:231]
	v_pk_fma_f32 v[40:41], v[40:41], v[236:237], v[232:233]
	s_nop 0
	v_cvt_pk_bf16_f32 v38, v38, v39
	v_cvt_pk_bf16_f32 v39, v40, v41
	global_store_dwordx2 v245, v[38:39], s[38:39] offset:512
	ds_read_b128 v[226:229], v238 offset:27648
	ds_read_b128 v[230:233], v238 offset:60416
	ds_read_b128 v[234:237], v239 offset:11264
	s_waitcnt lgkmcnt(3)
	v_pk_mul_f32 v[42:43], v[42:43], v[252:253] op_sel_hi:[1,0]
	v_pk_mul_f32 v[44:45], v[44:45], v[252:253] op_sel_hi:[1,0]
	v_pk_mul_f32 v[42:43], v[42:43], v[214:215]
	v_pk_mul_f32 v[44:45], v[44:45], v[216:217]
	v_pk_add_f32 v[222:223], v[222:223], 1.0 op_sel_hi:[1,0]
	v_pk_add_f32 v[224:225], v[224:225], 1.0 op_sel_hi:[1,0]
	v_pk_fma_f32 v[42:43], v[42:43], v[222:223], v[218:219]
	v_pk_fma_f32 v[44:45], v[44:45], v[224:225], v[220:221]
	s_nop 0
	v_cvt_pk_bf16_f32 v42, v42, v43
	v_cvt_pk_bf16_f32 v43, v44, v45
	global_store_dwordx2 v245, v[42:43], s[38:39] offset:1024
	ds_read_b128 v[214:217], v238 offset:28672
	ds_read_b128 v[218:221], v238 offset:61440
	ds_read_b128 v[222:225], v239 offset:12288
	s_waitcnt lgkmcnt(3)
	v_pk_mul_f32 v[46:47], v[46:47], v[252:253] op_sel_hi:[1,0]
	v_pk_mul_f32 v[48:49], v[48:49], v[252:253] op_sel_hi:[1,0]
	v_pk_mul_f32 v[46:47], v[46:47], v[226:227]
	v_pk_mul_f32 v[48:49], v[48:49], v[228:229]
	v_pk_add_f32 v[234:235], v[234:235], 1.0 op_sel_hi:[1,0]
	v_pk_add_f32 v[236:237], v[236:237], 1.0 op_sel_hi:[1,0]
	v_pk_fma_f32 v[46:47], v[46:47], v[234:235], v[230:231]
	v_pk_fma_f32 v[48:49], v[48:49], v[236:237], v[232:233]
	s_nop 0
	v_cvt_pk_bf16_f32 v46, v46, v47
	v_cvt_pk_bf16_f32 v47, v48, v49
	global_store_dwordx2 v245, v[46:47], s[38:39] offset:1536
	ds_read_b128 v[226:229], v238 offset:29696
	ds_read_b128 v[230:233], v238 offset:62464
	ds_read_b128 v[234:237], v239 offset:13312
	s_waitcnt lgkmcnt(3)
	v_pk_mul_f32 v[50:51], v[50:51], v[252:253] op_sel_hi:[1,0]
	v_pk_mul_f32 v[52:53], v[52:53], v[252:253] op_sel_hi:[1,0]
	v_pk_mul_f32 v[50:51], v[50:51], v[214:215]
	v_pk_mul_f32 v[52:53], v[52:53], v[216:217]
	v_pk_add_f32 v[222:223], v[222:223], 1.0 op_sel_hi:[1,0]
	v_pk_add_f32 v[224:225], v[224:225], 1.0 op_sel_hi:[1,0]
	v_pk_fma_f32 v[50:51], v[50:51], v[222:223], v[218:219]
	v_pk_fma_f32 v[52:53], v[52:53], v[224:225], v[220:221]
	s_nop 0
	v_cvt_pk_bf16_f32 v50, v50, v51
	v_cvt_pk_bf16_f32 v51, v52, v53
	global_store_dwordx2 v245, v[50:51], s[38:39] offset:2048
	ds_read_b128 v[214:217], v238 offset:30720
	ds_read_b128 v[218:221], v238 offset:63488
	ds_read_b128 v[222:225], v239 offset:14336
	s_waitcnt lgkmcnt(3)
	v_pk_mul_f32 v[54:55], v[54:55], v[252:253] op_sel_hi:[1,0]
	v_pk_mul_f32 v[56:57], v[56:57], v[252:253] op_sel_hi:[1,0]
	v_pk_mul_f32 v[54:55], v[54:55], v[226:227]
	v_pk_mul_f32 v[56:57], v[56:57], v[228:229]
	v_pk_add_f32 v[234:235], v[234:235], 1.0 op_sel_hi:[1,0]
	v_pk_add_f32 v[236:237], v[236:237], 1.0 op_sel_hi:[1,0]
	v_pk_fma_f32 v[54:55], v[54:55], v[234:235], v[230:231]
	v_pk_fma_f32 v[56:57], v[56:57], v[236:237], v[232:233]
	s_nop 0
	v_cvt_pk_bf16_f32 v54, v54, v55
	v_cvt_pk_bf16_f32 v55, v56, v57
	global_store_dwordx2 v245, v[54:55], s[38:39] offset:2560
	ds_read_b128 v[226:229], v238 offset:31744
	ds_read_b128 v[230:233], v238 offset:64512
	ds_read_b128 v[234:237], v239 offset:15360
	s_waitcnt lgkmcnt(3)
	v_pk_mul_f32 v[58:59], v[58:59], v[252:253] op_sel_hi:[1,0]
	v_pk_mul_f32 v[60:61], v[60:61], v[252:253] op_sel_hi:[1,0]
	v_pk_mul_f32 v[58:59], v[58:59], v[214:215]
	v_pk_mul_f32 v[60:61], v[60:61], v[216:217]
	v_pk_add_f32 v[222:223], v[222:223], 1.0 op_sel_hi:[1,0]
	v_pk_add_f32 v[224:225], v[224:225], 1.0 op_sel_hi:[1,0]
	v_pk_fma_f32 v[58:59], v[58:59], v[222:223], v[218:219]
	v_pk_fma_f32 v[60:61], v[60:61], v[224:225], v[220:221]
	s_nop 0
	v_cvt_pk_bf16_f32 v58, v58, v59
	v_cvt_pk_bf16_f32 v59, v60, v61
	global_store_dwordx2 v245, v[58:59], s[38:39] offset:3072
	s_waitcnt lgkmcnt(0)
	v_pk_mul_f32 v[62:63], v[62:63], v[252:253] op_sel_hi:[1,0]
	v_pk_mul_f32 v[64:65], v[64:65], v[252:253] op_sel_hi:[1,0]
	v_pk_mul_f32 v[62:63], v[62:63], v[226:227]
	v_pk_mul_f32 v[64:65], v[64:65], v[228:229]
	v_pk_add_f32 v[234:235], v[234:235], 1.0 op_sel_hi:[1,0]
	v_pk_add_f32 v[236:237], v[236:237], 1.0 op_sel_hi:[1,0]
	v_pk_fma_f32 v[62:63], v[62:63], v[234:235], v[230:231]
	v_pk_fma_f32 v[64:65], v[64:65], v[236:237], v[232:233]
	s_nop 0
	v_cvt_pk_bf16_f32 v62, v62, v63
	v_cvt_pk_bf16_f32 v63, v64, v65
	global_store_dwordx2 v245, v[62:63], s[38:39] offset:3584
	s_add_u32 s22, s22, 0x1000000
	s_addc_u32 s23, s23, 0
	s_add_u32 s38, s38, 0x1000000
	s_addc_u32 s39, s39, 0
	s_waitcnt vmcnt(16)
	global_load_dwordx4 v[2:5], v238, s[44:45] offset:0
	global_load_dwordx4 v[6:9], v238, s[44:45] offset:1024
	global_load_dwordx4 v[10:13], v238, s[44:45] offset:2048
	global_load_dwordx4 v[14:17], v238, s[44:45] offset:3072
	global_load_dwordx4 v[18:21], v241, s[44:45] offset:0
	global_load_dwordx4 v[22:25], v241, s[44:45] offset:1024
	global_load_dwordx4 v[26:29], v241, s[44:45] offset:2048
	global_load_dwordx4 v[30:33], v241, s[44:45] offset:3072
	global_load_dwordx4 v[34:37], v242, s[44:45] offset:0
	global_load_dwordx4 v[38:41], v242, s[44:45] offset:1024
	global_load_dwordx4 v[42:45], v242, s[44:45] offset:2048
	global_load_dwordx4 v[46:49], v242, s[44:45] offset:3072
	global_load_dwordx4 v[50:53], v243, s[44:45] offset:0
	global_load_dwordx4 v[54:57], v243, s[44:45] offset:1024
	global_load_dwordx4 v[58:61], v243, s[44:45] offset:2048
	global_load_dwordx4 v[62:65], v243, s[44:45] offset:3072
	ds_read_b128 v[214:217], v238 offset:0
	ds_read_b128 v[218:221], v238 offset:32768
	v_lshlrev_b32_e32 v162, 16, v130
	v_and_b32_e32 v163, 0xffff0000, v130
	v_lshlrev_b32_e32 v164, 16, v131
	v_and_b32_e32 v165, 0xffff0000, v131
	v_pk_mul_f32 v[170:171], v[162:163], v[162:163]
	v_pk_mul_f32 v[172:173], v[164:165], v[164:165]
	v_lshlrev_b32_e32 v166, 16, v132
	v_and_b32_e32 v167, 0xffff0000, v132
	v_lshlrev_b32_e32 v168, 16, v133
	v_and_b32_e32 v169, 0xffff0000, v133
	v_pk_fma_f32 v[170:171], v[166:167], v[166:167], v[170:171]
	v_pk_fma_f32 v[172:173], v[168:169], v[168:169], v[172:173]
	v_lshlrev_b32_e32 v162, 16, v134
	v_and_b32_e32 v163, 0xffff0000, v134
	v_lshlrev_b32_e32 v164, 16, v135
	v_and_b32_e32 v165, 0xffff0000, v135
	v_pk_fma_f32 v[170:171], v[162:163], v[162:163], v[170:171]
	v_pk_fma_f32 v[172:173], v[164:165], v[164:165], v[172:173]
	v_lshlrev_b32_e32 v166, 16, v136
	v_and_b32_e32 v167, 0xffff0000, v136
	v_lshlrev_b32_e32 v168, 16, v137
	v_and_b32_e32 v169, 0xffff0000, v137
	v_pk_fma_f32 v[170:171], v[166:167], v[166:167], v[170:171]
	v_pk_fma_f32 v[172:173], v[168:169], v[168:169], v[172:173]
	v_lshlrev_b32_e32 v162, 16, v138
	v_and_b32_e32 v163, 0xffff0000, v138
	v_lshlrev_b32_e32 v164, 16, v139
	v_and_b32_e32 v165, 0xffff0000, v139
	v_pk_fma_f32 v[170:171], v[162:163], v[162:163], v[170:171]
	v_pk_fma_f32 v[172:173], v[164:165], v[164:165], v[172:173]
	v_lshlrev_b32_e32 v166, 16, v140
	v_and_b32_e32 v167, 0xffff0000, v140
	v_lshlrev_b32_e32 v168, 16, v141
	v_and_b32_e32 v169, 0xffff0000, v141
	v_pk_fma_f32 v[170:171], v[166:167], v[166:167], v[170:171]
	v_pk_fma_f32 v[172:173], v[168:169], v[168:169], v[172:173]
	v_lshlrev_b32_e32 v162, 16, v142
	v_and_b32_e32 v163, 0xffff0000, v142
	v_lshlrev_b32_e32 v164, 16, v143
	v_and_b32_e32 v165, 0xffff0000, v143
	v_pk_fma_f32 v[170:171], v[162:163], v[162:163], v[170:171]
	v_pk_fma_f32 v[172:173], v[164:165], v[164:165], v[172:173]
	v_lshlrev_b32_e32 v166, 16, v144
	v_and_b32_e32 v167, 0xffff0000, v144
	v_lshlrev_b32_e32 v168, 16, v145
	v_and_b32_e32 v169, 0xffff0000, v145
	v_pk_fma_f32 v[170:171], v[166:167], v[166:167], v[170:171]
	v_pk_fma_f32 v[172:173], v[168:169], v[168:169], v[172:173]
	v_lshlrev_b32_e32 v162, 16, v146
	v_and_b32_e32 v163, 0xffff0000, v146
	v_lshlrev_b32_e32 v164, 16, v147
	v_and_b32_e32 v165, 0xffff0000, v147
	v_pk_fma_f32 v[170:171], v[162:163], v[162:163], v[170:171]
	v_pk_fma_f32 v[172:173], v[164:165], v[164:165], v[172:173]
	v_lshlrev_b32_e32 v166, 16, v148
	v_and_b32_e32 v167, 0xffff0000, v148
	v_lshlrev_b32_e32 v168, 16, v149
	v_and_b32_e32 v169, 0xffff0000, v149
	v_pk_fma_f32 v[170:171], v[166:167], v[166:167], v[170:171]
	v_pk_fma_f32 v[172:173], v[168:169], v[168:169], v[172:173]
	v_lshlrev_b32_e32 v162, 16, v150
	v_and_b32_e32 v163, 0xffff0000, v150
	v_lshlrev_b32_e32 v164, 16, v151
	v_and_b32_e32 v165, 0xffff0000, v151
	v_pk_fma_f32 v[170:171], v[162:163], v[162:163], v[170:171]
	v_pk_fma_f32 v[172:173], v[164:165], v[164:165], v[172:173]
	v_lshlrev_b32_e32 v166, 16, v152
	v_and_b32_e32 v167, 0xffff0000, v152
	v_lshlrev_b32_e32 v168, 16, v153
	v_and_b32_e32 v169, 0xffff0000, v153
	v_pk_fma_f32 v[170:171], v[166:167], v[166:167], v[170:171]
	v_pk_fma_f32 v[172:173], v[168:169], v[168:169], v[172:173]
	v_lshlrev_b32_e32 v162, 16, v154
	v_and_b32_e32 v163, 0xffff0000, v154
	v_lshlrev_b32_e32 v164, 16, v155
	v_and_b32_e32 v165, 0xffff0000, v155
	v_pk_fma_f32 v[170:171], v[162:163], v[162:163], v[170:171]
	v_pk_fma_f32 v[172:173], v[164:165], v[164:165], v[172:173]
	v_lshlrev_b32_e32 v166, 16, v156
	v_and_b32_e32 v167, 0xffff0000, v156
	v_lshlrev_b32_e32 v168, 16, v157
	v_and_b32_e32 v169, 0xffff0000, v157
	v_pk_fma_f32 v[170:171], v[166:167], v[166:167], v[170:171]
	v_pk_fma_f32 v[172:173], v[168:169], v[168:169], v[172:173]
	v_lshlrev_b32_e32 v162, 16, v158
	v_and_b32_e32 v163, 0xffff0000, v158
	v_lshlrev_b32_e32 v164, 16, v159
	v_and_b32_e32 v165, 0xffff0000, v159
	v_pk_fma_f32 v[170:171], v[162:163], v[162:163], v[170:171]
	v_pk_fma_f32 v[172:173], v[164:165], v[164:165], v[172:173]
	v_lshlrev_b32_e32 v166, 16, v160
	v_and_b32_e32 v167, 0xffff0000, v160
	v_lshlrev_b32_e32 v168, 16, v161
	v_and_b32_e32 v169, 0xffff0000, v161
	v_pk_fma_f32 v[170:171], v[166:167], v[166:167], v[170:171]
	v_pk_fma_f32 v[172:173], v[168:169], v[168:169], v[172:173]
	v_pk_add_f32 v[170:171], v[170:171], v[172:173]
	s_nop 0
	v_add_f32_e32 v252, v170, v171
	s_waitcnt lgkmcnt(0)
	ds_bpermute_b32 v254, v246, v252
	s_waitcnt lgkmcnt(0)
	v_add_f32_e32 v252, v252, v254
	ds_bpermute_b32 v254, v247, v252
	s_waitcnt lgkmcnt(0)
	v_add_f32_e32 v252, v252, v254
	ds_bpermute_b32 v254, v248, v252
	s_waitcnt lgkmcnt(0)
	v_add_f32_e32 v252, v252, v254
	ds_bpermute_b32 v254, v249, v252
	s_waitcnt lgkmcnt(0)
	v_add_f32_e32 v252, v252, v254
	ds_bpermute_b32 v254, v250, v252
	s_waitcnt lgkmcnt(0)
	v_add_f32_e32 v252, v252, v254
	ds_bpermute_b32 v254, v251, v252
	s_waitcnt lgkmcnt(0)
	v_add_f32_e32 v252, v252, v254
	v_mov_b32_e32 v254, 0x358637bd
	v_fmac_f32_e32 v254, 0x39800000, v252
	v_mul_f32_e32 v252, 0x4b800000, v254
	v_cmp_gt_f32_e32 vcc, s32, v254
	s_nop 1
	v_cndmask_b32_e32 v254, v254, v252, vcc
	v_rsq_f32_e32 v254, v254
	s_nop 0
	v_mul_f32_e32 v252, 0x45800000, v254
	v_cndmask_b32_e32 v252, v254, v252, vcc
	ds_read_b128 v[226:229], v238 offset:1024
	ds_read_b128 v[230:233], v238 offset:33792
	s_waitcnt lgkmcnt(2)
	v_lshlrev_b32_e32 v162, 16, v130
	v_and_b32_e32 v163, 0xffff0000, v130
	v_lshlrev_b32_e32 v164, 16, v131
	v_and_b32_e32 v165, 0xffff0000, v131
	v_pk_mul_f32 v[162:163], v[162:163], v[252:253] op_sel_hi:[1,0]
	v_pk_mul_f32 v[164:165], v[164:165], v[252:253] op_sel_hi:[1,0]
	v_pk_mul_f32 v[162:163], v[162:163], v[214:215]
	v_pk_mul_f32 v[164:165], v[164:165], v[216:217]
	v_pk_fma_f32 v[66:67], v[218:219], v[162:163], v[66:67]
	v_pk_fma_f32 v[68:69], v[220:221], v[164:165], v[68:69]
	v_pk_mul_f32 v[170:171], v[66:67], v[66:67]
	v_pk_mul_f32 v[172:173], v[68:69], v[68:69]
	v_cvt_pk_bf16_f32 v166, v66, v67
	v_cvt_pk_bf16_f32 v167, v68, v69
	global_store_dwordx2 v244, v[166:167], s[22:23] offset:0
	ds_read_b128 v[214:217], v238 offset:2048
	ds_read_b128 v[218:221], v238 offset:34816
	s_waitcnt lgkmcnt(2)
	v_lshlrev_b32_e32 v162, 16, v132
	v_and_b32_e32 v163, 0xffff0000, v132
	v_lshlrev_b32_e32 v164, 16, v133
	v_and_b32_e32 v165, 0xffff0000, v133
	v_pk_mul_f32 v[162:163], v[162:163], v[252:253] op_sel_hi:[1,0]
	v_pk_mul_f32 v[164:165], v[164:165], v[252:253] op_sel_hi:[1,0]
	v_pk_mul_f32 v[162:163], v[162:163], v[226:227]
	v_pk_mul_f32 v[164:165], v[164:165], v[228:229]
	v_pk_fma_f32 v[70:71], v[230:231], v[162:163], v[70:71]
	v_pk_fma_f32 v[72:73], v[232:233], v[164:165], v[72:73]
	v_pk_fma_f32 v[170:171], v[70:71], v[70:71], v[170:171]
	v_pk_fma_f32 v[172:173], v[72:73], v[72:73], v[172:173]
	v_cvt_pk_bf16_f32 v168, v70, v71
	v_cvt_pk_bf16_f32 v169, v72, v73
	global_store_dwordx2 v244, v[168:169], s[22:23] offset:512
	ds_read_b128 v[226:229], v238 offset:3072
	ds_read_b128 v[230:233], v238 offset:35840
	s_waitcnt lgkmcnt(2)
	v_lshlrev_b32_e32 v162, 16, v134
	v_and_b32_e32 v163, 0xffff0000, v134
	v_lshlrev_b32_e32 v164, 16, v135
	v_and_b32_e32 v165, 0xffff0000, v135
	v_pk_mul_f32 v[162:163], v[162:163], v[252:253] op_sel_hi:[1,0]
	v_pk_mul_f32 v[164:165], v[164:165], v[252:253] op_sel_hi:[1,0]
	v_pk_mul_f32 v[162:163], v[162:163], v[214:215]
	v_pk_mul_f32 v[164:165], v[164:165], v[216:217]
	v_pk_fma_f32 v[74:75], v[218:219], v[162:163], v[74:75]
	v_pk_fma_f32 v[76:77], v[220:221], v[164:165], v[76:77]
	v_pk_fma_f32 v[170:171], v[74:75], v[74:75], v[170:171]
	v_pk_fma_f32 v[172:173], v[76:77], v[76:77], v[172:173]
	v_cvt_pk_bf16_f32 v166, v74, v75
	v_cvt_pk_bf16_f32 v167, v76, v77
	global_store_dwordx2 v244, v[166:167], s[22:23] offset:1024
	ds_read_b128 v[214:217], v238 offset:4096
	ds_read_b128 v[218:221], v238 offset:36864
	s_waitcnt lgkmcnt(2)
	v_lshlrev_b32_e32 v162, 16, v136
	v_and_b32_e32 v163, 0xffff0000, v136
	v_lshlrev_b32_e32 v164, 16, v137
	v_and_b32_e32 v165, 0xffff0000, v137
	v_pk_mul_f32 v[162:163], v[162:163], v[252:253] op_sel_hi:[1,0]
	v_pk_mul_f32 v[164:165], v[164:165], v[252:253] op_sel_hi:[1,0]
	v_pk_mul_f32 v[162:163], v[162:163], v[226:227]
	v_pk_mul_f32 v[164:165], v[164:165], v[228:229]
	v_pk_fma_f32 v[78:79], v[230:231], v[162:163], v[78:79]
	v_pk_fma_f32 v[80:81], v[232:233], v[164:165], v[80:81]
	v_pk_fma_f32 v[170:171], v[78:79], v[78:79], v[170:171]
	v_pk_fma_f32 v[172:173], v[80:81], v[80:81], v[172:173]
	v_cvt_pk_bf16_f32 v168, v78, v79
	v_cvt_pk_bf16_f32 v169, v80, v81
	global_store_dwordx2 v244, v[168:169], s[22:23] offset:1536
	ds_read_b128 v[226:229], v238 offset:5120
	ds_read_b128 v[230:233], v238 offset:37888
	s_waitcnt lgkmcnt(2)
	v_lshlrev_b32_e32 v162, 16, v138
	v_and_b32_e32 v163, 0xffff0000, v138
	v_lshlrev_b32_e32 v164, 16, v139
	v_and_b32_e32 v165, 0xffff0000, v139
	v_pk_mul_f32 v[162:163], v[162:163], v[252:253] op_sel_hi:[1,0]
	v_pk_mul_f32 v[164:165], v[164:165], v[252:253] op_sel_hi:[1,0]
	v_pk_mul_f32 v[162:163], v[162:163], v[214:215]
	v_pk_mul_f32 v[164:165], v[164:165], v[216:217]
	v_pk_fma_f32 v[82:83], v[218:219], v[162:163], v[82:83]
	v_pk_fma_f32 v[84:85], v[220:221], v[164:165], v[84:85]
	v_pk_fma_f32 v[170:171], v[82:83], v[82:83], v[170:171]
	v_pk_fma_f32 v[172:173], v[84:85], v[84:85], v[172:173]
	v_cvt_pk_bf16_f32 v166, v82, v83
	v_cvt_pk_bf16_f32 v167, v84, v85
	global_store_dwordx2 v244, v[166:167], s[22:23] offset:2048
	ds_read_b128 v[214:217], v238 offset:6144
	ds_read_b128 v[218:221], v238 offset:38912
	s_waitcnt lgkmcnt(2)
	v_lshlrev_b32_e32 v162, 16, v140
	v_and_b32_e32 v163, 0xffff0000, v140
	v_lshlrev_b32_e32 v164, 16, v141
	v_and_b32_e32 v165, 0xffff0000, v141
	v_pk_mul_f32 v[162:163], v[162:163], v[252:253] op_sel_hi:[1,0]
	v_pk_mul_f32 v[164:165], v[164:165], v[252:253] op_sel_hi:[1,0]
	v_pk_mul_f32 v[162:163], v[162:163], v[226:227]
	v_pk_mul_f32 v[164:165], v[164:165], v[228:229]
	v_pk_fma_f32 v[86:87], v[230:231], v[162:163], v[86:87]
	v_pk_fma_f32 v[88:89], v[232:233], v[164:165], v[88:89]
	v_pk_fma_f32 v[170:171], v[86:87], v[86:87], v[170:171]
	v_pk_fma_f32 v[172:173], v[88:89], v[88:89], v[172:173]
	v_cvt_pk_bf16_f32 v168, v86, v87
	v_cvt_pk_bf16_f32 v169, v88, v89
	global_store_dwordx2 v244, v[168:169], s[22:23] offset:2560
	ds_read_b128 v[226:229], v238 offset:7168
	ds_read_b128 v[230:233], v238 offset:39936
	s_waitcnt lgkmcnt(2)
	v_lshlrev_b32_e32 v162, 16, v142
	v_and_b32_e32 v163, 0xffff0000, v142
	v_lshlrev_b32_e32 v164, 16, v143
	v_and_b32_e32 v165, 0xffff0000, v143
	v_pk_mul_f32 v[162:163], v[162:163], v[252:253] op_sel_hi:[1,0]
	v_pk_mul_f32 v[164:165], v[164:165], v[252:253] op_sel_hi:[1,0]
	v_pk_mul_f32 v[162:163], v[162:163], v[214:215]
	v_pk_mul_f32 v[164:165], v[164:165], v[216:217]
	v_pk_fma_f32 v[90:91], v[218:219], v[162:163], v[90:91]
	v_pk_fma_f32 v[92:93], v[220:221], v[164:165], v[92:93]
	v_pk_fma_f32 v[170:171], v[90:91], v[90:91], v[170:171]
	v_pk_fma_f32 v[172:173], v[92:93], v[92:93], v[172:173]
	v_cvt_pk_bf16_f32 v166, v90, v91
	v_cvt_pk_bf16_f32 v167, v92, v93
	global_store_dwordx2 v244, v[166:167], s[22:23] offset:3072
	ds_read_b128 v[214:217], v238 offset:8192
	ds_read_b128 v[218:221], v238 offset:40960
	s_waitcnt lgkmcnt(2)
	v_lshlrev_b32_e32 v162, 16, v144
	v_and_b32_e32 v163, 0xffff0000, v144
	v_lshlrev_b32_e32 v164, 16, v145
	v_and_b32_e32 v165, 0xffff0000, v145
	v_pk_mul_f32 v[162:163], v[162:163], v[252:253] op_sel_hi:[1,0]
	v_pk_mul_f32 v[164:165], v[164:165], v[252:253] op_sel_hi:[1,0]
	v_pk_mul_f32 v[162:163], v[162:163], v[226:227]
	v_pk_mul_f32 v[164:165], v[164:165], v[228:229]
	v_pk_fma_f32 v[94:95], v[230:231], v[162:163], v[94:95]
	v_pk_fma_f32 v[96:97], v[232:233], v[164:165], v[96:97]
	v_pk_fma_f32 v[170:171], v[94:95], v[94:95], v[170:171]
	v_pk_fma_f32 v[172:173], v[96:97], v[96:97], v[172:173]
	v_cvt_pk_bf16_f32 v168, v94, v95
	v_cvt_pk_bf16_f32 v169, v96, v97
	global_store_dwordx2 v244, v[168:169], s[22:23] offset:3584
	ds_read_b128 v[226:229], v238 offset:9216
	ds_read_b128 v[230:233], v238 offset:41984
	s_waitcnt lgkmcnt(2)
	v_lshlrev_b32_e32 v162, 16, v146
	v_and_b32_e32 v163, 0xffff0000, v146
	v_lshlrev_b32_e32 v164, 16, v147
	v_and_b32_e32 v165, 0xffff0000, v147
	v_pk_mul_f32 v[162:163], v[162:163], v[252:253] op_sel_hi:[1,0]
	v_pk_mul_f32 v[164:165], v[164:165], v[252:253] op_sel_hi:[1,0]
	v_pk_mul_f32 v[162:163], v[162:163], v[214:215]
	v_pk_mul_f32 v[164:165], v[164:165], v[216:217]
	v_pk_fma_f32 v[98:99], v[218:219], v[162:163], v[98:99]
	v_pk_fma_f32 v[100:101], v[220:221], v[164:165], v[100:101]
	v_pk_fma_f32 v[170:171], v[98:99], v[98:99], v[170:171]
	v_pk_fma_f32 v[172:173], v[100:101], v[100:101], v[172:173]
	v_cvt_pk_bf16_f32 v166, v98, v99
	v_cvt_pk_bf16_f32 v167, v100, v101
	global_store_dwordx2 v245, v[166:167], s[22:23] offset:0
	ds_read_b128 v[214:217], v238 offset:10240
	ds_read_b128 v[218:221], v238 offset:43008
	s_waitcnt lgkmcnt(2)
	v_lshlrev_b32_e32 v162, 16, v148
	v_and_b32_e32 v163, 0xffff0000, v148
	v_lshlrev_b32_e32 v164, 16, v149
	v_and_b32_e32 v165, 0xffff0000, v149
	v_pk_mul_f32 v[162:163], v[162:163], v[252:253] op_sel_hi:[1,0]
	v_pk_mul_f32 v[164:165], v[164:165], v[252:253] op_sel_hi:[1,0]
	v_pk_mul_f32 v[162:163], v[162:163], v[226:227]
	v_pk_mul_f32 v[164:165], v[164:165], v[228:229]
	v_pk_fma_f32 v[102:103], v[230:231], v[162:163], v[102:103]
	v_pk_fma_f32 v[104:105], v[232:233], v[164:165], v[104:105]
	v_pk_fma_f32 v[170:171], v[102:103], v[102:103], v[170:171]
	v_pk_fma_f32 v[172:173], v[104:105], v[104:105], v[172:173]
	v_cvt_pk_bf16_f32 v168, v102, v103
	v_cvt_pk_bf16_f32 v169, v104, v105
	global_store_dwordx2 v245, v[168:169], s[22:23] offset:512
	ds_read_b128 v[226:229], v238 offset:11264
	ds_read_b128 v[230:233], v238 offset:44032
	s_waitcnt lgkmcnt(2)
	v_lshlrev_b32_e32 v162, 16, v150
	v_and_b32_e32 v163, 0xffff0000, v150
	v_lshlrev_b32_e32 v164, 16, v151
	v_and_b32_e32 v165, 0xffff0000, v151
	v_pk_mul_f32 v[162:163], v[162:163], v[252:253] op_sel_hi:[1,0]
	v_pk_mul_f32 v[164:165], v[164:165], v[252:253] op_sel_hi:[1,0]
	v_pk_mul_f32 v[162:163], v[162:163], v[214:215]
	v_pk_mul_f32 v[164:165], v[164:165], v[216:217]
	v_pk_fma_f32 v[106:107], v[218:219], v[162:163], v[106:107]
	v_pk_fma_f32 v[108:109], v[220:221], v[164:165], v[108:109]
	v_pk_fma_f32 v[170:171], v[106:107], v[106:107], v[170:171]
	v_pk_fma_f32 v[172:173], v[108:109], v[108:109], v[172:173]
	v_cvt_pk_bf16_f32 v166, v106, v107
	v_cvt_pk_bf16_f32 v167, v108, v109
	global_store_dwordx2 v245, v[166:167], s[22:23] offset:1024
	ds_read_b128 v[214:217], v238 offset:12288
	ds_read_b128 v[218:221], v238 offset:45056
	s_waitcnt lgkmcnt(2)
	v_lshlrev_b32_e32 v162, 16, v152
	v_and_b32_e32 v163, 0xffff0000, v152
	v_lshlrev_b32_e32 v164, 16, v153
	v_and_b32_e32 v165, 0xffff0000, v153
	v_pk_mul_f32 v[162:163], v[162:163], v[252:253] op_sel_hi:[1,0]
	v_pk_mul_f32 v[164:165], v[164:165], v[252:253] op_sel_hi:[1,0]
	v_pk_mul_f32 v[162:163], v[162:163], v[226:227]
	v_pk_mul_f32 v[164:165], v[164:165], v[228:229]
	v_pk_fma_f32 v[110:111], v[230:231], v[162:163], v[110:111]
	v_pk_fma_f32 v[112:113], v[232:233], v[164:165], v[112:113]
	v_pk_fma_f32 v[170:171], v[110:111], v[110:111], v[170:171]
	v_pk_fma_f32 v[172:173], v[112:113], v[112:113], v[172:173]
	v_cvt_pk_bf16_f32 v168, v110, v111
	v_cvt_pk_bf16_f32 v169, v112, v113
	global_store_dwordx2 v245, v[168:169], s[22:23] offset:1536
	ds_read_b128 v[226:229], v238 offset:13312
	ds_read_b128 v[230:233], v238 offset:46080
	s_waitcnt lgkmcnt(2)
	v_lshlrev_b32_e32 v162, 16, v154
	v_and_b32_e32 v163, 0xffff0000, v154
	v_lshlrev_b32_e32 v164, 16, v155
	v_and_b32_e32 v165, 0xffff0000, v155
	v_pk_mul_f32 v[162:163], v[162:163], v[252:253] op_sel_hi:[1,0]
	v_pk_mul_f32 v[164:165], v[164:165], v[252:253] op_sel_hi:[1,0]
	v_pk_mul_f32 v[162:163], v[162:163], v[214:215]
	v_pk_mul_f32 v[164:165], v[164:165], v[216:217]
	v_pk_fma_f32 v[114:115], v[218:219], v[162:163], v[114:115]
	v_pk_fma_f32 v[116:117], v[220:221], v[164:165], v[116:117]
	v_pk_fma_f32 v[170:171], v[114:115], v[114:115], v[170:171]
	v_pk_fma_f32 v[172:173], v[116:117], v[116:117], v[172:173]
	v_cvt_pk_bf16_f32 v166, v114, v115
	v_cvt_pk_bf16_f32 v167, v116, v117
	global_store_dwordx2 v245, v[166:167], s[22:23] offset:2048
	ds_read_b128 v[214:217], v238 offset:14336
	ds_read_b128 v[218:221], v238 offset:47104
	s_waitcnt lgkmcnt(2)
	v_lshlrev_b32_e32 v162, 16, v156
	v_and_b32_e32 v163, 0xffff0000, v156
	v_lshlrev_b32_e32 v164, 16, v157
	v_and_b32_e32 v165, 0xffff0000, v157
	v_pk_mul_f32 v[162:163], v[162:163], v[252:253] op_sel_hi:[1,0]
	v_pk_mul_f32 v[164:165], v[164:165], v[252:253] op_sel_hi:[1,0]
	v_pk_mul_f32 v[162:163], v[162:163], v[226:227]
	v_pk_mul_f32 v[164:165], v[164:165], v[228:229]
	v_pk_fma_f32 v[118:119], v[230:231], v[162:163], v[118:119]
	v_pk_fma_f32 v[120:121], v[232:233], v[164:165], v[120:121]
	v_pk_fma_f32 v[170:171], v[118:119], v[118:119], v[170:171]
	v_pk_fma_f32 v[172:173], v[120:121], v[120:121], v[172:173]
	v_cvt_pk_bf16_f32 v168, v118, v119
	v_cvt_pk_bf16_f32 v169, v120, v121
	global_store_dwordx2 v245, v[168:169], s[22:23] offset:2560
	ds_read_b128 v[226:229], v238 offset:15360
	ds_read_b128 v[230:233], v238 offset:48128
	s_waitcnt lgkmcnt(2)
	v_lshlrev_b32_e32 v162, 16, v158
	v_and_b32_e32 v163, 0xffff0000, v158
	v_lshlrev_b32_e32 v164, 16, v159
	v_and_b32_e32 v165, 0xffff0000, v159
	v_pk_mul_f32 v[162:163], v[162:163], v[252:253] op_sel_hi:[1,0]
	v_pk_mul_f32 v[164:165], v[164:165], v[252:253] op_sel_hi:[1,0]
	v_pk_mul_f32 v[162:163], v[162:163], v[214:215]
	v_pk_mul_f32 v[164:165], v[164:165], v[216:217]
	v_pk_fma_f32 v[122:123], v[218:219], v[162:163], v[122:123]
	v_pk_fma_f32 v[124:125], v[220:221], v[164:165], v[124:125]
	v_pk_fma_f32 v[170:171], v[122:123], v[122:123], v[170:171]
	v_pk_fma_f32 v[172:173], v[124:125], v[124:125], v[172:173]
	v_cvt_pk_bf16_f32 v166, v122, v123
	v_cvt_pk_bf16_f32 v167, v124, v125
	global_store_dwordx2 v245, v[166:167], s[22:23] offset:3072
	s_waitcnt lgkmcnt(0)
	v_lshlrev_b32_e32 v162, 16, v160
	v_and_b32_e32 v163, 0xffff0000, v160
	v_lshlrev_b32_e32 v164, 16, v161
	v_and_b32_e32 v165, 0xffff0000, v161
	v_pk_mul_f32 v[162:163], v[162:163], v[252:253] op_sel_hi:[1,0]
	v_pk_mul_f32 v[164:165], v[164:165], v[252:253] op_sel_hi:[1,0]
	v_pk_mul_f32 v[162:163], v[162:163], v[226:227]
	v_pk_mul_f32 v[164:165], v[164:165], v[228:229]
	v_pk_fma_f32 v[126:127], v[230:231], v[162:163], v[126:127]
	v_pk_fma_f32 v[128:129], v[232:233], v[164:165], v[128:129]
	v_pk_fma_f32 v[170:171], v[126:127], v[126:127], v[170:171]
	v_pk_fma_f32 v[172:173], v[128:129], v[128:129], v[172:173]
	v_cvt_pk_bf16_f32 v168, v126, v127
	v_cvt_pk_bf16_f32 v169, v128, v129
	global_store_dwordx2 v245, v[168:169], s[22:23] offset:3584
	ds_read_b128 v[214:217], v238 offset:16384
	ds_read_b128 v[218:221], v238 offset:49152
	ds_read_b128 v[222:225], v239 offset:0
	v_pk_add_f32 v[170:171], v[170:171], v[172:173]
	s_nop 0
	v_add_f32_e32 v252, v170, v171
	s_waitcnt lgkmcnt(0)
	ds_bpermute_b32 v254, v246, v252
	s_waitcnt lgkmcnt(0)
	v_add_f32_e32 v252, v252, v254
	ds_bpermute_b32 v254, v247, v252
	s_waitcnt lgkmcnt(0)
	v_add_f32_e32 v252, v252, v254
	ds_bpermute_b32 v254, v248, v252
	s_waitcnt lgkmcnt(0)
	v_add_f32_e32 v252, v252, v254
	ds_bpermute_b32 v254, v249, v252
	s_waitcnt lgkmcnt(0)
	v_add_f32_e32 v252, v252, v254
	ds_bpermute_b32 v254, v250, v252
	s_waitcnt lgkmcnt(0)
	v_add_f32_e32 v252, v252, v254
	ds_bpermute_b32 v254, v251, v252
	s_waitcnt lgkmcnt(0)
	v_add_f32_e32 v252, v252, v254
	v_mov_b32_e32 v254, 0x358637bd
	v_fmac_f32_e32 v254, 0x39800000, v252
	v_mul_f32_e32 v252, 0x4b800000, v254
	v_cmp_gt_f32_e32 vcc, s32, v254
	s_nop 1
	v_cndmask_b32_e32 v254, v254, v252, vcc
	v_rsq_f32_e32 v254, v254
	s_nop 0
	v_mul_f32_e32 v252, 0x45800000, v254
	v_cndmask_b32_e32 v252, v254, v252, vcc
	s_add_u32 s16, s16, 0x1000000
	s_addc_u32 s17, s17, 0
	global_load_dwordx2 v[130:131], v244, s[16:17] offset:0
	global_load_dwordx2 v[132:133], v244, s[16:17] offset:512
	global_load_dwordx2 v[134:135], v244, s[16:17] offset:1024
	global_load_dwordx2 v[136:137], v244, s[16:17] offset:1536
	global_load_dwordx2 v[138:139], v244, s[16:17] offset:2048
	global_load_dwordx2 v[140:141], v244, s[16:17] offset:2560
	global_load_dwordx2 v[142:143], v244, s[16:17] offset:3072
	global_load_dwordx2 v[144:145], v244, s[16:17] offset:3584
	global_load_dwordx2 v[146:147], v245, s[16:17] offset:0
	global_load_dwordx2 v[148:149], v245, s[16:17] offset:512
	global_load_dwordx2 v[150:151], v245, s[16:17] offset:1024
	global_load_dwordx2 v[152:153], v245, s[16:17] offset:1536
	global_load_dwordx2 v[154:155], v245, s[16:17] offset:2048
	global_load_dwordx2 v[156:157], v245, s[16:17] offset:2560
	global_load_dwordx2 v[158:159], v245, s[16:17] offset:3072
	global_load_dwordx2 v[160:161], v245, s[16:17] offset:3584
	ds_read_b128 v[226:229], v238 offset:17408
	ds_read_b128 v[230:233], v238 offset:50176
	ds_read_b128 v[234:237], v239 offset:1024
	s_waitcnt lgkmcnt(3)
	v_pk_mul_f32 v[66:67], v[66:67], v[252:253] op_sel_hi:[1,0]
	v_pk_mul_f32 v[68:69], v[68:69], v[252:253] op_sel_hi:[1,0]
	v_pk_mul_f32 v[66:67], v[66:67], v[214:215]
	v_pk_mul_f32 v[68:69], v[68:69], v[216:217]
	v_pk_add_f32 v[222:223], v[222:223], 1.0 op_sel_hi:[1,0]
	v_pk_add_f32 v[224:225], v[224:225], 1.0 op_sel_hi:[1,0]
	v_pk_fma_f32 v[66:67], v[66:67], v[222:223], v[218:219]
	v_pk_fma_f32 v[68:69], v[68:69], v[224:225], v[220:221]
	s_nop 0
	v_cvt_pk_bf16_f32 v66, v66, v67
	v_cvt_pk_bf16_f32 v67, v68, v69
	global_store_dwordx2 v244, v[66:67], s[38:39] offset:0
	ds_read_b128 v[214:217], v238 offset:18432
	ds_read_b128 v[218:221], v238 offset:51200
	ds_read_b128 v[222:225], v239 offset:2048
	s_waitcnt lgkmcnt(3)
	v_pk_mul_f32 v[70:71], v[70:71], v[252:253] op_sel_hi:[1,0]
	v_pk_mul_f32 v[72:73], v[72:73], v[252:253] op_sel_hi:[1,0]
	v_pk_mul_f32 v[70:71], v[70:71], v[226:227]
	v_pk_mul_f32 v[72:73], v[72:73], v[228:229]
	v_pk_add_f32 v[234:235], v[234:235], 1.0 op_sel_hi:[1,0]
	v_pk_add_f32 v[236:237], v[236:237], 1.0 op_sel_hi:[1,0]
	v_pk_fma_f32 v[70:71], v[70:71], v[234:235], v[230:231]
	v_pk_fma_f32 v[72:73], v[72:73], v[236:237], v[232:233]
	s_nop 0
	v_cvt_pk_bf16_f32 v70, v70, v71
	v_cvt_pk_bf16_f32 v71, v72, v73
	global_store_dwordx2 v244, v[70:71], s[38:39] offset:512
	ds_read_b128 v[226:229], v238 offset:19456
	ds_read_b128 v[230:233], v238 offset:52224
	ds_read_b128 v[234:237], v239 offset:3072
	s_waitcnt lgkmcnt(3)
	v_pk_mul_f32 v[74:75], v[74:75], v[252:253] op_sel_hi:[1,0]
	v_pk_mul_f32 v[76:77], v[76:77], v[252:253] op_sel_hi:[1,0]
	v_pk_mul_f32 v[74:75], v[74:75], v[214:215]
	v_pk_mul_f32 v[76:77], v[76:77], v[216:217]
	v_pk_add_f32 v[222:223], v[222:223], 1.0 op_sel_hi:[1,0]
	v_pk_add_f32 v[224:225], v[224:225], 1.0 op_sel_hi:[1,0]
	v_pk_fma_f32 v[74:75], v[74:75], v[222:223], v[218:219]
	v_pk_fma_f32 v[76:77], v[76:77], v[224:225], v[220:221]
	s_nop 0
	v_cvt_pk_bf16_f32 v74, v74, v75
	v_cvt_pk_bf16_f32 v75, v76, v77
	global_store_dwordx2 v244, v[74:75], s[38:39] offset:1024
	ds_read_b128 v[214:217], v238 offset:20480
	ds_read_b128 v[218:221], v238 offset:53248
	ds_read_b128 v[222:225], v239 offset:4096
	s_waitcnt lgkmcnt(3)
	v_pk_mul_f32 v[78:79], v[78:79], v[252:253] op_sel_hi:[1,0]
	v_pk_mul_f32 v[80:81], v[80:81], v[252:253] op_sel_hi:[1,0]
	v_pk_mul_f32 v[78:79], v[78:79], v[226:227]
	v_pk_mul_f32 v[80:81], v[80:81], v[228:229]
	v_pk_add_f32 v[234:235], v[234:235], 1.0 op_sel_hi:[1,0]
	v_pk_add_f32 v[236:237], v[236:237], 1.0 op_sel_hi:[1,0]
	v_pk_fma_f32 v[78:79], v[78:79], v[234:235], v[230:231]
	v_pk_fma_f32 v[80:81], v[80:81], v[236:237], v[232:233]
	s_nop 0
	v_cvt_pk_bf16_f32 v78, v78, v79
	v_cvt_pk_bf16_f32 v79, v80, v81
	global_store_dwordx2 v244, v[78:79], s[38:39] offset:1536
	ds_read_b128 v[226:229], v238 offset:21504
	ds_read_b128 v[230:233], v238 offset:54272
	ds_read_b128 v[234:237], v239 offset:5120
	s_waitcnt lgkmcnt(3)
	v_pk_mul_f32 v[82:83], v[82:83], v[252:253] op_sel_hi:[1,0]
	v_pk_mul_f32 v[84:85], v[84:85], v[252:253] op_sel_hi:[1,0]
	v_pk_mul_f32 v[82:83], v[82:83], v[214:215]
	v_pk_mul_f32 v[84:85], v[84:85], v[216:217]
	v_pk_add_f32 v[222:223], v[222:223], 1.0 op_sel_hi:[1,0]
	v_pk_add_f32 v[224:225], v[224:225], 1.0 op_sel_hi:[1,0]
	v_pk_fma_f32 v[82:83], v[82:83], v[222:223], v[218:219]
	v_pk_fma_f32 v[84:85], v[84:85], v[224:225], v[220:221]
	s_nop 0
	v_cvt_pk_bf16_f32 v82, v82, v83
	v_cvt_pk_bf16_f32 v83, v84, v85
	global_store_dwordx2 v244, v[82:83], s[38:39] offset:2048
	ds_read_b128 v[214:217], v238 offset:22528
	ds_read_b128 v[218:221], v238 offset:55296
	ds_read_b128 v[222:225], v239 offset:6144
	s_waitcnt lgkmcnt(3)
	v_pk_mul_f32 v[86:87], v[86:87], v[252:253] op_sel_hi:[1,0]
	v_pk_mul_f32 v[88:89], v[88:89], v[252:253] op_sel_hi:[1,0]
	v_pk_mul_f32 v[86:87], v[86:87], v[226:227]
	v_pk_mul_f32 v[88:89], v[88:89], v[228:229]
	v_pk_add_f32 v[234:235], v[234:235], 1.0 op_sel_hi:[1,0]
	v_pk_add_f32 v[236:237], v[236:237], 1.0 op_sel_hi:[1,0]
	v_pk_fma_f32 v[86:87], v[86:87], v[234:235], v[230:231]
	v_pk_fma_f32 v[88:89], v[88:89], v[236:237], v[232:233]
	s_nop 0
	v_cvt_pk_bf16_f32 v86, v86, v87
	v_cvt_pk_bf16_f32 v87, v88, v89
	global_store_dwordx2 v244, v[86:87], s[38:39] offset:2560
	ds_read_b128 v[226:229], v238 offset:23552
	ds_read_b128 v[230:233], v238 offset:56320
	ds_read_b128 v[234:237], v239 offset:7168
	s_waitcnt lgkmcnt(3)
	v_pk_mul_f32 v[90:91], v[90:91], v[252:253] op_sel_hi:[1,0]
	v_pk_mul_f32 v[92:93], v[92:93], v[252:253] op_sel_hi:[1,0]
	v_pk_mul_f32 v[90:91], v[90:91], v[214:215]
	v_pk_mul_f32 v[92:93], v[92:93], v[216:217]
	v_pk_add_f32 v[222:223], v[222:223], 1.0 op_sel_hi:[1,0]
	v_pk_add_f32 v[224:225], v[224:225], 1.0 op_sel_hi:[1,0]
	v_pk_fma_f32 v[90:91], v[90:91], v[222:223], v[218:219]
	v_pk_fma_f32 v[92:93], v[92:93], v[224:225], v[220:221]
	s_nop 0
	v_cvt_pk_bf16_f32 v90, v90, v91
	v_cvt_pk_bf16_f32 v91, v92, v93
	global_store_dwordx2 v244, v[90:91], s[38:39] offset:3072
	ds_read_b128 v[214:217], v238 offset:24576
	ds_read_b128 v[218:221], v238 offset:57344
	ds_read_b128 v[222:225], v239 offset:8192
	s_waitcnt lgkmcnt(3)
	v_pk_mul_f32 v[94:95], v[94:95], v[252:253] op_sel_hi:[1,0]
	v_pk_mul_f32 v[96:97], v[96:97], v[252:253] op_sel_hi:[1,0]
	v_pk_mul_f32 v[94:95], v[94:95], v[226:227]
	v_pk_mul_f32 v[96:97], v[96:97], v[228:229]
	v_pk_add_f32 v[234:235], v[234:235], 1.0 op_sel_hi:[1,0]
	v_pk_add_f32 v[236:237], v[236:237], 1.0 op_sel_hi:[1,0]
	v_pk_fma_f32 v[94:95], v[94:95], v[234:235], v[230:231]
	v_pk_fma_f32 v[96:97], v[96:97], v[236:237], v[232:233]
	s_nop 0
	v_cvt_pk_bf16_f32 v94, v94, v95
	v_cvt_pk_bf16_f32 v95, v96, v97
	global_store_dwordx2 v244, v[94:95], s[38:39] offset:3584
	ds_read_b128 v[226:229], v238 offset:25600
	ds_read_b128 v[230:233], v238 offset:58368
	ds_read_b128 v[234:237], v239 offset:9216
	s_waitcnt lgkmcnt(3)
	v_pk_mul_f32 v[98:99], v[98:99], v[252:253] op_sel_hi:[1,0]
	v_pk_mul_f32 v[100:101], v[100:101], v[252:253] op_sel_hi:[1,0]
	v_pk_mul_f32 v[98:99], v[98:99], v[214:215]
	v_pk_mul_f32 v[100:101], v[100:101], v[216:217]
	v_pk_add_f32 v[222:223], v[222:223], 1.0 op_sel_hi:[1,0]
	v_pk_add_f32 v[224:225], v[224:225], 1.0 op_sel_hi:[1,0]
	v_pk_fma_f32 v[98:99], v[98:99], v[222:223], v[218:219]
	v_pk_fma_f32 v[100:101], v[100:101], v[224:225], v[220:221]
	s_nop 0
	v_cvt_pk_bf16_f32 v98, v98, v99
	v_cvt_pk_bf16_f32 v99, v100, v101
	global_store_dwordx2 v245, v[98:99], s[38:39] offset:0
	ds_read_b128 v[214:217], v238 offset:26624
	ds_read_b128 v[218:221], v238 offset:59392
	ds_read_b128 v[222:225], v239 offset:10240
	s_waitcnt lgkmcnt(3)
	v_pk_mul_f32 v[102:103], v[102:103], v[252:253] op_sel_hi:[1,0]
	v_pk_mul_f32 v[104:105], v[104:105], v[252:253] op_sel_hi:[1,0]
	v_pk_mul_f32 v[102:103], v[102:103], v[226:227]
	v_pk_mul_f32 v[104:105], v[104:105], v[228:229]
	v_pk_add_f32 v[234:235], v[234:235], 1.0 op_sel_hi:[1,0]
	v_pk_add_f32 v[236:237], v[236:237], 1.0 op_sel_hi:[1,0]
	v_pk_fma_f32 v[102:103], v[102:103], v[234:235], v[230:231]
	v_pk_fma_f32 v[104:105], v[104:105], v[236:237], v[232:233]
	s_nop 0
	v_cvt_pk_bf16_f32 v102, v102, v103
	v_cvt_pk_bf16_f32 v103, v104, v105
	global_store_dwordx2 v245, v[102:103], s[38:39] offset:512
	ds_read_b128 v[226:229], v238 offset:27648
	ds_read_b128 v[230:233], v238 offset:60416
	ds_read_b128 v[234:237], v239 offset:11264
	s_waitcnt lgkmcnt(3)
	v_pk_mul_f32 v[106:107], v[106:107], v[252:253] op_sel_hi:[1,0]
	v_pk_mul_f32 v[108:109], v[108:109], v[252:253] op_sel_hi:[1,0]
	v_pk_mul_f32 v[106:107], v[106:107], v[214:215]
	v_pk_mul_f32 v[108:109], v[108:109], v[216:217]
	v_pk_add_f32 v[222:223], v[222:223], 1.0 op_sel_hi:[1,0]
	v_pk_add_f32 v[224:225], v[224:225], 1.0 op_sel_hi:[1,0]
	v_pk_fma_f32 v[106:107], v[106:107], v[222:223], v[218:219]
	v_pk_fma_f32 v[108:109], v[108:109], v[224:225], v[220:221]
	s_nop 0
	v_cvt_pk_bf16_f32 v106, v106, v107
	v_cvt_pk_bf16_f32 v107, v108, v109
	global_store_dwordx2 v245, v[106:107], s[38:39] offset:1024
	ds_read_b128 v[214:217], v238 offset:28672
	ds_read_b128 v[218:221], v238 offset:61440
	ds_read_b128 v[222:225], v239 offset:12288
	s_waitcnt lgkmcnt(3)
	v_pk_mul_f32 v[110:111], v[110:111], v[252:253] op_sel_hi:[1,0]
	v_pk_mul_f32 v[112:113], v[112:113], v[252:253] op_sel_hi:[1,0]
	v_pk_mul_f32 v[110:111], v[110:111], v[226:227]
	v_pk_mul_f32 v[112:113], v[112:113], v[228:229]
	v_pk_add_f32 v[234:235], v[234:235], 1.0 op_sel_hi:[1,0]
	v_pk_add_f32 v[236:237], v[236:237], 1.0 op_sel_hi:[1,0]
	v_pk_fma_f32 v[110:111], v[110:111], v[234:235], v[230:231]
	v_pk_fma_f32 v[112:113], v[112:113], v[236:237], v[232:233]
	s_nop 0
	v_cvt_pk_bf16_f32 v110, v110, v111
	v_cvt_pk_bf16_f32 v111, v112, v113
	global_store_dwordx2 v245, v[110:111], s[38:39] offset:1536
	ds_read_b128 v[226:229], v238 offset:29696
	ds_read_b128 v[230:233], v238 offset:62464
	ds_read_b128 v[234:237], v239 offset:13312
	s_waitcnt lgkmcnt(3)
	v_pk_mul_f32 v[114:115], v[114:115], v[252:253] op_sel_hi:[1,0]
	v_pk_mul_f32 v[116:117], v[116:117], v[252:253] op_sel_hi:[1,0]
	v_pk_mul_f32 v[114:115], v[114:115], v[214:215]
	v_pk_mul_f32 v[116:117], v[116:117], v[216:217]
	v_pk_add_f32 v[222:223], v[222:223], 1.0 op_sel_hi:[1,0]
	v_pk_add_f32 v[224:225], v[224:225], 1.0 op_sel_hi:[1,0]
	v_pk_fma_f32 v[114:115], v[114:115], v[222:223], v[218:219]
	v_pk_fma_f32 v[116:117], v[116:117], v[224:225], v[220:221]
	s_nop 0
	v_cvt_pk_bf16_f32 v114, v114, v115
	v_cvt_pk_bf16_f32 v115, v116, v117
	global_store_dwordx2 v245, v[114:115], s[38:39] offset:2048
	ds_read_b128 v[214:217], v238 offset:30720
	ds_read_b128 v[218:221], v238 offset:63488
	ds_read_b128 v[222:225], v239 offset:14336
	s_waitcnt lgkmcnt(3)
	v_pk_mul_f32 v[118:119], v[118:119], v[252:253] op_sel_hi:[1,0]
	v_pk_mul_f32 v[120:121], v[120:121], v[252:253] op_sel_hi:[1,0]
	v_pk_mul_f32 v[118:119], v[118:119], v[226:227]
	v_pk_mul_f32 v[120:121], v[120:121], v[228:229]
	v_pk_add_f32 v[234:235], v[234:235], 1.0 op_sel_hi:[1,0]
	v_pk_add_f32 v[236:237], v[236:237], 1.0 op_sel_hi:[1,0]
	v_pk_fma_f32 v[118:119], v[118:119], v[234:235], v[230:231]
	v_pk_fma_f32 v[120:121], v[120:121], v[236:237], v[232:233]
	s_nop 0
	v_cvt_pk_bf16_f32 v118, v118, v119
	v_cvt_pk_bf16_f32 v119, v120, v121
	global_store_dwordx2 v245, v[118:119], s[38:39] offset:2560
	ds_read_b128 v[226:229], v238 offset:31744
	ds_read_b128 v[230:233], v238 offset:64512
	ds_read_b128 v[234:237], v239 offset:15360
	s_waitcnt lgkmcnt(3)
	v_pk_mul_f32 v[122:123], v[122:123], v[252:253] op_sel_hi:[1,0]
	v_pk_mul_f32 v[124:125], v[124:125], v[252:253] op_sel_hi:[1,0]
	v_pk_mul_f32 v[122:123], v[122:123], v[214:215]
	v_pk_mul_f32 v[124:125], v[124:125], v[216:217]
	v_pk_add_f32 v[222:223], v[222:223], 1.0 op_sel_hi:[1,0]
	v_pk_add_f32 v[224:225], v[224:225], 1.0 op_sel_hi:[1,0]
	v_pk_fma_f32 v[122:123], v[122:123], v[222:223], v[218:219]
	v_pk_fma_f32 v[124:125], v[124:125], v[224:225], v[220:221]
	s_nop 0
	v_cvt_pk_bf16_f32 v122, v122, v123
	v_cvt_pk_bf16_f32 v123, v124, v125
	global_store_dwordx2 v245, v[122:123], s[38:39] offset:3072
	s_waitcnt lgkmcnt(0)
	v_pk_mul_f32 v[126:127], v[126:127], v[252:253] op_sel_hi:[1,0]
	v_pk_mul_f32 v[128:129], v[128:129], v[252:253] op_sel_hi:[1,0]
	v_pk_mul_f32 v[126:127], v[126:127], v[226:227]
	v_pk_mul_f32 v[128:129], v[128:129], v[228:229]
	v_pk_add_f32 v[234:235], v[234:235], 1.0 op_sel_hi:[1,0]
	v_pk_add_f32 v[236:237], v[236:237], 1.0 op_sel_hi:[1,0]
	v_pk_fma_f32 v[126:127], v[126:127], v[234:235], v[230:231]
	v_pk_fma_f32 v[128:129], v[128:129], v[236:237], v[232:233]
	s_nop 0
	v_cvt_pk_bf16_f32 v126, v126, v127
	v_cvt_pk_bf16_f32 v127, v128, v129
	global_store_dwordx2 v245, v[126:127], s[38:39] offset:3584
	s_add_u32 s22, s22, 0x1000000
	s_addc_u32 s23, s23, 0
	s_add_u32 s38, s38, 0x1000000
	s_addc_u32 s39, s39, 0
	s_waitcnt vmcnt(16)
	s_barrier
	s_add_u32 s44, s44, 0x2000000
	s_addc_u32 s45, s45, 0
	global_load_dwordx4 v[66:69], v238, s[44:45] offset:0
	global_load_dwordx4 v[70:73], v238, s[44:45] offset:1024
	global_load_dwordx4 v[74:77], v238, s[44:45] offset:2048
	global_load_dwordx4 v[78:81], v238, s[44:45] offset:3072
	global_load_dwordx4 v[82:85], v241, s[44:45] offset:0
	global_load_dwordx4 v[86:89], v241, s[44:45] offset:1024
	global_load_dwordx4 v[90:93], v241, s[44:45] offset:2048
	global_load_dwordx4 v[94:97], v241, s[44:45] offset:3072
	global_load_dwordx4 v[98:101], v242, s[44:45] offset:0
	global_load_dwordx4 v[102:105], v242, s[44:45] offset:1024
	global_load_dwordx4 v[106:109], v242, s[44:45] offset:2048
	global_load_dwordx4 v[110:113], v242, s[44:45] offset:3072
	global_load_dwordx4 v[114:117], v243, s[44:45] offset:0
	global_load_dwordx4 v[118:121], v243, s[44:45] offset:1024
	global_load_dwordx4 v[122:125], v243, s[44:45] offset:2048
	global_load_dwordx4 v[126:129], v243, s[44:45] offset:3072
	s_add_i32 s9, s3, 3
	s_mul_i32 s9, s9, 0x18000
	s_add_u32 s10, s28, s9
	s_addc_u32 s11, s29, 0
	s_add_u32 s12, s10, 0x8000
	s_addc_u32 s13, s11, 0
	s_add_u32 s8, s7, 0x8000
	s_mov_b32 m0, s8
	s_nop 0
	global_load_lds_dwordx4 v240, s[12:13]
	global_load_lds_dwordx4 v240, s[12:13] offset:1024
	s_add_u32 s12, s10, 0xc000
	s_addc_u32 s13, s11, 0
	s_add_u32 s8, s7, 0xc000
	s_mov_b32 m0, s8
	s_nop 0
	global_load_lds_dwordx4 v240, s[12:13]
	global_load_lds_dwordx4 v240, s[12:13] offset:1024
	s_add_u32 s12, s10, 0x10000
	s_addc_u32 s13, s11, 0
	s_add_u32 s8, s7, 0x10000
	s_mov_b32 m0, s8
	s_nop 0
	global_load_lds_dwordx4 v240, s[12:13]
	global_load_lds_dwordx4 v240, s[12:13] offset:1024
	ds_read_b128 v[214:217], v238 offset:0
	ds_read_b128 v[218:221], v239 offset:16384
	v_lshlrev_b32_e32 v162, 16, v130
	v_and_b32_e32 v163, 0xffff0000, v130
	v_lshlrev_b32_e32 v164, 16, v131
	v_and_b32_e32 v165, 0xffff0000, v131
	v_pk_mul_f32 v[170:171], v[162:163], v[162:163]
	v_pk_mul_f32 v[172:173], v[164:165], v[164:165]
	v_lshlrev_b32_e32 v166, 16, v132
	v_and_b32_e32 v167, 0xffff0000, v132
	v_lshlrev_b32_e32 v168, 16, v133
	v_and_b32_e32 v169, 0xffff0000, v133
	v_pk_fma_f32 v[170:171], v[166:167], v[166:167], v[170:171]
	v_pk_fma_f32 v[172:173], v[168:169], v[168:169], v[172:173]
	v_lshlrev_b32_e32 v162, 16, v134
	v_and_b32_e32 v163, 0xffff0000, v134
	v_lshlrev_b32_e32 v164, 16, v135
	v_and_b32_e32 v165, 0xffff0000, v135
	v_pk_fma_f32 v[170:171], v[162:163], v[162:163], v[170:171]
	v_pk_fma_f32 v[172:173], v[164:165], v[164:165], v[172:173]
	v_lshlrev_b32_e32 v166, 16, v136
	v_and_b32_e32 v167, 0xffff0000, v136
	v_lshlrev_b32_e32 v168, 16, v137
	v_and_b32_e32 v169, 0xffff0000, v137
	v_pk_fma_f32 v[170:171], v[166:167], v[166:167], v[170:171]
	v_pk_fma_f32 v[172:173], v[168:169], v[168:169], v[172:173]
	v_lshlrev_b32_e32 v162, 16, v138
	v_and_b32_e32 v163, 0xffff0000, v138
	v_lshlrev_b32_e32 v164, 16, v139
	v_and_b32_e32 v165, 0xffff0000, v139
	v_pk_fma_f32 v[170:171], v[162:163], v[162:163], v[170:171]
	v_pk_fma_f32 v[172:173], v[164:165], v[164:165], v[172:173]
	v_lshlrev_b32_e32 v166, 16, v140
	v_and_b32_e32 v167, 0xffff0000, v140
	v_lshlrev_b32_e32 v168, 16, v141
	v_and_b32_e32 v169, 0xffff0000, v141
	v_pk_fma_f32 v[170:171], v[166:167], v[166:167], v[170:171]
	v_pk_fma_f32 v[172:173], v[168:169], v[168:169], v[172:173]
	v_lshlrev_b32_e32 v162, 16, v142
	v_and_b32_e32 v163, 0xffff0000, v142
	v_lshlrev_b32_e32 v164, 16, v143
	v_and_b32_e32 v165, 0xffff0000, v143
	v_pk_fma_f32 v[170:171], v[162:163], v[162:163], v[170:171]
	v_pk_fma_f32 v[172:173], v[164:165], v[164:165], v[172:173]
	v_lshlrev_b32_e32 v166, 16, v144
	v_and_b32_e32 v167, 0xffff0000, v144
	v_lshlrev_b32_e32 v168, 16, v145
	v_and_b32_e32 v169, 0xffff0000, v145
	v_pk_fma_f32 v[170:171], v[166:167], v[166:167], v[170:171]
	v_pk_fma_f32 v[172:173], v[168:169], v[168:169], v[172:173]
	v_lshlrev_b32_e32 v162, 16, v146
	v_and_b32_e32 v163, 0xffff0000, v146
	v_lshlrev_b32_e32 v164, 16, v147
	v_and_b32_e32 v165, 0xffff0000, v147
	v_pk_fma_f32 v[170:171], v[162:163], v[162:163], v[170:171]
	v_pk_fma_f32 v[172:173], v[164:165], v[164:165], v[172:173]
	v_lshlrev_b32_e32 v166, 16, v148
	v_and_b32_e32 v167, 0xffff0000, v148
	v_lshlrev_b32_e32 v168, 16, v149
	v_and_b32_e32 v169, 0xffff0000, v149
	v_pk_fma_f32 v[170:171], v[166:167], v[166:167], v[170:171]
	v_pk_fma_f32 v[172:173], v[168:169], v[168:169], v[172:173]
	v_lshlrev_b32_e32 v162, 16, v150
	v_and_b32_e32 v163, 0xffff0000, v150
	v_lshlrev_b32_e32 v164, 16, v151
	v_and_b32_e32 v165, 0xffff0000, v151
	v_pk_fma_f32 v[170:171], v[162:163], v[162:163], v[170:171]
	v_pk_fma_f32 v[172:173], v[164:165], v[164:165], v[172:173]
	v_lshlrev_b32_e32 v166, 16, v152
	v_and_b32_e32 v167, 0xffff0000, v152
	v_lshlrev_b32_e32 v168, 16, v153
	v_and_b32_e32 v169, 0xffff0000, v153
	v_pk_fma_f32 v[170:171], v[166:167], v[166:167], v[170:171]
	v_pk_fma_f32 v[172:173], v[168:169], v[168:169], v[172:173]
	v_lshlrev_b32_e32 v162, 16, v154
	v_and_b32_e32 v163, 0xffff0000, v154
	v_lshlrev_b32_e32 v164, 16, v155
	v_and_b32_e32 v165, 0xffff0000, v155
	v_pk_fma_f32 v[170:171], v[162:163], v[162:163], v[170:171]
	v_pk_fma_f32 v[172:173], v[164:165], v[164:165], v[172:173]
	v_lshlrev_b32_e32 v166, 16, v156
	v_and_b32_e32 v167, 0xffff0000, v156
	v_lshlrev_b32_e32 v168, 16, v157
	v_and_b32_e32 v169, 0xffff0000, v157
	v_pk_fma_f32 v[170:171], v[166:167], v[166:167], v[170:171]
	v_pk_fma_f32 v[172:173], v[168:169], v[168:169], v[172:173]
	v_lshlrev_b32_e32 v162, 16, v158
	v_and_b32_e32 v163, 0xffff0000, v158
	v_lshlrev_b32_e32 v164, 16, v159
	v_and_b32_e32 v165, 0xffff0000, v159
	v_pk_fma_f32 v[170:171], v[162:163], v[162:163], v[170:171]
	v_pk_fma_f32 v[172:173], v[164:165], v[164:165], v[172:173]
	v_lshlrev_b32_e32 v166, 16, v160
	v_and_b32_e32 v167, 0xffff0000, v160
	v_lshlrev_b32_e32 v168, 16, v161
	v_and_b32_e32 v169, 0xffff0000, v161
	v_pk_fma_f32 v[170:171], v[166:167], v[166:167], v[170:171]
	v_pk_fma_f32 v[172:173], v[168:169], v[168:169], v[172:173]
	v_pk_add_f32 v[170:171], v[170:171], v[172:173]
	s_nop 0
	v_add_f32_e32 v252, v170, v171
	s_waitcnt lgkmcnt(0)
	ds_bpermute_b32 v254, v246, v252
	s_waitcnt lgkmcnt(0)
	v_add_f32_e32 v252, v252, v254
	ds_bpermute_b32 v254, v247, v252
	s_waitcnt lgkmcnt(0)
	v_add_f32_e32 v252, v252, v254
	ds_bpermute_b32 v254, v248, v252
	s_waitcnt lgkmcnt(0)
	v_add_f32_e32 v252, v252, v254
	ds_bpermute_b32 v254, v249, v252
	s_waitcnt lgkmcnt(0)
	v_add_f32_e32 v252, v252, v254
	ds_bpermute_b32 v254, v250, v252
	s_waitcnt lgkmcnt(0)
	v_add_f32_e32 v252, v252, v254
	ds_bpermute_b32 v254, v251, v252
	s_waitcnt lgkmcnt(0)
	v_add_f32_e32 v252, v252, v254
	v_mov_b32_e32 v254, 0x358637bd
	v_fmac_f32_e32 v254, 0x39800000, v252
	v_mul_f32_e32 v252, 0x4b800000, v254
	v_cmp_gt_f32_e32 vcc, s32, v254
	s_nop 1
	v_cndmask_b32_e32 v254, v254, v252, vcc
	v_rsq_f32_e32 v254, v254
	s_nop 0
	v_mul_f32_e32 v252, 0x45800000, v254
	v_cndmask_b32_e32 v252, v254, v252, vcc
	ds_read_b128 v[226:229], v238 offset:1024
	ds_read_b128 v[230:233], v239 offset:17408
	s_waitcnt lgkmcnt(2)
	v_lshlrev_b32_e32 v162, 16, v130
	v_and_b32_e32 v163, 0xffff0000, v130
	v_lshlrev_b32_e32 v164, 16, v131
	v_and_b32_e32 v165, 0xffff0000, v131
	v_pk_mul_f32 v[162:163], v[162:163], v[252:253] op_sel_hi:[1,0]
	v_pk_mul_f32 v[164:165], v[164:165], v[252:253] op_sel_hi:[1,0]
	v_pk_mul_f32 v[162:163], v[162:163], v[214:215]
	v_pk_mul_f32 v[164:165], v[164:165], v[216:217]
	v_pk_fma_f32 v[2:3], v[218:219], v[162:163], v[2:3]
	v_pk_fma_f32 v[4:5], v[220:221], v[164:165], v[4:5]
	v_pk_mul_f32 v[170:171], v[2:3], v[2:3]
	v_pk_mul_f32 v[172:173], v[4:5], v[4:5]
	v_cvt_pk_bf16_f32 v166, v2, v3
	v_cvt_pk_bf16_f32 v167, v4, v5
	global_store_dwordx2 v244, v[166:167], s[22:23] offset:0
	ds_read_b128 v[214:217], v238 offset:2048
	ds_read_b128 v[218:221], v239 offset:18432
	s_waitcnt lgkmcnt(2)
	v_lshlrev_b32_e32 v162, 16, v132
	v_and_b32_e32 v163, 0xffff0000, v132
	v_lshlrev_b32_e32 v164, 16, v133
	v_and_b32_e32 v165, 0xffff0000, v133
	v_pk_mul_f32 v[162:163], v[162:163], v[252:253] op_sel_hi:[1,0]
	v_pk_mul_f32 v[164:165], v[164:165], v[252:253] op_sel_hi:[1,0]
	v_pk_mul_f32 v[162:163], v[162:163], v[226:227]
	v_pk_mul_f32 v[164:165], v[164:165], v[228:229]
	v_pk_fma_f32 v[6:7], v[230:231], v[162:163], v[6:7]
	v_pk_fma_f32 v[8:9], v[232:233], v[164:165], v[8:9]
	v_pk_fma_f32 v[170:171], v[6:7], v[6:7], v[170:171]
	v_pk_fma_f32 v[172:173], v[8:9], v[8:9], v[172:173]
	v_cvt_pk_bf16_f32 v168, v6, v7
	v_cvt_pk_bf16_f32 v169, v8, v9
	global_store_dwordx2 v244, v[168:169], s[22:23] offset:512
	ds_read_b128 v[226:229], v238 offset:3072
	ds_read_b128 v[230:233], v239 offset:19456
	s_waitcnt lgkmcnt(2)
	v_lshlrev_b32_e32 v162, 16, v134
	v_and_b32_e32 v163, 0xffff0000, v134
	v_lshlrev_b32_e32 v164, 16, v135
	v_and_b32_e32 v165, 0xffff0000, v135
	v_pk_mul_f32 v[162:163], v[162:163], v[252:253] op_sel_hi:[1,0]
	v_pk_mul_f32 v[164:165], v[164:165], v[252:253] op_sel_hi:[1,0]
	v_pk_mul_f32 v[162:163], v[162:163], v[214:215]
	v_pk_mul_f32 v[164:165], v[164:165], v[216:217]
	v_pk_fma_f32 v[10:11], v[218:219], v[162:163], v[10:11]
	v_pk_fma_f32 v[12:13], v[220:221], v[164:165], v[12:13]
	v_pk_fma_f32 v[170:171], v[10:11], v[10:11], v[170:171]
	v_pk_fma_f32 v[172:173], v[12:13], v[12:13], v[172:173]
	v_cvt_pk_bf16_f32 v166, v10, v11
	v_cvt_pk_bf16_f32 v167, v12, v13
	global_store_dwordx2 v244, v[166:167], s[22:23] offset:1024
	ds_read_b128 v[214:217], v238 offset:4096
	ds_read_b128 v[218:221], v239 offset:20480
	s_waitcnt lgkmcnt(2)
	v_lshlrev_b32_e32 v162, 16, v136
	v_and_b32_e32 v163, 0xffff0000, v136
	v_lshlrev_b32_e32 v164, 16, v137
	v_and_b32_e32 v165, 0xffff0000, v137
	v_pk_mul_f32 v[162:163], v[162:163], v[252:253] op_sel_hi:[1,0]
	v_pk_mul_f32 v[164:165], v[164:165], v[252:253] op_sel_hi:[1,0]
	v_pk_mul_f32 v[162:163], v[162:163], v[226:227]
	v_pk_mul_f32 v[164:165], v[164:165], v[228:229]
	v_pk_fma_f32 v[14:15], v[230:231], v[162:163], v[14:15]
	v_pk_fma_f32 v[16:17], v[232:233], v[164:165], v[16:17]
	v_pk_fma_f32 v[170:171], v[14:15], v[14:15], v[170:171]
	v_pk_fma_f32 v[172:173], v[16:17], v[16:17], v[172:173]
	v_cvt_pk_bf16_f32 v168, v14, v15
	v_cvt_pk_bf16_f32 v169, v16, v17
	global_store_dwordx2 v244, v[168:169], s[22:23] offset:1536
	ds_read_b128 v[226:229], v238 offset:5120
	ds_read_b128 v[230:233], v239 offset:21504
	s_waitcnt lgkmcnt(2)
	v_lshlrev_b32_e32 v162, 16, v138
	v_and_b32_e32 v163, 0xffff0000, v138
	v_lshlrev_b32_e32 v164, 16, v139
	v_and_b32_e32 v165, 0xffff0000, v139
	v_pk_mul_f32 v[162:163], v[162:163], v[252:253] op_sel_hi:[1,0]
	v_pk_mul_f32 v[164:165], v[164:165], v[252:253] op_sel_hi:[1,0]
	v_pk_mul_f32 v[162:163], v[162:163], v[214:215]
	v_pk_mul_f32 v[164:165], v[164:165], v[216:217]
	v_pk_fma_f32 v[18:19], v[218:219], v[162:163], v[18:19]
	v_pk_fma_f32 v[20:21], v[220:221], v[164:165], v[20:21]
	v_pk_fma_f32 v[170:171], v[18:19], v[18:19], v[170:171]
	v_pk_fma_f32 v[172:173], v[20:21], v[20:21], v[172:173]
	v_cvt_pk_bf16_f32 v166, v18, v19
	v_cvt_pk_bf16_f32 v167, v20, v21
	global_store_dwordx2 v244, v[166:167], s[22:23] offset:2048
	ds_read_b128 v[214:217], v238 offset:6144
	ds_read_b128 v[218:221], v239 offset:22528
	s_waitcnt lgkmcnt(2)
	v_lshlrev_b32_e32 v162, 16, v140
	v_and_b32_e32 v163, 0xffff0000, v140
	v_lshlrev_b32_e32 v164, 16, v141
	v_and_b32_e32 v165, 0xffff0000, v141
	v_pk_mul_f32 v[162:163], v[162:163], v[252:253] op_sel_hi:[1,0]
	v_pk_mul_f32 v[164:165], v[164:165], v[252:253] op_sel_hi:[1,0]
	v_pk_mul_f32 v[162:163], v[162:163], v[226:227]
	v_pk_mul_f32 v[164:165], v[164:165], v[228:229]
	v_pk_fma_f32 v[22:23], v[230:231], v[162:163], v[22:23]
	v_pk_fma_f32 v[24:25], v[232:233], v[164:165], v[24:25]
	v_pk_fma_f32 v[170:171], v[22:23], v[22:23], v[170:171]
	v_pk_fma_f32 v[172:173], v[24:25], v[24:25], v[172:173]
	v_cvt_pk_bf16_f32 v168, v22, v23
	v_cvt_pk_bf16_f32 v169, v24, v25
	global_store_dwordx2 v244, v[168:169], s[22:23] offset:2560
	ds_read_b128 v[226:229], v238 offset:7168
	ds_read_b128 v[230:233], v239 offset:23552
	s_waitcnt lgkmcnt(2)
	v_lshlrev_b32_e32 v162, 16, v142
	v_and_b32_e32 v163, 0xffff0000, v142
	v_lshlrev_b32_e32 v164, 16, v143
	v_and_b32_e32 v165, 0xffff0000, v143
	v_pk_mul_f32 v[162:163], v[162:163], v[252:253] op_sel_hi:[1,0]
	v_pk_mul_f32 v[164:165], v[164:165], v[252:253] op_sel_hi:[1,0]
	v_pk_mul_f32 v[162:163], v[162:163], v[214:215]
	v_pk_mul_f32 v[164:165], v[164:165], v[216:217]
	v_pk_fma_f32 v[26:27], v[218:219], v[162:163], v[26:27]
	v_pk_fma_f32 v[28:29], v[220:221], v[164:165], v[28:29]
	v_pk_fma_f32 v[170:171], v[26:27], v[26:27], v[170:171]
	v_pk_fma_f32 v[172:173], v[28:29], v[28:29], v[172:173]
	v_cvt_pk_bf16_f32 v166, v26, v27
	v_cvt_pk_bf16_f32 v167, v28, v29
	global_store_dwordx2 v244, v[166:167], s[22:23] offset:3072
	ds_read_b128 v[214:217], v238 offset:8192
	ds_read_b128 v[218:221], v239 offset:24576
	s_waitcnt lgkmcnt(2)
	v_lshlrev_b32_e32 v162, 16, v144
	v_and_b32_e32 v163, 0xffff0000, v144
	v_lshlrev_b32_e32 v164, 16, v145
	v_and_b32_e32 v165, 0xffff0000, v145
	v_pk_mul_f32 v[162:163], v[162:163], v[252:253] op_sel_hi:[1,0]
	v_pk_mul_f32 v[164:165], v[164:165], v[252:253] op_sel_hi:[1,0]
	v_pk_mul_f32 v[162:163], v[162:163], v[226:227]
	v_pk_mul_f32 v[164:165], v[164:165], v[228:229]
	v_pk_fma_f32 v[30:31], v[230:231], v[162:163], v[30:31]
	v_pk_fma_f32 v[32:33], v[232:233], v[164:165], v[32:33]
	v_pk_fma_f32 v[170:171], v[30:31], v[30:31], v[170:171]
	v_pk_fma_f32 v[172:173], v[32:33], v[32:33], v[172:173]
	v_cvt_pk_bf16_f32 v168, v30, v31
	v_cvt_pk_bf16_f32 v169, v32, v33
	global_store_dwordx2 v244, v[168:169], s[22:23] offset:3584
	ds_read_b128 v[226:229], v238 offset:9216
	ds_read_b128 v[230:233], v239 offset:25600
	s_waitcnt lgkmcnt(2)
	v_lshlrev_b32_e32 v162, 16, v146
	v_and_b32_e32 v163, 0xffff0000, v146
	v_lshlrev_b32_e32 v164, 16, v147
	v_and_b32_e32 v165, 0xffff0000, v147
	v_pk_mul_f32 v[162:163], v[162:163], v[252:253] op_sel_hi:[1,0]
	v_pk_mul_f32 v[164:165], v[164:165], v[252:253] op_sel_hi:[1,0]
	v_pk_mul_f32 v[162:163], v[162:163], v[214:215]
	v_pk_mul_f32 v[164:165], v[164:165], v[216:217]
	v_pk_fma_f32 v[34:35], v[218:219], v[162:163], v[34:35]
	v_pk_fma_f32 v[36:37], v[220:221], v[164:165], v[36:37]
	v_pk_fma_f32 v[170:171], v[34:35], v[34:35], v[170:171]
	v_pk_fma_f32 v[172:173], v[36:37], v[36:37], v[172:173]
	v_cvt_pk_bf16_f32 v166, v34, v35
	v_cvt_pk_bf16_f32 v167, v36, v37
	global_store_dwordx2 v245, v[166:167], s[22:23] offset:0
	ds_read_b128 v[214:217], v238 offset:10240
	ds_read_b128 v[218:221], v239 offset:26624
	s_waitcnt lgkmcnt(2)
	v_lshlrev_b32_e32 v162, 16, v148
	v_and_b32_e32 v163, 0xffff0000, v148
	v_lshlrev_b32_e32 v164, 16, v149
	v_and_b32_e32 v165, 0xffff0000, v149
	v_pk_mul_f32 v[162:163], v[162:163], v[252:253] op_sel_hi:[1,0]
	v_pk_mul_f32 v[164:165], v[164:165], v[252:253] op_sel_hi:[1,0]
	v_pk_mul_f32 v[162:163], v[162:163], v[226:227]
	v_pk_mul_f32 v[164:165], v[164:165], v[228:229]
	v_pk_fma_f32 v[38:39], v[230:231], v[162:163], v[38:39]
	v_pk_fma_f32 v[40:41], v[232:233], v[164:165], v[40:41]
	v_pk_fma_f32 v[170:171], v[38:39], v[38:39], v[170:171]
	v_pk_fma_f32 v[172:173], v[40:41], v[40:41], v[172:173]
	v_cvt_pk_bf16_f32 v168, v38, v39
	v_cvt_pk_bf16_f32 v169, v40, v41
	global_store_dwordx2 v245, v[168:169], s[22:23] offset:512
	ds_read_b128 v[226:229], v238 offset:11264
	ds_read_b128 v[230:233], v239 offset:27648
	s_waitcnt lgkmcnt(2)
	v_lshlrev_b32_e32 v162, 16, v150
	v_and_b32_e32 v163, 0xffff0000, v150
	v_lshlrev_b32_e32 v164, 16, v151
	v_and_b32_e32 v165, 0xffff0000, v151
	v_pk_mul_f32 v[162:163], v[162:163], v[252:253] op_sel_hi:[1,0]
	v_pk_mul_f32 v[164:165], v[164:165], v[252:253] op_sel_hi:[1,0]
	v_pk_mul_f32 v[162:163], v[162:163], v[214:215]
	v_pk_mul_f32 v[164:165], v[164:165], v[216:217]
	v_pk_fma_f32 v[42:43], v[218:219], v[162:163], v[42:43]
	v_pk_fma_f32 v[44:45], v[220:221], v[164:165], v[44:45]
	v_pk_fma_f32 v[170:171], v[42:43], v[42:43], v[170:171]
	v_pk_fma_f32 v[172:173], v[44:45], v[44:45], v[172:173]
	v_cvt_pk_bf16_f32 v166, v42, v43
	v_cvt_pk_bf16_f32 v167, v44, v45
	global_store_dwordx2 v245, v[166:167], s[22:23] offset:1024
	ds_read_b128 v[214:217], v238 offset:12288
	ds_read_b128 v[218:221], v239 offset:28672
	s_waitcnt lgkmcnt(2)
	v_lshlrev_b32_e32 v162, 16, v152
	v_and_b32_e32 v163, 0xffff0000, v152
	v_lshlrev_b32_e32 v164, 16, v153
	v_and_b32_e32 v165, 0xffff0000, v153
	v_pk_mul_f32 v[162:163], v[162:163], v[252:253] op_sel_hi:[1,0]
	v_pk_mul_f32 v[164:165], v[164:165], v[252:253] op_sel_hi:[1,0]
	v_pk_mul_f32 v[162:163], v[162:163], v[226:227]
	v_pk_mul_f32 v[164:165], v[164:165], v[228:229]
	v_pk_fma_f32 v[46:47], v[230:231], v[162:163], v[46:47]
	v_pk_fma_f32 v[48:49], v[232:233], v[164:165], v[48:49]
	v_pk_fma_f32 v[170:171], v[46:47], v[46:47], v[170:171]
	v_pk_fma_f32 v[172:173], v[48:49], v[48:49], v[172:173]
	v_cvt_pk_bf16_f32 v168, v46, v47
	v_cvt_pk_bf16_f32 v169, v48, v49
	global_store_dwordx2 v245, v[168:169], s[22:23] offset:1536
	ds_read_b128 v[226:229], v238 offset:13312
	ds_read_b128 v[230:233], v239 offset:29696
	s_waitcnt lgkmcnt(2)
	v_lshlrev_b32_e32 v162, 16, v154
	v_and_b32_e32 v163, 0xffff0000, v154
	v_lshlrev_b32_e32 v164, 16, v155
	v_and_b32_e32 v165, 0xffff0000, v155
	v_pk_mul_f32 v[162:163], v[162:163], v[252:253] op_sel_hi:[1,0]
	v_pk_mul_f32 v[164:165], v[164:165], v[252:253] op_sel_hi:[1,0]
	v_pk_mul_f32 v[162:163], v[162:163], v[214:215]
	v_pk_mul_f32 v[164:165], v[164:165], v[216:217]
	v_pk_fma_f32 v[50:51], v[218:219], v[162:163], v[50:51]
	v_pk_fma_f32 v[52:53], v[220:221], v[164:165], v[52:53]
	v_pk_fma_f32 v[170:171], v[50:51], v[50:51], v[170:171]
	v_pk_fma_f32 v[172:173], v[52:53], v[52:53], v[172:173]
	v_cvt_pk_bf16_f32 v166, v50, v51
	v_cvt_pk_bf16_f32 v167, v52, v53
	global_store_dwordx2 v245, v[166:167], s[22:23] offset:2048
	ds_read_b128 v[214:217], v238 offset:14336
	ds_read_b128 v[218:221], v239 offset:30720
	s_waitcnt lgkmcnt(2)
	v_lshlrev_b32_e32 v162, 16, v156
	v_and_b32_e32 v163, 0xffff0000, v156
	v_lshlrev_b32_e32 v164, 16, v157
	v_and_b32_e32 v165, 0xffff0000, v157
	v_pk_mul_f32 v[162:163], v[162:163], v[252:253] op_sel_hi:[1,0]
	v_pk_mul_f32 v[164:165], v[164:165], v[252:253] op_sel_hi:[1,0]
	v_pk_mul_f32 v[162:163], v[162:163], v[226:227]
	v_pk_mul_f32 v[164:165], v[164:165], v[228:229]
	v_pk_fma_f32 v[54:55], v[230:231], v[162:163], v[54:55]
	v_pk_fma_f32 v[56:57], v[232:233], v[164:165], v[56:57]
	v_pk_fma_f32 v[170:171], v[54:55], v[54:55], v[170:171]
	v_pk_fma_f32 v[172:173], v[56:57], v[56:57], v[172:173]
	v_cvt_pk_bf16_f32 v168, v54, v55
	v_cvt_pk_bf16_f32 v169, v56, v57
	global_store_dwordx2 v245, v[168:169], s[22:23] offset:2560
	ds_read_b128 v[226:229], v238 offset:15360
	ds_read_b128 v[230:233], v239 offset:31744
	s_waitcnt lgkmcnt(2)
	v_lshlrev_b32_e32 v162, 16, v158
	v_and_b32_e32 v163, 0xffff0000, v158
	v_lshlrev_b32_e32 v164, 16, v159
	v_and_b32_e32 v165, 0xffff0000, v159
	v_pk_mul_f32 v[162:163], v[162:163], v[252:253] op_sel_hi:[1,0]
	v_pk_mul_f32 v[164:165], v[164:165], v[252:253] op_sel_hi:[1,0]
	v_pk_mul_f32 v[162:163], v[162:163], v[214:215]
	v_pk_mul_f32 v[164:165], v[164:165], v[216:217]
	v_pk_fma_f32 v[58:59], v[218:219], v[162:163], v[58:59]
	v_pk_fma_f32 v[60:61], v[220:221], v[164:165], v[60:61]
	v_pk_fma_f32 v[170:171], v[58:59], v[58:59], v[170:171]
	v_pk_fma_f32 v[172:173], v[60:61], v[60:61], v[172:173]
	v_cvt_pk_bf16_f32 v166, v58, v59
	v_cvt_pk_bf16_f32 v167, v60, v61
	global_store_dwordx2 v245, v[166:167], s[22:23] offset:3072
	s_waitcnt lgkmcnt(0)
	v_lshlrev_b32_e32 v162, 16, v160
	v_and_b32_e32 v163, 0xffff0000, v160
	v_lshlrev_b32_e32 v164, 16, v161
	v_and_b32_e32 v165, 0xffff0000, v161
	v_pk_mul_f32 v[162:163], v[162:163], v[252:253] op_sel_hi:[1,0]
	v_pk_mul_f32 v[164:165], v[164:165], v[252:253] op_sel_hi:[1,0]
	v_pk_mul_f32 v[162:163], v[162:163], v[226:227]
	v_pk_mul_f32 v[164:165], v[164:165], v[228:229]
	v_pk_fma_f32 v[62:63], v[230:231], v[162:163], v[62:63]
	v_pk_fma_f32 v[64:65], v[232:233], v[164:165], v[64:65]
	v_pk_fma_f32 v[170:171], v[62:63], v[62:63], v[170:171]
	v_pk_fma_f32 v[172:173], v[64:65], v[64:65], v[172:173]
	v_cvt_pk_bf16_f32 v168, v62, v63
	v_cvt_pk_bf16_f32 v169, v64, v65
	global_store_dwordx2 v245, v[168:169], s[22:23] offset:3584
	ds_read_b128 v[214:217], v238 offset:16384
	ds_read_b128 v[218:221], v239 offset:32768
	ds_read_b128 v[222:225], v239 offset:49152
	v_pk_add_f32 v[170:171], v[170:171], v[172:173]
	s_nop 0
	v_add_f32_e32 v252, v170, v171
	s_waitcnt lgkmcnt(0)
	ds_bpermute_b32 v254, v246, v252
	s_waitcnt lgkmcnt(0)
	v_add_f32_e32 v252, v252, v254
	ds_bpermute_b32 v254, v247, v252
	s_waitcnt lgkmcnt(0)
	v_add_f32_e32 v252, v252, v254
	ds_bpermute_b32 v254, v248, v252
	s_waitcnt lgkmcnt(0)
	v_add_f32_e32 v252, v252, v254
	ds_bpermute_b32 v254, v249, v252
	s_waitcnt lgkmcnt(0)
	v_add_f32_e32 v252, v252, v254
	ds_bpermute_b32 v254, v250, v252
	s_waitcnt lgkmcnt(0)
	v_add_f32_e32 v252, v252, v254
	ds_bpermute_b32 v254, v251, v252
	s_waitcnt lgkmcnt(0)
	v_add_f32_e32 v252, v252, v254
	v_mov_b32_e32 v254, 0x358637bd
	v_fmac_f32_e32 v254, 0x39800000, v252
	v_mul_f32_e32 v252, 0x4b800000, v254
	v_cmp_gt_f32_e32 vcc, s32, v254
	s_nop 1
	v_cndmask_b32_e32 v254, v254, v252, vcc
	v_rsq_f32_e32 v254, v254
	s_nop 0
	v_mul_f32_e32 v252, 0x45800000, v254
	v_cndmask_b32_e32 v252, v254, v252, vcc
	s_add_u32 s16, s16, 0x1000000
	s_addc_u32 s17, s17, 0
	global_load_dwordx2 v[130:131], v244, s[16:17] offset:0
	global_load_dwordx2 v[132:133], v244, s[16:17] offset:512
	global_load_dwordx2 v[134:135], v244, s[16:17] offset:1024
	global_load_dwordx2 v[136:137], v244, s[16:17] offset:1536
	global_load_dwordx2 v[138:139], v244, s[16:17] offset:2048
	global_load_dwordx2 v[140:141], v244, s[16:17] offset:2560
	global_load_dwordx2 v[142:143], v244, s[16:17] offset:3072
	global_load_dwordx2 v[144:145], v244, s[16:17] offset:3584
	global_load_dwordx2 v[146:147], v245, s[16:17] offset:0
	global_load_dwordx2 v[148:149], v245, s[16:17] offset:512
	global_load_dwordx2 v[150:151], v245, s[16:17] offset:1024
	global_load_dwordx2 v[152:153], v245, s[16:17] offset:1536
	global_load_dwordx2 v[154:155], v245, s[16:17] offset:2048
	global_load_dwordx2 v[156:157], v245, s[16:17] offset:2560
	global_load_dwordx2 v[158:159], v245, s[16:17] offset:3072
	global_load_dwordx2 v[160:161], v245, s[16:17] offset:3584
	ds_read_b128 v[226:229], v238 offset:17408
	ds_read_b128 v[230:233], v239 offset:33792
	ds_read_b128 v[234:237], v239 offset:50176
	s_waitcnt lgkmcnt(3)
	v_pk_mul_f32 v[2:3], v[2:3], v[252:253] op_sel_hi:[1,0]
	v_pk_mul_f32 v[4:5], v[4:5], v[252:253] op_sel_hi:[1,0]
	v_pk_mul_f32 v[2:3], v[2:3], v[214:215]
	v_pk_mul_f32 v[4:5], v[4:5], v[216:217]
	v_pk_add_f32 v[222:223], v[222:223], 1.0 op_sel_hi:[1,0]
	v_pk_add_f32 v[224:225], v[224:225], 1.0 op_sel_hi:[1,0]
	v_pk_fma_f32 v[2:3], v[2:3], v[222:223], v[218:219]
	v_pk_fma_f32 v[4:5], v[4:5], v[224:225], v[220:221]
	s_nop 0
	v_cvt_pk_bf16_f32 v2, v2, v3
	v_cvt_pk_bf16_f32 v3, v4, v5
	global_store_dwordx2 v244, v[2:3], s[38:39] offset:0
	ds_read_b128 v[214:217], v238 offset:18432
	ds_read_b128 v[218:221], v239 offset:34816
	ds_read_b128 v[222:225], v239 offset:51200
	s_waitcnt lgkmcnt(3)
	v_pk_mul_f32 v[6:7], v[6:7], v[252:253] op_sel_hi:[1,0]
	v_pk_mul_f32 v[8:9], v[8:9], v[252:253] op_sel_hi:[1,0]
	v_pk_mul_f32 v[6:7], v[6:7], v[226:227]
	v_pk_mul_f32 v[8:9], v[8:9], v[228:229]
	v_pk_add_f32 v[234:235], v[234:235], 1.0 op_sel_hi:[1,0]
	v_pk_add_f32 v[236:237], v[236:237], 1.0 op_sel_hi:[1,0]
	v_pk_fma_f32 v[6:7], v[6:7], v[234:235], v[230:231]
	v_pk_fma_f32 v[8:9], v[8:9], v[236:237], v[232:233]
	s_nop 0
	v_cvt_pk_bf16_f32 v6, v6, v7
	v_cvt_pk_bf16_f32 v7, v8, v9
	global_store_dwordx2 v244, v[6:7], s[38:39] offset:512
	ds_read_b128 v[226:229], v238 offset:19456
	ds_read_b128 v[230:233], v239 offset:35840
	ds_read_b128 v[234:237], v239 offset:52224
	s_waitcnt lgkmcnt(3)
	v_pk_mul_f32 v[10:11], v[10:11], v[252:253] op_sel_hi:[1,0]
	v_pk_mul_f32 v[12:13], v[12:13], v[252:253] op_sel_hi:[1,0]
	v_pk_mul_f32 v[10:11], v[10:11], v[214:215]
	v_pk_mul_f32 v[12:13], v[12:13], v[216:217]
	v_pk_add_f32 v[222:223], v[222:223], 1.0 op_sel_hi:[1,0]
	v_pk_add_f32 v[224:225], v[224:225], 1.0 op_sel_hi:[1,0]
	v_pk_fma_f32 v[10:11], v[10:11], v[222:223], v[218:219]
	v_pk_fma_f32 v[12:13], v[12:13], v[224:225], v[220:221]
	s_nop 0
	v_cvt_pk_bf16_f32 v10, v10, v11
	v_cvt_pk_bf16_f32 v11, v12, v13
	global_store_dwordx2 v244, v[10:11], s[38:39] offset:1024
	ds_read_b128 v[214:217], v238 offset:20480
	ds_read_b128 v[218:221], v239 offset:36864
	ds_read_b128 v[222:225], v239 offset:53248
	s_waitcnt lgkmcnt(3)
	v_pk_mul_f32 v[14:15], v[14:15], v[252:253] op_sel_hi:[1,0]
	v_pk_mul_f32 v[16:17], v[16:17], v[252:253] op_sel_hi:[1,0]
	v_pk_mul_f32 v[14:15], v[14:15], v[226:227]
	v_pk_mul_f32 v[16:17], v[16:17], v[228:229]
	v_pk_add_f32 v[234:235], v[234:235], 1.0 op_sel_hi:[1,0]
	v_pk_add_f32 v[236:237], v[236:237], 1.0 op_sel_hi:[1,0]
	v_pk_fma_f32 v[14:15], v[14:15], v[234:235], v[230:231]
	v_pk_fma_f32 v[16:17], v[16:17], v[236:237], v[232:233]
	s_nop 0
	v_cvt_pk_bf16_f32 v14, v14, v15
	v_cvt_pk_bf16_f32 v15, v16, v17
	global_store_dwordx2 v244, v[14:15], s[38:39] offset:1536
	ds_read_b128 v[226:229], v238 offset:21504
	ds_read_b128 v[230:233], v239 offset:37888
	ds_read_b128 v[234:237], v239 offset:54272
	s_waitcnt lgkmcnt(3)
	v_pk_mul_f32 v[18:19], v[18:19], v[252:253] op_sel_hi:[1,0]
	v_pk_mul_f32 v[20:21], v[20:21], v[252:253] op_sel_hi:[1,0]
	v_pk_mul_f32 v[18:19], v[18:19], v[214:215]
	v_pk_mul_f32 v[20:21], v[20:21], v[216:217]
	v_pk_add_f32 v[222:223], v[222:223], 1.0 op_sel_hi:[1,0]
	v_pk_add_f32 v[224:225], v[224:225], 1.0 op_sel_hi:[1,0]
	v_pk_fma_f32 v[18:19], v[18:19], v[222:223], v[218:219]
	v_pk_fma_f32 v[20:21], v[20:21], v[224:225], v[220:221]
	s_nop 0
	v_cvt_pk_bf16_f32 v18, v18, v19
	v_cvt_pk_bf16_f32 v19, v20, v21
	global_store_dwordx2 v244, v[18:19], s[38:39] offset:2048
	ds_read_b128 v[214:217], v238 offset:22528
	ds_read_b128 v[218:221], v239 offset:38912
	ds_read_b128 v[222:225], v239 offset:55296
	s_waitcnt lgkmcnt(3)
	v_pk_mul_f32 v[22:23], v[22:23], v[252:253] op_sel_hi:[1,0]
	v_pk_mul_f32 v[24:25], v[24:25], v[252:253] op_sel_hi:[1,0]
	v_pk_mul_f32 v[22:23], v[22:23], v[226:227]
	v_pk_mul_f32 v[24:25], v[24:25], v[228:229]
	v_pk_add_f32 v[234:235], v[234:235], 1.0 op_sel_hi:[1,0]
	v_pk_add_f32 v[236:237], v[236:237], 1.0 op_sel_hi:[1,0]
	v_pk_fma_f32 v[22:23], v[22:23], v[234:235], v[230:231]
	v_pk_fma_f32 v[24:25], v[24:25], v[236:237], v[232:233]
	s_nop 0
	v_cvt_pk_bf16_f32 v22, v22, v23
	v_cvt_pk_bf16_f32 v23, v24, v25
	global_store_dwordx2 v244, v[22:23], s[38:39] offset:2560
	ds_read_b128 v[226:229], v238 offset:23552
	ds_read_b128 v[230:233], v239 offset:39936
	ds_read_b128 v[234:237], v239 offset:56320
	s_waitcnt lgkmcnt(3)
	v_pk_mul_f32 v[26:27], v[26:27], v[252:253] op_sel_hi:[1,0]
	v_pk_mul_f32 v[28:29], v[28:29], v[252:253] op_sel_hi:[1,0]
	v_pk_mul_f32 v[26:27], v[26:27], v[214:215]
	v_pk_mul_f32 v[28:29], v[28:29], v[216:217]
	v_pk_add_f32 v[222:223], v[222:223], 1.0 op_sel_hi:[1,0]
	v_pk_add_f32 v[224:225], v[224:225], 1.0 op_sel_hi:[1,0]
	v_pk_fma_f32 v[26:27], v[26:27], v[222:223], v[218:219]
	v_pk_fma_f32 v[28:29], v[28:29], v[224:225], v[220:221]
	s_nop 0
	v_cvt_pk_bf16_f32 v26, v26, v27
	v_cvt_pk_bf16_f32 v27, v28, v29
	global_store_dwordx2 v244, v[26:27], s[38:39] offset:3072
	ds_read_b128 v[214:217], v238 offset:24576
	ds_read_b128 v[218:221], v239 offset:40960
	ds_read_b128 v[222:225], v239 offset:57344
	s_waitcnt lgkmcnt(3)
	v_pk_mul_f32 v[30:31], v[30:31], v[252:253] op_sel_hi:[1,0]
	v_pk_mul_f32 v[32:33], v[32:33], v[252:253] op_sel_hi:[1,0]
	v_pk_mul_f32 v[30:31], v[30:31], v[226:227]
	v_pk_mul_f32 v[32:33], v[32:33], v[228:229]
	v_pk_add_f32 v[234:235], v[234:235], 1.0 op_sel_hi:[1,0]
	v_pk_add_f32 v[236:237], v[236:237], 1.0 op_sel_hi:[1,0]
	v_pk_fma_f32 v[30:31], v[30:31], v[234:235], v[230:231]
	v_pk_fma_f32 v[32:33], v[32:33], v[236:237], v[232:233]
	s_nop 0
	v_cvt_pk_bf16_f32 v30, v30, v31
	v_cvt_pk_bf16_f32 v31, v32, v33
	global_store_dwordx2 v244, v[30:31], s[38:39] offset:3584
	ds_read_b128 v[226:229], v238 offset:25600
	ds_read_b128 v[230:233], v239 offset:41984
	ds_read_b128 v[234:237], v239 offset:58368
	s_waitcnt lgkmcnt(3)
	v_pk_mul_f32 v[34:35], v[34:35], v[252:253] op_sel_hi:[1,0]
	v_pk_mul_f32 v[36:37], v[36:37], v[252:253] op_sel_hi:[1,0]
	v_pk_mul_f32 v[34:35], v[34:35], v[214:215]
	v_pk_mul_f32 v[36:37], v[36:37], v[216:217]
	v_pk_add_f32 v[222:223], v[222:223], 1.0 op_sel_hi:[1,0]
	v_pk_add_f32 v[224:225], v[224:225], 1.0 op_sel_hi:[1,0]
	v_pk_fma_f32 v[34:35], v[34:35], v[222:223], v[218:219]
	v_pk_fma_f32 v[36:37], v[36:37], v[224:225], v[220:221]
	s_nop 0
	v_cvt_pk_bf16_f32 v34, v34, v35
	v_cvt_pk_bf16_f32 v35, v36, v37
	global_store_dwordx2 v245, v[34:35], s[38:39] offset:0
	ds_read_b128 v[214:217], v238 offset:26624
	ds_read_b128 v[218:221], v239 offset:43008
	ds_read_b128 v[222:225], v239 offset:59392
	s_waitcnt lgkmcnt(3)
	v_pk_mul_f32 v[38:39], v[38:39], v[252:253] op_sel_hi:[1,0]
	v_pk_mul_f32 v[40:41], v[40:41], v[252:253] op_sel_hi:[1,0]
	v_pk_mul_f32 v[38:39], v[38:39], v[226:227]
	v_pk_mul_f32 v[40:41], v[40:41], v[228:229]
	v_pk_add_f32 v[234:235], v[234:235], 1.0 op_sel_hi:[1,0]
	v_pk_add_f32 v[236:237], v[236:237], 1.0 op_sel_hi:[1,0]
	v_pk_fma_f32 v[38:39], v[38:39], v[234:235], v[230:231]
	v_pk_fma_f32 v[40:41], v[40:41], v[236:237], v[232:233]
	s_nop 0
	v_cvt_pk_bf16_f32 v38, v38, v39
	v_cvt_pk_bf16_f32 v39, v40, v41
	global_store_dwordx2 v245, v[38:39], s[38:39] offset:512
	ds_read_b128 v[226:229], v238 offset:27648
	ds_read_b128 v[230:233], v239 offset:44032
	ds_read_b128 v[234:237], v239 offset:60416
	s_waitcnt lgkmcnt(3)
	v_pk_mul_f32 v[42:43], v[42:43], v[252:253] op_sel_hi:[1,0]
	v_pk_mul_f32 v[44:45], v[44:45], v[252:253] op_sel_hi:[1,0]
	v_pk_mul_f32 v[42:43], v[42:43], v[214:215]
	v_pk_mul_f32 v[44:45], v[44:45], v[216:217]
	v_pk_add_f32 v[222:223], v[222:223], 1.0 op_sel_hi:[1,0]
	v_pk_add_f32 v[224:225], v[224:225], 1.0 op_sel_hi:[1,0]
	v_pk_fma_f32 v[42:43], v[42:43], v[222:223], v[218:219]
	v_pk_fma_f32 v[44:45], v[44:45], v[224:225], v[220:221]
	s_nop 0
	v_cvt_pk_bf16_f32 v42, v42, v43
	v_cvt_pk_bf16_f32 v43, v44, v45
	global_store_dwordx2 v245, v[42:43], s[38:39] offset:1024
	ds_read_b128 v[214:217], v238 offset:28672
	ds_read_b128 v[218:221], v239 offset:45056
	ds_read_b128 v[222:225], v239 offset:61440
	s_waitcnt lgkmcnt(3)
	v_pk_mul_f32 v[46:47], v[46:47], v[252:253] op_sel_hi:[1,0]
	v_pk_mul_f32 v[48:49], v[48:49], v[252:253] op_sel_hi:[1,0]
	v_pk_mul_f32 v[46:47], v[46:47], v[226:227]
	v_pk_mul_f32 v[48:49], v[48:49], v[228:229]
	v_pk_add_f32 v[234:235], v[234:235], 1.0 op_sel_hi:[1,0]
	v_pk_add_f32 v[236:237], v[236:237], 1.0 op_sel_hi:[1,0]
	v_pk_fma_f32 v[46:47], v[46:47], v[234:235], v[230:231]
	v_pk_fma_f32 v[48:49], v[48:49], v[236:237], v[232:233]
	s_nop 0
	v_cvt_pk_bf16_f32 v46, v46, v47
	v_cvt_pk_bf16_f32 v47, v48, v49
	global_store_dwordx2 v245, v[46:47], s[38:39] offset:1536
	ds_read_b128 v[226:229], v238 offset:29696
	ds_read_b128 v[230:233], v239 offset:46080
	ds_read_b128 v[234:237], v239 offset:62464
	s_waitcnt lgkmcnt(3)
	v_pk_mul_f32 v[50:51], v[50:51], v[252:253] op_sel_hi:[1,0]
	v_pk_mul_f32 v[52:53], v[52:53], v[252:253] op_sel_hi:[1,0]
	v_pk_mul_f32 v[50:51], v[50:51], v[214:215]
	v_pk_mul_f32 v[52:53], v[52:53], v[216:217]
	v_pk_add_f32 v[222:223], v[222:223], 1.0 op_sel_hi:[1,0]
	v_pk_add_f32 v[224:225], v[224:225], 1.0 op_sel_hi:[1,0]
	v_pk_fma_f32 v[50:51], v[50:51], v[222:223], v[218:219]
	v_pk_fma_f32 v[52:53], v[52:53], v[224:225], v[220:221]
	s_nop 0
	v_cvt_pk_bf16_f32 v50, v50, v51
	v_cvt_pk_bf16_f32 v51, v52, v53
	global_store_dwordx2 v245, v[50:51], s[38:39] offset:2048
	ds_read_b128 v[214:217], v238 offset:30720
	ds_read_b128 v[218:221], v239 offset:47104
	ds_read_b128 v[222:225], v239 offset:63488
	s_waitcnt lgkmcnt(3)
	v_pk_mul_f32 v[54:55], v[54:55], v[252:253] op_sel_hi:[1,0]
	v_pk_mul_f32 v[56:57], v[56:57], v[252:253] op_sel_hi:[1,0]
	v_pk_mul_f32 v[54:55], v[54:55], v[226:227]
	v_pk_mul_f32 v[56:57], v[56:57], v[228:229]
	v_pk_add_f32 v[234:235], v[234:235], 1.0 op_sel_hi:[1,0]
	v_pk_add_f32 v[236:237], v[236:237], 1.0 op_sel_hi:[1,0]
	v_pk_fma_f32 v[54:55], v[54:55], v[234:235], v[230:231]
	v_pk_fma_f32 v[56:57], v[56:57], v[236:237], v[232:233]
	s_nop 0
	v_cvt_pk_bf16_f32 v54, v54, v55
	v_cvt_pk_bf16_f32 v55, v56, v57
	global_store_dwordx2 v245, v[54:55], s[38:39] offset:2560
	ds_read_b128 v[226:229], v238 offset:31744
	ds_read_b128 v[230:233], v239 offset:48128
	ds_read_b128 v[234:237], v239 offset:64512
	s_waitcnt lgkmcnt(3)
	v_pk_mul_f32 v[58:59], v[58:59], v[252:253] op_sel_hi:[1,0]
	v_pk_mul_f32 v[60:61], v[60:61], v[252:253] op_sel_hi:[1,0]
	v_pk_mul_f32 v[58:59], v[58:59], v[214:215]
	v_pk_mul_f32 v[60:61], v[60:61], v[216:217]
	v_pk_add_f32 v[222:223], v[222:223], 1.0 op_sel_hi:[1,0]
	v_pk_add_f32 v[224:225], v[224:225], 1.0 op_sel_hi:[1,0]
	v_pk_fma_f32 v[58:59], v[58:59], v[222:223], v[218:219]
	v_pk_fma_f32 v[60:61], v[60:61], v[224:225], v[220:221]
	s_nop 0
	v_cvt_pk_bf16_f32 v58, v58, v59
	v_cvt_pk_bf16_f32 v59, v60, v61
	global_store_dwordx2 v245, v[58:59], s[38:39] offset:3072
	s_waitcnt lgkmcnt(0)
	v_pk_mul_f32 v[62:63], v[62:63], v[252:253] op_sel_hi:[1,0]
	v_pk_mul_f32 v[64:65], v[64:65], v[252:253] op_sel_hi:[1,0]
	v_pk_mul_f32 v[62:63], v[62:63], v[226:227]
	v_pk_mul_f32 v[64:65], v[64:65], v[228:229]
	v_pk_add_f32 v[234:235], v[234:235], 1.0 op_sel_hi:[1,0]
	v_pk_add_f32 v[236:237], v[236:237], 1.0 op_sel_hi:[1,0]
	v_pk_fma_f32 v[62:63], v[62:63], v[234:235], v[230:231]
	v_pk_fma_f32 v[64:65], v[64:65], v[236:237], v[232:233]
	s_nop 0
	v_cvt_pk_bf16_f32 v62, v62, v63
	v_cvt_pk_bf16_f32 v63, v64, v65
	global_store_dwordx2 v245, v[62:63], s[38:39] offset:3584
	s_add_u32 s22, s22, 0x1000000
	s_addc_u32 s23, s23, 0
	s_add_u32 s38, s38, 0x1000000
	s_addc_u32 s39, s39, 0
	s_waitcnt vmcnt(16)
	s_barrier
	ds_read_b128 v[214:217], v238 offset:0
	ds_read_b128 v[218:221], v238 offset:32768
	v_lshlrev_b32_e32 v162, 16, v130
	v_and_b32_e32 v163, 0xffff0000, v130
	v_lshlrev_b32_e32 v164, 16, v131
	v_and_b32_e32 v165, 0xffff0000, v131
	v_pk_mul_f32 v[170:171], v[162:163], v[162:163]
	v_pk_mul_f32 v[172:173], v[164:165], v[164:165]
	v_lshlrev_b32_e32 v166, 16, v132
	v_and_b32_e32 v167, 0xffff0000, v132
	v_lshlrev_b32_e32 v168, 16, v133
	v_and_b32_e32 v169, 0xffff0000, v133
	v_pk_fma_f32 v[170:171], v[166:167], v[166:167], v[170:171]
	v_pk_fma_f32 v[172:173], v[168:169], v[168:169], v[172:173]
	v_lshlrev_b32_e32 v162, 16, v134
	v_and_b32_e32 v163, 0xffff0000, v134
	v_lshlrev_b32_e32 v164, 16, v135
	v_and_b32_e32 v165, 0xffff0000, v135
	v_pk_fma_f32 v[170:171], v[162:163], v[162:163], v[170:171]
	v_pk_fma_f32 v[172:173], v[164:165], v[164:165], v[172:173]
	v_lshlrev_b32_e32 v166, 16, v136
	v_and_b32_e32 v167, 0xffff0000, v136
	v_lshlrev_b32_e32 v168, 16, v137
	v_and_b32_e32 v169, 0xffff0000, v137
	v_pk_fma_f32 v[170:171], v[166:167], v[166:167], v[170:171]
	v_pk_fma_f32 v[172:173], v[168:169], v[168:169], v[172:173]
	v_lshlrev_b32_e32 v162, 16, v138
	v_and_b32_e32 v163, 0xffff0000, v138
	v_lshlrev_b32_e32 v164, 16, v139
	v_and_b32_e32 v165, 0xffff0000, v139
	v_pk_fma_f32 v[170:171], v[162:163], v[162:163], v[170:171]
	v_pk_fma_f32 v[172:173], v[164:165], v[164:165], v[172:173]
	v_lshlrev_b32_e32 v166, 16, v140
	v_and_b32_e32 v167, 0xffff0000, v140
	v_lshlrev_b32_e32 v168, 16, v141
	v_and_b32_e32 v169, 0xffff0000, v141
	v_pk_fma_f32 v[170:171], v[166:167], v[166:167], v[170:171]
	v_pk_fma_f32 v[172:173], v[168:169], v[168:169], v[172:173]
	v_lshlrev_b32_e32 v162, 16, v142
	v_and_b32_e32 v163, 0xffff0000, v142
	v_lshlrev_b32_e32 v164, 16, v143
	v_and_b32_e32 v165, 0xffff0000, v143
	v_pk_fma_f32 v[170:171], v[162:163], v[162:163], v[170:171]
	v_pk_fma_f32 v[172:173], v[164:165], v[164:165], v[172:173]
	v_lshlrev_b32_e32 v166, 16, v144
	v_and_b32_e32 v167, 0xffff0000, v144
	v_lshlrev_b32_e32 v168, 16, v145
	v_and_b32_e32 v169, 0xffff0000, v145
	v_pk_fma_f32 v[170:171], v[166:167], v[166:167], v[170:171]
	v_pk_fma_f32 v[172:173], v[168:169], v[168:169], v[172:173]
	v_lshlrev_b32_e32 v162, 16, v146
	v_and_b32_e32 v163, 0xffff0000, v146
	v_lshlrev_b32_e32 v164, 16, v147
	v_and_b32_e32 v165, 0xffff0000, v147
	v_pk_fma_f32 v[170:171], v[162:163], v[162:163], v[170:171]
	v_pk_fma_f32 v[172:173], v[164:165], v[164:165], v[172:173]
	v_lshlrev_b32_e32 v166, 16, v148
	v_and_b32_e32 v167, 0xffff0000, v148
	v_lshlrev_b32_e32 v168, 16, v149
	v_and_b32_e32 v169, 0xffff0000, v149
	v_pk_fma_f32 v[170:171], v[166:167], v[166:167], v[170:171]
	v_pk_fma_f32 v[172:173], v[168:169], v[168:169], v[172:173]
	v_lshlrev_b32_e32 v162, 16, v150
	v_and_b32_e32 v163, 0xffff0000, v150
	v_lshlrev_b32_e32 v164, 16, v151
	v_and_b32_e32 v165, 0xffff0000, v151
	v_pk_fma_f32 v[170:171], v[162:163], v[162:163], v[170:171]
	v_pk_fma_f32 v[172:173], v[164:165], v[164:165], v[172:173]
	v_lshlrev_b32_e32 v166, 16, v152
	v_and_b32_e32 v167, 0xffff0000, v152
	v_lshlrev_b32_e32 v168, 16, v153
	v_and_b32_e32 v169, 0xffff0000, v153
	v_pk_fma_f32 v[170:171], v[166:167], v[166:167], v[170:171]
	v_pk_fma_f32 v[172:173], v[168:169], v[168:169], v[172:173]
	v_lshlrev_b32_e32 v162, 16, v154
	v_and_b32_e32 v163, 0xffff0000, v154
	v_lshlrev_b32_e32 v164, 16, v155
	v_and_b32_e32 v165, 0xffff0000, v155
	v_pk_fma_f32 v[170:171], v[162:163], v[162:163], v[170:171]
	v_pk_fma_f32 v[172:173], v[164:165], v[164:165], v[172:173]
	v_lshlrev_b32_e32 v166, 16, v156
	v_and_b32_e32 v167, 0xffff0000, v156
	v_lshlrev_b32_e32 v168, 16, v157
	v_and_b32_e32 v169, 0xffff0000, v157
	v_pk_fma_f32 v[170:171], v[166:167], v[166:167], v[170:171]
	v_pk_fma_f32 v[172:173], v[168:169], v[168:169], v[172:173]
	v_lshlrev_b32_e32 v162, 16, v158
	v_and_b32_e32 v163, 0xffff0000, v158
	v_lshlrev_b32_e32 v164, 16, v159
	v_and_b32_e32 v165, 0xffff0000, v159
	v_pk_fma_f32 v[170:171], v[162:163], v[162:163], v[170:171]
	v_pk_fma_f32 v[172:173], v[164:165], v[164:165], v[172:173]
	v_lshlrev_b32_e32 v166, 16, v160
	v_and_b32_e32 v167, 0xffff0000, v160
	v_lshlrev_b32_e32 v168, 16, v161
	v_and_b32_e32 v169, 0xffff0000, v161
	v_pk_fma_f32 v[170:171], v[166:167], v[166:167], v[170:171]
	v_pk_fma_f32 v[172:173], v[168:169], v[168:169], v[172:173]
	v_pk_add_f32 v[170:171], v[170:171], v[172:173]
	s_nop 0
	v_add_f32_e32 v252, v170, v171
	s_waitcnt lgkmcnt(0)
	ds_bpermute_b32 v254, v246, v252
	s_waitcnt lgkmcnt(0)
	v_add_f32_e32 v252, v252, v254
	ds_bpermute_b32 v254, v247, v252
	s_waitcnt lgkmcnt(0)
	v_add_f32_e32 v252, v252, v254
	ds_bpermute_b32 v254, v248, v252
	s_waitcnt lgkmcnt(0)
	v_add_f32_e32 v252, v252, v254
	ds_bpermute_b32 v254, v249, v252
	s_waitcnt lgkmcnt(0)
	v_add_f32_e32 v252, v252, v254
	ds_bpermute_b32 v254, v250, v252
	s_waitcnt lgkmcnt(0)
	v_add_f32_e32 v252, v252, v254
	ds_bpermute_b32 v254, v251, v252
	s_waitcnt lgkmcnt(0)
	v_add_f32_e32 v252, v252, v254
	v_mov_b32_e32 v254, 0x358637bd
	v_fmac_f32_e32 v254, 0x39800000, v252
	v_mul_f32_e32 v252, 0x4b800000, v254
	v_cmp_gt_f32_e32 vcc, s32, v254
	s_nop 1
	v_cndmask_b32_e32 v254, v254, v252, vcc
	v_rsq_f32_e32 v254, v254
	s_nop 0
	v_mul_f32_e32 v252, 0x45800000, v254
	v_cndmask_b32_e32 v252, v254, v252, vcc
	ds_read_b128 v[226:229], v238 offset:1024
	ds_read_b128 v[230:233], v238 offset:33792
	s_waitcnt lgkmcnt(2)
	v_lshlrev_b32_e32 v162, 16, v130
	v_and_b32_e32 v163, 0xffff0000, v130
	v_lshlrev_b32_e32 v164, 16, v131
	v_and_b32_e32 v165, 0xffff0000, v131
	v_pk_mul_f32 v[162:163], v[162:163], v[252:253] op_sel_hi:[1,0]
	v_pk_mul_f32 v[164:165], v[164:165], v[252:253] op_sel_hi:[1,0]
	v_pk_mul_f32 v[162:163], v[162:163], v[214:215]
	v_pk_mul_f32 v[164:165], v[164:165], v[216:217]
	v_pk_fma_f32 v[66:67], v[218:219], v[162:163], v[66:67]
	v_pk_fma_f32 v[68:69], v[220:221], v[164:165], v[68:69]
	v_pk_mul_f32 v[170:171], v[66:67], v[66:67]
	v_pk_mul_f32 v[172:173], v[68:69], v[68:69]
	v_cvt_pk_bf16_f32 v166, v66, v67
	v_cvt_pk_bf16_f32 v167, v68, v69
	global_store_dwordx2 v244, v[166:167], s[22:23] offset:0
	ds_read_b128 v[214:217], v238 offset:2048
	ds_read_b128 v[218:221], v238 offset:34816
	s_waitcnt lgkmcnt(2)
	v_lshlrev_b32_e32 v162, 16, v132
	v_and_b32_e32 v163, 0xffff0000, v132
	v_lshlrev_b32_e32 v164, 16, v133
	v_and_b32_e32 v165, 0xffff0000, v133
	v_pk_mul_f32 v[162:163], v[162:163], v[252:253] op_sel_hi:[1,0]
	v_pk_mul_f32 v[164:165], v[164:165], v[252:253] op_sel_hi:[1,0]
	v_pk_mul_f32 v[162:163], v[162:163], v[226:227]
	v_pk_mul_f32 v[164:165], v[164:165], v[228:229]
	v_pk_fma_f32 v[70:71], v[230:231], v[162:163], v[70:71]
	v_pk_fma_f32 v[72:73], v[232:233], v[164:165], v[72:73]
	v_pk_fma_f32 v[170:171], v[70:71], v[70:71], v[170:171]
	v_pk_fma_f32 v[172:173], v[72:73], v[72:73], v[172:173]
	v_cvt_pk_bf16_f32 v168, v70, v71
	v_cvt_pk_bf16_f32 v169, v72, v73
	global_store_dwordx2 v244, v[168:169], s[22:23] offset:512
	ds_read_b128 v[226:229], v238 offset:3072
	ds_read_b128 v[230:233], v238 offset:35840
	s_waitcnt lgkmcnt(2)
	v_lshlrev_b32_e32 v162, 16, v134
	v_and_b32_e32 v163, 0xffff0000, v134
	v_lshlrev_b32_e32 v164, 16, v135
	v_and_b32_e32 v165, 0xffff0000, v135
	v_pk_mul_f32 v[162:163], v[162:163], v[252:253] op_sel_hi:[1,0]
	v_pk_mul_f32 v[164:165], v[164:165], v[252:253] op_sel_hi:[1,0]
	v_pk_mul_f32 v[162:163], v[162:163], v[214:215]
	v_pk_mul_f32 v[164:165], v[164:165], v[216:217]
	v_pk_fma_f32 v[74:75], v[218:219], v[162:163], v[74:75]
	v_pk_fma_f32 v[76:77], v[220:221], v[164:165], v[76:77]
	v_pk_fma_f32 v[170:171], v[74:75], v[74:75], v[170:171]
	v_pk_fma_f32 v[172:173], v[76:77], v[76:77], v[172:173]
	v_cvt_pk_bf16_f32 v166, v74, v75
	v_cvt_pk_bf16_f32 v167, v76, v77
	global_store_dwordx2 v244, v[166:167], s[22:23] offset:1024
	ds_read_b128 v[214:217], v238 offset:4096
	ds_read_b128 v[218:221], v238 offset:36864
	s_waitcnt lgkmcnt(2)
	v_lshlrev_b32_e32 v162, 16, v136
	v_and_b32_e32 v163, 0xffff0000, v136
	v_lshlrev_b32_e32 v164, 16, v137
	v_and_b32_e32 v165, 0xffff0000, v137
	v_pk_mul_f32 v[162:163], v[162:163], v[252:253] op_sel_hi:[1,0]
	v_pk_mul_f32 v[164:165], v[164:165], v[252:253] op_sel_hi:[1,0]
	v_pk_mul_f32 v[162:163], v[162:163], v[226:227]
	v_pk_mul_f32 v[164:165], v[164:165], v[228:229]
	v_pk_fma_f32 v[78:79], v[230:231], v[162:163], v[78:79]
	v_pk_fma_f32 v[80:81], v[232:233], v[164:165], v[80:81]
	v_pk_fma_f32 v[170:171], v[78:79], v[78:79], v[170:171]
	v_pk_fma_f32 v[172:173], v[80:81], v[80:81], v[172:173]
	v_cvt_pk_bf16_f32 v168, v78, v79
	v_cvt_pk_bf16_f32 v169, v80, v81
	global_store_dwordx2 v244, v[168:169], s[22:23] offset:1536
	ds_read_b128 v[226:229], v238 offset:5120
	ds_read_b128 v[230:233], v238 offset:37888
	s_waitcnt lgkmcnt(2)
	v_lshlrev_b32_e32 v162, 16, v138
	v_and_b32_e32 v163, 0xffff0000, v138
	v_lshlrev_b32_e32 v164, 16, v139
	v_and_b32_e32 v165, 0xffff0000, v139
	v_pk_mul_f32 v[162:163], v[162:163], v[252:253] op_sel_hi:[1,0]
	v_pk_mul_f32 v[164:165], v[164:165], v[252:253] op_sel_hi:[1,0]
	v_pk_mul_f32 v[162:163], v[162:163], v[214:215]
	v_pk_mul_f32 v[164:165], v[164:165], v[216:217]
	v_pk_fma_f32 v[82:83], v[218:219], v[162:163], v[82:83]
	v_pk_fma_f32 v[84:85], v[220:221], v[164:165], v[84:85]
	v_pk_fma_f32 v[170:171], v[82:83], v[82:83], v[170:171]
	v_pk_fma_f32 v[172:173], v[84:85], v[84:85], v[172:173]
	v_cvt_pk_bf16_f32 v166, v82, v83
	v_cvt_pk_bf16_f32 v167, v84, v85
	global_store_dwordx2 v244, v[166:167], s[22:23] offset:2048
	ds_read_b128 v[214:217], v238 offset:6144
	ds_read_b128 v[218:221], v238 offset:38912
	s_waitcnt lgkmcnt(2)
	v_lshlrev_b32_e32 v162, 16, v140
	v_and_b32_e32 v163, 0xffff0000, v140
	v_lshlrev_b32_e32 v164, 16, v141
	v_and_b32_e32 v165, 0xffff0000, v141
	v_pk_mul_f32 v[162:163], v[162:163], v[252:253] op_sel_hi:[1,0]
	v_pk_mul_f32 v[164:165], v[164:165], v[252:253] op_sel_hi:[1,0]
	v_pk_mul_f32 v[162:163], v[162:163], v[226:227]
	v_pk_mul_f32 v[164:165], v[164:165], v[228:229]
	v_pk_fma_f32 v[86:87], v[230:231], v[162:163], v[86:87]
	v_pk_fma_f32 v[88:89], v[232:233], v[164:165], v[88:89]
	v_pk_fma_f32 v[170:171], v[86:87], v[86:87], v[170:171]
	v_pk_fma_f32 v[172:173], v[88:89], v[88:89], v[172:173]
	v_cvt_pk_bf16_f32 v168, v86, v87
	v_cvt_pk_bf16_f32 v169, v88, v89
	global_store_dwordx2 v244, v[168:169], s[22:23] offset:2560
	ds_read_b128 v[226:229], v238 offset:7168
	ds_read_b128 v[230:233], v238 offset:39936
	s_waitcnt lgkmcnt(2)
	v_lshlrev_b32_e32 v162, 16, v142
	v_and_b32_e32 v163, 0xffff0000, v142
	v_lshlrev_b32_e32 v164, 16, v143
	v_and_b32_e32 v165, 0xffff0000, v143
	v_pk_mul_f32 v[162:163], v[162:163], v[252:253] op_sel_hi:[1,0]
	v_pk_mul_f32 v[164:165], v[164:165], v[252:253] op_sel_hi:[1,0]
	v_pk_mul_f32 v[162:163], v[162:163], v[214:215]
	v_pk_mul_f32 v[164:165], v[164:165], v[216:217]
	v_pk_fma_f32 v[90:91], v[218:219], v[162:163], v[90:91]
	v_pk_fma_f32 v[92:93], v[220:221], v[164:165], v[92:93]
	v_pk_fma_f32 v[170:171], v[90:91], v[90:91], v[170:171]
	v_pk_fma_f32 v[172:173], v[92:93], v[92:93], v[172:173]
	v_cvt_pk_bf16_f32 v166, v90, v91
	v_cvt_pk_bf16_f32 v167, v92, v93
	global_store_dwordx2 v244, v[166:167], s[22:23] offset:3072
	ds_read_b128 v[214:217], v238 offset:8192
	ds_read_b128 v[218:221], v238 offset:40960
	s_waitcnt lgkmcnt(2)
	v_lshlrev_b32_e32 v162, 16, v144
	v_and_b32_e32 v163, 0xffff0000, v144
	v_lshlrev_b32_e32 v164, 16, v145
	v_and_b32_e32 v165, 0xffff0000, v145
	v_pk_mul_f32 v[162:163], v[162:163], v[252:253] op_sel_hi:[1,0]
	v_pk_mul_f32 v[164:165], v[164:165], v[252:253] op_sel_hi:[1,0]
	v_pk_mul_f32 v[162:163], v[162:163], v[226:227]
	v_pk_mul_f32 v[164:165], v[164:165], v[228:229]
	v_pk_fma_f32 v[94:95], v[230:231], v[162:163], v[94:95]
	v_pk_fma_f32 v[96:97], v[232:233], v[164:165], v[96:97]
	v_pk_fma_f32 v[170:171], v[94:95], v[94:95], v[170:171]
	v_pk_fma_f32 v[172:173], v[96:97], v[96:97], v[172:173]
	v_cvt_pk_bf16_f32 v168, v94, v95
	v_cvt_pk_bf16_f32 v169, v96, v97
	global_store_dwordx2 v244, v[168:169], s[22:23] offset:3584
	ds_read_b128 v[226:229], v238 offset:9216
	ds_read_b128 v[230:233], v238 offset:41984
	s_waitcnt lgkmcnt(2)
	v_lshlrev_b32_e32 v162, 16, v146
	v_and_b32_e32 v163, 0xffff0000, v146
	v_lshlrev_b32_e32 v164, 16, v147
	v_and_b32_e32 v165, 0xffff0000, v147
	v_pk_mul_f32 v[162:163], v[162:163], v[252:253] op_sel_hi:[1,0]
	v_pk_mul_f32 v[164:165], v[164:165], v[252:253] op_sel_hi:[1,0]
	v_pk_mul_f32 v[162:163], v[162:163], v[214:215]
	v_pk_mul_f32 v[164:165], v[164:165], v[216:217]
	v_pk_fma_f32 v[98:99], v[218:219], v[162:163], v[98:99]
	v_pk_fma_f32 v[100:101], v[220:221], v[164:165], v[100:101]
	v_pk_fma_f32 v[170:171], v[98:99], v[98:99], v[170:171]
	v_pk_fma_f32 v[172:173], v[100:101], v[100:101], v[172:173]
	v_cvt_pk_bf16_f32 v166, v98, v99
	v_cvt_pk_bf16_f32 v167, v100, v101
	global_store_dwordx2 v245, v[166:167], s[22:23] offset:0
	ds_read_b128 v[214:217], v238 offset:10240
	ds_read_b128 v[218:221], v238 offset:43008
	s_waitcnt lgkmcnt(2)
	v_lshlrev_b32_e32 v162, 16, v148
	v_and_b32_e32 v163, 0xffff0000, v148
	v_lshlrev_b32_e32 v164, 16, v149
	v_and_b32_e32 v165, 0xffff0000, v149
	v_pk_mul_f32 v[162:163], v[162:163], v[252:253] op_sel_hi:[1,0]
	v_pk_mul_f32 v[164:165], v[164:165], v[252:253] op_sel_hi:[1,0]
	v_pk_mul_f32 v[162:163], v[162:163], v[226:227]
	v_pk_mul_f32 v[164:165], v[164:165], v[228:229]
	v_pk_fma_f32 v[102:103], v[230:231], v[162:163], v[102:103]
	v_pk_fma_f32 v[104:105], v[232:233], v[164:165], v[104:105]
	v_pk_fma_f32 v[170:171], v[102:103], v[102:103], v[170:171]
	v_pk_fma_f32 v[172:173], v[104:105], v[104:105], v[172:173]
	v_cvt_pk_bf16_f32 v168, v102, v103
	v_cvt_pk_bf16_f32 v169, v104, v105
	global_store_dwordx2 v245, v[168:169], s[22:23] offset:512
	ds_read_b128 v[226:229], v238 offset:11264
	ds_read_b128 v[230:233], v238 offset:44032
	s_waitcnt lgkmcnt(2)
	v_lshlrev_b32_e32 v162, 16, v150
	v_and_b32_e32 v163, 0xffff0000, v150
	v_lshlrev_b32_e32 v164, 16, v151
	v_and_b32_e32 v165, 0xffff0000, v151
	v_pk_mul_f32 v[162:163], v[162:163], v[252:253] op_sel_hi:[1,0]
	v_pk_mul_f32 v[164:165], v[164:165], v[252:253] op_sel_hi:[1,0]
	v_pk_mul_f32 v[162:163], v[162:163], v[214:215]
	v_pk_mul_f32 v[164:165], v[164:165], v[216:217]
	v_pk_fma_f32 v[106:107], v[218:219], v[162:163], v[106:107]
	v_pk_fma_f32 v[108:109], v[220:221], v[164:165], v[108:109]
	v_pk_fma_f32 v[170:171], v[106:107], v[106:107], v[170:171]
	v_pk_fma_f32 v[172:173], v[108:109], v[108:109], v[172:173]
	v_cvt_pk_bf16_f32 v166, v106, v107
	v_cvt_pk_bf16_f32 v167, v108, v109
	global_store_dwordx2 v245, v[166:167], s[22:23] offset:1024
	ds_read_b128 v[214:217], v238 offset:12288
	ds_read_b128 v[218:221], v238 offset:45056
	s_waitcnt lgkmcnt(2)
	v_lshlrev_b32_e32 v162, 16, v152
	v_and_b32_e32 v163, 0xffff0000, v152
	v_lshlrev_b32_e32 v164, 16, v153
	v_and_b32_e32 v165, 0xffff0000, v153
	v_pk_mul_f32 v[162:163], v[162:163], v[252:253] op_sel_hi:[1,0]
	v_pk_mul_f32 v[164:165], v[164:165], v[252:253] op_sel_hi:[1,0]
	v_pk_mul_f32 v[162:163], v[162:163], v[226:227]
	v_pk_mul_f32 v[164:165], v[164:165], v[228:229]
	v_pk_fma_f32 v[110:111], v[230:231], v[162:163], v[110:111]
	v_pk_fma_f32 v[112:113], v[232:233], v[164:165], v[112:113]
	v_pk_fma_f32 v[170:171], v[110:111], v[110:111], v[170:171]
	v_pk_fma_f32 v[172:173], v[112:113], v[112:113], v[172:173]
	v_cvt_pk_bf16_f32 v168, v110, v111
	v_cvt_pk_bf16_f32 v169, v112, v113
	global_store_dwordx2 v245, v[168:169], s[22:23] offset:1536
	ds_read_b128 v[226:229], v238 offset:13312
	ds_read_b128 v[230:233], v238 offset:46080
	s_waitcnt lgkmcnt(2)
	v_lshlrev_b32_e32 v162, 16, v154
	v_and_b32_e32 v163, 0xffff0000, v154
	v_lshlrev_b32_e32 v164, 16, v155
	v_and_b32_e32 v165, 0xffff0000, v155
	v_pk_mul_f32 v[162:163], v[162:163], v[252:253] op_sel_hi:[1,0]
	v_pk_mul_f32 v[164:165], v[164:165], v[252:253] op_sel_hi:[1,0]
	v_pk_mul_f32 v[162:163], v[162:163], v[214:215]
	v_pk_mul_f32 v[164:165], v[164:165], v[216:217]
	v_pk_fma_f32 v[114:115], v[218:219], v[162:163], v[114:115]
	v_pk_fma_f32 v[116:117], v[220:221], v[164:165], v[116:117]
	v_pk_fma_f32 v[170:171], v[114:115], v[114:115], v[170:171]
	v_pk_fma_f32 v[172:173], v[116:117], v[116:117], v[172:173]
	v_cvt_pk_bf16_f32 v166, v114, v115
	v_cvt_pk_bf16_f32 v167, v116, v117
	global_store_dwordx2 v245, v[166:167], s[22:23] offset:2048
	ds_read_b128 v[214:217], v238 offset:14336
	ds_read_b128 v[218:221], v238 offset:47104
	s_waitcnt lgkmcnt(2)
	v_lshlrev_b32_e32 v162, 16, v156
	v_and_b32_e32 v163, 0xffff0000, v156
	v_lshlrev_b32_e32 v164, 16, v157
	v_and_b32_e32 v165, 0xffff0000, v157
	v_pk_mul_f32 v[162:163], v[162:163], v[252:253] op_sel_hi:[1,0]
	v_pk_mul_f32 v[164:165], v[164:165], v[252:253] op_sel_hi:[1,0]
	v_pk_mul_f32 v[162:163], v[162:163], v[226:227]
	v_pk_mul_f32 v[164:165], v[164:165], v[228:229]
	v_pk_fma_f32 v[118:119], v[230:231], v[162:163], v[118:119]
	v_pk_fma_f32 v[120:121], v[232:233], v[164:165], v[120:121]
	v_pk_fma_f32 v[170:171], v[118:119], v[118:119], v[170:171]
	v_pk_fma_f32 v[172:173], v[120:121], v[120:121], v[172:173]
	v_cvt_pk_bf16_f32 v168, v118, v119
	v_cvt_pk_bf16_f32 v169, v120, v121
	global_store_dwordx2 v245, v[168:169], s[22:23] offset:2560
	ds_read_b128 v[226:229], v238 offset:15360
	ds_read_b128 v[230:233], v238 offset:48128
	s_waitcnt lgkmcnt(2)
	v_lshlrev_b32_e32 v162, 16, v158
	v_and_b32_e32 v163, 0xffff0000, v158
	v_lshlrev_b32_e32 v164, 16, v159
	v_and_b32_e32 v165, 0xffff0000, v159
	v_pk_mul_f32 v[162:163], v[162:163], v[252:253] op_sel_hi:[1,0]
	v_pk_mul_f32 v[164:165], v[164:165], v[252:253] op_sel_hi:[1,0]
	v_pk_mul_f32 v[162:163], v[162:163], v[214:215]
	v_pk_mul_f32 v[164:165], v[164:165], v[216:217]
	v_pk_fma_f32 v[122:123], v[218:219], v[162:163], v[122:123]
	v_pk_fma_f32 v[124:125], v[220:221], v[164:165], v[124:125]
	v_pk_fma_f32 v[170:171], v[122:123], v[122:123], v[170:171]
	v_pk_fma_f32 v[172:173], v[124:125], v[124:125], v[172:173]
	v_cvt_pk_bf16_f32 v166, v122, v123
	v_cvt_pk_bf16_f32 v167, v124, v125
	global_store_dwordx2 v245, v[166:167], s[22:23] offset:3072
	s_waitcnt lgkmcnt(0)
	v_lshlrev_b32_e32 v162, 16, v160
	v_and_b32_e32 v163, 0xffff0000, v160
	v_lshlrev_b32_e32 v164, 16, v161
	v_and_b32_e32 v165, 0xffff0000, v161
	v_pk_mul_f32 v[162:163], v[162:163], v[252:253] op_sel_hi:[1,0]
	v_pk_mul_f32 v[164:165], v[164:165], v[252:253] op_sel_hi:[1,0]
	v_pk_mul_f32 v[162:163], v[162:163], v[226:227]
	v_pk_mul_f32 v[164:165], v[164:165], v[228:229]
	v_pk_fma_f32 v[126:127], v[230:231], v[162:163], v[126:127]
	v_pk_fma_f32 v[128:129], v[232:233], v[164:165], v[128:129]
	v_pk_fma_f32 v[170:171], v[126:127], v[126:127], v[170:171]
	v_pk_fma_f32 v[172:173], v[128:129], v[128:129], v[172:173]
	v_cvt_pk_bf16_f32 v168, v126, v127
	v_cvt_pk_bf16_f32 v169, v128, v129
	global_store_dwordx2 v245, v[168:169], s[22:23] offset:3584
	ds_read_b128 v[214:217], v238 offset:16384
	ds_read_b128 v[218:221], v238 offset:49152
	ds_read_b128 v[222:225], v239 offset:0
	v_pk_add_f32 v[170:171], v[170:171], v[172:173]
	s_nop 0
	v_add_f32_e32 v252, v170, v171
	s_waitcnt lgkmcnt(0)
	ds_bpermute_b32 v254, v246, v252
	s_waitcnt lgkmcnt(0)
	v_add_f32_e32 v252, v252, v254
	ds_bpermute_b32 v254, v247, v252
	s_waitcnt lgkmcnt(0)
	v_add_f32_e32 v252, v252, v254
	ds_bpermute_b32 v254, v248, v252
	s_waitcnt lgkmcnt(0)
	v_add_f32_e32 v252, v252, v254
	ds_bpermute_b32 v254, v249, v252
	s_waitcnt lgkmcnt(0)
	v_add_f32_e32 v252, v252, v254
	ds_bpermute_b32 v254, v250, v252
	s_waitcnt lgkmcnt(0)
	v_add_f32_e32 v252, v252, v254
	ds_bpermute_b32 v254, v251, v252
	s_waitcnt lgkmcnt(0)
	v_add_f32_e32 v252, v252, v254
	v_mov_b32_e32 v254, 0x358637bd
	v_fmac_f32_e32 v254, 0x39800000, v252
	v_mul_f32_e32 v252, 0x4b800000, v254
	v_cmp_gt_f32_e32 vcc, s32, v254
	s_nop 1
	v_cndmask_b32_e32 v254, v254, v252, vcc
	v_rsq_f32_e32 v254, v254
	s_nop 0
	v_mul_f32_e32 v252, 0x45800000, v254
	v_cndmask_b32_e32 v252, v254, v252, vcc
	ds_read_b128 v[226:229], v238 offset:17408
	ds_read_b128 v[230:233], v238 offset:50176
	ds_read_b128 v[234:237], v239 offset:1024
	s_waitcnt lgkmcnt(3)
	v_pk_mul_f32 v[66:67], v[66:67], v[252:253] op_sel_hi:[1,0]
	v_pk_mul_f32 v[68:69], v[68:69], v[252:253] op_sel_hi:[1,0]
	v_pk_mul_f32 v[66:67], v[66:67], v[214:215]
	v_pk_mul_f32 v[68:69], v[68:69], v[216:217]
	v_pk_add_f32 v[222:223], v[222:223], 1.0 op_sel_hi:[1,0]
	v_pk_add_f32 v[224:225], v[224:225], 1.0 op_sel_hi:[1,0]
	v_pk_fma_f32 v[66:67], v[66:67], v[222:223], v[218:219]
	v_pk_fma_f32 v[68:69], v[68:69], v[224:225], v[220:221]
	s_nop 0
	v_cvt_pk_bf16_f32 v66, v66, v67
	v_cvt_pk_bf16_f32 v67, v68, v69
	global_store_dwordx2 v244, v[66:67], s[38:39] offset:0
	ds_read_b128 v[214:217], v238 offset:18432
	ds_read_b128 v[218:221], v238 offset:51200
	ds_read_b128 v[222:225], v239 offset:2048
	s_waitcnt lgkmcnt(3)
	v_pk_mul_f32 v[70:71], v[70:71], v[252:253] op_sel_hi:[1,0]
	v_pk_mul_f32 v[72:73], v[72:73], v[252:253] op_sel_hi:[1,0]
	v_pk_mul_f32 v[70:71], v[70:71], v[226:227]
	v_pk_mul_f32 v[72:73], v[72:73], v[228:229]
	v_pk_add_f32 v[234:235], v[234:235], 1.0 op_sel_hi:[1,0]
	v_pk_add_f32 v[236:237], v[236:237], 1.0 op_sel_hi:[1,0]
	v_pk_fma_f32 v[70:71], v[70:71], v[234:235], v[230:231]
	v_pk_fma_f32 v[72:73], v[72:73], v[236:237], v[232:233]
	s_nop 0
	v_cvt_pk_bf16_f32 v70, v70, v71
	v_cvt_pk_bf16_f32 v71, v72, v73
	global_store_dwordx2 v244, v[70:71], s[38:39] offset:512
	ds_read_b128 v[226:229], v238 offset:19456
	ds_read_b128 v[230:233], v238 offset:52224
	ds_read_b128 v[234:237], v239 offset:3072
	s_waitcnt lgkmcnt(3)
	v_pk_mul_f32 v[74:75], v[74:75], v[252:253] op_sel_hi:[1,0]
	v_pk_mul_f32 v[76:77], v[76:77], v[252:253] op_sel_hi:[1,0]
	v_pk_mul_f32 v[74:75], v[74:75], v[214:215]
	v_pk_mul_f32 v[76:77], v[76:77], v[216:217]
	v_pk_add_f32 v[222:223], v[222:223], 1.0 op_sel_hi:[1,0]
	v_pk_add_f32 v[224:225], v[224:225], 1.0 op_sel_hi:[1,0]
	v_pk_fma_f32 v[74:75], v[74:75], v[222:223], v[218:219]
	v_pk_fma_f32 v[76:77], v[76:77], v[224:225], v[220:221]
	s_nop 0
	v_cvt_pk_bf16_f32 v74, v74, v75
	v_cvt_pk_bf16_f32 v75, v76, v77
	global_store_dwordx2 v244, v[74:75], s[38:39] offset:1024
	ds_read_b128 v[214:217], v238 offset:20480
	ds_read_b128 v[218:221], v238 offset:53248
	ds_read_b128 v[222:225], v239 offset:4096
	s_waitcnt lgkmcnt(3)
	v_pk_mul_f32 v[78:79], v[78:79], v[252:253] op_sel_hi:[1,0]
	v_pk_mul_f32 v[80:81], v[80:81], v[252:253] op_sel_hi:[1,0]
	v_pk_mul_f32 v[78:79], v[78:79], v[226:227]
	v_pk_mul_f32 v[80:81], v[80:81], v[228:229]
	v_pk_add_f32 v[234:235], v[234:235], 1.0 op_sel_hi:[1,0]
	v_pk_add_f32 v[236:237], v[236:237], 1.0 op_sel_hi:[1,0]
	v_pk_fma_f32 v[78:79], v[78:79], v[234:235], v[230:231]
	v_pk_fma_f32 v[80:81], v[80:81], v[236:237], v[232:233]
	s_nop 0
	v_cvt_pk_bf16_f32 v78, v78, v79
	v_cvt_pk_bf16_f32 v79, v80, v81
	global_store_dwordx2 v244, v[78:79], s[38:39] offset:1536
	ds_read_b128 v[226:229], v238 offset:21504
	ds_read_b128 v[230:233], v238 offset:54272
	ds_read_b128 v[234:237], v239 offset:5120
	s_waitcnt lgkmcnt(3)
	v_pk_mul_f32 v[82:83], v[82:83], v[252:253] op_sel_hi:[1,0]
	v_pk_mul_f32 v[84:85], v[84:85], v[252:253] op_sel_hi:[1,0]
	v_pk_mul_f32 v[82:83], v[82:83], v[214:215]
	v_pk_mul_f32 v[84:85], v[84:85], v[216:217]
	v_pk_add_f32 v[222:223], v[222:223], 1.0 op_sel_hi:[1,0]
	v_pk_add_f32 v[224:225], v[224:225], 1.0 op_sel_hi:[1,0]
	v_pk_fma_f32 v[82:83], v[82:83], v[222:223], v[218:219]
	v_pk_fma_f32 v[84:85], v[84:85], v[224:225], v[220:221]
	s_nop 0
	v_cvt_pk_bf16_f32 v82, v82, v83
	v_cvt_pk_bf16_f32 v83, v84, v85
	global_store_dwordx2 v244, v[82:83], s[38:39] offset:2048
	ds_read_b128 v[214:217], v238 offset:22528
	ds_read_b128 v[218:221], v238 offset:55296
	ds_read_b128 v[222:225], v239 offset:6144
	s_waitcnt lgkmcnt(3)
	v_pk_mul_f32 v[86:87], v[86:87], v[252:253] op_sel_hi:[1,0]
	v_pk_mul_f32 v[88:89], v[88:89], v[252:253] op_sel_hi:[1,0]
	v_pk_mul_f32 v[86:87], v[86:87], v[226:227]
	v_pk_mul_f32 v[88:89], v[88:89], v[228:229]
	v_pk_add_f32 v[234:235], v[234:235], 1.0 op_sel_hi:[1,0]
	v_pk_add_f32 v[236:237], v[236:237], 1.0 op_sel_hi:[1,0]
	v_pk_fma_f32 v[86:87], v[86:87], v[234:235], v[230:231]
	v_pk_fma_f32 v[88:89], v[88:89], v[236:237], v[232:233]
	s_nop 0
	v_cvt_pk_bf16_f32 v86, v86, v87
	v_cvt_pk_bf16_f32 v87, v88, v89
	global_store_dwordx2 v244, v[86:87], s[38:39] offset:2560
	ds_read_b128 v[226:229], v238 offset:23552
	ds_read_b128 v[230:233], v238 offset:56320
	ds_read_b128 v[234:237], v239 offset:7168
	s_waitcnt lgkmcnt(3)
	v_pk_mul_f32 v[90:91], v[90:91], v[252:253] op_sel_hi:[1,0]
	v_pk_mul_f32 v[92:93], v[92:93], v[252:253] op_sel_hi:[1,0]
	v_pk_mul_f32 v[90:91], v[90:91], v[214:215]
	v_pk_mul_f32 v[92:93], v[92:93], v[216:217]
	v_pk_add_f32 v[222:223], v[222:223], 1.0 op_sel_hi:[1,0]
	v_pk_add_f32 v[224:225], v[224:225], 1.0 op_sel_hi:[1,0]
	v_pk_fma_f32 v[90:91], v[90:91], v[222:223], v[218:219]
	v_pk_fma_f32 v[92:93], v[92:93], v[224:225], v[220:221]
	s_nop 0
	v_cvt_pk_bf16_f32 v90, v90, v91
	v_cvt_pk_bf16_f32 v91, v92, v93
	global_store_dwordx2 v244, v[90:91], s[38:39] offset:3072
	ds_read_b128 v[214:217], v238 offset:24576
	ds_read_b128 v[218:221], v238 offset:57344
	ds_read_b128 v[222:225], v239 offset:8192
	s_waitcnt lgkmcnt(3)
	v_pk_mul_f32 v[94:95], v[94:95], v[252:253] op_sel_hi:[1,0]
	v_pk_mul_f32 v[96:97], v[96:97], v[252:253] op_sel_hi:[1,0]
	v_pk_mul_f32 v[94:95], v[94:95], v[226:227]
	v_pk_mul_f32 v[96:97], v[96:97], v[228:229]
	v_pk_add_f32 v[234:235], v[234:235], 1.0 op_sel_hi:[1,0]
	v_pk_add_f32 v[236:237], v[236:237], 1.0 op_sel_hi:[1,0]
	v_pk_fma_f32 v[94:95], v[94:95], v[234:235], v[230:231]
	v_pk_fma_f32 v[96:97], v[96:97], v[236:237], v[232:233]
	s_nop 0
	v_cvt_pk_bf16_f32 v94, v94, v95
	v_cvt_pk_bf16_f32 v95, v96, v97
	global_store_dwordx2 v244, v[94:95], s[38:39] offset:3584
	ds_read_b128 v[226:229], v238 offset:25600
	ds_read_b128 v[230:233], v238 offset:58368
	ds_read_b128 v[234:237], v239 offset:9216
	s_waitcnt lgkmcnt(3)
	v_pk_mul_f32 v[98:99], v[98:99], v[252:253] op_sel_hi:[1,0]
	v_pk_mul_f32 v[100:101], v[100:101], v[252:253] op_sel_hi:[1,0]
	v_pk_mul_f32 v[98:99], v[98:99], v[214:215]
	v_pk_mul_f32 v[100:101], v[100:101], v[216:217]
	v_pk_add_f32 v[222:223], v[222:223], 1.0 op_sel_hi:[1,0]
	v_pk_add_f32 v[224:225], v[224:225], 1.0 op_sel_hi:[1,0]
	v_pk_fma_f32 v[98:99], v[98:99], v[222:223], v[218:219]
	v_pk_fma_f32 v[100:101], v[100:101], v[224:225], v[220:221]
	s_nop 0
	v_cvt_pk_bf16_f32 v98, v98, v99
	v_cvt_pk_bf16_f32 v99, v100, v101
	global_store_dwordx2 v245, v[98:99], s[38:39] offset:0
	ds_read_b128 v[214:217], v238 offset:26624
	ds_read_b128 v[218:221], v238 offset:59392
	ds_read_b128 v[222:225], v239 offset:10240
	s_waitcnt lgkmcnt(3)
	v_pk_mul_f32 v[102:103], v[102:103], v[252:253] op_sel_hi:[1,0]
	v_pk_mul_f32 v[104:105], v[104:105], v[252:253] op_sel_hi:[1,0]
	v_pk_mul_f32 v[102:103], v[102:103], v[226:227]
	v_pk_mul_f32 v[104:105], v[104:105], v[228:229]
	v_pk_add_f32 v[234:235], v[234:235], 1.0 op_sel_hi:[1,0]
	v_pk_add_f32 v[236:237], v[236:237], 1.0 op_sel_hi:[1,0]
	v_pk_fma_f32 v[102:103], v[102:103], v[234:235], v[230:231]
	v_pk_fma_f32 v[104:105], v[104:105], v[236:237], v[232:233]
	s_nop 0
	v_cvt_pk_bf16_f32 v102, v102, v103
	v_cvt_pk_bf16_f32 v103, v104, v105
	global_store_dwordx2 v245, v[102:103], s[38:39] offset:512
	ds_read_b128 v[226:229], v238 offset:27648
	ds_read_b128 v[230:233], v238 offset:60416
	ds_read_b128 v[234:237], v239 offset:11264
	s_waitcnt lgkmcnt(3)
	v_pk_mul_f32 v[106:107], v[106:107], v[252:253] op_sel_hi:[1,0]
	v_pk_mul_f32 v[108:109], v[108:109], v[252:253] op_sel_hi:[1,0]
	v_pk_mul_f32 v[106:107], v[106:107], v[214:215]
	v_pk_mul_f32 v[108:109], v[108:109], v[216:217]
	v_pk_add_f32 v[222:223], v[222:223], 1.0 op_sel_hi:[1,0]
	v_pk_add_f32 v[224:225], v[224:225], 1.0 op_sel_hi:[1,0]
	v_pk_fma_f32 v[106:107], v[106:107], v[222:223], v[218:219]
	v_pk_fma_f32 v[108:109], v[108:109], v[224:225], v[220:221]
	s_nop 0
	v_cvt_pk_bf16_f32 v106, v106, v107
	v_cvt_pk_bf16_f32 v107, v108, v109
	global_store_dwordx2 v245, v[106:107], s[38:39] offset:1024
	ds_read_b128 v[214:217], v238 offset:28672
	ds_read_b128 v[218:221], v238 offset:61440
	ds_read_b128 v[222:225], v239 offset:12288
	s_waitcnt lgkmcnt(3)
	v_pk_mul_f32 v[110:111], v[110:111], v[252:253] op_sel_hi:[1,0]
	v_pk_mul_f32 v[112:113], v[112:113], v[252:253] op_sel_hi:[1,0]
	v_pk_mul_f32 v[110:111], v[110:111], v[226:227]
	v_pk_mul_f32 v[112:113], v[112:113], v[228:229]
	v_pk_add_f32 v[234:235], v[234:235], 1.0 op_sel_hi:[1,0]
	v_pk_add_f32 v[236:237], v[236:237], 1.0 op_sel_hi:[1,0]
	v_pk_fma_f32 v[110:111], v[110:111], v[234:235], v[230:231]
	v_pk_fma_f32 v[112:113], v[112:113], v[236:237], v[232:233]
	s_nop 0
	v_cvt_pk_bf16_f32 v110, v110, v111
	v_cvt_pk_bf16_f32 v111, v112, v113
	global_store_dwordx2 v245, v[110:111], s[38:39] offset:1536
	ds_read_b128 v[226:229], v238 offset:29696
	ds_read_b128 v[230:233], v238 offset:62464
	ds_read_b128 v[234:237], v239 offset:13312
	s_waitcnt lgkmcnt(3)
	v_pk_mul_f32 v[114:115], v[114:115], v[252:253] op_sel_hi:[1,0]
	v_pk_mul_f32 v[116:117], v[116:117], v[252:253] op_sel_hi:[1,0]
	v_pk_mul_f32 v[114:115], v[114:115], v[214:215]
	v_pk_mul_f32 v[116:117], v[116:117], v[216:217]
	v_pk_add_f32 v[222:223], v[222:223], 1.0 op_sel_hi:[1,0]
	v_pk_add_f32 v[224:225], v[224:225], 1.0 op_sel_hi:[1,0]
	v_pk_fma_f32 v[114:115], v[114:115], v[222:223], v[218:219]
	v_pk_fma_f32 v[116:117], v[116:117], v[224:225], v[220:221]
	s_nop 0
	v_cvt_pk_bf16_f32 v114, v114, v115
	v_cvt_pk_bf16_f32 v115, v116, v117
	global_store_dwordx2 v245, v[114:115], s[38:39] offset:2048
	ds_read_b128 v[214:217], v238 offset:30720
	ds_read_b128 v[218:221], v238 offset:63488
	ds_read_b128 v[222:225], v239 offset:14336
	s_waitcnt lgkmcnt(3)
	v_pk_mul_f32 v[118:119], v[118:119], v[252:253] op_sel_hi:[1,0]
	v_pk_mul_f32 v[120:121], v[120:121], v[252:253] op_sel_hi:[1,0]
	v_pk_mul_f32 v[118:119], v[118:119], v[226:227]
	v_pk_mul_f32 v[120:121], v[120:121], v[228:229]
	v_pk_add_f32 v[234:235], v[234:235], 1.0 op_sel_hi:[1,0]
	v_pk_add_f32 v[236:237], v[236:237], 1.0 op_sel_hi:[1,0]
	v_pk_fma_f32 v[118:119], v[118:119], v[234:235], v[230:231]
	v_pk_fma_f32 v[120:121], v[120:121], v[236:237], v[232:233]
	s_nop 0
	v_cvt_pk_bf16_f32 v118, v118, v119
	v_cvt_pk_bf16_f32 v119, v120, v121
	global_store_dwordx2 v245, v[118:119], s[38:39] offset:2560
	ds_read_b128 v[226:229], v238 offset:31744
	ds_read_b128 v[230:233], v238 offset:64512
	ds_read_b128 v[234:237], v239 offset:15360
	s_waitcnt lgkmcnt(3)
	v_pk_mul_f32 v[122:123], v[122:123], v[252:253] op_sel_hi:[1,0]
	v_pk_mul_f32 v[124:125], v[124:125], v[252:253] op_sel_hi:[1,0]
	v_pk_mul_f32 v[122:123], v[122:123], v[214:215]
	v_pk_mul_f32 v[124:125], v[124:125], v[216:217]
	v_pk_add_f32 v[222:223], v[222:223], 1.0 op_sel_hi:[1,0]
	v_pk_add_f32 v[224:225], v[224:225], 1.0 op_sel_hi:[1,0]
	v_pk_fma_f32 v[122:123], v[122:123], v[222:223], v[218:219]
	v_pk_fma_f32 v[124:125], v[124:125], v[224:225], v[220:221]
	s_nop 0
	v_cvt_pk_bf16_f32 v122, v122, v123
	v_cvt_pk_bf16_f32 v123, v124, v125
	global_store_dwordx2 v245, v[122:123], s[38:39] offset:3072
	s_waitcnt lgkmcnt(0)
	v_pk_mul_f32 v[126:127], v[126:127], v[252:253] op_sel_hi:[1,0]
	v_pk_mul_f32 v[128:129], v[128:129], v[252:253] op_sel_hi:[1,0]
	v_pk_mul_f32 v[126:127], v[126:127], v[226:227]
	v_pk_mul_f32 v[128:129], v[128:129], v[228:229]
	v_pk_add_f32 v[234:235], v[234:235], 1.0 op_sel_hi:[1,0]
	v_pk_add_f32 v[236:237], v[236:237], 1.0 op_sel_hi:[1,0]
	v_pk_fma_f32 v[126:127], v[126:127], v[234:235], v[230:231]
	v_pk_fma_f32 v[128:129], v[128:129], v[236:237], v[232:233]
	s_nop 0
	v_cvt_pk_bf16_f32 v126, v126, v127
	v_cvt_pk_bf16_f32 v127, v128, v129
	global_store_dwordx2 v245, v[126:127], s[38:39] offset:3584
	s_branch .LBB0_715

.LBB0_984:
	s_cmp_lt_i32 s72, 15
	s_cselect_b64 s[4:5], -1, 0
	s_and_b64 s[0:1], s[4:5], s[0:1]
	s_andn2_b64 vcc, exec, s[0:1]
	s_cbranch_vccnz .LBB0_988
	s_lshl_b32 s0, s2, 3
	s_add_i32 s0, s96, s0
	s_cmpk_gt_i32 s0, 0x2fff
	s_cbranch_scc1 .LBB0_988
	s_cmp_lg_u32 s33, 0x100
	s_cbranch_scc1 .LrB_old
	v_readlane_b32 s10, v255, 12
	v_readlane_b32 s11, v255, 13
	v_lshl_add_u32 v180, s96, 6, v174
	v_lshlrev_b32_e32 v180, 4, v180
	v_add_u32_e32 v181, 0x2000, v180
	s_lshr_b32 s3, s2, 7
	s_add_u32 s12, s28, 0x14000
	s_addc_u32 s13, s29, 0
	s_add_i32 s5, s3, 1
	s_mul_i32 s5, s5, 0x18000
	s_add_u32 s14, s12, s5
	s_addc_u32 s15, s13, 0
	s_add_i32 s5, s3, 3
	s_mul_i32 s5, s5, 0x18000
	s_add_u32 s16, s12, s5
	s_addc_u32 s17, s13, 0
	s_nop 4
	global_load_dwordx4 v[66:69], v180, s[10:11]
	global_load_dwordx4 v[70:73], v181, s[10:11]
	global_load_dwordx4 v[74:77], v180, s[12:13]
	global_load_dwordx4 v[78:81], v181, s[12:13]
	global_load_dwordx4 v[82:85], v180, s[14:15]
	global_load_dwordx4 v[86:89], v181, s[14:15]
	global_load_dwordx4 v[90:93], v180, s[16:17]
	global_load_dwordx4 v[94:97], v181, s[16:17]
	v_lshlrev_b32_e32 v238, 4, v174
	v_add_u32_e32 v241, 0x1000, v238
	v_add_u32_e32 v242, 0x2000, v238
	v_add_u32_e32 v243, 0x3000, v238
	v_lshlrev_b32_e32 v244, 3, v174
	v_add_u32_e32 v245, 0x1000, v244
	v_xor_b32_e32 v246, 1, v174
	v_lshlrev_b32_e32 v246, 2, v246
	v_xor_b32_e32 v247, 2, v174
	v_lshlrev_b32_e32 v247, 2, v247
	v_xor_b32_e32 v248, 4, v174
	v_lshlrev_b32_e32 v248, 2, v248
	v_xor_b32_e32 v249, 8, v174
	v_lshlrev_b32_e32 v249, 2, v249
	v_xor_b32_e32 v250, 16, v174
	v_lshlrev_b32_e32 v250, 2, v250
	v_xor_b32_e32 v251, 32, v174
	v_lshlrev_b32_e32 v251, 2, v251
	s_mov_b32 s20, 0x800000
	s_lshl_b32 s5, s0, 13
	s_add_u32 s18, s70, s5
	s_addc_u32 s19, s71, 0
	s_add_u32 s22, s18, 0x51000000
	s_addc_u32 s23, s19, 0
	s_add_u32 s24, s18, 0x3f000000
	s_addc_u32 s25, s19, 0
	s_lshl_b32 s5, s0, 14
	s_add_u32 s30, s68, s5
	s_addc_u32 s31, s69, 0
	global_load_dwordx2 v[2:3], v244, s[22:23] offset:0
	global_load_dwordx2 v[4:5], v244, s[22:23] offset:512
	global_load_dwordx2 v[6:7], v244, s[22:23] offset:1024
	global_load_dwordx2 v[8:9], v244, s[22:23] offset:1536
	global_load_dwordx2 v[10:11], v244, s[22:23] offset:2048
	global_load_dwordx2 v[12:13], v244, s[22:23] offset:2560
	global_load_dwordx2 v[14:15], v244, s[22:23] offset:3072
	global_load_dwordx2 v[16:17], v244, s[22:23] offset:3584
	global_load_dwordx2 v[18:19], v245, s[22:23] offset:0
	global_load_dwordx2 v[20:21], v245, s[22:23] offset:512
	global_load_dwordx2 v[22:23], v245, s[22:23] offset:1024
	global_load_dwordx2 v[24:25], v245, s[22:23] offset:1536
	global_load_dwordx2 v[26:27], v245, s[22:23] offset:2048
	global_load_dwordx2 v[28:29], v245, s[22:23] offset:2560
	global_load_dwordx2 v[30:31], v245, s[22:23] offset:3072
	global_load_dwordx2 v[32:33], v245, s[22:23] offset:3584
	global_load_dwordx2 v[34:35], v244, s[24:25] offset:0
	global_load_dwordx2 v[36:37], v244, s[24:25] offset:512
	global_load_dwordx2 v[38:39], v244, s[24:25] offset:1024
	global_load_dwordx2 v[40:41], v244, s[24:25] offset:1536
	global_load_dwordx2 v[42:43], v244, s[24:25] offset:2048
	global_load_dwordx2 v[44:45], v244, s[24:25] offset:2560
	global_load_dwordx2 v[46:47], v244, s[24:25] offset:3072
	global_load_dwordx2 v[48:49], v244, s[24:25] offset:3584
	global_load_dwordx2 v[50:51], v245, s[24:25] offset:0
	global_load_dwordx2 v[52:53], v245, s[24:25] offset:512
	global_load_dwordx2 v[54:55], v245, s[24:25] offset:1024
	global_load_dwordx2 v[56:57], v245, s[24:25] offset:1536
	global_load_dwordx2 v[58:59], v245, s[24:25] offset:2048
	global_load_dwordx2 v[60:61], v245, s[24:25] offset:2560
	global_load_dwordx2 v[62:63], v245, s[24:25] offset:3072
	global_load_dwordx2 v[64:65], v245, s[24:25] offset:3584
	s_waitcnt vmcnt(32)
	ds_write_b128 v180, v[66:69] offset:0
	ds_write_b128 v180, v[70:73] offset:8192
	ds_write_b128 v180, v[74:77] offset:16384
	ds_write_b128 v180, v[78:81] offset:24576
	ds_write_b128 v180, v[82:85] offset:32768
	ds_write_b128 v180, v[86:89] offset:40960
	ds_write_b128 v180, v[90:93] offset:49152
	ds_write_b128 v180, v[94:97] offset:57344
	s_waitcnt lgkmcnt(0)
	s_barrier
	s_waitcnt vmcnt(0)
	s_add_u32 s22, s22, 0x1000000
	s_addc_u32 s23, s23, 0
	s_add_u32 s24, s24, 0x1000000
	s_addc_u32 s25, s25, 0
	global_load_dwordx2 v[66:67], v244, s[22:23] offset:0
	global_load_dwordx2 v[68:69], v244, s[22:23] offset:512
	global_load_dwordx2 v[70:71], v244, s[22:23] offset:1024
	global_load_dwordx2 v[72:73], v244, s[22:23] offset:1536
	global_load_dwordx2 v[74:75], v244, s[22:23] offset:2048
	global_load_dwordx2 v[76:77], v244, s[22:23] offset:2560
	global_load_dwordx2 v[78:79], v244, s[22:23] offset:3072
	global_load_dwordx2 v[80:81], v244, s[22:23] offset:3584
	global_load_dwordx2 v[82:83], v245, s[22:23] offset:0
	global_load_dwordx2 v[84:85], v245, s[22:23] offset:512
	global_load_dwordx2 v[86:87], v245, s[22:23] offset:1024
	global_load_dwordx2 v[88:89], v245, s[22:23] offset:1536
	global_load_dwordx2 v[90:91], v245, s[22:23] offset:2048
	global_load_dwordx2 v[92:93], v245, s[22:23] offset:2560
	global_load_dwordx2 v[94:95], v245, s[22:23] offset:3072
	global_load_dwordx2 v[96:97], v245, s[22:23] offset:3584
	global_load_dwordx2 v[98:99], v244, s[24:25] offset:0
	global_load_dwordx2 v[100:101], v244, s[24:25] offset:512
	global_load_dwordx2 v[102:103], v244, s[24:25] offset:1024
	global_load_dwordx2 v[104:105], v244, s[24:25] offset:1536
	global_load_dwordx2 v[106:107], v244, s[24:25] offset:2048
	global_load_dwordx2 v[108:109], v244, s[24:25] offset:2560
	global_load_dwordx2 v[110:111], v244, s[24:25] offset:3072
	global_load_dwordx2 v[112:113], v244, s[24:25] offset:3584
	global_load_dwordx2 v[114:115], v245, s[24:25] offset:0
	global_load_dwordx2 v[116:117], v245, s[24:25] offset:512
	global_load_dwordx2 v[118:119], v245, s[24:25] offset:1024
	global_load_dwordx2 v[120:121], v245, s[24:25] offset:1536
	global_load_dwordx2 v[122:123], v245, s[24:25] offset:2048
	global_load_dwordx2 v[124:125], v245, s[24:25] offset:2560
	global_load_dwordx2 v[126:127], v245, s[24:25] offset:3072
	global_load_dwordx2 v[128:129], v245, s[24:25] offset:3584
	ds_read_b128 v[130:133], v238 offset:0
	ds_read_b128 v[134:137], v238 offset:16384
	ds_read_b128 v[138:141], v238 offset:1024
	ds_read_b128 v[142:145], v238 offset:17408
	v_lshlrev_b32_e32 v162, 16, v2
	v_and_b32_e32 v163, 0xffff0000, v2
	v_lshlrev_b32_e32 v164, 16, v3
	v_and_b32_e32 v165, 0xffff0000, v3
	v_pk_mul_f32 v[176:177], v[162:163], v[162:163]
	v_pk_mul_f32 v[178:179], v[164:165], v[164:165]
	v_lshlrev_b32_e32 v166, 16, v4
	v_and_b32_e32 v167, 0xffff0000, v4
	v_lshlrev_b32_e32 v168, 16, v5
	v_and_b32_e32 v169, 0xffff0000, v5
	v_pk_fma_f32 v[176:177], v[166:167], v[166:167], v[176:177]
	v_pk_fma_f32 v[178:179], v[168:169], v[168:169], v[178:179]
	v_lshlrev_b32_e32 v162, 16, v6
	v_and_b32_e32 v163, 0xffff0000, v6
	v_lshlrev_b32_e32 v164, 16, v7
	v_and_b32_e32 v165, 0xffff0000, v7
	v_pk_fma_f32 v[176:177], v[162:163], v[162:163], v[176:177]
	v_pk_fma_f32 v[178:179], v[164:165], v[164:165], v[178:179]
	v_lshlrev_b32_e32 v166, 16, v8
	v_and_b32_e32 v167, 0xffff0000, v8
	v_lshlrev_b32_e32 v168, 16, v9
	v_and_b32_e32 v169, 0xffff0000, v9
	v_pk_fma_f32 v[176:177], v[166:167], v[166:167], v[176:177]
	v_pk_fma_f32 v[178:179], v[168:169], v[168:169], v[178:179]
	v_lshlrev_b32_e32 v162, 16, v10
	v_and_b32_e32 v163, 0xffff0000, v10
	v_lshlrev_b32_e32 v164, 16, v11
	v_and_b32_e32 v165, 0xffff0000, v11
	v_pk_fma_f32 v[176:177], v[162:163], v[162:163], v[176:177]
	v_pk_fma_f32 v[178:179], v[164:165], v[164:165], v[178:179]
	v_lshlrev_b32_e32 v166, 16, v12
	v_and_b32_e32 v167, 0xffff0000, v12
	v_lshlrev_b32_e32 v168, 16, v13
	v_and_b32_e32 v169, 0xffff0000, v13
	v_pk_fma_f32 v[176:177], v[166:167], v[166:167], v[176:177]
	v_pk_fma_f32 v[178:179], v[168:169], v[168:169], v[178:179]
	v_lshlrev_b32_e32 v162, 16, v14
	v_and_b32_e32 v163, 0xffff0000, v14
	v_lshlrev_b32_e32 v164, 16, v15
	v_and_b32_e32 v165, 0xffff0000, v15
	v_pk_fma_f32 v[176:177], v[162:163], v[162:163], v[176:177]
	v_pk_fma_f32 v[178:179], v[164:165], v[164:165], v[178:179]
	v_lshlrev_b32_e32 v166, 16, v16
	v_and_b32_e32 v167, 0xffff0000, v16
	v_lshlrev_b32_e32 v168, 16, v17
	v_and_b32_e32 v169, 0xffff0000, v17
	v_pk_fma_f32 v[176:177], v[166:167], v[166:167], v[176:177]
	v_pk_fma_f32 v[178:179], v[168:169], v[168:169], v[178:179]
	v_lshlrev_b32_e32 v162, 16, v18
	v_and_b32_e32 v163, 0xffff0000, v18
	v_lshlrev_b32_e32 v164, 16, v19
	v_and_b32_e32 v165, 0xffff0000, v19
	v_pk_fma_f32 v[176:177], v[162:163], v[162:163], v[176:177]
	v_pk_fma_f32 v[178:179], v[164:165], v[164:165], v[178:179]
	v_lshlrev_b32_e32 v166, 16, v20
	v_and_b32_e32 v167, 0xffff0000, v20
	v_lshlrev_b32_e32 v168, 16, v21
	v_and_b32_e32 v169, 0xffff0000, v21
	v_pk_fma_f32 v[176:177], v[166:167], v[166:167], v[176:177]
	v_pk_fma_f32 v[178:179], v[168:169], v[168:169], v[178:179]
	v_lshlrev_b32_e32 v162, 16, v22
	v_and_b32_e32 v163, 0xffff0000, v22
	v_lshlrev_b32_e32 v164, 16, v23
	v_and_b32_e32 v165, 0xffff0000, v23
	v_pk_fma_f32 v[176:177], v[162:163], v[162:163], v[176:177]
	v_pk_fma_f32 v[178:179], v[164:165], v[164:165], v[178:179]
	v_lshlrev_b32_e32 v166, 16, v24
	v_and_b32_e32 v167, 0xffff0000, v24
	v_lshlrev_b32_e32 v168, 16, v25
	v_and_b32_e32 v169, 0xffff0000, v25
	v_pk_fma_f32 v[176:177], v[166:167], v[166:167], v[176:177]
	v_pk_fma_f32 v[178:179], v[168:169], v[168:169], v[178:179]
	v_lshlrev_b32_e32 v162, 16, v26
	v_and_b32_e32 v163, 0xffff0000, v26
	v_lshlrev_b32_e32 v164, 16, v27
	v_and_b32_e32 v165, 0xffff0000, v27
	v_pk_fma_f32 v[176:177], v[162:163], v[162:163], v[176:177]
	v_pk_fma_f32 v[178:179], v[164:165], v[164:165], v[178:179]
	v_lshlrev_b32_e32 v166, 16, v28
	v_and_b32_e32 v167, 0xffff0000, v28
	v_lshlrev_b32_e32 v168, 16, v29
	v_and_b32_e32 v169, 0xffff0000, v29
	v_pk_fma_f32 v[176:177], v[166:167], v[166:167], v[176:177]
	v_pk_fma_f32 v[178:179], v[168:169], v[168:169], v[178:179]
	v_lshlrev_b32_e32 v162, 16, v30
	v_and_b32_e32 v163, 0xffff0000, v30
	v_lshlrev_b32_e32 v164, 16, v31
	v_and_b32_e32 v165, 0xffff0000, v31
	v_pk_fma_f32 v[176:177], v[162:163], v[162:163], v[176:177]
	v_pk_fma_f32 v[178:179], v[164:165], v[164:165], v[178:179]
	v_lshlrev_b32_e32 v166, 16, v32
	v_and_b32_e32 v167, 0xffff0000, v32
	v_lshlrev_b32_e32 v168, 16, v33
	v_and_b32_e32 v169, 0xffff0000, v33
	v_pk_fma_f32 v[176:177], v[166:167], v[166:167], v[176:177]
	v_pk_fma_f32 v[178:179], v[168:169], v[168:169], v[178:179]
	v_pk_add_f32 v[176:177], v[176:177], v[178:179]
	s_nop 0
	v_add_f32_e32 v252, v176, v177
	s_waitcnt lgkmcnt(0)
	ds_bpermute_b32 v254, v246, v252
	s_waitcnt lgkmcnt(0)
	v_add_f32_e32 v252, v252, v254
	ds_bpermute_b32 v254, v247, v252
	s_waitcnt lgkmcnt(0)
	v_add_f32_e32 v252, v252, v254
	ds_bpermute_b32 v254, v248, v252
	s_waitcnt lgkmcnt(0)
	v_add_f32_e32 v252, v252, v254
	ds_bpermute_b32 v254, v249, v252
	s_waitcnt lgkmcnt(0)
	v_add_f32_e32 v252, v252, v254
	ds_bpermute_b32 v254, v250, v252
	s_waitcnt lgkmcnt(0)
	v_add_f32_e32 v252, v252, v254
	ds_bpermute_b32 v254, v251, v252
	s_waitcnt lgkmcnt(0)
	v_add_f32_e32 v252, v252, v254
	v_mov_b32_e32 v254, 0x358637bd
	v_fmac_f32_e32 v254, 0x39800000, v252
	v_mul_f32_e32 v252, 0x4b800000, v254
	v_cmp_gt_f32_e32 vcc, s20, v254
	s_nop 1
	v_cndmask_b32_e32 v254, v254, v252, vcc
	v_rsq_f32_e32 v254, v254
	s_nop 0
	v_mul_f32_e32 v252, 0x45800000, v254
	v_cndmask_b32_e32 v252, v254, v252, vcc
	ds_read_b128 v[146:149], v238 offset:2048
	ds_read_b128 v[150:153], v238 offset:18432
	ds_read_b128 v[154:157], v238 offset:3072
	ds_read_b128 v[158:161], v238 offset:19456
	s_waitcnt lgkmcnt(4)
	v_lshlrev_b32_e32 v162, 16, v2
	v_and_b32_e32 v163, 0xffff0000, v2
	v_lshlrev_b32_e32 v164, 16, v3
	v_and_b32_e32 v165, 0xffff0000, v3
	v_lshlrev_b32_e32 v166, 16, v34
	v_and_b32_e32 v167, 0xffff0000, v34
	v_lshlrev_b32_e32 v168, 16, v35
	v_and_b32_e32 v169, 0xffff0000, v35
	v_pk_mul_f32 v[162:163], v[162:163], v[252:253] op_sel_hi:[1,0]
	v_pk_mul_f32 v[164:165], v[164:165], v[252:253] op_sel_hi:[1,0]
	v_pk_mul_f32 v[162:163], v[162:163], v[130:131]
	v_pk_mul_f32 v[164:165], v[164:165], v[132:133]
	v_pk_fma_f32 v[162:163], v[134:135], v[162:163], v[166:167]
	v_pk_fma_f32 v[164:165], v[136:137], v[164:165], v[168:169]
	s_nop 0
	global_store_dwordx4 v238, v[162:165], s[30:31] offset:0 nt
	s_nop 1
	v_lshlrev_b32_e32 v162, 16, v4
	v_and_b32_e32 v163, 0xffff0000, v4
	v_lshlrev_b32_e32 v164, 16, v5
	v_and_b32_e32 v165, 0xffff0000, v5
	v_lshlrev_b32_e32 v166, 16, v36
	v_and_b32_e32 v167, 0xffff0000, v36
	v_lshlrev_b32_e32 v168, 16, v37
	v_and_b32_e32 v169, 0xffff0000, v37
	v_pk_mul_f32 v[162:163], v[162:163], v[252:253] op_sel_hi:[1,0]
	v_pk_mul_f32 v[164:165], v[164:165], v[252:253] op_sel_hi:[1,0]
	v_pk_mul_f32 v[162:163], v[162:163], v[138:139]
	v_pk_mul_f32 v[164:165], v[164:165], v[140:141]
	v_pk_fma_f32 v[162:163], v[142:143], v[162:163], v[166:167]
	v_pk_fma_f32 v[164:165], v[144:145], v[164:165], v[168:169]
	s_nop 0
	global_store_dwordx4 v238, v[162:165], s[30:31] offset:1024 nt
	s_nop 1
	ds_read_b128 v[130:133], v238 offset:4096
	ds_read_b128 v[134:137], v238 offset:20480
	ds_read_b128 v[138:141], v238 offset:5120
	ds_read_b128 v[142:145], v238 offset:21504
	s_waitcnt lgkmcnt(4)
	v_lshlrev_b32_e32 v162, 16, v6
	v_and_b32_e32 v163, 0xffff0000, v6
	v_lshlrev_b32_e32 v164, 16, v7
	v_and_b32_e32 v165, 0xffff0000, v7
	v_lshlrev_b32_e32 v166, 16, v38
	v_and_b32_e32 v167, 0xffff0000, v38
	v_lshlrev_b32_e32 v168, 16, v39
	v_and_b32_e32 v169, 0xffff0000, v39
	v_pk_mul_f32 v[162:163], v[162:163], v[252:253] op_sel_hi:[1,0]
	v_pk_mul_f32 v[164:165], v[164:165], v[252:253] op_sel_hi:[1,0]
	v_pk_mul_f32 v[162:163], v[162:163], v[146:147]
	v_pk_mul_f32 v[164:165], v[164:165], v[148:149]
	v_pk_fma_f32 v[162:163], v[150:151], v[162:163], v[166:167]
	v_pk_fma_f32 v[164:165], v[152:153], v[164:165], v[168:169]
	s_nop 0
	global_store_dwordx4 v238, v[162:165], s[30:31] offset:2048 nt
	s_nop 1
	v_lshlrev_b32_e32 v162, 16, v8
	v_and_b32_e32 v163, 0xffff0000, v8
	v_lshlrev_b32_e32 v164, 16, v9
	v_and_b32_e32 v165, 0xffff0000, v9
	v_lshlrev_b32_e32 v166, 16, v40
	v_and_b32_e32 v167, 0xffff0000, v40
	v_lshlrev_b32_e32 v168, 16, v41
	v_and_b32_e32 v169, 0xffff0000, v41
	v_pk_mul_f32 v[162:163], v[162:163], v[252:253] op_sel_hi:[1,0]
	v_pk_mul_f32 v[164:165], v[164:165], v[252:253] op_sel_hi:[1,0]
	v_pk_mul_f32 v[162:163], v[162:163], v[154:155]
	v_pk_mul_f32 v[164:165], v[164:165], v[156:157]
	v_pk_fma_f32 v[162:163], v[158:159], v[162:163], v[166:167]
	v_pk_fma_f32 v[164:165], v[160:161], v[164:165], v[168:169]
	s_nop 0
	global_store_dwordx4 v238, v[162:165], s[30:31] offset:3072 nt
	s_nop 1
	ds_read_b128 v[146:149], v238 offset:6144
	ds_read_b128 v[150:153], v238 offset:22528
	ds_read_b128 v[154:157], v238 offset:7168
	ds_read_b128 v[158:161], v238 offset:23552
	s_waitcnt lgkmcnt(4)
	v_lshlrev_b32_e32 v162, 16, v10
	v_and_b32_e32 v163, 0xffff0000, v10
	v_lshlrev_b32_e32 v164, 16, v11
	v_and_b32_e32 v165, 0xffff0000, v11
	v_lshlrev_b32_e32 v166, 16, v42
	v_and_b32_e32 v167, 0xffff0000, v42
	v_lshlrev_b32_e32 v168, 16, v43
	v_and_b32_e32 v169, 0xffff0000, v43
	v_pk_mul_f32 v[162:163], v[162:163], v[252:253] op_sel_hi:[1,0]
	v_pk_mul_f32 v[164:165], v[164:165], v[252:253] op_sel_hi:[1,0]
	v_pk_mul_f32 v[162:163], v[162:163], v[130:131]
	v_pk_mul_f32 v[164:165], v[164:165], v[132:133]
	v_pk_fma_f32 v[162:163], v[134:135], v[162:163], v[166:167]
	v_pk_fma_f32 v[164:165], v[136:137], v[164:165], v[168:169]
	s_nop 0
	global_store_dwordx4 v241, v[162:165], s[30:31] offset:0 nt
	s_nop 1
	v_lshlrev_b32_e32 v162, 16, v12
	v_and_b32_e32 v163, 0xffff0000, v12
	v_lshlrev_b32_e32 v164, 16, v13
	v_and_b32_e32 v165, 0xffff0000, v13
	v_lshlrev_b32_e32 v166, 16, v44
	v_and_b32_e32 v167, 0xffff0000, v44
	v_lshlrev_b32_e32 v168, 16, v45
	v_and_b32_e32 v169, 0xffff0000, v45
	v_pk_mul_f32 v[162:163], v[162:163], v[252:253] op_sel_hi:[1,0]
	v_pk_mul_f32 v[164:165], v[164:165], v[252:253] op_sel_hi:[1,0]
	v_pk_mul_f32 v[162:163], v[162:163], v[138:139]
	v_pk_mul_f32 v[164:165], v[164:165], v[140:141]
	v_pk_fma_f32 v[162:163], v[142:143], v[162:163], v[166:167]
	v_pk_fma_f32 v[164:165], v[144:145], v[164:165], v[168:169]
	s_nop 0
	global_store_dwordx4 v241, v[162:165], s[30:31] offset:1024 nt
	s_nop 1
	ds_read_b128 v[130:133], v238 offset:8192
	ds_read_b128 v[134:137], v238 offset:24576
	ds_read_b128 v[138:141], v238 offset:9216
	ds_read_b128 v[142:145], v238 offset:25600
	s_waitcnt lgkmcnt(4)
	v_lshlrev_b32_e32 v162, 16, v14
	v_and_b32_e32 v163, 0xffff0000, v14
	v_lshlrev_b32_e32 v164, 16, v15
	v_and_b32_e32 v165, 0xffff0000, v15
	v_lshlrev_b32_e32 v166, 16, v46
	v_and_b32_e32 v167, 0xffff0000, v46
	v_lshlrev_b32_e32 v168, 16, v47
	v_and_b32_e32 v169, 0xffff0000, v47
	v_pk_mul_f32 v[162:163], v[162:163], v[252:253] op_sel_hi:[1,0]
	v_pk_mul_f32 v[164:165], v[164:165], v[252:253] op_sel_hi:[1,0]
	v_pk_mul_f32 v[162:163], v[162:163], v[146:147]
	v_pk_mul_f32 v[164:165], v[164:165], v[148:149]
	v_pk_fma_f32 v[162:163], v[150:151], v[162:163], v[166:167]
	v_pk_fma_f32 v[164:165], v[152:153], v[164:165], v[168:169]
	s_nop 0
	global_store_dwordx4 v241, v[162:165], s[30:31] offset:2048 nt
	s_nop 1
	v_lshlrev_b32_e32 v162, 16, v16
	v_and_b32_e32 v163, 0xffff0000, v16
	v_lshlrev_b32_e32 v164, 16, v17
	v_and_b32_e32 v165, 0xffff0000, v17
	v_lshlrev_b32_e32 v166, 16, v48
	v_and_b32_e32 v167, 0xffff0000, v48
	v_lshlrev_b32_e32 v168, 16, v49
	v_and_b32_e32 v169, 0xffff0000, v49
	v_pk_mul_f32 v[162:163], v[162:163], v[252:253] op_sel_hi:[1,0]
	v_pk_mul_f32 v[164:165], v[164:165], v[252:253] op_sel_hi:[1,0]
	v_pk_mul_f32 v[162:163], v[162:163], v[154:155]
	v_pk_mul_f32 v[164:165], v[164:165], v[156:157]
	v_pk_fma_f32 v[162:163], v[158:159], v[162:163], v[166:167]
	v_pk_fma_f32 v[164:165], v[160:161], v[164:165], v[168:169]
	s_nop 0
	global_store_dwordx4 v241, v[162:165], s[30:31] offset:3072 nt
	s_nop 1
	ds_read_b128 v[146:149], v238 offset:10240
	ds_read_b128 v[150:153], v238 offset:26624
	ds_read_b128 v[154:157], v238 offset:11264
	ds_read_b128 v[158:161], v238 offset:27648
	s_waitcnt lgkmcnt(4)
	v_lshlrev_b32_e32 v162, 16, v18
	v_and_b32_e32 v163, 0xffff0000, v18
	v_lshlrev_b32_e32 v164, 16, v19
	v_and_b32_e32 v165, 0xffff0000, v19
	v_lshlrev_b32_e32 v166, 16, v50
	v_and_b32_e32 v167, 0xffff0000, v50
	v_lshlrev_b32_e32 v168, 16, v51
	v_and_b32_e32 v169, 0xffff0000, v51
	v_pk_mul_f32 v[162:163], v[162:163], v[252:253] op_sel_hi:[1,0]
	v_pk_mul_f32 v[164:165], v[164:165], v[252:253] op_sel_hi:[1,0]
	v_pk_mul_f32 v[162:163], v[162:163], v[130:131]
	v_pk_mul_f32 v[164:165], v[164:165], v[132:133]
	v_pk_fma_f32 v[162:163], v[134:135], v[162:163], v[166:167]
	v_pk_fma_f32 v[164:165], v[136:137], v[164:165], v[168:169]
	s_nop 0
	global_store_dwordx4 v242, v[162:165], s[30:31] offset:0 nt
	s_nop 1
	v_lshlrev_b32_e32 v162, 16, v20
	v_and_b32_e32 v163, 0xffff0000, v20
	v_lshlrev_b32_e32 v164, 16, v21
	v_and_b32_e32 v165, 0xffff0000, v21
	v_lshlrev_b32_e32 v166, 16, v52
	v_and_b32_e32 v167, 0xffff0000, v52
	v_lshlrev_b32_e32 v168, 16, v53
	v_and_b32_e32 v169, 0xffff0000, v53
	v_pk_mul_f32 v[162:163], v[162:163], v[252:253] op_sel_hi:[1,0]
	v_pk_mul_f32 v[164:165], v[164:165], v[252:253] op_sel_hi:[1,0]
	v_pk_mul_f32 v[162:163], v[162:163], v[138:139]
	v_pk_mul_f32 v[164:165], v[164:165], v[140:141]
	v_pk_fma_f32 v[162:163], v[142:143], v[162:163], v[166:167]
	v_pk_fma_f32 v[164:165], v[144:145], v[164:165], v[168:169]
	s_nop 0
	global_store_dwordx4 v242, v[162:165], s[30:31] offset:1024 nt
	s_nop 1
	ds_read_b128 v[130:133], v238 offset:12288
	ds_read_b128 v[134:137], v238 offset:28672
	ds_read_b128 v[138:141], v238 offset:13312
	ds_read_b128 v[142:145], v238 offset:29696
	s_waitcnt lgkmcnt(4)
	v_lshlrev_b32_e32 v162, 16, v22
	v_and_b32_e32 v163, 0xffff0000, v22
	v_lshlrev_b32_e32 v164, 16, v23
	v_and_b32_e32 v165, 0xffff0000, v23
	v_lshlrev_b32_e32 v166, 16, v54
	v_and_b32_e32 v167, 0xffff0000, v54
	v_lshlrev_b32_e32 v168, 16, v55
	v_and_b32_e32 v169, 0xffff0000, v55
	v_pk_mul_f32 v[162:163], v[162:163], v[252:253] op_sel_hi:[1,0]
	v_pk_mul_f32 v[164:165], v[164:165], v[252:253] op_sel_hi:[1,0]
	v_pk_mul_f32 v[162:163], v[162:163], v[146:147]
	v_pk_mul_f32 v[164:165], v[164:165], v[148:149]
	v_pk_fma_f32 v[162:163], v[150:151], v[162:163], v[166:167]
	v_pk_fma_f32 v[164:165], v[152:153], v[164:165], v[168:169]
	s_nop 0
	global_store_dwordx4 v242, v[162:165], s[30:31] offset:2048 nt
	s_nop 1
	v_lshlrev_b32_e32 v162, 16, v24
	v_and_b32_e32 v163, 0xffff0000, v24
	v_lshlrev_b32_e32 v164, 16, v25
	v_and_b32_e32 v165, 0xffff0000, v25
	v_lshlrev_b32_e32 v166, 16, v56
	v_and_b32_e32 v167, 0xffff0000, v56
	v_lshlrev_b32_e32 v168, 16, v57
	v_and_b32_e32 v169, 0xffff0000, v57
	v_pk_mul_f32 v[162:163], v[162:163], v[252:253] op_sel_hi:[1,0]
	v_pk_mul_f32 v[164:165], v[164:165], v[252:253] op_sel_hi:[1,0]
	v_pk_mul_f32 v[162:163], v[162:163], v[154:155]
	v_pk_mul_f32 v[164:165], v[164:165], v[156:157]
	v_pk_fma_f32 v[162:163], v[158:159], v[162:163], v[166:167]
	v_pk_fma_f32 v[164:165], v[160:161], v[164:165], v[168:169]
	s_nop 0
	global_store_dwordx4 v242, v[162:165], s[30:31] offset:3072 nt
	s_nop 1
	ds_read_b128 v[146:149], v238 offset:14336
	ds_read_b128 v[150:153], v238 offset:30720
	ds_read_b128 v[154:157], v238 offset:15360
	ds_read_b128 v[158:161], v238 offset:31744
	s_waitcnt lgkmcnt(4)
	v_lshlrev_b32_e32 v162, 16, v26
	v_and_b32_e32 v163, 0xffff0000, v26
	v_lshlrev_b32_e32 v164, 16, v27
	v_and_b32_e32 v165, 0xffff0000, v27
	v_lshlrev_b32_e32 v166, 16, v58
	v_and_b32_e32 v167, 0xffff0000, v58
	v_lshlrev_b32_e32 v168, 16, v59
	v_and_b32_e32 v169, 0xffff0000, v59
	v_pk_mul_f32 v[162:163], v[162:163], v[252:253] op_sel_hi:[1,0]
	v_pk_mul_f32 v[164:165], v[164:165], v[252:253] op_sel_hi:[1,0]
	v_pk_mul_f32 v[162:163], v[162:163], v[130:131]
	v_pk_mul_f32 v[164:165], v[164:165], v[132:133]
	v_pk_fma_f32 v[162:163], v[134:135], v[162:163], v[166:167]
	v_pk_fma_f32 v[164:165], v[136:137], v[164:165], v[168:169]
	s_nop 0
	global_store_dwordx4 v243, v[162:165], s[30:31] offset:0 nt
	s_nop 1
	v_lshlrev_b32_e32 v162, 16, v28
	v_and_b32_e32 v163, 0xffff0000, v28
	v_lshlrev_b32_e32 v164, 16, v29
	v_and_b32_e32 v165, 0xffff0000, v29
	v_lshlrev_b32_e32 v166, 16, v60
	v_and_b32_e32 v167, 0xffff0000, v60
	v_lshlrev_b32_e32 v168, 16, v61
	v_and_b32_e32 v169, 0xffff0000, v61
	v_pk_mul_f32 v[162:163], v[162:163], v[252:253] op_sel_hi:[1,0]
	v_pk_mul_f32 v[164:165], v[164:165], v[252:253] op_sel_hi:[1,0]
	v_pk_mul_f32 v[162:163], v[162:163], v[138:139]
	v_pk_mul_f32 v[164:165], v[164:165], v[140:141]
	v_pk_fma_f32 v[162:163], v[142:143], v[162:163], v[166:167]
	v_pk_fma_f32 v[164:165], v[144:145], v[164:165], v[168:169]
	s_nop 0
	global_store_dwordx4 v243, v[162:165], s[30:31] offset:1024 nt
	s_nop 1
	s_waitcnt lgkmcnt(0)
	v_lshlrev_b32_e32 v162, 16, v30
	v_and_b32_e32 v163, 0xffff0000, v30
	v_lshlrev_b32_e32 v164, 16, v31
	v_and_b32_e32 v165, 0xffff0000, v31
	v_lshlrev_b32_e32 v166, 16, v62
	v_and_b32_e32 v167, 0xffff0000, v62
	v_lshlrev_b32_e32 v168, 16, v63
	v_and_b32_e32 v169, 0xffff0000, v63
	v_pk_mul_f32 v[162:163], v[162:163], v[252:253] op_sel_hi:[1,0]
	v_pk_mul_f32 v[164:165], v[164:165], v[252:253] op_sel_hi:[1,0]
	v_pk_mul_f32 v[162:163], v[162:163], v[146:147]
	v_pk_mul_f32 v[164:165], v[164:165], v[148:149]
	v_pk_fma_f32 v[162:163], v[150:151], v[162:163], v[166:167]
	v_pk_fma_f32 v[164:165], v[152:153], v[164:165], v[168:169]
	s_nop 0
	global_store_dwordx4 v243, v[162:165], s[30:31] offset:2048 nt
	s_nop 1
	v_lshlrev_b32_e32 v162, 16, v32
	v_and_b32_e32 v163, 0xffff0000, v32
	v_lshlrev_b32_e32 v164, 16, v33
	v_and_b32_e32 v165, 0xffff0000, v33
	v_lshlrev_b32_e32 v166, 16, v64
	v_and_b32_e32 v167, 0xffff0000, v64
	v_lshlrev_b32_e32 v168, 16, v65
	v_and_b32_e32 v169, 0xffff0000, v65
	v_pk_mul_f32 v[162:163], v[162:163], v[252:253] op_sel_hi:[1,0]
	v_pk_mul_f32 v[164:165], v[164:165], v[252:253] op_sel_hi:[1,0]
	v_pk_mul_f32 v[162:163], v[162:163], v[154:155]
	v_pk_mul_f32 v[164:165], v[164:165], v[156:157]
	v_pk_fma_f32 v[162:163], v[158:159], v[162:163], v[166:167]
	v_pk_fma_f32 v[164:165], v[160:161], v[164:165], v[168:169]
	s_nop 0
	global_store_dwordx4 v243, v[162:165], s[30:31] offset:3072 nt
	s_nop 1
	s_add_u32 s30, s30, 0x2000000
	s_addc_u32 s31, s31, 0
	s_waitcnt vmcnt(16)
	s_add_u32 s22, s22, 0x1000000
	s_addc_u32 s23, s23, 0
	s_add_u32 s24, s24, 0x1000000
	s_addc_u32 s25, s25, 0
	global_load_dwordx2 v[2:3], v244, s[22:23] offset:0
	global_load_dwordx2 v[4:5], v244, s[22:23] offset:512
	global_load_dwordx2 v[6:7], v244, s[22:23] offset:1024
	global_load_dwordx2 v[8:9], v244, s[22:23] offset:1536
	global_load_dwordx2 v[10:11], v244, s[22:23] offset:2048
	global_load_dwordx2 v[12:13], v244, s[22:23] offset:2560
	global_load_dwordx2 v[14:15], v244, s[22:23] offset:3072
	global_load_dwordx2 v[16:17], v244, s[22:23] offset:3584
	global_load_dwordx2 v[18:19], v245, s[22:23] offset:0
	global_load_dwordx2 v[20:21], v245, s[22:23] offset:512
	global_load_dwordx2 v[22:23], v245, s[22:23] offset:1024
	global_load_dwordx2 v[24:25], v245, s[22:23] offset:1536
	global_load_dwordx2 v[26:27], v245, s[22:23] offset:2048
	global_load_dwordx2 v[28:29], v245, s[22:23] offset:2560
	global_load_dwordx2 v[30:31], v245, s[22:23] offset:3072
	global_load_dwordx2 v[32:33], v245, s[22:23] offset:3584
	global_load_dwordx2 v[34:35], v244, s[24:25] offset:0
	global_load_dwordx2 v[36:37], v244, s[24:25] offset:512
	global_load_dwordx2 v[38:39], v244, s[24:25] offset:1024
	global_load_dwordx2 v[40:41], v244, s[24:25] offset:1536
	global_load_dwordx2 v[42:43], v244, s[24:25] offset:2048
	global_load_dwordx2 v[44:45], v244, s[24:25] offset:2560
	global_load_dwordx2 v[46:47], v244, s[24:25] offset:3072
	global_load_dwordx2 v[48:49], v244, s[24:25] offset:3584
	global_load_dwordx2 v[50:51], v245, s[24:25] offset:0
	global_load_dwordx2 v[52:53], v245, s[24:25] offset:512
	global_load_dwordx2 v[54:55], v245, s[24:25] offset:1024
	global_load_dwordx2 v[56:57], v245, s[24:25] offset:1536
	global_load_dwordx2 v[58:59], v245, s[24:25] offset:2048
	global_load_dwordx2 v[60:61], v245, s[24:25] offset:2560
	global_load_dwordx2 v[62:63], v245, s[24:25] offset:3072
	global_load_dwordx2 v[64:65], v245, s[24:25] offset:3584
	ds_read_b128 v[130:133], v238 offset:0
	ds_read_b128 v[134:137], v238 offset:16384
	ds_read_b128 v[138:141], v238 offset:1024
	ds_read_b128 v[142:145], v238 offset:17408
	v_lshlrev_b32_e32 v162, 16, v66
	v_and_b32_e32 v163, 0xffff0000, v66
	v_lshlrev_b32_e32 v164, 16, v67
	v_and_b32_e32 v165, 0xffff0000, v67
	v_pk_mul_f32 v[176:177], v[162:163], v[162:163]
	v_pk_mul_f32 v[178:179], v[164:165], v[164:165]
	v_lshlrev_b32_e32 v166, 16, v68
	v_and_b32_e32 v167, 0xffff0000, v68
	v_lshlrev_b32_e32 v168, 16, v69
	v_and_b32_e32 v169, 0xffff0000, v69
	v_pk_fma_f32 v[176:177], v[166:167], v[166:167], v[176:177]
	v_pk_fma_f32 v[178:179], v[168:169], v[168:169], v[178:179]
	v_lshlrev_b32_e32 v162, 16, v70
	v_and_b32_e32 v163, 0xffff0000, v70
	v_lshlrev_b32_e32 v164, 16, v71
	v_and_b32_e32 v165, 0xffff0000, v71
	v_pk_fma_f32 v[176:177], v[162:163], v[162:163], v[176:177]
	v_pk_fma_f32 v[178:179], v[164:165], v[164:165], v[178:179]
	v_lshlrev_b32_e32 v166, 16, v72
	v_and_b32_e32 v167, 0xffff0000, v72
	v_lshlrev_b32_e32 v168, 16, v73
	v_and_b32_e32 v169, 0xffff0000, v73
	v_pk_fma_f32 v[176:177], v[166:167], v[166:167], v[176:177]
	v_pk_fma_f32 v[178:179], v[168:169], v[168:169], v[178:179]
	v_lshlrev_b32_e32 v162, 16, v74
	v_and_b32_e32 v163, 0xffff0000, v74
	v_lshlrev_b32_e32 v164, 16, v75
	v_and_b32_e32 v165, 0xffff0000, v75
	v_pk_fma_f32 v[176:177], v[162:163], v[162:163], v[176:177]
	v_pk_fma_f32 v[178:179], v[164:165], v[164:165], v[178:179]
	v_lshlrev_b32_e32 v166, 16, v76
	v_and_b32_e32 v167, 0xffff0000, v76
	v_lshlrev_b32_e32 v168, 16, v77
	v_and_b32_e32 v169, 0xffff0000, v77
	v_pk_fma_f32 v[176:177], v[166:167], v[166:167], v[176:177]
	v_pk_fma_f32 v[178:179], v[168:169], v[168:169], v[178:179]
	v_lshlrev_b32_e32 v162, 16, v78
	v_and_b32_e32 v163, 0xffff0000, v78
	v_lshlrev_b32_e32 v164, 16, v79
	v_and_b32_e32 v165, 0xffff0000, v79
	v_pk_fma_f32 v[176:177], v[162:163], v[162:163], v[176:177]
	v_pk_fma_f32 v[178:179], v[164:165], v[164:165], v[178:179]
	v_lshlrev_b32_e32 v166, 16, v80
	v_and_b32_e32 v167, 0xffff0000, v80
	v_lshlrev_b32_e32 v168, 16, v81
	v_and_b32_e32 v169, 0xffff0000, v81
	v_pk_fma_f32 v[176:177], v[166:167], v[166:167], v[176:177]
	v_pk_fma_f32 v[178:179], v[168:169], v[168:169], v[178:179]
	v_lshlrev_b32_e32 v162, 16, v82
	v_and_b32_e32 v163, 0xffff0000, v82
	v_lshlrev_b32_e32 v164, 16, v83
	v_and_b32_e32 v165, 0xffff0000, v83
	v_pk_fma_f32 v[176:177], v[162:163], v[162:163], v[176:177]
	v_pk_fma_f32 v[178:179], v[164:165], v[164:165], v[178:179]
	v_lshlrev_b32_e32 v166, 16, v84
	v_and_b32_e32 v167, 0xffff0000, v84
	v_lshlrev_b32_e32 v168, 16, v85
	v_and_b32_e32 v169, 0xffff0000, v85
	v_pk_fma_f32 v[176:177], v[166:167], v[166:167], v[176:177]
	v_pk_fma_f32 v[178:179], v[168:169], v[168:169], v[178:179]
	v_lshlrev_b32_e32 v162, 16, v86
	v_and_b32_e32 v163, 0xffff0000, v86
	v_lshlrev_b32_e32 v164, 16, v87
	v_and_b32_e32 v165, 0xffff0000, v87
	v_pk_fma_f32 v[176:177], v[162:163], v[162:163], v[176:177]
	v_pk_fma_f32 v[178:179], v[164:165], v[164:165], v[178:179]
	v_lshlrev_b32_e32 v166, 16, v88
	v_and_b32_e32 v167, 0xffff0000, v88
	v_lshlrev_b32_e32 v168, 16, v89
	v_and_b32_e32 v169, 0xffff0000, v89
	v_pk_fma_f32 v[176:177], v[166:167], v[166:167], v[176:177]
	v_pk_fma_f32 v[178:179], v[168:169], v[168:169], v[178:179]
	v_lshlrev_b32_e32 v162, 16, v90
	v_and_b32_e32 v163, 0xffff0000, v90
	v_lshlrev_b32_e32 v164, 16, v91
	v_and_b32_e32 v165, 0xffff0000, v91
	v_pk_fma_f32 v[176:177], v[162:163], v[162:163], v[176:177]
	v_pk_fma_f32 v[178:179], v[164:165], v[164:165], v[178:179]
	v_lshlrev_b32_e32 v166, 16, v92
	v_and_b32_e32 v167, 0xffff0000, v92
	v_lshlrev_b32_e32 v168, 16, v93
	v_and_b32_e32 v169, 0xffff0000, v93
	v_pk_fma_f32 v[176:177], v[166:167], v[166:167], v[176:177]
	v_pk_fma_f32 v[178:179], v[168:169], v[168:169], v[178:179]
	v_lshlrev_b32_e32 v162, 16, v94
	v_and_b32_e32 v163, 0xffff0000, v94
	v_lshlrev_b32_e32 v164, 16, v95
	v_and_b32_e32 v165, 0xffff0000, v95
	v_pk_fma_f32 v[176:177], v[162:163], v[162:163], v[176:177]
	v_pk_fma_f32 v[178:179], v[164:165], v[164:165], v[178:179]
	v_lshlrev_b32_e32 v166, 16, v96
	v_and_b32_e32 v167, 0xffff0000, v96
	v_lshlrev_b32_e32 v168, 16, v97
	v_and_b32_e32 v169, 0xffff0000, v97
	v_pk_fma_f32 v[176:177], v[166:167], v[166:167], v[176:177]
	v_pk_fma_f32 v[178:179], v[168:169], v[168:169], v[178:179]
	v_pk_add_f32 v[176:177], v[176:177], v[178:179]
	s_nop 0
	v_add_f32_e32 v252, v176, v177
	s_waitcnt lgkmcnt(0)
	ds_bpermute_b32 v254, v246, v252
	s_waitcnt lgkmcnt(0)
	v_add_f32_e32 v252, v252, v254
	ds_bpermute_b32 v254, v247, v252
	s_waitcnt lgkmcnt(0)
	v_add_f32_e32 v252, v252, v254
	ds_bpermute_b32 v254, v248, v252
	s_waitcnt lgkmcnt(0)
	v_add_f32_e32 v252, v252, v254
	ds_bpermute_b32 v254, v249, v252
	s_waitcnt lgkmcnt(0)
	v_add_f32_e32 v252, v252, v254
	ds_bpermute_b32 v254, v250, v252
	s_waitcnt lgkmcnt(0)
	v_add_f32_e32 v252, v252, v254
	ds_bpermute_b32 v254, v251, v252
	s_waitcnt lgkmcnt(0)
	v_add_f32_e32 v252, v252, v254
	v_mov_b32_e32 v254, 0x358637bd
	v_fmac_f32_e32 v254, 0x39800000, v252
	v_mul_f32_e32 v252, 0x4b800000, v254
	v_cmp_gt_f32_e32 vcc, s20, v254
	s_nop 1
	v_cndmask_b32_e32 v254, v254, v252, vcc
	v_rsq_f32_e32 v254, v254
	s_nop 0
	v_mul_f32_e32 v252, 0x45800000, v254
	v_cndmask_b32_e32 v252, v254, v252, vcc
	ds_read_b128 v[146:149], v238 offset:2048
	ds_read_b128 v[150:153], v238 offset:18432
	ds_read_b128 v[154:157], v238 offset:3072
	ds_read_b128 v[158:161], v238 offset:19456
	s_waitcnt lgkmcnt(4)
	v_lshlrev_b32_e32 v162, 16, v66
	v_and_b32_e32 v163, 0xffff0000, v66
	v_lshlrev_b32_e32 v164, 16, v67
	v_and_b32_e32 v165, 0xffff0000, v67
	v_lshlrev_b32_e32 v166, 16, v98
	v_and_b32_e32 v167, 0xffff0000, v98
	v_lshlrev_b32_e32 v168, 16, v99
	v_and_b32_e32 v169, 0xffff0000, v99
	v_pk_mul_f32 v[162:163], v[162:163], v[252:253] op_sel_hi:[1,0]
	v_pk_mul_f32 v[164:165], v[164:165], v[252:253] op_sel_hi:[1,0]
	v_pk_mul_f32 v[162:163], v[162:163], v[130:131]
	v_pk_mul_f32 v[164:165], v[164:165], v[132:133]
	v_pk_fma_f32 v[162:163], v[134:135], v[162:163], v[166:167]
	v_pk_fma_f32 v[164:165], v[136:137], v[164:165], v[168:169]
	s_nop 0
	global_store_dwordx4 v238, v[162:165], s[30:31] offset:0 nt
	s_nop 1
	v_lshlrev_b32_e32 v162, 16, v68
	v_and_b32_e32 v163, 0xffff0000, v68
	v_lshlrev_b32_e32 v164, 16, v69
	v_and_b32_e32 v165, 0xffff0000, v69
	v_lshlrev_b32_e32 v166, 16, v100
	v_and_b32_e32 v167, 0xffff0000, v100
	v_lshlrev_b32_e32 v168, 16, v101
	v_and_b32_e32 v169, 0xffff0000, v101
	v_pk_mul_f32 v[162:163], v[162:163], v[252:253] op_sel_hi:[1,0]
	v_pk_mul_f32 v[164:165], v[164:165], v[252:253] op_sel_hi:[1,0]
	v_pk_mul_f32 v[162:163], v[162:163], v[138:139]
	v_pk_mul_f32 v[164:165], v[164:165], v[140:141]
	v_pk_fma_f32 v[162:163], v[142:143], v[162:163], v[166:167]
	v_pk_fma_f32 v[164:165], v[144:145], v[164:165], v[168:169]
	s_nop 0
	global_store_dwordx4 v238, v[162:165], s[30:31] offset:1024 nt
	s_nop 1
	ds_read_b128 v[130:133], v238 offset:4096
	ds_read_b128 v[134:137], v238 offset:20480
	ds_read_b128 v[138:141], v238 offset:5120
	ds_read_b128 v[142:145], v238 offset:21504
	s_waitcnt lgkmcnt(4)
	v_lshlrev_b32_e32 v162, 16, v70
	v_and_b32_e32 v163, 0xffff0000, v70
	v_lshlrev_b32_e32 v164, 16, v71
	v_and_b32_e32 v165, 0xffff0000, v71
	v_lshlrev_b32_e32 v166, 16, v102
	v_and_b32_e32 v167, 0xffff0000, v102
	v_lshlrev_b32_e32 v168, 16, v103
	v_and_b32_e32 v169, 0xffff0000, v103
	v_pk_mul_f32 v[162:163], v[162:163], v[252:253] op_sel_hi:[1,0]
	v_pk_mul_f32 v[164:165], v[164:165], v[252:253] op_sel_hi:[1,0]
	v_pk_mul_f32 v[162:163], v[162:163], v[146:147]
	v_pk_mul_f32 v[164:165], v[164:165], v[148:149]
	v_pk_fma_f32 v[162:163], v[150:151], v[162:163], v[166:167]
	v_pk_fma_f32 v[164:165], v[152:153], v[164:165], v[168:169]
	s_nop 0
	global_store_dwordx4 v238, v[162:165], s[30:31] offset:2048 nt
	s_nop 1
	v_lshlrev_b32_e32 v162, 16, v72
	v_and_b32_e32 v163, 0xffff0000, v72
	v_lshlrev_b32_e32 v164, 16, v73
	v_and_b32_e32 v165, 0xffff0000, v73
	v_lshlrev_b32_e32 v166, 16, v104
	v_and_b32_e32 v167, 0xffff0000, v104
	v_lshlrev_b32_e32 v168, 16, v105
	v_and_b32_e32 v169, 0xffff0000, v105
	v_pk_mul_f32 v[162:163], v[162:163], v[252:253] op_sel_hi:[1,0]
	v_pk_mul_f32 v[164:165], v[164:165], v[252:253] op_sel_hi:[1,0]
	v_pk_mul_f32 v[162:163], v[162:163], v[154:155]
	v_pk_mul_f32 v[164:165], v[164:165], v[156:157]
	v_pk_fma_f32 v[162:163], v[158:159], v[162:163], v[166:167]
	v_pk_fma_f32 v[164:165], v[160:161], v[164:165], v[168:169]
	s_nop 0
	global_store_dwordx4 v238, v[162:165], s[30:31] offset:3072 nt
	s_nop 1
	ds_read_b128 v[146:149], v238 offset:6144
	ds_read_b128 v[150:153], v238 offset:22528
	ds_read_b128 v[154:157], v238 offset:7168
	ds_read_b128 v[158:161], v238 offset:23552
	s_waitcnt lgkmcnt(4)
	v_lshlrev_b32_e32 v162, 16, v74
	v_and_b32_e32 v163, 0xffff0000, v74
	v_lshlrev_b32_e32 v164, 16, v75
	v_and_b32_e32 v165, 0xffff0000, v75
	v_lshlrev_b32_e32 v166, 16, v106
	v_and_b32_e32 v167, 0xffff0000, v106
	v_lshlrev_b32_e32 v168, 16, v107
	v_and_b32_e32 v169, 0xffff0000, v107
	v_pk_mul_f32 v[162:163], v[162:163], v[252:253] op_sel_hi:[1,0]
	v_pk_mul_f32 v[164:165], v[164:165], v[252:253] op_sel_hi:[1,0]
	v_pk_mul_f32 v[162:163], v[162:163], v[130:131]
	v_pk_mul_f32 v[164:165], v[164:165], v[132:133]
	v_pk_fma_f32 v[162:163], v[134:135], v[162:163], v[166:167]
	v_pk_fma_f32 v[164:165], v[136:137], v[164:165], v[168:169]
	s_nop 0
	global_store_dwordx4 v241, v[162:165], s[30:31] offset:0 nt
	s_nop 1
	v_lshlrev_b32_e32 v162, 16, v76
	v_and_b32_e32 v163, 0xffff0000, v76
	v_lshlrev_b32_e32 v164, 16, v77
	v_and_b32_e32 v165, 0xffff0000, v77
	v_lshlrev_b32_e32 v166, 16, v108
	v_and_b32_e32 v167, 0xffff0000, v108
	v_lshlrev_b32_e32 v168, 16, v109
	v_and_b32_e32 v169, 0xffff0000, v109
	v_pk_mul_f32 v[162:163], v[162:163], v[252:253] op_sel_hi:[1,0]
	v_pk_mul_f32 v[164:165], v[164:165], v[252:253] op_sel_hi:[1,0]
	v_pk_mul_f32 v[162:163], v[162:163], v[138:139]
	v_pk_mul_f32 v[164:165], v[164:165], v[140:141]
	v_pk_fma_f32 v[162:163], v[142:143], v[162:163], v[166:167]
	v_pk_fma_f32 v[164:165], v[144:145], v[164:165], v[168:169]
	s_nop 0
	global_store_dwordx4 v241, v[162:165], s[30:31] offset:1024 nt
	s_nop 1
	ds_read_b128 v[130:133], v238 offset:8192
	ds_read_b128 v[134:137], v238 offset:24576
	ds_read_b128 v[138:141], v238 offset:9216
	ds_read_b128 v[142:145], v238 offset:25600
	s_waitcnt lgkmcnt(4)
	v_lshlrev_b32_e32 v162, 16, v78
	v_and_b32_e32 v163, 0xffff0000, v78
	v_lshlrev_b32_e32 v164, 16, v79
	v_and_b32_e32 v165, 0xffff0000, v79
	v_lshlrev_b32_e32 v166, 16, v110
	v_and_b32_e32 v167, 0xffff0000, v110
	v_lshlrev_b32_e32 v168, 16, v111
	v_and_b32_e32 v169, 0xffff0000, v111
	v_pk_mul_f32 v[162:163], v[162:163], v[252:253] op_sel_hi:[1,0]
	v_pk_mul_f32 v[164:165], v[164:165], v[252:253] op_sel_hi:[1,0]
	v_pk_mul_f32 v[162:163], v[162:163], v[146:147]
	v_pk_mul_f32 v[164:165], v[164:165], v[148:149]
	v_pk_fma_f32 v[162:163], v[150:151], v[162:163], v[166:167]
	v_pk_fma_f32 v[164:165], v[152:153], v[164:165], v[168:169]
	s_nop 0
	global_store_dwordx4 v241, v[162:165], s[30:31] offset:2048 nt
	s_nop 1
	v_lshlrev_b32_e32 v162, 16, v80
	v_and_b32_e32 v163, 0xffff0000, v80
	v_lshlrev_b32_e32 v164, 16, v81
	v_and_b32_e32 v165, 0xffff0000, v81
	v_lshlrev_b32_e32 v166, 16, v112
	v_and_b32_e32 v167, 0xffff0000, v112
	v_lshlrev_b32_e32 v168, 16, v113
	v_and_b32_e32 v169, 0xffff0000, v113
	v_pk_mul_f32 v[162:163], v[162:163], v[252:253] op_sel_hi:[1,0]
	v_pk_mul_f32 v[164:165], v[164:165], v[252:253] op_sel_hi:[1,0]
	v_pk_mul_f32 v[162:163], v[162:163], v[154:155]
	v_pk_mul_f32 v[164:165], v[164:165], v[156:157]
	v_pk_fma_f32 v[162:163], v[158:159], v[162:163], v[166:167]
	v_pk_fma_f32 v[164:165], v[160:161], v[164:165], v[168:169]
	s_nop 0
	global_store_dwordx4 v241, v[162:165], s[30:31] offset:3072 nt
	s_nop 1
	ds_read_b128 v[146:149], v238 offset:10240
	ds_read_b128 v[150:153], v238 offset:26624
	ds_read_b128 v[154:157], v238 offset:11264
	ds_read_b128 v[158:161], v238 offset:27648
	s_waitcnt lgkmcnt(4)
	v_lshlrev_b32_e32 v162, 16, v82
	v_and_b32_e32 v163, 0xffff0000, v82
	v_lshlrev_b32_e32 v164, 16, v83
	v_and_b32_e32 v165, 0xffff0000, v83
	v_lshlrev_b32_e32 v166, 16, v114
	v_and_b32_e32 v167, 0xffff0000, v114
	v_lshlrev_b32_e32 v168, 16, v115
	v_and_b32_e32 v169, 0xffff0000, v115
	v_pk_mul_f32 v[162:163], v[162:163], v[252:253] op_sel_hi:[1,0]
	v_pk_mul_f32 v[164:165], v[164:165], v[252:253] op_sel_hi:[1,0]
	v_pk_mul_f32 v[162:163], v[162:163], v[130:131]
	v_pk_mul_f32 v[164:165], v[164:165], v[132:133]
	v_pk_fma_f32 v[162:163], v[134:135], v[162:163], v[166:167]
	v_pk_fma_f32 v[164:165], v[136:137], v[164:165], v[168:169]
	s_nop 0
	global_store_dwordx4 v242, v[162:165], s[30:31] offset:0 nt
	s_nop 1
	v_lshlrev_b32_e32 v162, 16, v84
	v_and_b32_e32 v163, 0xffff0000, v84
	v_lshlrev_b32_e32 v164, 16, v85
	v_and_b32_e32 v165, 0xffff0000, v85
	v_lshlrev_b32_e32 v166, 16, v116
	v_and_b32_e32 v167, 0xffff0000, v116
	v_lshlrev_b32_e32 v168, 16, v117
	v_and_b32_e32 v169, 0xffff0000, v117
	v_pk_mul_f32 v[162:163], v[162:163], v[252:253] op_sel_hi:[1,0]
	v_pk_mul_f32 v[164:165], v[164:165], v[252:253] op_sel_hi:[1,0]
	v_pk_mul_f32 v[162:163], v[162:163], v[138:139]
	v_pk_mul_f32 v[164:165], v[164:165], v[140:141]
	v_pk_fma_f32 v[162:163], v[142:143], v[162:163], v[166:167]
	v_pk_fma_f32 v[164:165], v[144:145], v[164:165], v[168:169]
	s_nop 0
	global_store_dwordx4 v242, v[162:165], s[30:31] offset:1024 nt
	s_nop 1
	ds_read_b128 v[130:133], v238 offset:12288
	ds_read_b128 v[134:137], v238 offset:28672
	ds_read_b128 v[138:141], v238 offset:13312
	ds_read_b128 v[142:145], v238 offset:29696
	s_waitcnt lgkmcnt(4)
	v_lshlrev_b32_e32 v162, 16, v86
	v_and_b32_e32 v163, 0xffff0000, v86
	v_lshlrev_b32_e32 v164, 16, v87
	v_and_b32_e32 v165, 0xffff0000, v87
	v_lshlrev_b32_e32 v166, 16, v118
	v_and_b32_e32 v167, 0xffff0000, v118
	v_lshlrev_b32_e32 v168, 16, v119
	v_and_b32_e32 v169, 0xffff0000, v119
	v_pk_mul_f32 v[162:163], v[162:163], v[252:253] op_sel_hi:[1,0]
	v_pk_mul_f32 v[164:165], v[164:165], v[252:253] op_sel_hi:[1,0]
	v_pk_mul_f32 v[162:163], v[162:163], v[146:147]
	v_pk_mul_f32 v[164:165], v[164:165], v[148:149]
	v_pk_fma_f32 v[162:163], v[150:151], v[162:163], v[166:167]
	v_pk_fma_f32 v[164:165], v[152:153], v[164:165], v[168:169]
	s_nop 0
	global_store_dwordx4 v242, v[162:165], s[30:31] offset:2048 nt
	s_nop 1
	v_lshlrev_b32_e32 v162, 16, v88
	v_and_b32_e32 v163, 0xffff0000, v88
	v_lshlrev_b32_e32 v164, 16, v89
	v_and_b32_e32 v165, 0xffff0000, v89
	v_lshlrev_b32_e32 v166, 16, v120
	v_and_b32_e32 v167, 0xffff0000, v120
	v_lshlrev_b32_e32 v168, 16, v121
	v_and_b32_e32 v169, 0xffff0000, v121
	v_pk_mul_f32 v[162:163], v[162:163], v[252:253] op_sel_hi:[1,0]
	v_pk_mul_f32 v[164:165], v[164:165], v[252:253] op_sel_hi:[1,0]
	v_pk_mul_f32 v[162:163], v[162:163], v[154:155]
	v_pk_mul_f32 v[164:165], v[164:165], v[156:157]
	v_pk_fma_f32 v[162:163], v[158:159], v[162:163], v[166:167]
	v_pk_fma_f32 v[164:165], v[160:161], v[164:165], v[168:169]
	s_nop 0
	global_store_dwordx4 v242, v[162:165], s[30:31] offset:3072 nt
	s_nop 1
	ds_read_b128 v[146:149], v238 offset:14336
	ds_read_b128 v[150:153], v238 offset:30720
	ds_read_b128 v[154:157], v238 offset:15360
	ds_read_b128 v[158:161], v238 offset:31744
	s_waitcnt lgkmcnt(4)
	v_lshlrev_b32_e32 v162, 16, v90
	v_and_b32_e32 v163, 0xffff0000, v90
	v_lshlrev_b32_e32 v164, 16, v91
	v_and_b32_e32 v165, 0xffff0000, v91
	v_lshlrev_b32_e32 v166, 16, v122
	v_and_b32_e32 v167, 0xffff0000, v122
	v_lshlrev_b32_e32 v168, 16, v123
	v_and_b32_e32 v169, 0xffff0000, v123
	v_pk_mul_f32 v[162:163], v[162:163], v[252:253] op_sel_hi:[1,0]
	v_pk_mul_f32 v[164:165], v[164:165], v[252:253] op_sel_hi:[1,0]
	v_pk_mul_f32 v[162:163], v[162:163], v[130:131]
	v_pk_mul_f32 v[164:165], v[164:165], v[132:133]
	v_pk_fma_f32 v[162:163], v[134:135], v[162:163], v[166:167]
	v_pk_fma_f32 v[164:165], v[136:137], v[164:165], v[168:169]
	s_nop 0
	global_store_dwordx4 v243, v[162:165], s[30:31] offset:0 nt
	s_nop 1
	v_lshlrev_b32_e32 v162, 16, v92
	v_and_b32_e32 v163, 0xffff0000, v92
	v_lshlrev_b32_e32 v164, 16, v93
	v_and_b32_e32 v165, 0xffff0000, v93
	v_lshlrev_b32_e32 v166, 16, v124
	v_and_b32_e32 v167, 0xffff0000, v124
	v_lshlrev_b32_e32 v168, 16, v125
	v_and_b32_e32 v169, 0xffff0000, v125
	v_pk_mul_f32 v[162:163], v[162:163], v[252:253] op_sel_hi:[1,0]
	v_pk_mul_f32 v[164:165], v[164:165], v[252:253] op_sel_hi:[1,0]
	v_pk_mul_f32 v[162:163], v[162:163], v[138:139]
	v_pk_mul_f32 v[164:165], v[164:165], v[140:141]
	v_pk_fma_f32 v[162:163], v[142:143], v[162:163], v[166:167]
	v_pk_fma_f32 v[164:165], v[144:145], v[164:165], v[168:169]
	s_nop 0
	global_store_dwordx4 v243, v[162:165], s[30:31] offset:1024 nt
	s_nop 1
	s_waitcnt lgkmcnt(0)
	v_lshlrev_b32_e32 v162, 16, v94
	v_and_b32_e32 v163, 0xffff0000, v94
	v_lshlrev_b32_e32 v164, 16, v95
	v_and_b32_e32 v165, 0xffff0000, v95
	v_lshlrev_b32_e32 v166, 16, v126
	v_and_b32_e32 v167, 0xffff0000, v126
	v_lshlrev_b32_e32 v168, 16, v127
	v_and_b32_e32 v169, 0xffff0000, v127
	v_pk_mul_f32 v[162:163], v[162:163], v[252:253] op_sel_hi:[1,0]
	v_pk_mul_f32 v[164:165], v[164:165], v[252:253] op_sel_hi:[1,0]
	v_pk_mul_f32 v[162:163], v[162:163], v[146:147]
	v_pk_mul_f32 v[164:165], v[164:165], v[148:149]
	v_pk_fma_f32 v[162:163], v[150:151], v[162:163], v[166:167]
	v_pk_fma_f32 v[164:165], v[152:153], v[164:165], v[168:169]
	s_nop 0
	global_store_dwordx4 v243, v[162:165], s[30:31] offset:2048 nt
	s_nop 1
	v_lshlrev_b32_e32 v162, 16, v96
	v_and_b32_e32 v163, 0xffff0000, v96
	v_lshlrev_b32_e32 v164, 16, v97
	v_and_b32_e32 v165, 0xffff0000, v97
	v_lshlrev_b32_e32 v166, 16, v128
	v_and_b32_e32 v167, 0xffff0000, v128
	v_lshlrev_b32_e32 v168, 16, v129
	v_and_b32_e32 v169, 0xffff0000, v129
	v_pk_mul_f32 v[162:163], v[162:163], v[252:253] op_sel_hi:[1,0]
	v_pk_mul_f32 v[164:165], v[164:165], v[252:253] op_sel_hi:[1,0]
	v_pk_mul_f32 v[162:163], v[162:163], v[154:155]
	v_pk_mul_f32 v[164:165], v[164:165], v[156:157]
	v_pk_fma_f32 v[162:163], v[158:159], v[162:163], v[166:167]
	v_pk_fma_f32 v[164:165], v[160:161], v[164:165], v[168:169]
	s_nop 0
	global_store_dwordx4 v243, v[162:165], s[30:31] offset:3072 nt
	s_nop 1
	s_add_u32 s30, s30, 0x2000000
	s_addc_u32 s31, s31, 0
	s_waitcnt vmcnt(16)
	s_add_u32 s22, s22, 0x1000000
	s_addc_u32 s23, s23, 0
	s_add_u32 s24, s24, 0x1000000
	s_addc_u32 s25, s25, 0
	global_load_dwordx2 v[66:67], v244, s[22:23] offset:0
	global_load_dwordx2 v[68:69], v244, s[22:23] offset:512
	global_load_dwordx2 v[70:71], v244, s[22:23] offset:1024
	global_load_dwordx2 v[72:73], v244, s[22:23] offset:1536
	global_load_dwordx2 v[74:75], v244, s[22:23] offset:2048
	global_load_dwordx2 v[76:77], v244, s[22:23] offset:2560
	global_load_dwordx2 v[78:79], v244, s[22:23] offset:3072
	global_load_dwordx2 v[80:81], v244, s[22:23] offset:3584
	global_load_dwordx2 v[82:83], v245, s[22:23] offset:0
	global_load_dwordx2 v[84:85], v245, s[22:23] offset:512
	global_load_dwordx2 v[86:87], v245, s[22:23] offset:1024
	global_load_dwordx2 v[88:89], v245, s[22:23] offset:1536
	global_load_dwordx2 v[90:91], v245, s[22:23] offset:2048
	global_load_dwordx2 v[92:93], v245, s[22:23] offset:2560
	global_load_dwordx2 v[94:95], v245, s[22:23] offset:3072
	global_load_dwordx2 v[96:97], v245, s[22:23] offset:3584
	global_load_dwordx2 v[98:99], v244, s[24:25] offset:0
	global_load_dwordx2 v[100:101], v244, s[24:25] offset:512
	global_load_dwordx2 v[102:103], v244, s[24:25] offset:1024
	global_load_dwordx2 v[104:105], v244, s[24:25] offset:1536
	global_load_dwordx2 v[106:107], v244, s[24:25] offset:2048
	global_load_dwordx2 v[108:109], v244, s[24:25] offset:2560
	global_load_dwordx2 v[110:111], v244, s[24:25] offset:3072
	global_load_dwordx2 v[112:113], v244, s[24:25] offset:3584
	global_load_dwordx2 v[114:115], v245, s[24:25] offset:0
	global_load_dwordx2 v[116:117], v245, s[24:25] offset:512
	global_load_dwordx2 v[118:119], v245, s[24:25] offset:1024
	global_load_dwordx2 v[120:121], v245, s[24:25] offset:1536
	global_load_dwordx2 v[122:123], v245, s[24:25] offset:2048
	global_load_dwordx2 v[124:125], v245, s[24:25] offset:2560
	global_load_dwordx2 v[126:127], v245, s[24:25] offset:3072
	global_load_dwordx2 v[128:129], v245, s[24:25] offset:3584
	ds_read_b128 v[130:133], v238 offset:0
	ds_read_b128 v[134:137], v238 offset:16384
	ds_read_b128 v[138:141], v238 offset:1024
	ds_read_b128 v[142:145], v238 offset:17408
	v_lshlrev_b32_e32 v162, 16, v2
	v_and_b32_e32 v163, 0xffff0000, v2
	v_lshlrev_b32_e32 v164, 16, v3
	v_and_b32_e32 v165, 0xffff0000, v3
	v_pk_mul_f32 v[176:177], v[162:163], v[162:163]
	v_pk_mul_f32 v[178:179], v[164:165], v[164:165]
	v_lshlrev_b32_e32 v166, 16, v4
	v_and_b32_e32 v167, 0xffff0000, v4
	v_lshlrev_b32_e32 v168, 16, v5
	v_and_b32_e32 v169, 0xffff0000, v5
	v_pk_fma_f32 v[176:177], v[166:167], v[166:167], v[176:177]
	v_pk_fma_f32 v[178:179], v[168:169], v[168:169], v[178:179]
	v_lshlrev_b32_e32 v162, 16, v6
	v_and_b32_e32 v163, 0xffff0000, v6
	v_lshlrev_b32_e32 v164, 16, v7
	v_and_b32_e32 v165, 0xffff0000, v7
	v_pk_fma_f32 v[176:177], v[162:163], v[162:163], v[176:177]
	v_pk_fma_f32 v[178:179], v[164:165], v[164:165], v[178:179]
	v_lshlrev_b32_e32 v166, 16, v8
	v_and_b32_e32 v167, 0xffff0000, v8
	v_lshlrev_b32_e32 v168, 16, v9
	v_and_b32_e32 v169, 0xffff0000, v9
	v_pk_fma_f32 v[176:177], v[166:167], v[166:167], v[176:177]
	v_pk_fma_f32 v[178:179], v[168:169], v[168:169], v[178:179]
	v_lshlrev_b32_e32 v162, 16, v10
	v_and_b32_e32 v163, 0xffff0000, v10
	v_lshlrev_b32_e32 v164, 16, v11
	v_and_b32_e32 v165, 0xffff0000, v11
	v_pk_fma_f32 v[176:177], v[162:163], v[162:163], v[176:177]
	v_pk_fma_f32 v[178:179], v[164:165], v[164:165], v[178:179]
	v_lshlrev_b32_e32 v166, 16, v12
	v_and_b32_e32 v167, 0xffff0000, v12
	v_lshlrev_b32_e32 v168, 16, v13
	v_and_b32_e32 v169, 0xffff0000, v13
	v_pk_fma_f32 v[176:177], v[166:167], v[166:167], v[176:177]
	v_pk_fma_f32 v[178:179], v[168:169], v[168:169], v[178:179]
	v_lshlrev_b32_e32 v162, 16, v14
	v_and_b32_e32 v163, 0xffff0000, v14
	v_lshlrev_b32_e32 v164, 16, v15
	v_and_b32_e32 v165, 0xffff0000, v15
	v_pk_fma_f32 v[176:177], v[162:163], v[162:163], v[176:177]
	v_pk_fma_f32 v[178:179], v[164:165], v[164:165], v[178:179]
	v_lshlrev_b32_e32 v166, 16, v16
	v_and_b32_e32 v167, 0xffff0000, v16
	v_lshlrev_b32_e32 v168, 16, v17
	v_and_b32_e32 v169, 0xffff0000, v17
	v_pk_fma_f32 v[176:177], v[166:167], v[166:167], v[176:177]
	v_pk_fma_f32 v[178:179], v[168:169], v[168:169], v[178:179]
	v_lshlrev_b32_e32 v162, 16, v18
	v_and_b32_e32 v163, 0xffff0000, v18
	v_lshlrev_b32_e32 v164, 16, v19
	v_and_b32_e32 v165, 0xffff0000, v19
	v_pk_fma_f32 v[176:177], v[162:163], v[162:163], v[176:177]
	v_pk_fma_f32 v[178:179], v[164:165], v[164:165], v[178:179]
	v_lshlrev_b32_e32 v166, 16, v20
	v_and_b32_e32 v167, 0xffff0000, v20
	v_lshlrev_b32_e32 v168, 16, v21
	v_and_b32_e32 v169, 0xffff0000, v21
	v_pk_fma_f32 v[176:177], v[166:167], v[166:167], v[176:177]
	v_pk_fma_f32 v[178:179], v[168:169], v[168:169], v[178:179]
	v_lshlrev_b32_e32 v162, 16, v22
	v_and_b32_e32 v163, 0xffff0000, v22
	v_lshlrev_b32_e32 v164, 16, v23
	v_and_b32_e32 v165, 0xffff0000, v23
	v_pk_fma_f32 v[176:177], v[162:163], v[162:163], v[176:177]
	v_pk_fma_f32 v[178:179], v[164:165], v[164:165], v[178:179]
	v_lshlrev_b32_e32 v166, 16, v24
	v_and_b32_e32 v167, 0xffff0000, v24
	v_lshlrev_b32_e32 v168, 16, v25
	v_and_b32_e32 v169, 0xffff0000, v25
	v_pk_fma_f32 v[176:177], v[166:167], v[166:167], v[176:177]
	v_pk_fma_f32 v[178:179], v[168:169], v[168:169], v[178:179]
	v_lshlrev_b32_e32 v162, 16, v26
	v_and_b32_e32 v163, 0xffff0000, v26
	v_lshlrev_b32_e32 v164, 16, v27
	v_and_b32_e32 v165, 0xffff0000, v27
	v_pk_fma_f32 v[176:177], v[162:163], v[162:163], v[176:177]
	v_pk_fma_f32 v[178:179], v[164:165], v[164:165], v[178:179]
	v_lshlrev_b32_e32 v166, 16, v28
	v_and_b32_e32 v167, 0xffff0000, v28
	v_lshlrev_b32_e32 v168, 16, v29
	v_and_b32_e32 v169, 0xffff0000, v29
	v_pk_fma_f32 v[176:177], v[166:167], v[166:167], v[176:177]
	v_pk_fma_f32 v[178:179], v[168:169], v[168:169], v[178:179]
	v_lshlrev_b32_e32 v162, 16, v30
	v_and_b32_e32 v163, 0xffff0000, v30
	v_lshlrev_b32_e32 v164, 16, v31
	v_and_b32_e32 v165, 0xffff0000, v31
	v_pk_fma_f32 v[176:177], v[162:163], v[162:163], v[176:177]
	v_pk_fma_f32 v[178:179], v[164:165], v[164:165], v[178:179]
	v_lshlrev_b32_e32 v166, 16, v32
	v_and_b32_e32 v167, 0xffff0000, v32
	v_lshlrev_b32_e32 v168, 16, v33
	v_and_b32_e32 v169, 0xffff0000, v33
	v_pk_fma_f32 v[176:177], v[166:167], v[166:167], v[176:177]
	v_pk_fma_f32 v[178:179], v[168:169], v[168:169], v[178:179]
	v_pk_add_f32 v[176:177], v[176:177], v[178:179]
	s_nop 0
	v_add_f32_e32 v252, v176, v177
	s_waitcnt lgkmcnt(0)
	ds_bpermute_b32 v254, v246, v252
	s_waitcnt lgkmcnt(0)
	v_add_f32_e32 v252, v252, v254
	ds_bpermute_b32 v254, v247, v252
	s_waitcnt lgkmcnt(0)
	v_add_f32_e32 v252, v252, v254
	ds_bpermute_b32 v254, v248, v252
	s_waitcnt lgkmcnt(0)
	v_add_f32_e32 v252, v252, v254
	ds_bpermute_b32 v254, v249, v252
	s_waitcnt lgkmcnt(0)
	v_add_f32_e32 v252, v252, v254
	ds_bpermute_b32 v254, v250, v252
	s_waitcnt lgkmcnt(0)
	v_add_f32_e32 v252, v252, v254
	ds_bpermute_b32 v254, v251, v252
	s_waitcnt lgkmcnt(0)
	v_add_f32_e32 v252, v252, v254
	v_mov_b32_e32 v254, 0x358637bd
	v_fmac_f32_e32 v254, 0x39800000, v252
	v_mul_f32_e32 v252, 0x4b800000, v254
	v_cmp_gt_f32_e32 vcc, s20, v254
	s_nop 1
	v_cndmask_b32_e32 v254, v254, v252, vcc
	v_rsq_f32_e32 v254, v254
	s_nop 0
	v_mul_f32_e32 v252, 0x45800000, v254
	v_cndmask_b32_e32 v252, v254, v252, vcc
	ds_read_b128 v[146:149], v238 offset:2048
	ds_read_b128 v[150:153], v238 offset:18432
	ds_read_b128 v[154:157], v238 offset:3072
	ds_read_b128 v[158:161], v238 offset:19456
	s_waitcnt lgkmcnt(4)
	v_lshlrev_b32_e32 v162, 16, v2
	v_and_b32_e32 v163, 0xffff0000, v2
	v_lshlrev_b32_e32 v164, 16, v3
	v_and_b32_e32 v165, 0xffff0000, v3
	v_lshlrev_b32_e32 v166, 16, v34
	v_and_b32_e32 v167, 0xffff0000, v34
	v_lshlrev_b32_e32 v168, 16, v35
	v_and_b32_e32 v169, 0xffff0000, v35
	v_pk_mul_f32 v[162:163], v[162:163], v[252:253] op_sel_hi:[1,0]
	v_pk_mul_f32 v[164:165], v[164:165], v[252:253] op_sel_hi:[1,0]
	v_pk_mul_f32 v[162:163], v[162:163], v[130:131]
	v_pk_mul_f32 v[164:165], v[164:165], v[132:133]
	v_pk_fma_f32 v[162:163], v[134:135], v[162:163], v[166:167]
	v_pk_fma_f32 v[164:165], v[136:137], v[164:165], v[168:169]
	s_nop 0
	global_store_dwordx4 v238, v[162:165], s[30:31] offset:0 nt
	s_nop 1
	v_lshlrev_b32_e32 v162, 16, v4
	v_and_b32_e32 v163, 0xffff0000, v4
	v_lshlrev_b32_e32 v164, 16, v5
	v_and_b32_e32 v165, 0xffff0000, v5
	v_lshlrev_b32_e32 v166, 16, v36
	v_and_b32_e32 v167, 0xffff0000, v36
	v_lshlrev_b32_e32 v168, 16, v37
	v_and_b32_e32 v169, 0xffff0000, v37
	v_pk_mul_f32 v[162:163], v[162:163], v[252:253] op_sel_hi:[1,0]
	v_pk_mul_f32 v[164:165], v[164:165], v[252:253] op_sel_hi:[1,0]
	v_pk_mul_f32 v[162:163], v[162:163], v[138:139]
	v_pk_mul_f32 v[164:165], v[164:165], v[140:141]
	v_pk_fma_f32 v[162:163], v[142:143], v[162:163], v[166:167]
	v_pk_fma_f32 v[164:165], v[144:145], v[164:165], v[168:169]
	s_nop 0
	global_store_dwordx4 v238, v[162:165], s[30:31] offset:1024 nt
	s_nop 1
	ds_read_b128 v[130:133], v238 offset:4096
	ds_read_b128 v[134:137], v238 offset:20480
	ds_read_b128 v[138:141], v238 offset:5120
	ds_read_b128 v[142:145], v238 offset:21504
	s_waitcnt lgkmcnt(4)
	v_lshlrev_b32_e32 v162, 16, v6
	v_and_b32_e32 v163, 0xffff0000, v6
	v_lshlrev_b32_e32 v164, 16, v7
	v_and_b32_e32 v165, 0xffff0000, v7
	v_lshlrev_b32_e32 v166, 16, v38
	v_and_b32_e32 v167, 0xffff0000, v38
	v_lshlrev_b32_e32 v168, 16, v39
	v_and_b32_e32 v169, 0xffff0000, v39
	v_pk_mul_f32 v[162:163], v[162:163], v[252:253] op_sel_hi:[1,0]
	v_pk_mul_f32 v[164:165], v[164:165], v[252:253] op_sel_hi:[1,0]
	v_pk_mul_f32 v[162:163], v[162:163], v[146:147]
	v_pk_mul_f32 v[164:165], v[164:165], v[148:149]
	v_pk_fma_f32 v[162:163], v[150:151], v[162:163], v[166:167]
	v_pk_fma_f32 v[164:165], v[152:153], v[164:165], v[168:169]
	s_nop 0
	global_store_dwordx4 v238, v[162:165], s[30:31] offset:2048 nt
	s_nop 1
	v_lshlrev_b32_e32 v162, 16, v8
	v_and_b32_e32 v163, 0xffff0000, v8
	v_lshlrev_b32_e32 v164, 16, v9
	v_and_b32_e32 v165, 0xffff0000, v9
	v_lshlrev_b32_e32 v166, 16, v40
	v_and_b32_e32 v167, 0xffff0000, v40
	v_lshlrev_b32_e32 v168, 16, v41
	v_and_b32_e32 v169, 0xffff0000, v41
	v_pk_mul_f32 v[162:163], v[162:163], v[252:253] op_sel_hi:[1,0]
	v_pk_mul_f32 v[164:165], v[164:165], v[252:253] op_sel_hi:[1,0]
	v_pk_mul_f32 v[162:163], v[162:163], v[154:155]
	v_pk_mul_f32 v[164:165], v[164:165], v[156:157]
	v_pk_fma_f32 v[162:163], v[158:159], v[162:163], v[166:167]
	v_pk_fma_f32 v[164:165], v[160:161], v[164:165], v[168:169]
	s_nop 0
	global_store_dwordx4 v238, v[162:165], s[30:31] offset:3072 nt
	s_nop 1
	ds_read_b128 v[146:149], v238 offset:6144
	ds_read_b128 v[150:153], v238 offset:22528
	ds_read_b128 v[154:157], v238 offset:7168
	ds_read_b128 v[158:161], v238 offset:23552
	s_waitcnt lgkmcnt(4)
	v_lshlrev_b32_e32 v162, 16, v10
	v_and_b32_e32 v163, 0xffff0000, v10
	v_lshlrev_b32_e32 v164, 16, v11
	v_and_b32_e32 v165, 0xffff0000, v11
	v_lshlrev_b32_e32 v166, 16, v42
	v_and_b32_e32 v167, 0xffff0000, v42
	v_lshlrev_b32_e32 v168, 16, v43
	v_and_b32_e32 v169, 0xffff0000, v43
	v_pk_mul_f32 v[162:163], v[162:163], v[252:253] op_sel_hi:[1,0]
	v_pk_mul_f32 v[164:165], v[164:165], v[252:253] op_sel_hi:[1,0]
	v_pk_mul_f32 v[162:163], v[162:163], v[130:131]
	v_pk_mul_f32 v[164:165], v[164:165], v[132:133]
	v_pk_fma_f32 v[162:163], v[134:135], v[162:163], v[166:167]
	v_pk_fma_f32 v[164:165], v[136:137], v[164:165], v[168:169]
	s_nop 0
	global_store_dwordx4 v241, v[162:165], s[30:31] offset:0 nt
	s_nop 1
	v_lshlrev_b32_e32 v162, 16, v12
	v_and_b32_e32 v163, 0xffff0000, v12
	v_lshlrev_b32_e32 v164, 16, v13
	v_and_b32_e32 v165, 0xffff0000, v13
	v_lshlrev_b32_e32 v166, 16, v44
	v_and_b32_e32 v167, 0xffff0000, v44
	v_lshlrev_b32_e32 v168, 16, v45
	v_and_b32_e32 v169, 0xffff0000, v45
	v_pk_mul_f32 v[162:163], v[162:163], v[252:253] op_sel_hi:[1,0]
	v_pk_mul_f32 v[164:165], v[164:165], v[252:253] op_sel_hi:[1,0]
	v_pk_mul_f32 v[162:163], v[162:163], v[138:139]
	v_pk_mul_f32 v[164:165], v[164:165], v[140:141]
	v_pk_fma_f32 v[162:163], v[142:143], v[162:163], v[166:167]
	v_pk_fma_f32 v[164:165], v[144:145], v[164:165], v[168:169]
	s_nop 0
	global_store_dwordx4 v241, v[162:165], s[30:31] offset:1024 nt
	s_nop 1
	ds_read_b128 v[130:133], v238 offset:8192
	ds_read_b128 v[134:137], v238 offset:24576
	ds_read_b128 v[138:141], v238 offset:9216
	ds_read_b128 v[142:145], v238 offset:25600
	s_waitcnt lgkmcnt(4)
	v_lshlrev_b32_e32 v162, 16, v14
	v_and_b32_e32 v163, 0xffff0000, v14
	v_lshlrev_b32_e32 v164, 16, v15
	v_and_b32_e32 v165, 0xffff0000, v15
	v_lshlrev_b32_e32 v166, 16, v46
	v_and_b32_e32 v167, 0xffff0000, v46
	v_lshlrev_b32_e32 v168, 16, v47
	v_and_b32_e32 v169, 0xffff0000, v47
	v_pk_mul_f32 v[162:163], v[162:163], v[252:253] op_sel_hi:[1,0]
	v_pk_mul_f32 v[164:165], v[164:165], v[252:253] op_sel_hi:[1,0]
	v_pk_mul_f32 v[162:163], v[162:163], v[146:147]
	v_pk_mul_f32 v[164:165], v[164:165], v[148:149]
	v_pk_fma_f32 v[162:163], v[150:151], v[162:163], v[166:167]
	v_pk_fma_f32 v[164:165], v[152:153], v[164:165], v[168:169]
	s_nop 0
	global_store_dwordx4 v241, v[162:165], s[30:31] offset:2048 nt
	s_nop 1
	v_lshlrev_b32_e32 v162, 16, v16
	v_and_b32_e32 v163, 0xffff0000, v16
	v_lshlrev_b32_e32 v164, 16, v17
	v_and_b32_e32 v165, 0xffff0000, v17
	v_lshlrev_b32_e32 v166, 16, v48
	v_and_b32_e32 v167, 0xffff0000, v48
	v_lshlrev_b32_e32 v168, 16, v49
	v_and_b32_e32 v169, 0xffff0000, v49
	v_pk_mul_f32 v[162:163], v[162:163], v[252:253] op_sel_hi:[1,0]
	v_pk_mul_f32 v[164:165], v[164:165], v[252:253] op_sel_hi:[1,0]
	v_pk_mul_f32 v[162:163], v[162:163], v[154:155]
	v_pk_mul_f32 v[164:165], v[164:165], v[156:157]
	v_pk_fma_f32 v[162:163], v[158:159], v[162:163], v[166:167]
	v_pk_fma_f32 v[164:165], v[160:161], v[164:165], v[168:169]
	s_nop 0
	global_store_dwordx4 v241, v[162:165], s[30:31] offset:3072 nt
	s_nop 1
	ds_read_b128 v[146:149], v238 offset:10240
	ds_read_b128 v[150:153], v238 offset:26624
	ds_read_b128 v[154:157], v238 offset:11264
	ds_read_b128 v[158:161], v238 offset:27648
	s_waitcnt lgkmcnt(4)
	v_lshlrev_b32_e32 v162, 16, v18
	v_and_b32_e32 v163, 0xffff0000, v18
	v_lshlrev_b32_e32 v164, 16, v19
	v_and_b32_e32 v165, 0xffff0000, v19
	v_lshlrev_b32_e32 v166, 16, v50
	v_and_b32_e32 v167, 0xffff0000, v50
	v_lshlrev_b32_e32 v168, 16, v51
	v_and_b32_e32 v169, 0xffff0000, v51
	v_pk_mul_f32 v[162:163], v[162:163], v[252:253] op_sel_hi:[1,0]
	v_pk_mul_f32 v[164:165], v[164:165], v[252:253] op_sel_hi:[1,0]
	v_pk_mul_f32 v[162:163], v[162:163], v[130:131]
	v_pk_mul_f32 v[164:165], v[164:165], v[132:133]
	v_pk_fma_f32 v[162:163], v[134:135], v[162:163], v[166:167]
	v_pk_fma_f32 v[164:165], v[136:137], v[164:165], v[168:169]
	s_nop 0
	global_store_dwordx4 v242, v[162:165], s[30:31] offset:0 nt
	s_nop 1
	v_lshlrev_b32_e32 v162, 16, v20
	v_and_b32_e32 v163, 0xffff0000, v20
	v_lshlrev_b32_e32 v164, 16, v21
	v_and_b32_e32 v165, 0xffff0000, v21
	v_lshlrev_b32_e32 v166, 16, v52
	v_and_b32_e32 v167, 0xffff0000, v52
	v_lshlrev_b32_e32 v168, 16, v53
	v_and_b32_e32 v169, 0xffff0000, v53
	v_pk_mul_f32 v[162:163], v[162:163], v[252:253] op_sel_hi:[1,0]
	v_pk_mul_f32 v[164:165], v[164:165], v[252:253] op_sel_hi:[1,0]
	v_pk_mul_f32 v[162:163], v[162:163], v[138:139]
	v_pk_mul_f32 v[164:165], v[164:165], v[140:141]
	v_pk_fma_f32 v[162:163], v[142:143], v[162:163], v[166:167]
	v_pk_fma_f32 v[164:165], v[144:145], v[164:165], v[168:169]
	s_nop 0
	global_store_dwordx4 v242, v[162:165], s[30:31] offset:1024 nt
	s_nop 1
	ds_read_b128 v[130:133], v238 offset:12288
	ds_read_b128 v[134:137], v238 offset:28672
	ds_read_b128 v[138:141], v238 offset:13312
	ds_read_b128 v[142:145], v238 offset:29696
	s_waitcnt lgkmcnt(4)
	v_lshlrev_b32_e32 v162, 16, v22
	v_and_b32_e32 v163, 0xffff0000, v22
	v_lshlrev_b32_e32 v164, 16, v23
	v_and_b32_e32 v165, 0xffff0000, v23
	v_lshlrev_b32_e32 v166, 16, v54
	v_and_b32_e32 v167, 0xffff0000, v54
	v_lshlrev_b32_e32 v168, 16, v55
	v_and_b32_e32 v169, 0xffff0000, v55
	v_pk_mul_f32 v[162:163], v[162:163], v[252:253] op_sel_hi:[1,0]
	v_pk_mul_f32 v[164:165], v[164:165], v[252:253] op_sel_hi:[1,0]
	v_pk_mul_f32 v[162:163], v[162:163], v[146:147]
	v_pk_mul_f32 v[164:165], v[164:165], v[148:149]
	v_pk_fma_f32 v[162:163], v[150:151], v[162:163], v[166:167]
	v_pk_fma_f32 v[164:165], v[152:153], v[164:165], v[168:169]
	s_nop 0
	global_store_dwordx4 v242, v[162:165], s[30:31] offset:2048 nt
	s_nop 1
	v_lshlrev_b32_e32 v162, 16, v24
	v_and_b32_e32 v163, 0xffff0000, v24
	v_lshlrev_b32_e32 v164, 16, v25
	v_and_b32_e32 v165, 0xffff0000, v25
	v_lshlrev_b32_e32 v166, 16, v56
	v_and_b32_e32 v167, 0xffff0000, v56
	v_lshlrev_b32_e32 v168, 16, v57
	v_and_b32_e32 v169, 0xffff0000, v57
	v_pk_mul_f32 v[162:163], v[162:163], v[252:253] op_sel_hi:[1,0]
	v_pk_mul_f32 v[164:165], v[164:165], v[252:253] op_sel_hi:[1,0]
	v_pk_mul_f32 v[162:163], v[162:163], v[154:155]
	v_pk_mul_f32 v[164:165], v[164:165], v[156:157]
	v_pk_fma_f32 v[162:163], v[158:159], v[162:163], v[166:167]
	v_pk_fma_f32 v[164:165], v[160:161], v[164:165], v[168:169]
	s_nop 0
	global_store_dwordx4 v242, v[162:165], s[30:31] offset:3072 nt
	s_nop 1
	ds_read_b128 v[146:149], v238 offset:14336
	ds_read_b128 v[150:153], v238 offset:30720
	ds_read_b128 v[154:157], v238 offset:15360
	ds_read_b128 v[158:161], v238 offset:31744
	s_waitcnt lgkmcnt(4)
	v_lshlrev_b32_e32 v162, 16, v26
	v_and_b32_e32 v163, 0xffff0000, v26
	v_lshlrev_b32_e32 v164, 16, v27
	v_and_b32_e32 v165, 0xffff0000, v27
	v_lshlrev_b32_e32 v166, 16, v58
	v_and_b32_e32 v167, 0xffff0000, v58
	v_lshlrev_b32_e32 v168, 16, v59
	v_and_b32_e32 v169, 0xffff0000, v59
	v_pk_mul_f32 v[162:163], v[162:163], v[252:253] op_sel_hi:[1,0]
	v_pk_mul_f32 v[164:165], v[164:165], v[252:253] op_sel_hi:[1,0]
	v_pk_mul_f32 v[162:163], v[162:163], v[130:131]
	v_pk_mul_f32 v[164:165], v[164:165], v[132:133]
	v_pk_fma_f32 v[162:163], v[134:135], v[162:163], v[166:167]
	v_pk_fma_f32 v[164:165], v[136:137], v[164:165], v[168:169]
	s_nop 0
	global_store_dwordx4 v243, v[162:165], s[30:31] offset:0 nt
	s_nop 1
	v_lshlrev_b32_e32 v162, 16, v28
	v_and_b32_e32 v163, 0xffff0000, v28
	v_lshlrev_b32_e32 v164, 16, v29
	v_and_b32_e32 v165, 0xffff0000, v29
	v_lshlrev_b32_e32 v166, 16, v60
	v_and_b32_e32 v167, 0xffff0000, v60
	v_lshlrev_b32_e32 v168, 16, v61
	v_and_b32_e32 v169, 0xffff0000, v61
	v_pk_mul_f32 v[162:163], v[162:163], v[252:253] op_sel_hi:[1,0]
	v_pk_mul_f32 v[164:165], v[164:165], v[252:253] op_sel_hi:[1,0]
	v_pk_mul_f32 v[162:163], v[162:163], v[138:139]
	v_pk_mul_f32 v[164:165], v[164:165], v[140:141]
	v_pk_fma_f32 v[162:163], v[142:143], v[162:163], v[166:167]
	v_pk_fma_f32 v[164:165], v[144:145], v[164:165], v[168:169]
	s_nop 0
	global_store_dwordx4 v243, v[162:165], s[30:31] offset:1024 nt
	s_nop 1
	s_waitcnt lgkmcnt(0)
	v_lshlrev_b32_e32 v162, 16, v30
	v_and_b32_e32 v163, 0xffff0000, v30
	v_lshlrev_b32_e32 v164, 16, v31
	v_and_b32_e32 v165, 0xffff0000, v31
	v_lshlrev_b32_e32 v166, 16, v62
	v_and_b32_e32 v167, 0xffff0000, v62
	v_lshlrev_b32_e32 v168, 16, v63
	v_and_b32_e32 v169, 0xffff0000, v63
	v_pk_mul_f32 v[162:163], v[162:163], v[252:253] op_sel_hi:[1,0]
	v_pk_mul_f32 v[164:165], v[164:165], v[252:253] op_sel_hi:[1,0]
	v_pk_mul_f32 v[162:163], v[162:163], v[146:147]
	v_pk_mul_f32 v[164:165], v[164:165], v[148:149]
	v_pk_fma_f32 v[162:163], v[150:151], v[162:163], v[166:167]
	v_pk_fma_f32 v[164:165], v[152:153], v[164:165], v[168:169]
	s_nop 0
	global_store_dwordx4 v243, v[162:165], s[30:31] offset:2048 nt
	s_nop 1
	v_lshlrev_b32_e32 v162, 16, v32
	v_and_b32_e32 v163, 0xffff0000, v32
	v_lshlrev_b32_e32 v164, 16, v33
	v_and_b32_e32 v165, 0xffff0000, v33
	v_lshlrev_b32_e32 v166, 16, v64
	v_and_b32_e32 v167, 0xffff0000, v64
	v_lshlrev_b32_e32 v168, 16, v65
	v_and_b32_e32 v169, 0xffff0000, v65
	v_pk_mul_f32 v[162:163], v[162:163], v[252:253] op_sel_hi:[1,0]
	v_pk_mul_f32 v[164:165], v[164:165], v[252:253] op_sel_hi:[1,0]
	v_pk_mul_f32 v[162:163], v[162:163], v[154:155]
	v_pk_mul_f32 v[164:165], v[164:165], v[156:157]
	v_pk_fma_f32 v[162:163], v[158:159], v[162:163], v[166:167]
	v_pk_fma_f32 v[164:165], v[160:161], v[164:165], v[168:169]
	s_nop 0
	global_store_dwordx4 v243, v[162:165], s[30:31] offset:3072 nt
	s_nop 1
	s_add_u32 s30, s30, 0x2000000
	s_addc_u32 s31, s31, 0
	s_waitcnt vmcnt(16)
	s_add_u32 s22, s22, 0x1000000
	s_addc_u32 s23, s23, 0
	s_add_u32 s24, s24, 0x1000000
	s_addc_u32 s25, s25, 0
	global_load_dwordx2 v[2:3], v244, s[22:23] offset:0
	global_load_dwordx2 v[4:5], v244, s[22:23] offset:512
	global_load_dwordx2 v[6:7], v244, s[22:23] offset:1024
	global_load_dwordx2 v[8:9], v244, s[22:23] offset:1536
	global_load_dwordx2 v[10:11], v244, s[22:23] offset:2048
	global_load_dwordx2 v[12:13], v244, s[22:23] offset:2560
	global_load_dwordx2 v[14:15], v244, s[22:23] offset:3072
	global_load_dwordx2 v[16:17], v244, s[22:23] offset:3584
	global_load_dwordx2 v[18:19], v245, s[22:23] offset:0
	global_load_dwordx2 v[20:21], v245, s[22:23] offset:512
	global_load_dwordx2 v[22:23], v245, s[22:23] offset:1024
	global_load_dwordx2 v[24:25], v245, s[22:23] offset:1536
	global_load_dwordx2 v[26:27], v245, s[22:23] offset:2048
	global_load_dwordx2 v[28:29], v245, s[22:23] offset:2560
	global_load_dwordx2 v[30:31], v245, s[22:23] offset:3072
	global_load_dwordx2 v[32:33], v245, s[22:23] offset:3584
	global_load_dwordx2 v[34:35], v244, s[24:25] offset:0
	global_load_dwordx2 v[36:37], v244, s[24:25] offset:512
	global_load_dwordx2 v[38:39], v244, s[24:25] offset:1024
	global_load_dwordx2 v[40:41], v244, s[24:25] offset:1536
	global_load_dwordx2 v[42:43], v244, s[24:25] offset:2048
	global_load_dwordx2 v[44:45], v244, s[24:25] offset:2560
	global_load_dwordx2 v[46:47], v244, s[24:25] offset:3072
	global_load_dwordx2 v[48:49], v244, s[24:25] offset:3584
	global_load_dwordx2 v[50:51], v245, s[24:25] offset:0
	global_load_dwordx2 v[52:53], v245, s[24:25] offset:512
	global_load_dwordx2 v[54:55], v245, s[24:25] offset:1024
	global_load_dwordx2 v[56:57], v245, s[24:25] offset:1536
	global_load_dwordx2 v[58:59], v245, s[24:25] offset:2048
	global_load_dwordx2 v[60:61], v245, s[24:25] offset:2560
	global_load_dwordx2 v[62:63], v245, s[24:25] offset:3072
	global_load_dwordx2 v[64:65], v245, s[24:25] offset:3584
	ds_read_b128 v[130:133], v238 offset:0
	ds_read_b128 v[134:137], v238 offset:16384
	ds_read_b128 v[138:141], v238 offset:1024
	ds_read_b128 v[142:145], v238 offset:17408
	v_lshlrev_b32_e32 v162, 16, v66
	v_and_b32_e32 v163, 0xffff0000, v66
	v_lshlrev_b32_e32 v164, 16, v67
	v_and_b32_e32 v165, 0xffff0000, v67
	v_pk_mul_f32 v[176:177], v[162:163], v[162:163]
	v_pk_mul_f32 v[178:179], v[164:165], v[164:165]
	v_lshlrev_b32_e32 v166, 16, v68
	v_and_b32_e32 v167, 0xffff0000, v68
	v_lshlrev_b32_e32 v168, 16, v69
	v_and_b32_e32 v169, 0xffff0000, v69
	v_pk_fma_f32 v[176:177], v[166:167], v[166:167], v[176:177]
	v_pk_fma_f32 v[178:179], v[168:169], v[168:169], v[178:179]
	v_lshlrev_b32_e32 v162, 16, v70
	v_and_b32_e32 v163, 0xffff0000, v70
	v_lshlrev_b32_e32 v164, 16, v71
	v_and_b32_e32 v165, 0xffff0000, v71
	v_pk_fma_f32 v[176:177], v[162:163], v[162:163], v[176:177]
	v_pk_fma_f32 v[178:179], v[164:165], v[164:165], v[178:179]
	v_lshlrev_b32_e32 v166, 16, v72
	v_and_b32_e32 v167, 0xffff0000, v72
	v_lshlrev_b32_e32 v168, 16, v73
	v_and_b32_e32 v169, 0xffff0000, v73
	v_pk_fma_f32 v[176:177], v[166:167], v[166:167], v[176:177]
	v_pk_fma_f32 v[178:179], v[168:169], v[168:169], v[178:179]
	v_lshlrev_b32_e32 v162, 16, v74
	v_and_b32_e32 v163, 0xffff0000, v74
	v_lshlrev_b32_e32 v164, 16, v75
	v_and_b32_e32 v165, 0xffff0000, v75
	v_pk_fma_f32 v[176:177], v[162:163], v[162:163], v[176:177]
	v_pk_fma_f32 v[178:179], v[164:165], v[164:165], v[178:179]
	v_lshlrev_b32_e32 v166, 16, v76
	v_and_b32_e32 v167, 0xffff0000, v76
	v_lshlrev_b32_e32 v168, 16, v77
	v_and_b32_e32 v169, 0xffff0000, v77
	v_pk_fma_f32 v[176:177], v[166:167], v[166:167], v[176:177]
	v_pk_fma_f32 v[178:179], v[168:169], v[168:169], v[178:179]
	v_lshlrev_b32_e32 v162, 16, v78
	v_and_b32_e32 v163, 0xffff0000, v78
	v_lshlrev_b32_e32 v164, 16, v79
	v_and_b32_e32 v165, 0xffff0000, v79
	v_pk_fma_f32 v[176:177], v[162:163], v[162:163], v[176:177]
	v_pk_fma_f32 v[178:179], v[164:165], v[164:165], v[178:179]
	v_lshlrev_b32_e32 v166, 16, v80
	v_and_b32_e32 v167, 0xffff0000, v80
	v_lshlrev_b32_e32 v168, 16, v81
	v_and_b32_e32 v169, 0xffff0000, v81
	v_pk_fma_f32 v[176:177], v[166:167], v[166:167], v[176:177]
	v_pk_fma_f32 v[178:179], v[168:169], v[168:169], v[178:179]
	v_lshlrev_b32_e32 v162, 16, v82
	v_and_b32_e32 v163, 0xffff0000, v82
	v_lshlrev_b32_e32 v164, 16, v83
	v_and_b32_e32 v165, 0xffff0000, v83
	v_pk_fma_f32 v[176:177], v[162:163], v[162:163], v[176:177]
	v_pk_fma_f32 v[178:179], v[164:165], v[164:165], v[178:179]
	v_lshlrev_b32_e32 v166, 16, v84
	v_and_b32_e32 v167, 0xffff0000, v84
	v_lshlrev_b32_e32 v168, 16, v85
	v_and_b32_e32 v169, 0xffff0000, v85
	v_pk_fma_f32 v[176:177], v[166:167], v[166:167], v[176:177]
	v_pk_fma_f32 v[178:179], v[168:169], v[168:169], v[178:179]
	v_lshlrev_b32_e32 v162, 16, v86
	v_and_b32_e32 v163, 0xffff0000, v86
	v_lshlrev_b32_e32 v164, 16, v87
	v_and_b32_e32 v165, 0xffff0000, v87
	v_pk_fma_f32 v[176:177], v[162:163], v[162:163], v[176:177]
	v_pk_fma_f32 v[178:179], v[164:165], v[164:165], v[178:179]
	v_lshlrev_b32_e32 v166, 16, v88
	v_and_b32_e32 v167, 0xffff0000, v88
	v_lshlrev_b32_e32 v168, 16, v89
	v_and_b32_e32 v169, 0xffff0000, v89
	v_pk_fma_f32 v[176:177], v[166:167], v[166:167], v[176:177]
	v_pk_fma_f32 v[178:179], v[168:169], v[168:169], v[178:179]
	v_lshlrev_b32_e32 v162, 16, v90
	v_and_b32_e32 v163, 0xffff0000, v90
	v_lshlrev_b32_e32 v164, 16, v91
	v_and_b32_e32 v165, 0xffff0000, v91
	v_pk_fma_f32 v[176:177], v[162:163], v[162:163], v[176:177]
	v_pk_fma_f32 v[178:179], v[164:165], v[164:165], v[178:179]
	v_lshlrev_b32_e32 v166, 16, v92
	v_and_b32_e32 v167, 0xffff0000, v92
	v_lshlrev_b32_e32 v168, 16, v93
	v_and_b32_e32 v169, 0xffff0000, v93
	v_pk_fma_f32 v[176:177], v[166:167], v[166:167], v[176:177]
	v_pk_fma_f32 v[178:179], v[168:169], v[168:169], v[178:179]
	v_lshlrev_b32_e32 v162, 16, v94
	v_and_b32_e32 v163, 0xffff0000, v94
	v_lshlrev_b32_e32 v164, 16, v95
	v_and_b32_e32 v165, 0xffff0000, v95
	v_pk_fma_f32 v[176:177], v[162:163], v[162:163], v[176:177]
	v_pk_fma_f32 v[178:179], v[164:165], v[164:165], v[178:179]
	v_lshlrev_b32_e32 v166, 16, v96
	v_and_b32_e32 v167, 0xffff0000, v96
	v_lshlrev_b32_e32 v168, 16, v97
	v_and_b32_e32 v169, 0xffff0000, v97
	v_pk_fma_f32 v[176:177], v[166:167], v[166:167], v[176:177]
	v_pk_fma_f32 v[178:179], v[168:169], v[168:169], v[178:179]
	v_pk_add_f32 v[176:177], v[176:177], v[178:179]
	s_nop 0
	v_add_f32_e32 v252, v176, v177
	s_waitcnt lgkmcnt(0)
	ds_bpermute_b32 v254, v246, v252
	s_waitcnt lgkmcnt(0)
	v_add_f32_e32 v252, v252, v254
	ds_bpermute_b32 v254, v247, v252
	s_waitcnt lgkmcnt(0)
	v_add_f32_e32 v252, v252, v254
	ds_bpermute_b32 v254, v248, v252
	s_waitcnt lgkmcnt(0)
	v_add_f32_e32 v252, v252, v254
	ds_bpermute_b32 v254, v249, v252
	s_waitcnt lgkmcnt(0)
	v_add_f32_e32 v252, v252, v254
	ds_bpermute_b32 v254, v250, v252
	s_waitcnt lgkmcnt(0)
	v_add_f32_e32 v252, v252, v254
	ds_bpermute_b32 v254, v251, v252
	s_waitcnt lgkmcnt(0)
	v_add_f32_e32 v252, v252, v254
	v_mov_b32_e32 v254, 0x358637bd
	v_fmac_f32_e32 v254, 0x39800000, v252
	v_mul_f32_e32 v252, 0x4b800000, v254
	v_cmp_gt_f32_e32 vcc, s20, v254
	s_nop 1
	v_cndmask_b32_e32 v254, v254, v252, vcc
	v_rsq_f32_e32 v254, v254
	s_nop 0
	v_mul_f32_e32 v252, 0x45800000, v254
	v_cndmask_b32_e32 v252, v254, v252, vcc
	ds_read_b128 v[146:149], v238 offset:2048
	ds_read_b128 v[150:153], v238 offset:18432
	ds_read_b128 v[154:157], v238 offset:3072
	ds_read_b128 v[158:161], v238 offset:19456
	s_waitcnt lgkmcnt(4)
	v_lshlrev_b32_e32 v162, 16, v66
	v_and_b32_e32 v163, 0xffff0000, v66
	v_lshlrev_b32_e32 v164, 16, v67
	v_and_b32_e32 v165, 0xffff0000, v67
	v_lshlrev_b32_e32 v166, 16, v98
	v_and_b32_e32 v167, 0xffff0000, v98
	v_lshlrev_b32_e32 v168, 16, v99
	v_and_b32_e32 v169, 0xffff0000, v99
	v_pk_mul_f32 v[162:163], v[162:163], v[252:253] op_sel_hi:[1,0]
	v_pk_mul_f32 v[164:165], v[164:165], v[252:253] op_sel_hi:[1,0]
	v_pk_mul_f32 v[162:163], v[162:163], v[130:131]
	v_pk_mul_f32 v[164:165], v[164:165], v[132:133]
	v_pk_fma_f32 v[162:163], v[134:135], v[162:163], v[166:167]
	v_pk_fma_f32 v[164:165], v[136:137], v[164:165], v[168:169]
	s_nop 0
	global_store_dwordx4 v238, v[162:165], s[30:31] offset:0 nt
	s_nop 1
	v_lshlrev_b32_e32 v162, 16, v68
	v_and_b32_e32 v163, 0xffff0000, v68
	v_lshlrev_b32_e32 v164, 16, v69
	v_and_b32_e32 v165, 0xffff0000, v69
	v_lshlrev_b32_e32 v166, 16, v100
	v_and_b32_e32 v167, 0xffff0000, v100
	v_lshlrev_b32_e32 v168, 16, v101
	v_and_b32_e32 v169, 0xffff0000, v101
	v_pk_mul_f32 v[162:163], v[162:163], v[252:253] op_sel_hi:[1,0]
	v_pk_mul_f32 v[164:165], v[164:165], v[252:253] op_sel_hi:[1,0]
	v_pk_mul_f32 v[162:163], v[162:163], v[138:139]
	v_pk_mul_f32 v[164:165], v[164:165], v[140:141]
	v_pk_fma_f32 v[162:163], v[142:143], v[162:163], v[166:167]
	v_pk_fma_f32 v[164:165], v[144:145], v[164:165], v[168:169]
	s_nop 0
	global_store_dwordx4 v238, v[162:165], s[30:31] offset:1024 nt
	s_nop 1
	ds_read_b128 v[130:133], v238 offset:4096
	ds_read_b128 v[134:137], v238 offset:20480
	ds_read_b128 v[138:141], v238 offset:5120
	ds_read_b128 v[142:145], v238 offset:21504
	s_waitcnt lgkmcnt(4)
	v_lshlrev_b32_e32 v162, 16, v70
	v_and_b32_e32 v163, 0xffff0000, v70
	v_lshlrev_b32_e32 v164, 16, v71
	v_and_b32_e32 v165, 0xffff0000, v71
	v_lshlrev_b32_e32 v166, 16, v102
	v_and_b32_e32 v167, 0xffff0000, v102
	v_lshlrev_b32_e32 v168, 16, v103
	v_and_b32_e32 v169, 0xffff0000, v103
	v_pk_mul_f32 v[162:163], v[162:163], v[252:253] op_sel_hi:[1,0]
	v_pk_mul_f32 v[164:165], v[164:165], v[252:253] op_sel_hi:[1,0]
	v_pk_mul_f32 v[162:163], v[162:163], v[146:147]
	v_pk_mul_f32 v[164:165], v[164:165], v[148:149]
	v_pk_fma_f32 v[162:163], v[150:151], v[162:163], v[166:167]
	v_pk_fma_f32 v[164:165], v[152:153], v[164:165], v[168:169]
	s_nop 0
	global_store_dwordx4 v238, v[162:165], s[30:31] offset:2048 nt
	s_nop 1
	v_lshlrev_b32_e32 v162, 16, v72
	v_and_b32_e32 v163, 0xffff0000, v72
	v_lshlrev_b32_e32 v164, 16, v73
	v_and_b32_e32 v165, 0xffff0000, v73
	v_lshlrev_b32_e32 v166, 16, v104
	v_and_b32_e32 v167, 0xffff0000, v104
	v_lshlrev_b32_e32 v168, 16, v105
	v_and_b32_e32 v169, 0xffff0000, v105
	v_pk_mul_f32 v[162:163], v[162:163], v[252:253] op_sel_hi:[1,0]
	v_pk_mul_f32 v[164:165], v[164:165], v[252:253] op_sel_hi:[1,0]
	v_pk_mul_f32 v[162:163], v[162:163], v[154:155]
	v_pk_mul_f32 v[164:165], v[164:165], v[156:157]
	v_pk_fma_f32 v[162:163], v[158:159], v[162:163], v[166:167]
	v_pk_fma_f32 v[164:165], v[160:161], v[164:165], v[168:169]
	s_nop 0
	global_store_dwordx4 v238, v[162:165], s[30:31] offset:3072 nt
	s_nop 1
	ds_read_b128 v[146:149], v238 offset:6144
	ds_read_b128 v[150:153], v238 offset:22528
	ds_read_b128 v[154:157], v238 offset:7168
	ds_read_b128 v[158:161], v238 offset:23552
	s_waitcnt lgkmcnt(4)
	v_lshlrev_b32_e32 v162, 16, v74
	v_and_b32_e32 v163, 0xffff0000, v74
	v_lshlrev_b32_e32 v164, 16, v75
	v_and_b32_e32 v165, 0xffff0000, v75
	v_lshlrev_b32_e32 v166, 16, v106
	v_and_b32_e32 v167, 0xffff0000, v106
	v_lshlrev_b32_e32 v168, 16, v107
	v_and_b32_e32 v169, 0xffff0000, v107
	v_pk_mul_f32 v[162:163], v[162:163], v[252:253] op_sel_hi:[1,0]
	v_pk_mul_f32 v[164:165], v[164:165], v[252:253] op_sel_hi:[1,0]
	v_pk_mul_f32 v[162:163], v[162:163], v[130:131]
	v_pk_mul_f32 v[164:165], v[164:165], v[132:133]
	v_pk_fma_f32 v[162:163], v[134:135], v[162:163], v[166:167]
	v_pk_fma_f32 v[164:165], v[136:137], v[164:165], v[168:169]
	s_nop 0
	global_store_dwordx4 v241, v[162:165], s[30:31] offset:0 nt
	s_nop 1
	v_lshlrev_b32_e32 v162, 16, v76
	v_and_b32_e32 v163, 0xffff0000, v76
	v_lshlrev_b32_e32 v164, 16, v77
	v_and_b32_e32 v165, 0xffff0000, v77
	v_lshlrev_b32_e32 v166, 16, v108
	v_and_b32_e32 v167, 0xffff0000, v108
	v_lshlrev_b32_e32 v168, 16, v109
	v_and_b32_e32 v169, 0xffff0000, v109
	v_pk_mul_f32 v[162:163], v[162:163], v[252:253] op_sel_hi:[1,0]
	v_pk_mul_f32 v[164:165], v[164:165], v[252:253] op_sel_hi:[1,0]
	v_pk_mul_f32 v[162:163], v[162:163], v[138:139]
	v_pk_mul_f32 v[164:165], v[164:165], v[140:141]
	v_pk_fma_f32 v[162:163], v[142:143], v[162:163], v[166:167]
	v_pk_fma_f32 v[164:165], v[144:145], v[164:165], v[168:169]
	s_nop 0
	global_store_dwordx4 v241, v[162:165], s[30:31] offset:1024 nt
	s_nop 1
	ds_read_b128 v[130:133], v238 offset:8192
	ds_read_b128 v[134:137], v238 offset:24576
	ds_read_b128 v[138:141], v238 offset:9216
	ds_read_b128 v[142:145], v238 offset:25600
	s_waitcnt lgkmcnt(4)
	v_lshlrev_b32_e32 v162, 16, v78
	v_and_b32_e32 v163, 0xffff0000, v78
	v_lshlrev_b32_e32 v164, 16, v79
	v_and_b32_e32 v165, 0xffff0000, v79
	v_lshlrev_b32_e32 v166, 16, v110
	v_and_b32_e32 v167, 0xffff0000, v110
	v_lshlrev_b32_e32 v168, 16, v111
	v_and_b32_e32 v169, 0xffff0000, v111
	v_pk_mul_f32 v[162:163], v[162:163], v[252:253] op_sel_hi:[1,0]
	v_pk_mul_f32 v[164:165], v[164:165], v[252:253] op_sel_hi:[1,0]
	v_pk_mul_f32 v[162:163], v[162:163], v[146:147]
	v_pk_mul_f32 v[164:165], v[164:165], v[148:149]
	v_pk_fma_f32 v[162:163], v[150:151], v[162:163], v[166:167]
	v_pk_fma_f32 v[164:165], v[152:153], v[164:165], v[168:169]
	s_nop 0
	global_store_dwordx4 v241, v[162:165], s[30:31] offset:2048 nt
	s_nop 1
	v_lshlrev_b32_e32 v162, 16, v80
	v_and_b32_e32 v163, 0xffff0000, v80
	v_lshlrev_b32_e32 v164, 16, v81
	v_and_b32_e32 v165, 0xffff0000, v81
	v_lshlrev_b32_e32 v166, 16, v112
	v_and_b32_e32 v167, 0xffff0000, v112
	v_lshlrev_b32_e32 v168, 16, v113
	v_and_b32_e32 v169, 0xffff0000, v113
	v_pk_mul_f32 v[162:163], v[162:163], v[252:253] op_sel_hi:[1,0]
	v_pk_mul_f32 v[164:165], v[164:165], v[252:253] op_sel_hi:[1,0]
	v_pk_mul_f32 v[162:163], v[162:163], v[154:155]
	v_pk_mul_f32 v[164:165], v[164:165], v[156:157]
	v_pk_fma_f32 v[162:163], v[158:159], v[162:163], v[166:167]
	v_pk_fma_f32 v[164:165], v[160:161], v[164:165], v[168:169]
	s_nop 0
	global_store_dwordx4 v241, v[162:165], s[30:31] offset:3072 nt
	s_nop 1
	ds_read_b128 v[146:149], v238 offset:10240
	ds_read_b128 v[150:153], v238 offset:26624
	ds_read_b128 v[154:157], v238 offset:11264
	ds_read_b128 v[158:161], v238 offset:27648
	s_waitcnt lgkmcnt(4)
	v_lshlrev_b32_e32 v162, 16, v82
	v_and_b32_e32 v163, 0xffff0000, v82
	v_lshlrev_b32_e32 v164, 16, v83
	v_and_b32_e32 v165, 0xffff0000, v83
	v_lshlrev_b32_e32 v166, 16, v114
	v_and_b32_e32 v167, 0xffff0000, v114
	v_lshlrev_b32_e32 v168, 16, v115
	v_and_b32_e32 v169, 0xffff0000, v115
	v_pk_mul_f32 v[162:163], v[162:163], v[252:253] op_sel_hi:[1,0]
	v_pk_mul_f32 v[164:165], v[164:165], v[252:253] op_sel_hi:[1,0]
	v_pk_mul_f32 v[162:163], v[162:163], v[130:131]
	v_pk_mul_f32 v[164:165], v[164:165], v[132:133]
	v_pk_fma_f32 v[162:163], v[134:135], v[162:163], v[166:167]
	v_pk_fma_f32 v[164:165], v[136:137], v[164:165], v[168:169]
	s_nop 0
	global_store_dwordx4 v242, v[162:165], s[30:31] offset:0 nt
	s_nop 1
	v_lshlrev_b32_e32 v162, 16, v84
	v_and_b32_e32 v163, 0xffff0000, v84
	v_lshlrev_b32_e32 v164, 16, v85
	v_and_b32_e32 v165, 0xffff0000, v85
	v_lshlrev_b32_e32 v166, 16, v116
	v_and_b32_e32 v167, 0xffff0000, v116
	v_lshlrev_b32_e32 v168, 16, v117
	v_and_b32_e32 v169, 0xffff0000, v117
	v_pk_mul_f32 v[162:163], v[162:163], v[252:253] op_sel_hi:[1,0]
	v_pk_mul_f32 v[164:165], v[164:165], v[252:253] op_sel_hi:[1,0]
	v_pk_mul_f32 v[162:163], v[162:163], v[138:139]
	v_pk_mul_f32 v[164:165], v[164:165], v[140:141]
	v_pk_fma_f32 v[162:163], v[142:143], v[162:163], v[166:167]
	v_pk_fma_f32 v[164:165], v[144:145], v[164:165], v[168:169]
	s_nop 0
	global_store_dwordx4 v242, v[162:165], s[30:31] offset:1024 nt
	s_nop 1
	ds_read_b128 v[130:133], v238 offset:12288
	ds_read_b128 v[134:137], v238 offset:28672
	ds_read_b128 v[138:141], v238 offset:13312
	ds_read_b128 v[142:145], v238 offset:29696
	s_waitcnt lgkmcnt(4)
	v_lshlrev_b32_e32 v162, 16, v86
	v_and_b32_e32 v163, 0xffff0000, v86
	v_lshlrev_b32_e32 v164, 16, v87
	v_and_b32_e32 v165, 0xffff0000, v87
	v_lshlrev_b32_e32 v166, 16, v118
	v_and_b32_e32 v167, 0xffff0000, v118
	v_lshlrev_b32_e32 v168, 16, v119
	v_and_b32_e32 v169, 0xffff0000, v119
	v_pk_mul_f32 v[162:163], v[162:163], v[252:253] op_sel_hi:[1,0]
	v_pk_mul_f32 v[164:165], v[164:165], v[252:253] op_sel_hi:[1,0]
	v_pk_mul_f32 v[162:163], v[162:163], v[146:147]
	v_pk_mul_f32 v[164:165], v[164:165], v[148:149]
	v_pk_fma_f32 v[162:163], v[150:151], v[162:163], v[166:167]
	v_pk_fma_f32 v[164:165], v[152:153], v[164:165], v[168:169]
	s_nop 0
	global_store_dwordx4 v242, v[162:165], s[30:31] offset:2048 nt
	s_nop 1
	v_lshlrev_b32_e32 v162, 16, v88
	v_and_b32_e32 v163, 0xffff0000, v88
	v_lshlrev_b32_e32 v164, 16, v89
	v_and_b32_e32 v165, 0xffff0000, v89
	v_lshlrev_b32_e32 v166, 16, v120
	v_and_b32_e32 v167, 0xffff0000, v120
	v_lshlrev_b32_e32 v168, 16, v121
	v_and_b32_e32 v169, 0xffff0000, v121
	v_pk_mul_f32 v[162:163], v[162:163], v[252:253] op_sel_hi:[1,0]
	v_pk_mul_f32 v[164:165], v[164:165], v[252:253] op_sel_hi:[1,0]
	v_pk_mul_f32 v[162:163], v[162:163], v[154:155]
	v_pk_mul_f32 v[164:165], v[164:165], v[156:157]
	v_pk_fma_f32 v[162:163], v[158:159], v[162:163], v[166:167]
	v_pk_fma_f32 v[164:165], v[160:161], v[164:165], v[168:169]
	s_nop 0
	global_store_dwordx4 v242, v[162:165], s[30:31] offset:3072 nt
	s_nop 1
	ds_read_b128 v[146:149], v238 offset:14336
	ds_read_b128 v[150:153], v238 offset:30720
	ds_read_b128 v[154:157], v238 offset:15360
	ds_read_b128 v[158:161], v238 offset:31744
	s_waitcnt lgkmcnt(4)
	v_lshlrev_b32_e32 v162, 16, v90
	v_and_b32_e32 v163, 0xffff0000, v90
	v_lshlrev_b32_e32 v164, 16, v91
	v_and_b32_e32 v165, 0xffff0000, v91
	v_lshlrev_b32_e32 v166, 16, v122
	v_and_b32_e32 v167, 0xffff0000, v122
	v_lshlrev_b32_e32 v168, 16, v123
	v_and_b32_e32 v169, 0xffff0000, v123
	v_pk_mul_f32 v[162:163], v[162:163], v[252:253] op_sel_hi:[1,0]
	v_pk_mul_f32 v[164:165], v[164:165], v[252:253] op_sel_hi:[1,0]
	v_pk_mul_f32 v[162:163], v[162:163], v[130:131]
	v_pk_mul_f32 v[164:165], v[164:165], v[132:133]
	v_pk_fma_f32 v[162:163], v[134:135], v[162:163], v[166:167]
	v_pk_fma_f32 v[164:165], v[136:137], v[164:165], v[168:169]
	s_nop 0
	global_store_dwordx4 v243, v[162:165], s[30:31] offset:0 nt
	s_nop 1
	v_lshlrev_b32_e32 v162, 16, v92
	v_and_b32_e32 v163, 0xffff0000, v92
	v_lshlrev_b32_e32 v164, 16, v93
	v_and_b32_e32 v165, 0xffff0000, v93
	v_lshlrev_b32_e32 v166, 16, v124
	v_and_b32_e32 v167, 0xffff0000, v124
	v_lshlrev_b32_e32 v168, 16, v125
	v_and_b32_e32 v169, 0xffff0000, v125
	v_pk_mul_f32 v[162:163], v[162:163], v[252:253] op_sel_hi:[1,0]
	v_pk_mul_f32 v[164:165], v[164:165], v[252:253] op_sel_hi:[1,0]
	v_pk_mul_f32 v[162:163], v[162:163], v[138:139]
	v_pk_mul_f32 v[164:165], v[164:165], v[140:141]
	v_pk_fma_f32 v[162:163], v[142:143], v[162:163], v[166:167]
	v_pk_fma_f32 v[164:165], v[144:145], v[164:165], v[168:169]
	s_nop 0
	global_store_dwordx4 v243, v[162:165], s[30:31] offset:1024 nt
	s_nop 1
	s_waitcnt lgkmcnt(0)
	v_lshlrev_b32_e32 v162, 16, v94
	v_and_b32_e32 v163, 0xffff0000, v94
	v_lshlrev_b32_e32 v164, 16, v95
	v_and_b32_e32 v165, 0xffff0000, v95
	v_lshlrev_b32_e32 v166, 16, v126
	v_and_b32_e32 v167, 0xffff0000, v126
	v_lshlrev_b32_e32 v168, 16, v127
	v_and_b32_e32 v169, 0xffff0000, v127
	v_pk_mul_f32 v[162:163], v[162:163], v[252:253] op_sel_hi:[1,0]
	v_pk_mul_f32 v[164:165], v[164:165], v[252:253] op_sel_hi:[1,0]
	v_pk_mul_f32 v[162:163], v[162:163], v[146:147]
	v_pk_mul_f32 v[164:165], v[164:165], v[148:149]
	v_pk_fma_f32 v[162:163], v[150:151], v[162:163], v[166:167]
	v_pk_fma_f32 v[164:165], v[152:153], v[164:165], v[168:169]
	s_nop 0
	global_store_dwordx4 v243, v[162:165], s[30:31] offset:2048 nt
	s_nop 1
	v_lshlrev_b32_e32 v162, 16, v96
	v_and_b32_e32 v163, 0xffff0000, v96
	v_lshlrev_b32_e32 v164, 16, v97
	v_and_b32_e32 v165, 0xffff0000, v97
	v_lshlrev_b32_e32 v166, 16, v128
	v_and_b32_e32 v167, 0xffff0000, v128
	v_lshlrev_b32_e32 v168, 16, v129
	v_and_b32_e32 v169, 0xffff0000, v129
	v_pk_mul_f32 v[162:163], v[162:163], v[252:253] op_sel_hi:[1,0]
	v_pk_mul_f32 v[164:165], v[164:165], v[252:253] op_sel_hi:[1,0]
	v_pk_mul_f32 v[162:163], v[162:163], v[154:155]
	v_pk_mul_f32 v[164:165], v[164:165], v[156:157]
	v_pk_fma_f32 v[162:163], v[158:159], v[162:163], v[166:167]
	v_pk_fma_f32 v[164:165], v[160:161], v[164:165], v[168:169]
	s_nop 0
	global_store_dwordx4 v243, v[162:165], s[30:31] offset:3072 nt
	s_nop 1
	s_add_u32 s30, s30, 0x2000000
	s_addc_u32 s31, s31, 0
	s_waitcnt vmcnt(16)
	s_add_u32 s22, s22, 0x1000000
	s_addc_u32 s23, s23, 0
	s_add_u32 s24, s24, 0x1000000
	s_addc_u32 s25, s25, 0
	global_load_dwordx2 v[66:67], v244, s[22:23] offset:0
	global_load_dwordx2 v[68:69], v244, s[22:23] offset:512
	global_load_dwordx2 v[70:71], v244, s[22:23] offset:1024
	global_load_dwordx2 v[72:73], v244, s[22:23] offset:1536
	global_load_dwordx2 v[74:75], v244, s[22:23] offset:2048
	global_load_dwordx2 v[76:77], v244, s[22:23] offset:2560
	global_load_dwordx2 v[78:79], v244, s[22:23] offset:3072
	global_load_dwordx2 v[80:81], v244, s[22:23] offset:3584
	global_load_dwordx2 v[82:83], v245, s[22:23] offset:0
	global_load_dwordx2 v[84:85], v245, s[22:23] offset:512
	global_load_dwordx2 v[86:87], v245, s[22:23] offset:1024
	global_load_dwordx2 v[88:89], v245, s[22:23] offset:1536
	global_load_dwordx2 v[90:91], v245, s[22:23] offset:2048
	global_load_dwordx2 v[92:93], v245, s[22:23] offset:2560
	global_load_dwordx2 v[94:95], v245, s[22:23] offset:3072
	global_load_dwordx2 v[96:97], v245, s[22:23] offset:3584
	global_load_dwordx2 v[98:99], v244, s[24:25] offset:0
	global_load_dwordx2 v[100:101], v244, s[24:25] offset:512
	global_load_dwordx2 v[102:103], v244, s[24:25] offset:1024
	global_load_dwordx2 v[104:105], v244, s[24:25] offset:1536
	global_load_dwordx2 v[106:107], v244, s[24:25] offset:2048
	global_load_dwordx2 v[108:109], v244, s[24:25] offset:2560
	global_load_dwordx2 v[110:111], v244, s[24:25] offset:3072
	global_load_dwordx2 v[112:113], v244, s[24:25] offset:3584
	global_load_dwordx2 v[114:115], v245, s[24:25] offset:0
	global_load_dwordx2 v[116:117], v245, s[24:25] offset:512
	global_load_dwordx2 v[118:119], v245, s[24:25] offset:1024
	global_load_dwordx2 v[120:121], v245, s[24:25] offset:1536
	global_load_dwordx2 v[122:123], v245, s[24:25] offset:2048
	global_load_dwordx2 v[124:125], v245, s[24:25] offset:2560
	global_load_dwordx2 v[126:127], v245, s[24:25] offset:3072
	global_load_dwordx2 v[128:129], v245, s[24:25] offset:3584
	ds_read_b128 v[130:133], v238 offset:0
	ds_read_b128 v[134:137], v238 offset:32768
	ds_read_b128 v[138:141], v238 offset:1024
	ds_read_b128 v[142:145], v238 offset:33792
	v_lshlrev_b32_e32 v162, 16, v2
	v_and_b32_e32 v163, 0xffff0000, v2
	v_lshlrev_b32_e32 v164, 16, v3
	v_and_b32_e32 v165, 0xffff0000, v3
	v_pk_mul_f32 v[176:177], v[162:163], v[162:163]
	v_pk_mul_f32 v[178:179], v[164:165], v[164:165]
	v_lshlrev_b32_e32 v166, 16, v4
	v_and_b32_e32 v167, 0xffff0000, v4
	v_lshlrev_b32_e32 v168, 16, v5
	v_and_b32_e32 v169, 0xffff0000, v5
	v_pk_fma_f32 v[176:177], v[166:167], v[166:167], v[176:177]
	v_pk_fma_f32 v[178:179], v[168:169], v[168:169], v[178:179]
	v_lshlrev_b32_e32 v162, 16, v6
	v_and_b32_e32 v163, 0xffff0000, v6
	v_lshlrev_b32_e32 v164, 16, v7
	v_and_b32_e32 v165, 0xffff0000, v7
	v_pk_fma_f32 v[176:177], v[162:163], v[162:163], v[176:177]
	v_pk_fma_f32 v[178:179], v[164:165], v[164:165], v[178:179]
	v_lshlrev_b32_e32 v166, 16, v8
	v_and_b32_e32 v167, 0xffff0000, v8
	v_lshlrev_b32_e32 v168, 16, v9
	v_and_b32_e32 v169, 0xffff0000, v9
	v_pk_fma_f32 v[176:177], v[166:167], v[166:167], v[176:177]
	v_pk_fma_f32 v[178:179], v[168:169], v[168:169], v[178:179]
	v_lshlrev_b32_e32 v162, 16, v10
	v_and_b32_e32 v163, 0xffff0000, v10
	v_lshlrev_b32_e32 v164, 16, v11
	v_and_b32_e32 v165, 0xffff0000, v11
	v_pk_fma_f32 v[176:177], v[162:163], v[162:163], v[176:177]
	v_pk_fma_f32 v[178:179], v[164:165], v[164:165], v[178:179]
	v_lshlrev_b32_e32 v166, 16, v12
	v_and_b32_e32 v167, 0xffff0000, v12
	v_lshlrev_b32_e32 v168, 16, v13
	v_and_b32_e32 v169, 0xffff0000, v13
	v_pk_fma_f32 v[176:177], v[166:167], v[166:167], v[176:177]
	v_pk_fma_f32 v[178:179], v[168:169], v[168:169], v[178:179]
	v_lshlrev_b32_e32 v162, 16, v14
	v_and_b32_e32 v163, 0xffff0000, v14
	v_lshlrev_b32_e32 v164, 16, v15
	v_and_b32_e32 v165, 0xffff0000, v15
	v_pk_fma_f32 v[176:177], v[162:163], v[162:163], v[176:177]
	v_pk_fma_f32 v[178:179], v[164:165], v[164:165], v[178:179]
	v_lshlrev_b32_e32 v166, 16, v16
	v_and_b32_e32 v167, 0xffff0000, v16
	v_lshlrev_b32_e32 v168, 16, v17
	v_and_b32_e32 v169, 0xffff0000, v17
	v_pk_fma_f32 v[176:177], v[166:167], v[166:167], v[176:177]
	v_pk_fma_f32 v[178:179], v[168:169], v[168:169], v[178:179]
	v_lshlrev_b32_e32 v162, 16, v18
	v_and_b32_e32 v163, 0xffff0000, v18
	v_lshlrev_b32_e32 v164, 16, v19
	v_and_b32_e32 v165, 0xffff0000, v19
	v_pk_fma_f32 v[176:177], v[162:163], v[162:163], v[176:177]
	v_pk_fma_f32 v[178:179], v[164:165], v[164:165], v[178:179]
	v_lshlrev_b32_e32 v166, 16, v20
	v_and_b32_e32 v167, 0xffff0000, v20
	v_lshlrev_b32_e32 v168, 16, v21
	v_and_b32_e32 v169, 0xffff0000, v21
	v_pk_fma_f32 v[176:177], v[166:167], v[166:167], v[176:177]
	v_pk_fma_f32 v[178:179], v[168:169], v[168:169], v[178:179]
	v_lshlrev_b32_e32 v162, 16, v22
	v_and_b32_e32 v163, 0xffff0000, v22
	v_lshlrev_b32_e32 v164, 16, v23
	v_and_b32_e32 v165, 0xffff0000, v23
	v_pk_fma_f32 v[176:177], v[162:163], v[162:163], v[176:177]
	v_pk_fma_f32 v[178:179], v[164:165], v[164:165], v[178:179]
	v_lshlrev_b32_e32 v166, 16, v24
	v_and_b32_e32 v167, 0xffff0000, v24
	v_lshlrev_b32_e32 v168, 16, v25
	v_and_b32_e32 v169, 0xffff0000, v25
	v_pk_fma_f32 v[176:177], v[166:167], v[166:167], v[176:177]
	v_pk_fma_f32 v[178:179], v[168:169], v[168:169], v[178:179]
	v_lshlrev_b32_e32 v162, 16, v26
	v_and_b32_e32 v163, 0xffff0000, v26
	v_lshlrev_b32_e32 v164, 16, v27
	v_and_b32_e32 v165, 0xffff0000, v27
	v_pk_fma_f32 v[176:177], v[162:163], v[162:163], v[176:177]
	v_pk_fma_f32 v[178:179], v[164:165], v[164:165], v[178:179]
	v_lshlrev_b32_e32 v166, 16, v28
	v_and_b32_e32 v167, 0xffff0000, v28
	v_lshlrev_b32_e32 v168, 16, v29
	v_and_b32_e32 v169, 0xffff0000, v29
	v_pk_fma_f32 v[176:177], v[166:167], v[166:167], v[176:177]
	v_pk_fma_f32 v[178:179], v[168:169], v[168:169], v[178:179]
	v_lshlrev_b32_e32 v162, 16, v30
	v_and_b32_e32 v163, 0xffff0000, v30
	v_lshlrev_b32_e32 v164, 16, v31
	v_and_b32_e32 v165, 0xffff0000, v31
	v_pk_fma_f32 v[176:177], v[162:163], v[162:163], v[176:177]
	v_pk_fma_f32 v[178:179], v[164:165], v[164:165], v[178:179]
	v_lshlrev_b32_e32 v166, 16, v32
	v_and_b32_e32 v167, 0xffff0000, v32
	v_lshlrev_b32_e32 v168, 16, v33
	v_and_b32_e32 v169, 0xffff0000, v33
	v_pk_fma_f32 v[176:177], v[166:167], v[166:167], v[176:177]
	v_pk_fma_f32 v[178:179], v[168:169], v[168:169], v[178:179]
	v_pk_add_f32 v[176:177], v[176:177], v[178:179]
	s_nop 0
	v_add_f32_e32 v252, v176, v177
	s_waitcnt lgkmcnt(0)
	ds_bpermute_b32 v254, v246, v252
	s_waitcnt lgkmcnt(0)
	v_add_f32_e32 v252, v252, v254
	ds_bpermute_b32 v254, v247, v252
	s_waitcnt lgkmcnt(0)
	v_add_f32_e32 v252, v252, v254
	ds_bpermute_b32 v254, v248, v252
	s_waitcnt lgkmcnt(0)
	v_add_f32_e32 v252, v252, v254
	ds_bpermute_b32 v254, v249, v252
	s_waitcnt lgkmcnt(0)
	v_add_f32_e32 v252, v252, v254
	ds_bpermute_b32 v254, v250, v252
	s_waitcnt lgkmcnt(0)
	v_add_f32_e32 v252, v252, v254
	ds_bpermute_b32 v254, v251, v252
	s_waitcnt lgkmcnt(0)
	v_add_f32_e32 v252, v252, v254
	v_mov_b32_e32 v254, 0x358637bd
	v_fmac_f32_e32 v254, 0x39800000, v252
	v_mul_f32_e32 v252, 0x4b800000, v254
	v_cmp_gt_f32_e32 vcc, s20, v254
	s_nop 1
	v_cndmask_b32_e32 v254, v254, v252, vcc
	v_rsq_f32_e32 v254, v254
	s_nop 0
	v_mul_f32_e32 v252, 0x45800000, v254
	v_cndmask_b32_e32 v252, v254, v252, vcc
	ds_read_b128 v[146:149], v238 offset:2048
	ds_read_b128 v[150:153], v238 offset:34816
	ds_read_b128 v[154:157], v238 offset:3072
	ds_read_b128 v[158:161], v238 offset:35840
	s_waitcnt lgkmcnt(4)
	v_lshlrev_b32_e32 v162, 16, v2
	v_and_b32_e32 v163, 0xffff0000, v2
	v_lshlrev_b32_e32 v164, 16, v3
	v_and_b32_e32 v165, 0xffff0000, v3
	v_lshlrev_b32_e32 v166, 16, v34
	v_and_b32_e32 v167, 0xffff0000, v34
	v_lshlrev_b32_e32 v168, 16, v35
	v_and_b32_e32 v169, 0xffff0000, v35
	v_pk_mul_f32 v[162:163], v[162:163], v[252:253] op_sel_hi:[1,0]
	v_pk_mul_f32 v[164:165], v[164:165], v[252:253] op_sel_hi:[1,0]
	v_pk_mul_f32 v[162:163], v[162:163], v[130:131]
	v_pk_mul_f32 v[164:165], v[164:165], v[132:133]
	v_pk_fma_f32 v[162:163], v[134:135], v[162:163], v[166:167]
	v_pk_fma_f32 v[164:165], v[136:137], v[164:165], v[168:169]
	s_nop 0
	global_store_dwordx4 v238, v[162:165], s[30:31] offset:0 nt
	s_nop 1
	v_lshlrev_b32_e32 v162, 16, v4
	v_and_b32_e32 v163, 0xffff0000, v4
	v_lshlrev_b32_e32 v164, 16, v5
	v_and_b32_e32 v165, 0xffff0000, v5
	v_lshlrev_b32_e32 v166, 16, v36
	v_and_b32_e32 v167, 0xffff0000, v36
	v_lshlrev_b32_e32 v168, 16, v37
	v_and_b32_e32 v169, 0xffff0000, v37
	v_pk_mul_f32 v[162:163], v[162:163], v[252:253] op_sel_hi:[1,0]
	v_pk_mul_f32 v[164:165], v[164:165], v[252:253] op_sel_hi:[1,0]
	v_pk_mul_f32 v[162:163], v[162:163], v[138:139]
	v_pk_mul_f32 v[164:165], v[164:165], v[140:141]
	v_pk_fma_f32 v[162:163], v[142:143], v[162:163], v[166:167]
	v_pk_fma_f32 v[164:165], v[144:145], v[164:165], v[168:169]
	s_nop 0
	global_store_dwordx4 v238, v[162:165], s[30:31] offset:1024 nt
	s_nop 1
	ds_read_b128 v[130:133], v238 offset:4096
	ds_read_b128 v[134:137], v238 offset:36864
	ds_read_b128 v[138:141], v238 offset:5120
	ds_read_b128 v[142:145], v238 offset:37888
	s_waitcnt lgkmcnt(4)
	v_lshlrev_b32_e32 v162, 16, v6
	v_and_b32_e32 v163, 0xffff0000, v6
	v_lshlrev_b32_e32 v164, 16, v7
	v_and_b32_e32 v165, 0xffff0000, v7
	v_lshlrev_b32_e32 v166, 16, v38
	v_and_b32_e32 v167, 0xffff0000, v38
	v_lshlrev_b32_e32 v168, 16, v39
	v_and_b32_e32 v169, 0xffff0000, v39
	v_pk_mul_f32 v[162:163], v[162:163], v[252:253] op_sel_hi:[1,0]
	v_pk_mul_f32 v[164:165], v[164:165], v[252:253] op_sel_hi:[1,0]
	v_pk_mul_f32 v[162:163], v[162:163], v[146:147]
	v_pk_mul_f32 v[164:165], v[164:165], v[148:149]
	v_pk_fma_f32 v[162:163], v[150:151], v[162:163], v[166:167]
	v_pk_fma_f32 v[164:165], v[152:153], v[164:165], v[168:169]
	s_nop 0
	global_store_dwordx4 v238, v[162:165], s[30:31] offset:2048 nt
	s_nop 1
	v_lshlrev_b32_e32 v162, 16, v8
	v_and_b32_e32 v163, 0xffff0000, v8
	v_lshlrev_b32_e32 v164, 16, v9
	v_and_b32_e32 v165, 0xffff0000, v9
	v_lshlrev_b32_e32 v166, 16, v40
	v_and_b32_e32 v167, 0xffff0000, v40
	v_lshlrev_b32_e32 v168, 16, v41
	v_and_b32_e32 v169, 0xffff0000, v41
	v_pk_mul_f32 v[162:163], v[162:163], v[252:253] op_sel_hi:[1,0]
	v_pk_mul_f32 v[164:165], v[164:165], v[252:253] op_sel_hi:[1,0]
	v_pk_mul_f32 v[162:163], v[162:163], v[154:155]
	v_pk_mul_f32 v[164:165], v[164:165], v[156:157]
	v_pk_fma_f32 v[162:163], v[158:159], v[162:163], v[166:167]
	v_pk_fma_f32 v[164:165], v[160:161], v[164:165], v[168:169]
	s_nop 0
	global_store_dwordx4 v238, v[162:165], s[30:31] offset:3072 nt
	s_nop 1
	ds_read_b128 v[146:149], v238 offset:6144
	ds_read_b128 v[150:153], v238 offset:38912
	ds_read_b128 v[154:157], v238 offset:7168
	ds_read_b128 v[158:161], v238 offset:39936
	s_waitcnt lgkmcnt(4)
	v_lshlrev_b32_e32 v162, 16, v10
	v_and_b32_e32 v163, 0xffff0000, v10
	v_lshlrev_b32_e32 v164, 16, v11
	v_and_b32_e32 v165, 0xffff0000, v11
	v_lshlrev_b32_e32 v166, 16, v42
	v_and_b32_e32 v167, 0xffff0000, v42
	v_lshlrev_b32_e32 v168, 16, v43
	v_and_b32_e32 v169, 0xffff0000, v43
	v_pk_mul_f32 v[162:163], v[162:163], v[252:253] op_sel_hi:[1,0]
	v_pk_mul_f32 v[164:165], v[164:165], v[252:253] op_sel_hi:[1,0]
	v_pk_mul_f32 v[162:163], v[162:163], v[130:131]
	v_pk_mul_f32 v[164:165], v[164:165], v[132:133]
	v_pk_fma_f32 v[162:163], v[134:135], v[162:163], v[166:167]
	v_pk_fma_f32 v[164:165], v[136:137], v[164:165], v[168:169]
	s_nop 0
	global_store_dwordx4 v241, v[162:165], s[30:31] offset:0 nt
	s_nop 1
	v_lshlrev_b32_e32 v162, 16, v12
	v_and_b32_e32 v163, 0xffff0000, v12
	v_lshlrev_b32_e32 v164, 16, v13
	v_and_b32_e32 v165, 0xffff0000, v13
	v_lshlrev_b32_e32 v166, 16, v44
	v_and_b32_e32 v167, 0xffff0000, v44
	v_lshlrev_b32_e32 v168, 16, v45
	v_and_b32_e32 v169, 0xffff0000, v45
	v_pk_mul_f32 v[162:163], v[162:163], v[252:253] op_sel_hi:[1,0]
	v_pk_mul_f32 v[164:165], v[164:165], v[252:253] op_sel_hi:[1,0]
	v_pk_mul_f32 v[162:163], v[162:163], v[138:139]
	v_pk_mul_f32 v[164:165], v[164:165], v[140:141]
	v_pk_fma_f32 v[162:163], v[142:143], v[162:163], v[166:167]
	v_pk_fma_f32 v[164:165], v[144:145], v[164:165], v[168:169]
	s_nop 0
	global_store_dwordx4 v241, v[162:165], s[30:31] offset:1024 nt
	s_nop 1
	ds_read_b128 v[130:133], v238 offset:8192
	ds_read_b128 v[134:137], v238 offset:40960
	ds_read_b128 v[138:141], v238 offset:9216
	ds_read_b128 v[142:145], v238 offset:41984
	s_waitcnt lgkmcnt(4)
	v_lshlrev_b32_e32 v162, 16, v14
	v_and_b32_e32 v163, 0xffff0000, v14
	v_lshlrev_b32_e32 v164, 16, v15
	v_and_b32_e32 v165, 0xffff0000, v15
	v_lshlrev_b32_e32 v166, 16, v46
	v_and_b32_e32 v167, 0xffff0000, v46
	v_lshlrev_b32_e32 v168, 16, v47
	v_and_b32_e32 v169, 0xffff0000, v47
	v_pk_mul_f32 v[162:163], v[162:163], v[252:253] op_sel_hi:[1,0]
	v_pk_mul_f32 v[164:165], v[164:165], v[252:253] op_sel_hi:[1,0]
	v_pk_mul_f32 v[162:163], v[162:163], v[146:147]
	v_pk_mul_f32 v[164:165], v[164:165], v[148:149]
	v_pk_fma_f32 v[162:163], v[150:151], v[162:163], v[166:167]
	v_pk_fma_f32 v[164:165], v[152:153], v[164:165], v[168:169]
	s_nop 0
	global_store_dwordx4 v241, v[162:165], s[30:31] offset:2048 nt
	s_nop 1
	v_lshlrev_b32_e32 v162, 16, v16
	v_and_b32_e32 v163, 0xffff0000, v16
	v_lshlrev_b32_e32 v164, 16, v17
	v_and_b32_e32 v165, 0xffff0000, v17
	v_lshlrev_b32_e32 v166, 16, v48
	v_and_b32_e32 v167, 0xffff0000, v48
	v_lshlrev_b32_e32 v168, 16, v49
	v_and_b32_e32 v169, 0xffff0000, v49
	v_pk_mul_f32 v[162:163], v[162:163], v[252:253] op_sel_hi:[1,0]
	v_pk_mul_f32 v[164:165], v[164:165], v[252:253] op_sel_hi:[1,0]
	v_pk_mul_f32 v[162:163], v[162:163], v[154:155]
	v_pk_mul_f32 v[164:165], v[164:165], v[156:157]
	v_pk_fma_f32 v[162:163], v[158:159], v[162:163], v[166:167]
	v_pk_fma_f32 v[164:165], v[160:161], v[164:165], v[168:169]
	s_nop 0
	global_store_dwordx4 v241, v[162:165], s[30:31] offset:3072 nt
	s_nop 1
	ds_read_b128 v[146:149], v238 offset:10240
	ds_read_b128 v[150:153], v238 offset:43008
	ds_read_b128 v[154:157], v238 offset:11264
	ds_read_b128 v[158:161], v238 offset:44032
	s_waitcnt lgkmcnt(4)
	v_lshlrev_b32_e32 v162, 16, v18
	v_and_b32_e32 v163, 0xffff0000, v18
	v_lshlrev_b32_e32 v164, 16, v19
	v_and_b32_e32 v165, 0xffff0000, v19
	v_lshlrev_b32_e32 v166, 16, v50
	v_and_b32_e32 v167, 0xffff0000, v50
	v_lshlrev_b32_e32 v168, 16, v51
	v_and_b32_e32 v169, 0xffff0000, v51
	v_pk_mul_f32 v[162:163], v[162:163], v[252:253] op_sel_hi:[1,0]
	v_pk_mul_f32 v[164:165], v[164:165], v[252:253] op_sel_hi:[1,0]
	v_pk_mul_f32 v[162:163], v[162:163], v[130:131]
	v_pk_mul_f32 v[164:165], v[164:165], v[132:133]
	v_pk_fma_f32 v[162:163], v[134:135], v[162:163], v[166:167]
	v_pk_fma_f32 v[164:165], v[136:137], v[164:165], v[168:169]
	s_nop 0
	global_store_dwordx4 v242, v[162:165], s[30:31] offset:0 nt
	s_nop 1
	v_lshlrev_b32_e32 v162, 16, v20
	v_and_b32_e32 v163, 0xffff0000, v20
	v_lshlrev_b32_e32 v164, 16, v21
	v_and_b32_e32 v165, 0xffff0000, v21
	v_lshlrev_b32_e32 v166, 16, v52
	v_and_b32_e32 v167, 0xffff0000, v52
	v_lshlrev_b32_e32 v168, 16, v53
	v_and_b32_e32 v169, 0xffff0000, v53
	v_pk_mul_f32 v[162:163], v[162:163], v[252:253] op_sel_hi:[1,0]
	v_pk_mul_f32 v[164:165], v[164:165], v[252:253] op_sel_hi:[1,0]
	v_pk_mul_f32 v[162:163], v[162:163], v[138:139]
	v_pk_mul_f32 v[164:165], v[164:165], v[140:141]
	v_pk_fma_f32 v[162:163], v[142:143], v[162:163], v[166:167]
	v_pk_fma_f32 v[164:165], v[144:145], v[164:165], v[168:169]
	s_nop 0
	global_store_dwordx4 v242, v[162:165], s[30:31] offset:1024 nt
	s_nop 1
	ds_read_b128 v[130:133], v238 offset:12288
	ds_read_b128 v[134:137], v238 offset:45056
	ds_read_b128 v[138:141], v238 offset:13312
	ds_read_b128 v[142:145], v238 offset:46080
	s_waitcnt lgkmcnt(4)
	v_lshlrev_b32_e32 v162, 16, v22
	v_and_b32_e32 v163, 0xffff0000, v22
	v_lshlrev_b32_e32 v164, 16, v23
	v_and_b32_e32 v165, 0xffff0000, v23
	v_lshlrev_b32_e32 v166, 16, v54
	v_and_b32_e32 v167, 0xffff0000, v54
	v_lshlrev_b32_e32 v168, 16, v55
	v_and_b32_e32 v169, 0xffff0000, v55
	v_pk_mul_f32 v[162:163], v[162:163], v[252:253] op_sel_hi:[1,0]
	v_pk_mul_f32 v[164:165], v[164:165], v[252:253] op_sel_hi:[1,0]
	v_pk_mul_f32 v[162:163], v[162:163], v[146:147]
	v_pk_mul_f32 v[164:165], v[164:165], v[148:149]
	v_pk_fma_f32 v[162:163], v[150:151], v[162:163], v[166:167]
	v_pk_fma_f32 v[164:165], v[152:153], v[164:165], v[168:169]
	s_nop 0
	global_store_dwordx4 v242, v[162:165], s[30:31] offset:2048 nt
	s_nop 1
	v_lshlrev_b32_e32 v162, 16, v24
	v_and_b32_e32 v163, 0xffff0000, v24
	v_lshlrev_b32_e32 v164, 16, v25
	v_and_b32_e32 v165, 0xffff0000, v25
	v_lshlrev_b32_e32 v166, 16, v56
	v_and_b32_e32 v167, 0xffff0000, v56
	v_lshlrev_b32_e32 v168, 16, v57
	v_and_b32_e32 v169, 0xffff0000, v57
	v_pk_mul_f32 v[162:163], v[162:163], v[252:253] op_sel_hi:[1,0]
	v_pk_mul_f32 v[164:165], v[164:165], v[252:253] op_sel_hi:[1,0]
	v_pk_mul_f32 v[162:163], v[162:163], v[154:155]
	v_pk_mul_f32 v[164:165], v[164:165], v[156:157]
	v_pk_fma_f32 v[162:163], v[158:159], v[162:163], v[166:167]
	v_pk_fma_f32 v[164:165], v[160:161], v[164:165], v[168:169]
	s_nop 0
	global_store_dwordx4 v242, v[162:165], s[30:31] offset:3072 nt
	s_nop 1
	ds_read_b128 v[146:149], v238 offset:14336
	ds_read_b128 v[150:153], v238 offset:47104
	ds_read_b128 v[154:157], v238 offset:15360
	ds_read_b128 v[158:161], v238 offset:48128
	s_waitcnt lgkmcnt(4)
	v_lshlrev_b32_e32 v162, 16, v26
	v_and_b32_e32 v163, 0xffff0000, v26
	v_lshlrev_b32_e32 v164, 16, v27
	v_and_b32_e32 v165, 0xffff0000, v27
	v_lshlrev_b32_e32 v166, 16, v58
	v_and_b32_e32 v167, 0xffff0000, v58
	v_lshlrev_b32_e32 v168, 16, v59
	v_and_b32_e32 v169, 0xffff0000, v59
	v_pk_mul_f32 v[162:163], v[162:163], v[252:253] op_sel_hi:[1,0]
	v_pk_mul_f32 v[164:165], v[164:165], v[252:253] op_sel_hi:[1,0]
	v_pk_mul_f32 v[162:163], v[162:163], v[130:131]
	v_pk_mul_f32 v[164:165], v[164:165], v[132:133]
	v_pk_fma_f32 v[162:163], v[134:135], v[162:163], v[166:167]
	v_pk_fma_f32 v[164:165], v[136:137], v[164:165], v[168:169]
	s_nop 0
	global_store_dwordx4 v243, v[162:165], s[30:31] offset:0 nt
	s_nop 1
	v_lshlrev_b32_e32 v162, 16, v28
	v_and_b32_e32 v163, 0xffff0000, v28
	v_lshlrev_b32_e32 v164, 16, v29
	v_and_b32_e32 v165, 0xffff0000, v29
	v_lshlrev_b32_e32 v166, 16, v60
	v_and_b32_e32 v167, 0xffff0000, v60
	v_lshlrev_b32_e32 v168, 16, v61
	v_and_b32_e32 v169, 0xffff0000, v61
	v_pk_mul_f32 v[162:163], v[162:163], v[252:253] op_sel_hi:[1,0]
	v_pk_mul_f32 v[164:165], v[164:165], v[252:253] op_sel_hi:[1,0]
	v_pk_mul_f32 v[162:163], v[162:163], v[138:139]
	v_pk_mul_f32 v[164:165], v[164:165], v[140:141]
	v_pk_fma_f32 v[162:163], v[142:143], v[162:163], v[166:167]
	v_pk_fma_f32 v[164:165], v[144:145], v[164:165], v[168:169]
	s_nop 0
	global_store_dwordx4 v243, v[162:165], s[30:31] offset:1024 nt
	s_nop 1
	s_waitcnt lgkmcnt(0)
	v_lshlrev_b32_e32 v162, 16, v30
	v_and_b32_e32 v163, 0xffff0000, v30
	v_lshlrev_b32_e32 v164, 16, v31
	v_and_b32_e32 v165, 0xffff0000, v31
	v_lshlrev_b32_e32 v166, 16, v62
	v_and_b32_e32 v167, 0xffff0000, v62
	v_lshlrev_b32_e32 v168, 16, v63
	v_and_b32_e32 v169, 0xffff0000, v63
	v_pk_mul_f32 v[162:163], v[162:163], v[252:253] op_sel_hi:[1,0]
	v_pk_mul_f32 v[164:165], v[164:165], v[252:253] op_sel_hi:[1,0]
	v_pk_mul_f32 v[162:163], v[162:163], v[146:147]
	v_pk_mul_f32 v[164:165], v[164:165], v[148:149]
	v_pk_fma_f32 v[162:163], v[150:151], v[162:163], v[166:167]
	v_pk_fma_f32 v[164:165], v[152:153], v[164:165], v[168:169]
	s_nop 0
	global_store_dwordx4 v243, v[162:165], s[30:31] offset:2048 nt
	s_nop 1
	v_lshlrev_b32_e32 v162, 16, v32
	v_and_b32_e32 v163, 0xffff0000, v32
	v_lshlrev_b32_e32 v164, 16, v33
	v_and_b32_e32 v165, 0xffff0000, v33
	v_lshlrev_b32_e32 v166, 16, v64
	v_and_b32_e32 v167, 0xffff0000, v64
	v_lshlrev_b32_e32 v168, 16, v65
	v_and_b32_e32 v169, 0xffff0000, v65
	v_pk_mul_f32 v[162:163], v[162:163], v[252:253] op_sel_hi:[1,0]
	v_pk_mul_f32 v[164:165], v[164:165], v[252:253] op_sel_hi:[1,0]
	v_pk_mul_f32 v[162:163], v[162:163], v[154:155]
	v_pk_mul_f32 v[164:165], v[164:165], v[156:157]
	v_pk_fma_f32 v[162:163], v[158:159], v[162:163], v[166:167]
	v_pk_fma_f32 v[164:165], v[160:161], v[164:165], v[168:169]
	s_nop 0
	global_store_dwordx4 v243, v[162:165], s[30:31] offset:3072 nt
	s_nop 1
	s_add_u32 s30, s30, 0x2000000
	s_addc_u32 s31, s31, 0
	s_waitcnt vmcnt(16)
	ds_read_b128 v[130:133], v238 offset:0
	ds_read_b128 v[134:137], v238 offset:49152
	ds_read_b128 v[138:141], v238 offset:1024
	ds_read_b128 v[142:145], v238 offset:50176
	v_lshlrev_b32_e32 v162, 16, v66
	v_and_b32_e32 v163, 0xffff0000, v66
	v_lshlrev_b32_e32 v164, 16, v67
	v_and_b32_e32 v165, 0xffff0000, v67
	v_pk_mul_f32 v[176:177], v[162:163], v[162:163]
	v_pk_mul_f32 v[178:179], v[164:165], v[164:165]
	v_lshlrev_b32_e32 v166, 16, v68
	v_and_b32_e32 v167, 0xffff0000, v68
	v_lshlrev_b32_e32 v168, 16, v69
	v_and_b32_e32 v169, 0xffff0000, v69
	v_pk_fma_f32 v[176:177], v[166:167], v[166:167], v[176:177]
	v_pk_fma_f32 v[178:179], v[168:169], v[168:169], v[178:179]
	v_lshlrev_b32_e32 v162, 16, v70
	v_and_b32_e32 v163, 0xffff0000, v70
	v_lshlrev_b32_e32 v164, 16, v71
	v_and_b32_e32 v165, 0xffff0000, v71
	v_pk_fma_f32 v[176:177], v[162:163], v[162:163], v[176:177]
	v_pk_fma_f32 v[178:179], v[164:165], v[164:165], v[178:179]
	v_lshlrev_b32_e32 v166, 16, v72
	v_and_b32_e32 v167, 0xffff0000, v72
	v_lshlrev_b32_e32 v168, 16, v73
	v_and_b32_e32 v169, 0xffff0000, v73
	v_pk_fma_f32 v[176:177], v[166:167], v[166:167], v[176:177]
	v_pk_fma_f32 v[178:179], v[168:169], v[168:169], v[178:179]
	v_lshlrev_b32_e32 v162, 16, v74
	v_and_b32_e32 v163, 0xffff0000, v74
	v_lshlrev_b32_e32 v164, 16, v75
	v_and_b32_e32 v165, 0xffff0000, v75
	v_pk_fma_f32 v[176:177], v[162:163], v[162:163], v[176:177]
	v_pk_fma_f32 v[178:179], v[164:165], v[164:165], v[178:179]
	v_lshlrev_b32_e32 v166, 16, v76
	v_and_b32_e32 v167, 0xffff0000, v76
	v_lshlrev_b32_e32 v168, 16, v77
	v_and_b32_e32 v169, 0xffff0000, v77
	v_pk_fma_f32 v[176:177], v[166:167], v[166:167], v[176:177]
	v_pk_fma_f32 v[178:179], v[168:169], v[168:169], v[178:179]
	v_lshlrev_b32_e32 v162, 16, v78
	v_and_b32_e32 v163, 0xffff0000, v78
	v_lshlrev_b32_e32 v164, 16, v79
	v_and_b32_e32 v165, 0xffff0000, v79
	v_pk_fma_f32 v[176:177], v[162:163], v[162:163], v[176:177]
	v_pk_fma_f32 v[178:179], v[164:165], v[164:165], v[178:179]
	v_lshlrev_b32_e32 v166, 16, v80
	v_and_b32_e32 v167, 0xffff0000, v80
	v_lshlrev_b32_e32 v168, 16, v81
	v_and_b32_e32 v169, 0xffff0000, v81
	v_pk_fma_f32 v[176:177], v[166:167], v[166:167], v[176:177]
	v_pk_fma_f32 v[178:179], v[168:169], v[168:169], v[178:179]
	v_lshlrev_b32_e32 v162, 16, v82
	v_and_b32_e32 v163, 0xffff0000, v82
	v_lshlrev_b32_e32 v164, 16, v83
	v_and_b32_e32 v165, 0xffff0000, v83
	v_pk_fma_f32 v[176:177], v[162:163], v[162:163], v[176:177]
	v_pk_fma_f32 v[178:179], v[164:165], v[164:165], v[178:179]
	v_lshlrev_b32_e32 v166, 16, v84
	v_and_b32_e32 v167, 0xffff0000, v84
	v_lshlrev_b32_e32 v168, 16, v85
	v_and_b32_e32 v169, 0xffff0000, v85
	v_pk_fma_f32 v[176:177], v[166:167], v[166:167], v[176:177]
	v_pk_fma_f32 v[178:179], v[168:169], v[168:169], v[178:179]
	v_lshlrev_b32_e32 v162, 16, v86
	v_and_b32_e32 v163, 0xffff0000, v86
	v_lshlrev_b32_e32 v164, 16, v87
	v_and_b32_e32 v165, 0xffff0000, v87
	v_pk_fma_f32 v[176:177], v[162:163], v[162:163], v[176:177]
	v_pk_fma_f32 v[178:179], v[164:165], v[164:165], v[178:179]
	v_lshlrev_b32_e32 v166, 16, v88
	v_and_b32_e32 v167, 0xffff0000, v88
	v_lshlrev_b32_e32 v168, 16, v89
	v_and_b32_e32 v169, 0xffff0000, v89
	v_pk_fma_f32 v[176:177], v[166:167], v[166:167], v[176:177]
	v_pk_fma_f32 v[178:179], v[168:169], v[168:169], v[178:179]
	v_lshlrev_b32_e32 v162, 16, v90
	v_and_b32_e32 v163, 0xffff0000, v90
	v_lshlrev_b32_e32 v164, 16, v91
	v_and_b32_e32 v165, 0xffff0000, v91
	v_pk_fma_f32 v[176:177], v[162:163], v[162:163], v[176:177]
	v_pk_fma_f32 v[178:179], v[164:165], v[164:165], v[178:179]
	v_lshlrev_b32_e32 v166, 16, v92
	v_and_b32_e32 v167, 0xffff0000, v92
	v_lshlrev_b32_e32 v168, 16, v93
	v_and_b32_e32 v169, 0xffff0000, v93
	v_pk_fma_f32 v[176:177], v[166:167], v[166:167], v[176:177]
	v_pk_fma_f32 v[178:179], v[168:169], v[168:169], v[178:179]
	v_lshlrev_b32_e32 v162, 16, v94
	v_and_b32_e32 v163, 0xffff0000, v94
	v_lshlrev_b32_e32 v164, 16, v95
	v_and_b32_e32 v165, 0xffff0000, v95
	v_pk_fma_f32 v[176:177], v[162:163], v[162:163], v[176:177]
	v_pk_fma_f32 v[178:179], v[164:165], v[164:165], v[178:179]
	v_lshlrev_b32_e32 v166, 16, v96
	v_and_b32_e32 v167, 0xffff0000, v96
	v_lshlrev_b32_e32 v168, 16, v97
	v_and_b32_e32 v169, 0xffff0000, v97
	v_pk_fma_f32 v[176:177], v[166:167], v[166:167], v[176:177]
	v_pk_fma_f32 v[178:179], v[168:169], v[168:169], v[178:179]
	v_pk_add_f32 v[176:177], v[176:177], v[178:179]
	s_nop 0
	v_add_f32_e32 v252, v176, v177
	s_waitcnt lgkmcnt(0)
	ds_bpermute_b32 v254, v246, v252
	s_waitcnt lgkmcnt(0)
	v_add_f32_e32 v252, v252, v254
	ds_bpermute_b32 v254, v247, v252
	s_waitcnt lgkmcnt(0)
	v_add_f32_e32 v252, v252, v254
	ds_bpermute_b32 v254, v248, v252
	s_waitcnt lgkmcnt(0)
	v_add_f32_e32 v252, v252, v254
	ds_bpermute_b32 v254, v249, v252
	s_waitcnt lgkmcnt(0)
	v_add_f32_e32 v252, v252, v254
	ds_bpermute_b32 v254, v250, v252
	s_waitcnt lgkmcnt(0)
	v_add_f32_e32 v252, v252, v254
	ds_bpermute_b32 v254, v251, v252
	s_waitcnt lgkmcnt(0)
	v_add_f32_e32 v252, v252, v254
	v_mov_b32_e32 v254, 0x358637bd
	v_fmac_f32_e32 v254, 0x39800000, v252
	v_mul_f32_e32 v252, 0x4b800000, v254
	v_cmp_gt_f32_e32 vcc, s20, v254
	s_nop 1
	v_cndmask_b32_e32 v254, v254, v252, vcc
	v_rsq_f32_e32 v254, v254
	s_nop 0
	v_mul_f32_e32 v252, 0x45800000, v254
	v_cndmask_b32_e32 v252, v254, v252, vcc
	ds_read_b128 v[146:149], v238 offset:2048
	ds_read_b128 v[150:153], v238 offset:51200
	ds_read_b128 v[154:157], v238 offset:3072
	ds_read_b128 v[158:161], v238 offset:52224
	s_waitcnt lgkmcnt(4)
	v_lshlrev_b32_e32 v162, 16, v66
	v_and_b32_e32 v163, 0xffff0000, v66
	v_lshlrev_b32_e32 v164, 16, v67
	v_and_b32_e32 v165, 0xffff0000, v67
	v_lshlrev_b32_e32 v166, 16, v98
	v_and_b32_e32 v167, 0xffff0000, v98
	v_lshlrev_b32_e32 v168, 16, v99
	v_and_b32_e32 v169, 0xffff0000, v99
	v_pk_mul_f32 v[162:163], v[162:163], v[252:253] op_sel_hi:[1,0]
	v_pk_mul_f32 v[164:165], v[164:165], v[252:253] op_sel_hi:[1,0]
	v_pk_mul_f32 v[162:163], v[162:163], v[130:131]
	v_pk_mul_f32 v[164:165], v[164:165], v[132:133]
	v_pk_fma_f32 v[162:163], v[134:135], v[162:163], v[166:167]
	v_pk_fma_f32 v[164:165], v[136:137], v[164:165], v[168:169]
	s_nop 0
	global_store_dwordx4 v238, v[162:165], s[30:31] offset:0 nt
	s_nop 1
	v_lshlrev_b32_e32 v162, 16, v68
	v_and_b32_e32 v163, 0xffff0000, v68
	v_lshlrev_b32_e32 v164, 16, v69
	v_and_b32_e32 v165, 0xffff0000, v69
	v_lshlrev_b32_e32 v166, 16, v100
	v_and_b32_e32 v167, 0xffff0000, v100
	v_lshlrev_b32_e32 v168, 16, v101
	v_and_b32_e32 v169, 0xffff0000, v101
	v_pk_mul_f32 v[162:163], v[162:163], v[252:253] op_sel_hi:[1,0]
	v_pk_mul_f32 v[164:165], v[164:165], v[252:253] op_sel_hi:[1,0]
	v_pk_mul_f32 v[162:163], v[162:163], v[138:139]
	v_pk_mul_f32 v[164:165], v[164:165], v[140:141]
	v_pk_fma_f32 v[162:163], v[142:143], v[162:163], v[166:167]
	v_pk_fma_f32 v[164:165], v[144:145], v[164:165], v[168:169]
	s_nop 0
	global_store_dwordx4 v238, v[162:165], s[30:31] offset:1024 nt
	s_nop 1
	ds_read_b128 v[130:133], v238 offset:4096
	ds_read_b128 v[134:137], v238 offset:53248
	ds_read_b128 v[138:141], v238 offset:5120
	ds_read_b128 v[142:145], v238 offset:54272
	s_waitcnt lgkmcnt(4)
	v_lshlrev_b32_e32 v162, 16, v70
	v_and_b32_e32 v163, 0xffff0000, v70
	v_lshlrev_b32_e32 v164, 16, v71
	v_and_b32_e32 v165, 0xffff0000, v71
	v_lshlrev_b32_e32 v166, 16, v102
	v_and_b32_e32 v167, 0xffff0000, v102
	v_lshlrev_b32_e32 v168, 16, v103
	v_and_b32_e32 v169, 0xffff0000, v103
	v_pk_mul_f32 v[162:163], v[162:163], v[252:253] op_sel_hi:[1,0]
	v_pk_mul_f32 v[164:165], v[164:165], v[252:253] op_sel_hi:[1,0]
	v_pk_mul_f32 v[162:163], v[162:163], v[146:147]
	v_pk_mul_f32 v[164:165], v[164:165], v[148:149]
	v_pk_fma_f32 v[162:163], v[150:151], v[162:163], v[166:167]
	v_pk_fma_f32 v[164:165], v[152:153], v[164:165], v[168:169]
	s_nop 0
	global_store_dwordx4 v238, v[162:165], s[30:31] offset:2048 nt
	s_nop 1
	v_lshlrev_b32_e32 v162, 16, v72
	v_and_b32_e32 v163, 0xffff0000, v72
	v_lshlrev_b32_e32 v164, 16, v73
	v_and_b32_e32 v165, 0xffff0000, v73
	v_lshlrev_b32_e32 v166, 16, v104
	v_and_b32_e32 v167, 0xffff0000, v104
	v_lshlrev_b32_e32 v168, 16, v105
	v_and_b32_e32 v169, 0xffff0000, v105
	v_pk_mul_f32 v[162:163], v[162:163], v[252:253] op_sel_hi:[1,0]
	v_pk_mul_f32 v[164:165], v[164:165], v[252:253] op_sel_hi:[1,0]
	v_pk_mul_f32 v[162:163], v[162:163], v[154:155]
	v_pk_mul_f32 v[164:165], v[164:165], v[156:157]
	v_pk_fma_f32 v[162:163], v[158:159], v[162:163], v[166:167]
	v_pk_fma_f32 v[164:165], v[160:161], v[164:165], v[168:169]
	s_nop 0
	global_store_dwordx4 v238, v[162:165], s[30:31] offset:3072 nt
	s_nop 1
	ds_read_b128 v[146:149], v238 offset:6144
	ds_read_b128 v[150:153], v238 offset:55296
	ds_read_b128 v[154:157], v238 offset:7168
	ds_read_b128 v[158:161], v238 offset:56320
	s_waitcnt lgkmcnt(4)
	v_lshlrev_b32_e32 v162, 16, v74
	v_and_b32_e32 v163, 0xffff0000, v74
	v_lshlrev_b32_e32 v164, 16, v75
	v_and_b32_e32 v165, 0xffff0000, v75
	v_lshlrev_b32_e32 v166, 16, v106
	v_and_b32_e32 v167, 0xffff0000, v106
	v_lshlrev_b32_e32 v168, 16, v107
	v_and_b32_e32 v169, 0xffff0000, v107
	v_pk_mul_f32 v[162:163], v[162:163], v[252:253] op_sel_hi:[1,0]
	v_pk_mul_f32 v[164:165], v[164:165], v[252:253] op_sel_hi:[1,0]
	v_pk_mul_f32 v[162:163], v[162:163], v[130:131]
	v_pk_mul_f32 v[164:165], v[164:165], v[132:133]
	v_pk_fma_f32 v[162:163], v[134:135], v[162:163], v[166:167]
	v_pk_fma_f32 v[164:165], v[136:137], v[164:165], v[168:169]
	s_nop 0
	global_store_dwordx4 v241, v[162:165], s[30:31] offset:0 nt
	s_nop 1
	v_lshlrev_b32_e32 v162, 16, v76
	v_and_b32_e32 v163, 0xffff0000, v76
	v_lshlrev_b32_e32 v164, 16, v77
	v_and_b32_e32 v165, 0xffff0000, v77
	v_lshlrev_b32_e32 v166, 16, v108
	v_and_b32_e32 v167, 0xffff0000, v108
	v_lshlrev_b32_e32 v168, 16, v109
	v_and_b32_e32 v169, 0xffff0000, v109
	v_pk_mul_f32 v[162:163], v[162:163], v[252:253] op_sel_hi:[1,0]
	v_pk_mul_f32 v[164:165], v[164:165], v[252:253] op_sel_hi:[1,0]
	v_pk_mul_f32 v[162:163], v[162:163], v[138:139]
	v_pk_mul_f32 v[164:165], v[164:165], v[140:141]
	v_pk_fma_f32 v[162:163], v[142:143], v[162:163], v[166:167]
	v_pk_fma_f32 v[164:165], v[144:145], v[164:165], v[168:169]
	s_nop 0
	global_store_dwordx4 v241, v[162:165], s[30:31] offset:1024 nt
	s_nop 1
	ds_read_b128 v[130:133], v238 offset:8192
	ds_read_b128 v[134:137], v238 offset:57344
	ds_read_b128 v[138:141], v238 offset:9216
	ds_read_b128 v[142:145], v238 offset:58368
	s_waitcnt lgkmcnt(4)
	v_lshlrev_b32_e32 v162, 16, v78
	v_and_b32_e32 v163, 0xffff0000, v78
	v_lshlrev_b32_e32 v164, 16, v79
	v_and_b32_e32 v165, 0xffff0000, v79
	v_lshlrev_b32_e32 v166, 16, v110
	v_and_b32_e32 v167, 0xffff0000, v110
	v_lshlrev_b32_e32 v168, 16, v111
	v_and_b32_e32 v169, 0xffff0000, v111
	v_pk_mul_f32 v[162:163], v[162:163], v[252:253] op_sel_hi:[1,0]
	v_pk_mul_f32 v[164:165], v[164:165], v[252:253] op_sel_hi:[1,0]
	v_pk_mul_f32 v[162:163], v[162:163], v[146:147]
	v_pk_mul_f32 v[164:165], v[164:165], v[148:149]
	v_pk_fma_f32 v[162:163], v[150:151], v[162:163], v[166:167]
	v_pk_fma_f32 v[164:165], v[152:153], v[164:165], v[168:169]
	s_nop 0
	global_store_dwordx4 v241, v[162:165], s[30:31] offset:2048 nt
	s_nop 1
	v_lshlrev_b32_e32 v162, 16, v80
	v_and_b32_e32 v163, 0xffff0000, v80
	v_lshlrev_b32_e32 v164, 16, v81
	v_and_b32_e32 v165, 0xffff0000, v81
	v_lshlrev_b32_e32 v166, 16, v112
	v_and_b32_e32 v167, 0xffff0000, v112
	v_lshlrev_b32_e32 v168, 16, v113
	v_and_b32_e32 v169, 0xffff0000, v113
	v_pk_mul_f32 v[162:163], v[162:163], v[252:253] op_sel_hi:[1,0]
	v_pk_mul_f32 v[164:165], v[164:165], v[252:253] op_sel_hi:[1,0]
	v_pk_mul_f32 v[162:163], v[162:163], v[154:155]
	v_pk_mul_f32 v[164:165], v[164:165], v[156:157]
	v_pk_fma_f32 v[162:163], v[158:159], v[162:163], v[166:167]
	v_pk_fma_f32 v[164:165], v[160:161], v[164:165], v[168:169]
	s_nop 0
	global_store_dwordx4 v241, v[162:165], s[30:31] offset:3072 nt
	s_nop 1
	ds_read_b128 v[146:149], v238 offset:10240
	ds_read_b128 v[150:153], v238 offset:59392
	ds_read_b128 v[154:157], v238 offset:11264
	ds_read_b128 v[158:161], v238 offset:60416
	s_waitcnt lgkmcnt(4)
	v_lshlrev_b32_e32 v162, 16, v82
	v_and_b32_e32 v163, 0xffff0000, v82
	v_lshlrev_b32_e32 v164, 16, v83
	v_and_b32_e32 v165, 0xffff0000, v83
	v_lshlrev_b32_e32 v166, 16, v114
	v_and_b32_e32 v167, 0xffff0000, v114
	v_lshlrev_b32_e32 v168, 16, v115
	v_and_b32_e32 v169, 0xffff0000, v115
	v_pk_mul_f32 v[162:163], v[162:163], v[252:253] op_sel_hi:[1,0]
	v_pk_mul_f32 v[164:165], v[164:165], v[252:253] op_sel_hi:[1,0]
	v_pk_mul_f32 v[162:163], v[162:163], v[130:131]
	v_pk_mul_f32 v[164:165], v[164:165], v[132:133]
	v_pk_fma_f32 v[162:163], v[134:135], v[162:163], v[166:167]
	v_pk_fma_f32 v[164:165], v[136:137], v[164:165], v[168:169]
	s_nop 0
	global_store_dwordx4 v242, v[162:165], s[30:31] offset:0 nt
	s_nop 1
	v_lshlrev_b32_e32 v162, 16, v84
	v_and_b32_e32 v163, 0xffff0000, v84
	v_lshlrev_b32_e32 v164, 16, v85
	v_and_b32_e32 v165, 0xffff0000, v85
	v_lshlrev_b32_e32 v166, 16, v116
	v_and_b32_e32 v167, 0xffff0000, v116
	v_lshlrev_b32_e32 v168, 16, v117
	v_and_b32_e32 v169, 0xffff0000, v117
	v_pk_mul_f32 v[162:163], v[162:163], v[252:253] op_sel_hi:[1,0]
	v_pk_mul_f32 v[164:165], v[164:165], v[252:253] op_sel_hi:[1,0]
	v_pk_mul_f32 v[162:163], v[162:163], v[138:139]
	v_pk_mul_f32 v[164:165], v[164:165], v[140:141]
	v_pk_fma_f32 v[162:163], v[142:143], v[162:163], v[166:167]
	v_pk_fma_f32 v[164:165], v[144:145], v[164:165], v[168:169]
	s_nop 0
	global_store_dwordx4 v242, v[162:165], s[30:31] offset:1024 nt
	s_nop 1
	ds_read_b128 v[130:133], v238 offset:12288
	ds_read_b128 v[134:137], v238 offset:61440
	ds_read_b128 v[138:141], v238 offset:13312
	ds_read_b128 v[142:145], v238 offset:62464
	s_waitcnt lgkmcnt(4)
	v_lshlrev_b32_e32 v162, 16, v86
	v_and_b32_e32 v163, 0xffff0000, v86
	v_lshlrev_b32_e32 v164, 16, v87
	v_and_b32_e32 v165, 0xffff0000, v87
	v_lshlrev_b32_e32 v166, 16, v118
	v_and_b32_e32 v167, 0xffff0000, v118
	v_lshlrev_b32_e32 v168, 16, v119
	v_and_b32_e32 v169, 0xffff0000, v119
	v_pk_mul_f32 v[162:163], v[162:163], v[252:253] op_sel_hi:[1,0]
	v_pk_mul_f32 v[164:165], v[164:165], v[252:253] op_sel_hi:[1,0]
	v_pk_mul_f32 v[162:163], v[162:163], v[146:147]
	v_pk_mul_f32 v[164:165], v[164:165], v[148:149]
	v_pk_fma_f32 v[162:163], v[150:151], v[162:163], v[166:167]
	v_pk_fma_f32 v[164:165], v[152:153], v[164:165], v[168:169]
	s_nop 0
	global_store_dwordx4 v242, v[162:165], s[30:31] offset:2048 nt
	s_nop 1
	v_lshlrev_b32_e32 v162, 16, v88
	v_and_b32_e32 v163, 0xffff0000, v88
	v_lshlrev_b32_e32 v164, 16, v89
	v_and_b32_e32 v165, 0xffff0000, v89
	v_lshlrev_b32_e32 v166, 16, v120
	v_and_b32_e32 v167, 0xffff0000, v120
	v_lshlrev_b32_e32 v168, 16, v121
	v_and_b32_e32 v169, 0xffff0000, v121
	v_pk_mul_f32 v[162:163], v[162:163], v[252:253] op_sel_hi:[1,0]
	v_pk_mul_f32 v[164:165], v[164:165], v[252:253] op_sel_hi:[1,0]
	v_pk_mul_f32 v[162:163], v[162:163], v[154:155]
	v_pk_mul_f32 v[164:165], v[164:165], v[156:157]
	v_pk_fma_f32 v[162:163], v[158:159], v[162:163], v[166:167]
	v_pk_fma_f32 v[164:165], v[160:161], v[164:165], v[168:169]
	s_nop 0
	global_store_dwordx4 v242, v[162:165], s[30:31] offset:3072 nt
	s_nop 1
	ds_read_b128 v[146:149], v238 offset:14336
	ds_read_b128 v[150:153], v238 offset:63488
	ds_read_b128 v[154:157], v238 offset:15360
	ds_read_b128 v[158:161], v238 offset:64512
	s_waitcnt lgkmcnt(4)
	v_lshlrev_b32_e32 v162, 16, v90
	v_and_b32_e32 v163, 0xffff0000, v90
	v_lshlrev_b32_e32 v164, 16, v91
	v_and_b32_e32 v165, 0xffff0000, v91
	v_lshlrev_b32_e32 v166, 16, v122
	v_and_b32_e32 v167, 0xffff0000, v122
	v_lshlrev_b32_e32 v168, 16, v123
	v_and_b32_e32 v169, 0xffff0000, v123
	v_pk_mul_f32 v[162:163], v[162:163], v[252:253] op_sel_hi:[1,0]
	v_pk_mul_f32 v[164:165], v[164:165], v[252:253] op_sel_hi:[1,0]
	v_pk_mul_f32 v[162:163], v[162:163], v[130:131]
	v_pk_mul_f32 v[164:165], v[164:165], v[132:133]
	v_pk_fma_f32 v[162:163], v[134:135], v[162:163], v[166:167]
	v_pk_fma_f32 v[164:165], v[136:137], v[164:165], v[168:169]
	s_nop 0
	global_store_dwordx4 v243, v[162:165], s[30:31] offset:0 nt
	s_nop 1
	v_lshlrev_b32_e32 v162, 16, v92
	v_and_b32_e32 v163, 0xffff0000, v92
	v_lshlrev_b32_e32 v164, 16, v93
	v_and_b32_e32 v165, 0xffff0000, v93
	v_lshlrev_b32_e32 v166, 16, v124
	v_and_b32_e32 v167, 0xffff0000, v124
	v_lshlrev_b32_e32 v168, 16, v125
	v_and_b32_e32 v169, 0xffff0000, v125
	v_pk_mul_f32 v[162:163], v[162:163], v[252:253] op_sel_hi:[1,0]
	v_pk_mul_f32 v[164:165], v[164:165], v[252:253] op_sel_hi:[1,0]
	v_pk_mul_f32 v[162:163], v[162:163], v[138:139]
	v_pk_mul_f32 v[164:165], v[164:165], v[140:141]
	v_pk_fma_f32 v[162:163], v[142:143], v[162:163], v[166:167]
	v_pk_fma_f32 v[164:165], v[144:145], v[164:165], v[168:169]
	s_nop 0
	global_store_dwordx4 v243, v[162:165], s[30:31] offset:1024 nt
	s_nop 1
	s_waitcnt lgkmcnt(0)
	v_lshlrev_b32_e32 v162, 16, v94
	v_and_b32_e32 v163, 0xffff0000, v94
	v_lshlrev_b32_e32 v164, 16, v95
	v_and_b32_e32 v165, 0xffff0000, v95
	v_lshlrev_b32_e32 v166, 16, v126
	v_and_b32_e32 v167, 0xffff0000, v126
	v_lshlrev_b32_e32 v168, 16, v127
	v_and_b32_e32 v169, 0xffff0000, v127
	v_pk_mul_f32 v[162:163], v[162:163], v[252:253] op_sel_hi:[1,0]
	v_pk_mul_f32 v[164:165], v[164:165], v[252:253] op_sel_hi:[1,0]
	v_pk_mul_f32 v[162:163], v[162:163], v[146:147]
	v_pk_mul_f32 v[164:165], v[164:165], v[148:149]
	v_pk_fma_f32 v[162:163], v[150:151], v[162:163], v[166:167]
	v_pk_fma_f32 v[164:165], v[152:153], v[164:165], v[168:169]
	s_nop 0
	global_store_dwordx4 v243, v[162:165], s[30:31] offset:2048 nt
	s_nop 1
	v_lshlrev_b32_e32 v162, 16, v96
	v_and_b32_e32 v163, 0xffff0000, v96
	v_lshlrev_b32_e32 v164, 16, v97
	v_and_b32_e32 v165, 0xffff0000, v97
	v_lshlrev_b32_e32 v166, 16, v128
	v_and_b32_e32 v167, 0xffff0000, v128
	v_lshlrev_b32_e32 v168, 16, v129
	v_and_b32_e32 v169, 0xffff0000, v129
	v_pk_mul_f32 v[162:163], v[162:163], v[252:253] op_sel_hi:[1,0]
	v_pk_mul_f32 v[164:165], v[164:165], v[252:253] op_sel_hi:[1,0]
	v_pk_mul_f32 v[162:163], v[162:163], v[154:155]
	v_pk_mul_f32 v[164:165], v[164:165], v[156:157]
	v_pk_fma_f32 v[162:163], v[158:159], v[162:163], v[166:167]
	v_pk_fma_f32 v[164:165], v[160:161], v[164:165], v[168:169]
	s_nop 0
	global_store_dwordx4 v243, v[162:165], s[30:31] offset:3072 nt
	s_nop 1
	s_branch .LBB0_988
